# all global stores write-through (sc0 sc1) so the barrier's L2 writeback has nothing left to flush
# baseline (speedup 1.0000x reference)
; #define LAS __attribute__((address_space(3)))
; __device__ __forceinline__ unsigned pk2(float lo, float hi) { unsigned r; asm("v_cvt_pk_bf16_f32 %0, %1, %2" : "=v"(r) : "v"(lo), "v"(hi)); return r; }
; __device__ __forceinline__ void tr_item(const float* W, int K, int N, bf16_t* WT, int ldt, LAS float* scr, int item, int lane, int mapmode, int p0, int p1) {
;     ...
;     for (int j = 0; j < 4; ++j) { const int n = (lane >> 3) + 8 * j; const LAS float* s = scr + (8 * c) * 33 + n;
;         u32x4 o; o.x = pk2(s[0 * 33], s[1 * 33]); o.y = pk2(s[2 * 33], s[3 * 33]); o.z = pk2(s[4 * 33], s[5 * 33]); o.w = pk2(s[6 * 33], s[7 * 33]);
;         const int ns = n0 + n; int dst;
;         if (mapmode == 0) dst = p0 + (ns & ~255) + 128 * ((ns >> 5) & 1) + 32 * ((ns >> 6) & 3) + (ns & 31);
;         else if (mapmode == 1) dst = (ns >= p0 && ns < p1) ? ((ns & ~127) + il128(ns & 127)) : ns;
;         else dst = 256 * (ns >> 7) + 128 * ((ns >> 2) & 1) + 32 * ((ns >> 5) & 3) + 8 * ((ns >> 3) & 3) + 4 * p0 + (ns & 3);
;         *(u32x4*)(WT + (size_t)dst * ldt + k0 + 8 * c) = o; }
.LBB0_11:
	v_mul_lo_u32 v48, v8, s12
	v_ashrrev_i32_e32 v49, 31, v48
	v_lshl_add_u64 v[34:35], v[34:35], 0, v[48:49]
	global_store_dwordx4 v[34:35], v[2:5], off sc0 sc1
	s_waitcnt lgkmcnt(0)

; __device__ __forceinline__ void tr_item(const float* W, int K, int N, bf16_t* WT, int ldt, LAS float* scr, int item, int lane, int mapmode, int p0, int p1) {
;     const int nblk = N / 32, kb = item / nblk, nb = item % nblk, k0 = 64 * kb, n0 = 32 * nb;
; #pragma unroll 8
;     for (int i = 0; i < 32; ++i) { const int kk = 2 * i + (lane >> 5); scr[kk * 33 + (lane & 31)] = W[(size_t)(k0 + kk) * N + n0 + (lane & 31)]; }
;     asm volatile("s_waitcnt lgkmcnt(0)" ::: "memory");
.LBB0_20:
	s_lshl_b32 s17, s9, 1
	s_lshl_b32 s18, s15, 1
	v_or_b32_e32 v8, s17, v1
	v_or_b32_e32 v33, s18, v6
	s_add_i32 s19, s17, 4
	s_add_i32 s20, s18, 4
	s_add_i32 s21, s17, 8
	s_add_i32 s22, s18, 8
	s_add_i32 s23, s17, 12
	s_add_i32 s25, s18, 12
	s_add_i32 s27, s17, 16
	s_add_i32 s33, s18, 16
	s_add_i32 s35, s17, 20
	s_add_i32 s36, s18, 20
	s_add_i32 s37, s17, 24
	s_add_i32 s38, s18, 24
	s_add_i32 s17, s17, 28
	s_add_i32 s18, s18, 28
	v_add_u32_e32 v34, s0, v33
	v_or_b32_e32 v76, s19, v1
	v_or_b32_e32 v77, s20, v6
	v_or_b32_e32 v78, s21, v1
	v_or_b32_e32 v79, s22, v6
	v_or_b32_e32 v80, s23, v1
	v_or_b32_e32 v81, s25, v6
	v_or_b32_e32 v82, s27, v1
	v_or_b32_e32 v83, s33, v6
	v_or_b32_e32 v84, s35, v1
	v_or_b32_e32 v85, s36, v6
	v_or_b32_e32 v86, s37, v1
	v_or_b32_e32 v87, s38, v6
	v_or_b32_e32 v88, s17, v1
	v_or_b32_e32 v89, s18, v6
	v_add_u32_e32 v4, s1, v8
	v_ashrrev_i32_e32 v35, 31, v34
	v_add_u32_e32 v48, s1, v76
	v_add_u32_e32 v50, s0, v77
	v_add_u32_e32 v52, s1, v78
	v_add_u32_e32 v54, s0, v79
	v_add_u32_e32 v56, s1, v80
	v_add_u32_e32 v58, s0, v81
	v_add_u32_e32 v60, s1, v82
	v_add_u32_e32 v62, s0, v83
	v_add_u32_e32 v64, s1, v84
	v_add_u32_e32 v66, s0, v85
	v_add_u32_e32 v68, s1, v86
	v_add_u32_e32 v70, s0, v87
	v_add_u32_e32 v72, s1, v88
	v_add_u32_e32 v74, s0, v89
	v_ashrrev_i32_e32 v5, 31, v4
	v_lshlrev_b64 v[34:35], 13, v[34:35]
	v_ashrrev_i32_e32 v51, 31, v50
	v_ashrrev_i32_e32 v49, 31, v48
	v_ashrrev_i32_e32 v55, 31, v54
	v_ashrrev_i32_e32 v53, 31, v52
	v_ashrrev_i32_e32 v59, 31, v58
	v_ashrrev_i32_e32 v57, 31, v56
	v_ashrrev_i32_e32 v63, 31, v62
	v_ashrrev_i32_e32 v61, 31, v60
	v_ashrrev_i32_e32 v67, 31, v66
	v_ashrrev_i32_e32 v65, 31, v64
	v_ashrrev_i32_e32 v71, 31, v70
	v_ashrrev_i32_e32 v69, 31, v68
	v_ashrrev_i32_e32 v75, 31, v74
	v_ashrrev_i32_e32 v73, 31, v72
	v_lshlrev_b64 v[4:5], 13, v[4:5]
	v_lshl_add_u64 v[34:35], v[2:3], 0, v[34:35]
	v_lshlrev_b64 v[48:49], 13, v[48:49]
	v_lshlrev_b64 v[50:51], 13, v[50:51]
	v_lshlrev_b64 v[52:53], 13, v[52:53]
	v_lshlrev_b64 v[54:55], 13, v[54:55]
	v_lshlrev_b64 v[56:57], 13, v[56:57]
	v_lshlrev_b64 v[58:59], 13, v[58:59]
	v_lshlrev_b64 v[60:61], 13, v[60:61]
	v_lshlrev_b64 v[62:63], 13, v[62:63]
	v_lshlrev_b64 v[64:65], 13, v[64:65]
	v_lshlrev_b64 v[66:67], 13, v[66:67]
	v_lshlrev_b64 v[68:69], 13, v[68:69]
	v_lshlrev_b64 v[70:71], 13, v[70:71]
	v_lshlrev_b64 v[72:73], 13, v[72:73]
	v_lshlrev_b64 v[74:75], 13, v[74:75]
	v_lshl_add_u64 v[4:5], v[2:3], 0, v[4:5]
	v_lshl_add_u64 v[50:51], v[2:3], 0, v[50:51]
	v_lshl_add_u64 v[48:49], v[2:3], 0, v[48:49]
	v_lshl_add_u64 v[54:55], v[2:3], 0, v[54:55]
	v_lshl_add_u64 v[52:53], v[2:3], 0, v[52:53]
	v_lshl_add_u64 v[58:59], v[2:3], 0, v[58:59]
	v_lshl_add_u64 v[56:57], v[2:3], 0, v[56:57]
	v_lshl_add_u64 v[62:63], v[2:3], 0, v[62:63]
	v_lshl_add_u64 v[60:61], v[2:3], 0, v[60:61]
	v_lshl_add_u64 v[66:67], v[2:3], 0, v[66:67]
	v_lshl_add_u64 v[64:65], v[2:3], 0, v[64:65]
	v_lshl_add_u64 v[70:71], v[2:3], 0, v[70:71]
	v_lshl_add_u64 v[68:69], v[2:3], 0, v[68:69]
	v_lshl_add_u64 v[74:75], v[2:3], 0, v[74:75]
	v_lshl_add_u64 v[72:73], v[2:3], 0, v[72:73]
	global_load_dword v90, v[34:35], off
	global_load_dword v91, v[4:5], off
	global_load_dword v92, v[50:51], off
	global_load_dword v93, v[48:49], off
	global_load_dword v94, v[54:55], off
	global_load_dword v95, v[52:53], off
	global_load_dword v96, v[58:59], off
	global_load_dword v97, v[56:57], off
	global_load_dword v98, v[62:63], off
	global_load_dword v99, v[60:61], off
	global_load_dword v100, v[66:67], off
	global_load_dword v101, v[64:65], off
	global_load_dword v102, v[70:71], off
	global_load_dword v103, v[68:69], off
	global_load_dword v104, v[74:75], off
	global_load_dword v105, v[72:73], off
	s_add_i32 s15, s15, 16
	s_add_i32 s9, s9, 16
	s_add_i32 s16, s16, -16
	v_mad_u64_u32 v[4:5], s[18:19], v33, s10, v[12:13]
	s_cmp_lg_u32 s16, 0
	v_mad_u64_u32 v[34:35], s[18:19], v8, s10, v[12:13]
	v_mad_u64_u32 v[48:49], s[18:19], v77, s10, v[12:13]
	v_mad_u64_u32 v[50:51], s[18:19], v76, s10, v[12:13]
	v_mad_u64_u32 v[52:53], s[18:19], v79, s10, v[12:13]
	v_mad_u64_u32 v[54:55], s[18:19], v78, s10, v[12:13]
	v_mad_u64_u32 v[56:57], s[18:19], v81, s10, v[12:13]
	v_mad_u64_u32 v[58:59], s[18:19], v80, s10, v[12:13]
	v_mad_u64_u32 v[60:61], s[18:19], v83, s10, v[12:13]
	v_mad_u64_u32 v[62:63], s[18:19], v82, s10, v[12:13]
	v_mad_u64_u32 v[64:65], s[18:19], v85, s10, v[12:13]
	v_mad_u64_u32 v[66:67], s[18:19], v84, s10, v[12:13]
	v_mad_u64_u32 v[68:69], s[18:19], v87, s10, v[12:13]
	v_mad_u64_u32 v[70:71], s[18:19], v86, s10, v[12:13]
	v_mad_u64_u32 v[72:73], s[18:19], v89, s10, v[12:13]
	v_mad_u64_u32 v[74:75], s[18:19], v88, s10, v[12:13]
	s_waitcnt vmcnt(15)
	ds_write_b32 v4, v90
	s_waitcnt vmcnt(14)
	ds_write_b32 v34, v91
	s_waitcnt vmcnt(13)
	ds_write_b32 v48, v92
	s_waitcnt vmcnt(12)
	ds_write_b32 v50, v93
	s_waitcnt vmcnt(11)
	ds_write_b32 v52, v94
	s_waitcnt vmcnt(10)
	ds_write_b32 v54, v95
	s_waitcnt vmcnt(9)
	ds_write_b32 v56, v96
	s_waitcnt vmcnt(8)
	ds_write_b32 v58, v97
	s_waitcnt vmcnt(7)
	ds_write_b32 v60, v98
	s_waitcnt vmcnt(6)
	ds_write_b32 v62, v99
	s_waitcnt vmcnt(5)
	ds_write_b32 v64, v100
	s_waitcnt vmcnt(4)
	ds_write_b32 v66, v101
	s_waitcnt vmcnt(3)
	ds_write_b32 v68, v102
	s_waitcnt vmcnt(2)
	ds_write_b32 v70, v103
	s_waitcnt vmcnt(1)
	ds_write_b32 v72, v104
	s_waitcnt vmcnt(0)
	ds_write_b32 v74, v105
	s_cbranch_scc1 .LBB0_20
; #define LAS __attribute__((address_space(3)))
; __device__ __forceinline__ unsigned pk2(float lo, float hi) { unsigned r; asm("v_cvt_pk_bf16_f32 %0, %1, %2" : "=v"(r) : "v"(lo), "v"(hi)); return r; }
; __device__ __forceinline__ void tr_item(const float* W, int K, int N, bf16_t* WT, int ldt, LAS float* scr, int item, int lane, int mapmode, int p0, int p1) {
;     ...
;     const int c = lane & 7;
; #pragma unroll
;     for (int j = 0; j < 4; ++j) { const int n = (lane >> 3) + 8 * j; const LAS float* s = scr + (8 * c) * 33 + n;
;         u32x4 o; o.x = pk2(s[0 * 33], s[1 * 33]); o.y = pk2(s[2 * 33], s[3 * 33]); o.z = pk2(s[4 * 33], s[5 * 33]); o.w = pk2(s[6 * 33], s[7 * 33]);
;         const int ns = n0 + n; int dst;
;         if (mapmode == 0) dst = p0 + (ns & ~255) + 128 * ((ns >> 5) & 1) + 32 * ((ns >> 6) & 3) + (ns & 31);
;         else if (mapmode == 1) dst = (ns >= p0 && ns < p1) ? ((ns & ~127) + il128(ns & 127)) : ns;
;         else dst = 256 * (ns >> 7) + 128 * ((ns >> 2) & 1) + 32 * ((ns >> 5) & 3) + 8 * ((ns >> 3) & 3) + 4 * p0 + (ns & 3);
;         *(u32x4*)(WT + (size_t)dst * ldt + k0 + 8 * c) = o; }
;     asm volatile("s_waitcnt lgkmcnt(0)" ::: "memory");
	s_mov_b32 s1, s3
	v_lshl_add_u64 v[62:63], s[0:1], 1, v[14:15]
	s_and_b32 s1, s2, 0x80
	s_lshl_b32 s2, s14, 4
	s_waitcnt lgkmcnt(0)
	s_and_b32 s0, s8, 0x700
	s_and_b32 s2, s2, 0x60
	ds_read2_b32 v[34:35], v13 offset0:33 offset1:41
	ds_read2_b32 v[48:49], v13 offset1:8
	ds_read2_b32 v[50:51], v13 offset0:66 offset1:74
	ds_read2_b32 v[52:53], v13 offset0:99 offset1:107
	ds_read2_b32 v[54:55], v13 offset0:132 offset1:140
	ds_read2_b32 v[56:57], v13 offset0:165 offset1:173
	ds_read2_b32 v[58:59], v13 offset0:198 offset1:206
	ds_read2_b32 v[60:61], v13 offset0:231 offset1:239
	s_or_b32 s0, s0, s2
	s_or_b32 s0, s0, s1
	v_or_b32_e32 v8, s0, v7
	v_mul_u32_u24_e32 v8, 0x2c80, v8
	v_lshl_add_u64 v[64:65], v[62:63], 0, v[8:9]
	s_waitcnt lgkmcnt(6)
	v_cvt_pk_bf16_f32 v2, v48, v34
	s_waitcnt lgkmcnt(4)
	v_cvt_pk_bf16_f32 v3, v50, v52
	s_waitcnt lgkmcnt(2)
	v_cvt_pk_bf16_f32 v4, v54, v56
	s_waitcnt lgkmcnt(0)
	v_cvt_pk_bf16_f32 v5, v58, v60
	global_store_dwordx4 v[64:65], v[2:5], off sc0 sc1
	v_or_b32_e32 v8, s0, v36
	v_mul_u32_u24_e32 v8, 0x2c80, v8
	v_cvt_pk_bf16_f32 v2, v49, v35
	v_cvt_pk_bf16_f32 v3, v51, v53
	v_cvt_pk_bf16_f32 v4, v55, v57
	v_cvt_pk_bf16_f32 v5, v59, v61
	ds_read2_b32 v[48:49], v13 offset0:16 offset1:24
	ds_read2_b32 v[50:51], v13 offset0:49 offset1:57
	ds_read2_b32 v[52:53], v13 offset0:82 offset1:90
	ds_read2_b32 v[54:55], v13 offset0:115 offset1:123
	ds_read2_b32 v[56:57], v13 offset0:148 offset1:156
	ds_read2_b32 v[58:59], v13 offset0:181 offset1:189
	ds_read2_b32 v[60:61], v13 offset0:214 offset1:222
	ds_read2_b32 v[64:65], v13 offset0:247 offset1:255
	v_lshl_add_u64 v[34:35], v[62:63], 0, v[8:9]
	v_or_b32_e32 v8, s0, v37
	v_mul_u32_u24_e32 v8, 0x2c80, v8
	global_store_dwordx4 v[34:35], v[2:5], off sc0 sc1
	v_lshl_add_u64 v[34:35], v[62:63], 0, v[8:9]
	v_or_b32_e32 v8, s0, v38
	v_mul_u32_u24_e32 v8, 0x2c80, v8
	s_waitcnt lgkmcnt(6)
	v_cvt_pk_bf16_f32 v2, v48, v50
	s_waitcnt lgkmcnt(4)
	v_cvt_pk_bf16_f32 v3, v52, v54
	s_waitcnt lgkmcnt(2)
	v_cvt_pk_bf16_f32 v4, v56, v58
	s_waitcnt lgkmcnt(0)
	v_cvt_pk_bf16_f32 v5, v60, v64
	global_store_dwordx4 v[34:35], v[2:5], off sc0 sc1
	v_lshl_add_u64 v[34:35], v[62:63], 0, v[8:9]
	s_mov_b64 s[0:1], 0
	v_cvt_pk_bf16_f32 v2, v49, v51
	v_cvt_pk_bf16_f32 v3, v53, v55
	v_cvt_pk_bf16_f32 v4, v57, v59
	v_cvt_pk_bf16_f32 v5, v61, v65
	global_store_dwordx4 v[34:35], v[2:5], off sc0 sc1
	s_waitcnt lgkmcnt(0)

; #define LAS __attribute__((address_space(3)))
; __device__ __forceinline__ unsigned pk2(float lo, float hi) { unsigned r; asm("v_cvt_pk_bf16_f32 %0, %1, %2" : "=v"(r) : "v"(lo), "v"(hi)); return r; }
; __device__ __forceinline__ void tr_item(const float* W, int K, int N, bf16_t* WT, int ldt, LAS float* scr, int item, int lane, int mapmode, int p0, int p1) {
;     const int nblk = N / 32, kb = item / nblk, nb = item % nblk, k0 = 64 * kb, n0 = 32 * nb;
; #pragma unroll 8
;     for (int i = 0; i < 32; ++i) { const int kk = 2 * i + (lane >> 5); scr[kk * 33 + (lane & 31)] = W[(size_t)(k0 + kk) * N + n0 + (lane & 31)]; }
;     asm volatile("s_waitcnt lgkmcnt(0)" ::: "memory");
;     const int c = lane & 7;
; #pragma unroll
;     for (int j = 0; j < 4; ++j) { const int n = (lane >> 3) + 8 * j; const LAS float* s = scr + (8 * c) * 33 + n;
;         u32x4 o; o.x = pk2(s[0 * 33], s[1 * 33]); o.y = pk2(s[2 * 33], s[3 * 33]); o.z = pk2(s[4 * 33], s[5 * 33]); o.w = pk2(s[6 * 33], s[7 * 33]);
;         const int ns = n0 + n; int dst;
;         if (mapmode == 0) dst = p0 + (ns & ~255) + 128 * ((ns >> 5) & 1) + 32 * ((ns >> 6) & 3) + (ns & 31);
;         else if (mapmode == 1) dst = (ns >= p0 && ns < p1) ? ((ns & ~127) + il128(ns & 127)) : ns;
;         else dst = 256 * (ns >> 7) + 128 * ((ns >> 2) & 1) + 32 * ((ns >> 5) & 3) + 8 * ((ns >> 3) & 3) + 4 * p0 + (ns & 3);
;         *(u32x4*)(WT + (size_t)dst * ldt + k0 + 8 * c) = o; }
;     asm volatile("s_waitcnt lgkmcnt(0)" ::: "memory");
.LBB0_24:
	s_lshl_b32 s16, s8, 1
	s_lshl_b32 s17, s9, 1
	v_or_b32_e32 v8, s16, v1
	v_or_b32_e32 v33, s17, v6
	s_add_i32 s18, s16, 4
	s_add_i32 s19, s17, 4
	s_add_i32 s20, s16, 8
	s_add_i32 s21, s17, 8
	s_add_i32 s22, s16, 12
	s_add_i32 s23, s17, 12
	s_add_i32 s25, s16, 16
	s_add_i32 s27, s17, 16
	s_add_i32 s33, s16, 20
	s_add_i32 s35, s17, 20
	s_add_i32 s36, s16, 24
	s_add_i32 s37, s17, 24
	s_add_i32 s16, s16, 28
	s_add_i32 s17, s17, 28
	v_add_u32_e32 v4, s0, v33
	v_or_b32_e32 v76, s18, v1
	v_or_b32_e32 v77, s19, v6
	v_or_b32_e32 v78, s20, v1
	v_or_b32_e32 v79, s21, v6
	v_or_b32_e32 v80, s22, v1
	v_or_b32_e32 v81, s23, v6
	v_or_b32_e32 v82, s25, v1
	v_or_b32_e32 v83, s27, v6
	v_or_b32_e32 v84, s33, v1
	v_or_b32_e32 v85, s35, v6
	v_or_b32_e32 v86, s36, v1
	v_or_b32_e32 v87, s37, v6
	v_or_b32_e32 v88, s16, v1
	v_or_b32_e32 v89, s17, v6
	v_add_u32_e32 v34, s2, v8
	v_mad_u64_u32 v[4:5], s[16:17], v4, s11, v[2:3]
	v_add_u32_e32 v50, s2, v76
	v_add_u32_e32 v48, s0, v77
	v_add_u32_e32 v54, s2, v78
	v_add_u32_e32 v52, s0, v79
	v_add_u32_e32 v58, s2, v80
	v_add_u32_e32 v56, s0, v81
	v_add_u32_e32 v62, s2, v82
	v_add_u32_e32 v60, s0, v83
	v_add_u32_e32 v66, s2, v84
	v_add_u32_e32 v64, s0, v85
	v_add_u32_e32 v70, s2, v86
	v_add_u32_e32 v68, s0, v87
	v_add_u32_e32 v74, s2, v88
	v_add_u32_e32 v72, s0, v89
	v_mad_u64_u32 v[34:35], s[16:17], v34, s11, v[2:3]
	v_mad_u64_u32 v[48:49], s[16:17], v48, s11, v[2:3]
	v_mad_u64_u32 v[50:51], s[16:17], v50, s11, v[2:3]
	v_mad_u64_u32 v[52:53], s[16:17], v52, s11, v[2:3]
	v_mad_u64_u32 v[54:55], s[16:17], v54, s11, v[2:3]
	v_mad_u64_u32 v[56:57], s[16:17], v56, s11, v[2:3]
	v_mad_u64_u32 v[58:59], s[16:17], v58, s11, v[2:3]
	v_mad_u64_u32 v[60:61], s[16:17], v60, s11, v[2:3]
	v_mad_u64_u32 v[62:63], s[16:17], v62, s11, v[2:3]
	v_mad_u64_u32 v[64:65], s[16:17], v64, s11, v[2:3]
	v_mad_u64_u32 v[66:67], s[16:17], v66, s11, v[2:3]
	v_mad_u64_u32 v[68:69], s[16:17], v68, s11, v[2:3]
	v_mad_u64_u32 v[70:71], s[16:17], v70, s11, v[2:3]
	v_mad_u64_u32 v[72:73], s[16:17], v72, s11, v[2:3]
	v_mad_u64_u32 v[74:75], s[16:17], v74, s11, v[2:3]
	global_load_dword v90, v[4:5], off
	global_load_dword v91, v[34:35], off
	global_load_dword v92, v[48:49], off
	global_load_dword v93, v[50:51], off
	global_load_dword v94, v[52:53], off
	global_load_dword v95, v[54:55], off
	global_load_dword v96, v[56:57], off
	global_load_dword v97, v[58:59], off
	global_load_dword v98, v[60:61], off
	global_load_dword v99, v[62:63], off
	global_load_dword v100, v[64:65], off
	global_load_dword v101, v[66:67], off
	global_load_dword v102, v[68:69], off
	global_load_dword v103, v[70:71], off
	global_load_dword v104, v[72:73], off
	global_load_dword v105, v[74:75], off
	s_add_i32 s9, s9, 16
	s_add_i32 s8, s8, 16
	s_add_i32 s15, s15, -16
	v_mad_u64_u32 v[4:5], s[16:17], v33, s10, v[12:13]
	s_cmp_lg_u32 s15, 0
	v_mad_u64_u32 v[34:35], s[16:17], v8, s10, v[12:13]
	v_mad_u64_u32 v[48:49], s[16:17], v77, s10, v[12:13]
	v_mad_u64_u32 v[50:51], s[16:17], v76, s10, v[12:13]
	v_mad_u64_u32 v[52:53], s[16:17], v79, s10, v[12:13]
	v_mad_u64_u32 v[54:55], s[16:17], v78, s10, v[12:13]
	v_mad_u64_u32 v[56:57], s[16:17], v81, s10, v[12:13]
	v_mad_u64_u32 v[58:59], s[16:17], v80, s10, v[12:13]
	v_mad_u64_u32 v[60:61], s[16:17], v83, s10, v[12:13]
	v_mad_u64_u32 v[62:63], s[16:17], v82, s10, v[12:13]
	v_mad_u64_u32 v[64:65], s[16:17], v85, s10, v[12:13]
	v_mad_u64_u32 v[66:67], s[16:17], v84, s10, v[12:13]
	v_mad_u64_u32 v[68:69], s[16:17], v87, s10, v[12:13]
	v_mad_u64_u32 v[70:71], s[16:17], v86, s10, v[12:13]
	v_mad_u64_u32 v[72:73], s[16:17], v89, s10, v[12:13]
	v_mad_u64_u32 v[74:75], s[16:17], v88, s10, v[12:13]
	s_waitcnt vmcnt(15)
	ds_write_b32 v4, v90
	s_waitcnt vmcnt(14)
	ds_write_b32 v34, v91
	s_waitcnt vmcnt(13)
	ds_write_b32 v48, v92
	s_waitcnt vmcnt(12)
	ds_write_b32 v50, v93
	s_waitcnt vmcnt(11)
	ds_write_b32 v52, v94
	s_waitcnt vmcnt(10)
	ds_write_b32 v54, v95
	s_waitcnt vmcnt(9)
	ds_write_b32 v56, v96
	s_waitcnt vmcnt(8)
	ds_write_b32 v58, v97
	s_waitcnt vmcnt(7)
	ds_write_b32 v60, v98
	s_waitcnt vmcnt(6)
	ds_write_b32 v62, v99
	s_waitcnt vmcnt(5)
	ds_write_b32 v64, v100
	s_waitcnt vmcnt(4)
	ds_write_b32 v66, v101
	s_waitcnt vmcnt(3)
	ds_write_b32 v68, v102
	s_waitcnt vmcnt(2)
	ds_write_b32 v70, v103
	s_waitcnt vmcnt(1)
	ds_write_b32 v72, v104
	s_waitcnt vmcnt(0)
	ds_write_b32 v74, v105
	s_cbranch_scc1 .LBB0_24
	s_and_b32 s1, 0xffff, s1
	s_and_b32 s0, 0xffff, s0
	s_waitcnt lgkmcnt(0)
	s_lshl_b32 s2, s0, 1
	s_lshl_b32 s0, s1, 1
	ds_read2_b32 v[34:35], v13 offset0:33 offset1:41
	ds_read2_b32 v[48:49], v13 offset1:8
	ds_read2_b32 v[50:51], v13 offset0:66 offset1:74
	ds_read2_b32 v[52:53], v13 offset0:99 offset1:107
	ds_read2_b32 v[54:55], v13 offset0:132 offset1:140
	ds_read2_b32 v[56:57], v13 offset0:165 offset1:173
	ds_read2_b32 v[58:59], v13 offset0:198 offset1:206
	ds_read2_b32 v[60:61], v13 offset0:231 offset1:239
	s_and_b32 s0, s0, 0x3f00
	s_and_b32 s1, s1, 0x60
	s_or_b32 s0, s1, s0
	v_or_b32_e32 v8, s0, v41
	v_lshl_add_u64 v[62:63], v[18:19], 0, s[2:3]
	v_mul_u32_u24_e32 v8, 0x1080, v8
	v_lshl_add_u64 v[64:65], v[62:63], 0, v[8:9]
	s_waitcnt lgkmcnt(6)
	v_cvt_pk_bf16_f32 v2, v48, v34
	s_waitcnt lgkmcnt(4)
	v_cvt_pk_bf16_f32 v3, v50, v52
	s_waitcnt lgkmcnt(2)
	v_cvt_pk_bf16_f32 v4, v54, v56
	s_waitcnt lgkmcnt(0)
	v_cvt_pk_bf16_f32 v5, v58, v60
	global_store_dwordx4 v[64:65], v[2:5], off sc0 sc1
	v_or_b32_e32 v8, s0, v42
	v_mul_u32_u24_e32 v8, 0x1080, v8
	v_cvt_pk_bf16_f32 v2, v49, v35
	v_cvt_pk_bf16_f32 v3, v51, v53
	v_cvt_pk_bf16_f32 v4, v55, v57
	v_cvt_pk_bf16_f32 v5, v59, v61
	ds_read2_b32 v[48:49], v13 offset0:16 offset1:24
	ds_read2_b32 v[50:51], v13 offset0:49 offset1:57
	ds_read2_b32 v[52:53], v13 offset0:82 offset1:90
	ds_read2_b32 v[54:55], v13 offset0:115 offset1:123
	ds_read2_b32 v[56:57], v13 offset0:148 offset1:156
	ds_read2_b32 v[58:59], v13 offset0:181 offset1:189
	ds_read2_b32 v[60:61], v13 offset0:214 offset1:222
	ds_read2_b32 v[64:65], v13 offset0:247 offset1:255
	v_lshl_add_u64 v[34:35], v[62:63], 0, v[8:9]
	v_or_b32_e32 v8, s0, v43
	v_mul_u32_u24_e32 v8, 0x1080, v8
	global_store_dwordx4 v[34:35], v[2:5], off sc0 sc1
	v_lshl_add_u64 v[34:35], v[62:63], 0, v[8:9]
	v_or_b32_e32 v8, s0, v44
	v_mul_u32_u24_e32 v8, 0x1080, v8
	s_waitcnt lgkmcnt(6)
	v_cvt_pk_bf16_f32 v2, v48, v50
	s_waitcnt lgkmcnt(4)
	v_cvt_pk_bf16_f32 v3, v52, v54
	s_waitcnt lgkmcnt(2)
	v_cvt_pk_bf16_f32 v4, v56, v58
	s_waitcnt lgkmcnt(0)
	v_cvt_pk_bf16_f32 v5, v60, v64
	global_store_dwordx4 v[34:35], v[2:5], off sc0 sc1
	v_lshl_add_u64 v[34:35], v[62:63], 0, v[8:9]
	s_nop 0
	v_cvt_pk_bf16_f32 v2, v49, v51
	v_cvt_pk_bf16_f32 v3, v53, v55
	v_cvt_pk_bf16_f32 v4, v57, v59
	v_cvt_pk_bf16_f32 v5, v61, v65
	global_store_dwordx4 v[34:35], v[2:5], off sc0 sc1
	s_waitcnt lgkmcnt(0)

; #define LAS __attribute__((address_space(3)))
; __device__ __forceinline__ unsigned pk2(float lo, float hi) { unsigned r; asm("v_cvt_pk_bf16_f32 %0, %1, %2" : "=v"(r) : "v"(lo), "v"(hi)); return r; }
; __device__ __forceinline__ void tr_item(const float* W, int K, int N, bf16_t* WT, int ldt, LAS float* scr, int item, int lane, int mapmode, int p0, int p1) {
;     const int nblk = N / 32, kb = item / nblk, nb = item % nblk, k0 = 64 * kb, n0 = 32 * nb;
; #pragma unroll 8
;     for (int i = 0; i < 32; ++i) { const int kk = 2 * i + (lane >> 5); scr[kk * 33 + (lane & 31)] = W[(size_t)(k0 + kk) * N + n0 + (lane & 31)]; }
;     asm volatile("s_waitcnt lgkmcnt(0)" ::: "memory");
;     const int c = lane & 7;
; #pragma unroll
;     for (int j = 0; j < 4; ++j) { const int n = (lane >> 3) + 8 * j; const LAS float* s = scr + (8 * c) * 33 + n;
;         u32x4 o; o.x = pk2(s[0 * 33], s[1 * 33]); o.y = pk2(s[2 * 33], s[3 * 33]); o.z = pk2(s[4 * 33], s[5 * 33]); o.w = pk2(s[6 * 33], s[7 * 33]);
;         const int ns = n0 + n; int dst;
;         if (mapmode == 0) dst = p0 + (ns & ~255) + 128 * ((ns >> 5) & 1) + 32 * ((ns >> 6) & 3) + (ns & 31);
;         else if (mapmode == 1) dst = (ns >= p0 && ns < p1) ? ((ns & ~127) + il128(ns & 127)) : ns;
;         else dst = 256 * (ns >> 7) + 128 * ((ns >> 2) & 1) + 32 * ((ns >> 5) & 3) + 8 * ((ns >> 3) & 3) + 4 * p0 + (ns & 3);
;         *(u32x4*)(WT + (size_t)dst * ldt + k0 + 8 * c) = o; }
;     asm volatile("s_waitcnt lgkmcnt(0)" ::: "memory");
.LBB0_29:
	s_lshl_b32 s16, s8, 1
	s_lshl_b32 s17, s9, 1
	v_or_b32_e32 v8, s16, v1
	v_or_b32_e32 v33, s17, v6
	s_add_i32 s18, s16, 4
	s_add_i32 s19, s17, 4
	s_add_i32 s20, s16, 8
	s_add_i32 s21, s17, 8
	s_add_i32 s22, s16, 12
	s_add_i32 s23, s17, 12
	s_add_i32 s25, s16, 16
	s_add_i32 s27, s17, 16
	s_add_i32 s33, s16, 20
	s_add_i32 s35, s17, 20
	s_add_i32 s36, s16, 24
	s_add_i32 s37, s17, 24
	s_add_i32 s16, s16, 28
	s_add_i32 s17, s17, 28
	v_add_u32_e32 v4, s0, v33
	v_or_b32_e32 v76, s18, v1
	v_or_b32_e32 v77, s19, v6
	v_or_b32_e32 v78, s20, v1
	v_or_b32_e32 v79, s21, v6
	v_or_b32_e32 v80, s22, v1
	v_or_b32_e32 v81, s23, v6
	v_or_b32_e32 v82, s25, v1
	v_or_b32_e32 v83, s27, v6
	v_or_b32_e32 v84, s33, v1
	v_or_b32_e32 v85, s35, v6
	v_or_b32_e32 v86, s36, v1
	v_or_b32_e32 v87, s37, v6
	v_or_b32_e32 v88, s16, v1
	v_or_b32_e32 v89, s17, v6
	v_add_u32_e32 v34, s2, v8
	v_mad_u64_u32 v[4:5], s[16:17], v4, s11, v[2:3]
	v_add_u32_e32 v50, s2, v76
	v_add_u32_e32 v48, s0, v77
	v_add_u32_e32 v54, s2, v78
	v_add_u32_e32 v52, s0, v79
	v_add_u32_e32 v58, s2, v80
	v_add_u32_e32 v56, s0, v81
	v_add_u32_e32 v62, s2, v82
	v_add_u32_e32 v60, s0, v83
	v_add_u32_e32 v66, s2, v84
	v_add_u32_e32 v64, s0, v85
	v_add_u32_e32 v70, s2, v86
	v_add_u32_e32 v68, s0, v87
	v_add_u32_e32 v74, s2, v88
	v_add_u32_e32 v72, s0, v89
	v_mad_u64_u32 v[34:35], s[16:17], v34, s11, v[2:3]
	v_mad_u64_u32 v[48:49], s[16:17], v48, s11, v[2:3]
	v_mad_u64_u32 v[50:51], s[16:17], v50, s11, v[2:3]
	v_mad_u64_u32 v[52:53], s[16:17], v52, s11, v[2:3]
	v_mad_u64_u32 v[54:55], s[16:17], v54, s11, v[2:3]
	v_mad_u64_u32 v[56:57], s[16:17], v56, s11, v[2:3]
	v_mad_u64_u32 v[58:59], s[16:17], v58, s11, v[2:3]
	v_mad_u64_u32 v[60:61], s[16:17], v60, s11, v[2:3]
	v_mad_u64_u32 v[62:63], s[16:17], v62, s11, v[2:3]
	v_mad_u64_u32 v[64:65], s[16:17], v64, s11, v[2:3]
	v_mad_u64_u32 v[66:67], s[16:17], v66, s11, v[2:3]
	v_mad_u64_u32 v[68:69], s[16:17], v68, s11, v[2:3]
	v_mad_u64_u32 v[70:71], s[16:17], v70, s11, v[2:3]
	v_mad_u64_u32 v[72:73], s[16:17], v72, s11, v[2:3]
	v_mad_u64_u32 v[74:75], s[16:17], v74, s11, v[2:3]
	global_load_dword v90, v[4:5], off
	global_load_dword v91, v[34:35], off
	global_load_dword v92, v[48:49], off
	global_load_dword v93, v[50:51], off
	global_load_dword v94, v[52:53], off
	global_load_dword v95, v[54:55], off
	global_load_dword v96, v[56:57], off
	global_load_dword v97, v[58:59], off
	global_load_dword v98, v[60:61], off
	global_load_dword v99, v[62:63], off
	global_load_dword v100, v[64:65], off
	global_load_dword v101, v[66:67], off
	global_load_dword v102, v[68:69], off
	global_load_dword v103, v[70:71], off
	global_load_dword v104, v[72:73], off
	global_load_dword v105, v[74:75], off
	s_add_i32 s9, s9, 16
	s_add_i32 s8, s8, 16
	s_add_i32 s15, s15, -16
	v_mad_u64_u32 v[4:5], s[16:17], v33, s10, v[12:13]
	s_cmp_lg_u32 s15, 0
	v_mad_u64_u32 v[34:35], s[16:17], v8, s10, v[12:13]
	v_mad_u64_u32 v[48:49], s[16:17], v77, s10, v[12:13]
	v_mad_u64_u32 v[50:51], s[16:17], v76, s10, v[12:13]
	v_mad_u64_u32 v[52:53], s[16:17], v79, s10, v[12:13]
	v_mad_u64_u32 v[54:55], s[16:17], v78, s10, v[12:13]
	v_mad_u64_u32 v[56:57], s[16:17], v81, s10, v[12:13]
	v_mad_u64_u32 v[58:59], s[16:17], v80, s10, v[12:13]
	v_mad_u64_u32 v[60:61], s[16:17], v83, s10, v[12:13]
	v_mad_u64_u32 v[62:63], s[16:17], v82, s10, v[12:13]
	v_mad_u64_u32 v[64:65], s[16:17], v85, s10, v[12:13]
	v_mad_u64_u32 v[66:67], s[16:17], v84, s10, v[12:13]
	v_mad_u64_u32 v[68:69], s[16:17], v87, s10, v[12:13]
	v_mad_u64_u32 v[70:71], s[16:17], v86, s10, v[12:13]
	v_mad_u64_u32 v[72:73], s[16:17], v89, s10, v[12:13]
	v_mad_u64_u32 v[74:75], s[16:17], v88, s10, v[12:13]
	s_waitcnt vmcnt(15)
	ds_write_b32 v4, v90
	s_waitcnt vmcnt(14)
	ds_write_b32 v34, v91
	s_waitcnt vmcnt(13)
	ds_write_b32 v48, v92
	s_waitcnt vmcnt(12)
	ds_write_b32 v50, v93
	s_waitcnt vmcnt(11)
	ds_write_b32 v52, v94
	s_waitcnt vmcnt(10)
	ds_write_b32 v54, v95
	s_waitcnt vmcnt(9)
	ds_write_b32 v56, v96
	s_waitcnt vmcnt(8)
	ds_write_b32 v58, v97
	s_waitcnt vmcnt(7)
	ds_write_b32 v60, v98
	s_waitcnt vmcnt(6)
	ds_write_b32 v62, v99
	s_waitcnt vmcnt(5)
	ds_write_b32 v64, v100
	s_waitcnt vmcnt(4)
	ds_write_b32 v66, v101
	s_waitcnt vmcnt(3)
	ds_write_b32 v68, v102
	s_waitcnt vmcnt(2)
	ds_write_b32 v70, v103
	s_waitcnt vmcnt(1)
	ds_write_b32 v72, v104
	s_waitcnt vmcnt(0)
	ds_write_b32 v74, v105
	s_cbranch_scc1 .LBB0_29
	s_and_b32 s1, 0xffff, s1
	s_and_b32 s0, 0xffff, s0
	s_waitcnt lgkmcnt(0)
	s_lshl_b32 s2, s0, 1
	s_lshl_b32 s0, s1, 1
	ds_read2_b32 v[34:35], v13 offset0:33 offset1:41
	ds_read2_b32 v[48:49], v13 offset1:8
	ds_read2_b32 v[50:51], v13 offset0:66 offset1:74
	ds_read2_b32 v[52:53], v13 offset0:99 offset1:107
	ds_read2_b32 v[54:55], v13 offset0:132 offset1:140
	ds_read2_b32 v[56:57], v13 offset0:165 offset1:173
	ds_read2_b32 v[58:59], v13 offset0:198 offset1:206
	ds_read2_b32 v[60:61], v13 offset0:231 offset1:239
	s_and_b32 s0, s0, 0x3f00
	s_and_b32 s1, s1, 0x60
	s_or_b32 s0, s1, s0
	v_or_b32_e32 v8, s0, v40
	v_lshl_add_u64 v[62:63], v[18:19], 0, s[2:3]
	v_mul_u32_u24_e32 v8, 0x1080, v8
	v_lshl_add_u64 v[64:65], v[62:63], 0, v[8:9]
	s_waitcnt lgkmcnt(6)
	v_cvt_pk_bf16_f32 v2, v48, v34
	s_waitcnt lgkmcnt(4)
	v_cvt_pk_bf16_f32 v3, v50, v52
	s_waitcnt lgkmcnt(2)
	v_cvt_pk_bf16_f32 v4, v54, v56
	s_waitcnt lgkmcnt(0)
	v_cvt_pk_bf16_f32 v5, v58, v60
	global_store_dwordx4 v[64:65], v[2:5], off sc0 sc1
	v_or_b32_e32 v8, s0, v45
	v_mul_u32_u24_e32 v8, 0x1080, v8
	v_cvt_pk_bf16_f32 v2, v49, v35
	v_cvt_pk_bf16_f32 v3, v51, v53
	v_cvt_pk_bf16_f32 v4, v55, v57
	v_cvt_pk_bf16_f32 v5, v59, v61
	ds_read2_b32 v[48:49], v13 offset0:16 offset1:24
	ds_read2_b32 v[50:51], v13 offset0:49 offset1:57
	ds_read2_b32 v[52:53], v13 offset0:82 offset1:90
	ds_read2_b32 v[54:55], v13 offset0:115 offset1:123
	ds_read2_b32 v[56:57], v13 offset0:148 offset1:156
	ds_read2_b32 v[58:59], v13 offset0:181 offset1:189
	ds_read2_b32 v[60:61], v13 offset0:214 offset1:222
	ds_read2_b32 v[64:65], v13 offset0:247 offset1:255
	v_lshl_add_u64 v[34:35], v[62:63], 0, v[8:9]
	v_or_b32_e32 v8, s0, v46
	v_mul_u32_u24_e32 v8, 0x1080, v8
	global_store_dwordx4 v[34:35], v[2:5], off sc0 sc1
	v_lshl_add_u64 v[34:35], v[62:63], 0, v[8:9]
	v_or_b32_e32 v8, s0, v47
	v_mul_u32_u24_e32 v8, 0x1080, v8
	s_waitcnt lgkmcnt(6)
	v_cvt_pk_bf16_f32 v2, v48, v50
	s_waitcnt lgkmcnt(4)
	v_cvt_pk_bf16_f32 v3, v52, v54
	s_waitcnt lgkmcnt(2)
	v_cvt_pk_bf16_f32 v4, v56, v58
	s_waitcnt lgkmcnt(0)
	v_cvt_pk_bf16_f32 v5, v60, v64
	global_store_dwordx4 v[34:35], v[2:5], off sc0 sc1
	v_lshl_add_u64 v[34:35], v[62:63], 0, v[8:9]
	s_nop 0
	v_cvt_pk_bf16_f32 v2, v49, v51
	v_cvt_pk_bf16_f32 v3, v53, v55
	v_cvt_pk_bf16_f32 v4, v57, v59
	v_cvt_pk_bf16_f32 v5, v61, v65
	global_store_dwordx4 v[34:35], v[2:5], off sc0 sc1
	s_waitcnt lgkmcnt(0)

; __device__ __forceinline__ void tr_item(const float* W, int K, int N, bf16_t* WT, int ldt, LAS float* scr, int item, int lane, int mapmode, int p0, int p1) {
;     ...
; #pragma unroll 8
;     for (int i = 0; i < 32; ++i) { const int kk = 2 * i + (lane >> 5); scr[kk * 33 + (lane & 31)] = W[(size_t)(k0 + kk) * N + n0 + (lane & 31)]; }
.LBB0_34:
	s_lshl_b32 s16, s8, 1
	s_lshl_b32 s17, s9, 1
	v_or_b32_e32 v66, s17, v6
	s_add_i32 s18, s16, 4
	s_add_i32 s19, s17, 4
	s_add_i32 s21, s17, 8
	v_add_u32_e32 v8, s7, v66
	v_or_b32_e32 v67, s18, v1
	v_or_b32_e32 v68, s19, v6
	v_mov_b32_e32 v35, v9
	v_or_b32_e32 v33, s16, v1
	s_add_i32 s23, s17, 12
	v_or_b32_e32 v70, s21, v6
	v_lshlrev_b64 v[60:61], 13, v[8:9]
	v_add_u32_e32 v34, s2, v67
	v_add_u32_e32 v8, s7, v68
	v_mov_b32_e32 v5, v9
	s_add_i32 s20, s16, 8
	s_add_i32 s22, s16, 12
	s_add_i32 s27, s17, 16
	v_add_u32_e32 v4, s2, v33
	v_or_b32_e32 v72, s23, v6
	v_lshlrev_b64 v[34:35], 13, v[34:35]
	v_lshlrev_b64 v[62:63], 13, v[8:9]
	v_add_u32_e32 v8, s7, v70
	s_add_i32 s35, s17, 20
	v_or_b32_e32 v69, s20, v1
	v_or_b32_e32 v71, s22, v1
	v_or_b32_e32 v74, s27, v6
	v_lshlrev_b64 v[4:5], 13, v[4:5]
	v_lshl_add_u64 v[60:61], v[2:3], 0, v[60:61]
	v_lshl_add_u64 v[34:35], v[2:3], 0, v[34:35]
	v_lshlrev_b64 v[64:65], 13, v[8:9]
	v_add_u32_e32 v8, s7, v72
	v_mov_b32_e32 v49, v9
	v_mov_b32_e32 v51, v9
	s_add_i32 s25, s16, 16
	s_add_i32 s33, s16, 20
	s_add_i32 s37, s17, 24
	v_or_b32_e32 v76, s35, v6
	v_add_u32_e32 v48, s2, v69
	v_add_u32_e32 v50, s2, v71
	v_lshl_add_u64 v[4:5], v[2:3], 0, v[4:5]
	v_lshl_add_u64 v[62:63], v[2:3], 0, v[62:63]
	global_load_dword v81, v[60:61], off
	global_load_dword v82, v[4:5], off
	global_load_dword v83, v[62:63], off
	global_load_dword v84, v[34:35], off
	v_lshlrev_b64 v[34:35], 13, v[8:9]
	v_add_u32_e32 v8, s7, v74
	s_add_i32 s36, s16, 24
	s_add_i32 s16, s16, 28
	s_add_i32 s17, s17, 28
	v_or_b32_e32 v73, s25, v1
	v_or_b32_e32 v75, s33, v1
	v_or_b32_e32 v78, s37, v6
	v_lshlrev_b64 v[48:49], 13, v[48:49]
	v_lshlrev_b64 v[50:51], 13, v[50:51]
	v_lshl_add_u64 v[4:5], v[2:3], 0, v[64:65]
	v_lshl_add_u64 v[34:35], v[2:3], 0, v[34:35]
	v_lshlrev_b64 v[60:61], 13, v[8:9]
	v_add_u32_e32 v8, s7, v76
	v_mov_b32_e32 v53, v9
	v_mov_b32_e32 v55, v9
	v_or_b32_e32 v77, s36, v1
	v_or_b32_e32 v79, s16, v1
	v_or_b32_e32 v80, s17, v6
	v_add_u32_e32 v52, s2, v73
	v_add_u32_e32 v54, s2, v75
	v_lshl_add_u64 v[48:49], v[2:3], 0, v[48:49]
	v_lshl_add_u64 v[50:51], v[2:3], 0, v[50:51]
	global_load_dword v85, v[4:5], off
	global_load_dword v86, v[48:49], off
	global_load_dword v87, v[34:35], off
	global_load_dword v88, v[50:51], off
	v_lshlrev_b64 v[34:35], 13, v[8:9]
	v_add_u32_e32 v8, s7, v78
	v_mov_b32_e32 v57, v9
	v_mov_b32_e32 v59, v9
	v_add_u32_e32 v56, s2, v77
	v_add_u32_e32 v58, s2, v79
	v_lshlrev_b64 v[52:53], 13, v[52:53]
	v_lshlrev_b64 v[54:55], 13, v[54:55]
	v_lshl_add_u64 v[4:5], v[2:3], 0, v[60:61]
	v_lshl_add_u64 v[34:35], v[2:3], 0, v[34:35]
	v_lshlrev_b64 v[48:49], 13, v[8:9]
	v_add_u32_e32 v8, s7, v80
	v_lshlrev_b64 v[56:57], 13, v[56:57]
	v_lshlrev_b64 v[58:59], 13, v[58:59]
	v_lshl_add_u64 v[52:53], v[2:3], 0, v[52:53]
	v_lshl_add_u64 v[54:55], v[2:3], 0, v[54:55]
	global_load_dword v89, v[4:5], off
	global_load_dword v90, v[52:53], off
	global_load_dword v91, v[34:35], off
	global_load_dword v92, v[54:55], off
	v_lshl_add_u64 v[4:5], v[2:3], 0, v[48:49]
	v_lshlrev_b64 v[34:35], 13, v[8:9]
	v_lshl_add_u64 v[56:57], v[2:3], 0, v[56:57]
	v_lshl_add_u64 v[58:59], v[2:3], 0, v[58:59]
	v_lshl_add_u64 v[34:35], v[2:3], 0, v[34:35]
	global_load_dword v8, v[4:5], off
	global_load_dword v93, v[56:57], off
	global_load_dword v94, v[34:35], off
	global_load_dword v95, v[58:59], off
	s_add_i32 s9, s9, 16
	s_add_i32 s8, s8, 16
	s_add_i32 s15, s15, -16
	v_mad_u64_u32 v[4:5], s[16:17], v66, s10, v[12:13]
	s_cmp_lg_u32 s15, 0
	v_mad_u64_u32 v[34:35], s[16:17], v33, s10, v[12:13]
	v_mad_u64_u32 v[48:49], s[16:17], v68, s10, v[12:13]
	v_mad_u64_u32 v[50:51], s[16:17], v67, s10, v[12:13]
	v_mad_u64_u32 v[52:53], s[16:17], v70, s10, v[12:13]
	v_mad_u64_u32 v[54:55], s[16:17], v69, s10, v[12:13]
	v_mad_u64_u32 v[56:57], s[16:17], v72, s10, v[12:13]
	v_mad_u64_u32 v[58:59], s[16:17], v71, s10, v[12:13]
	v_mad_u64_u32 v[60:61], s[16:17], v74, s10, v[12:13]
	v_mad_u64_u32 v[62:63], s[16:17], v73, s10, v[12:13]
	v_mad_u64_u32 v[64:65], s[16:17], v76, s10, v[12:13]
	v_mad_u64_u32 v[66:67], s[16:17], v75, s10, v[12:13]
	v_mad_u64_u32 v[68:69], s[16:17], v78, s10, v[12:13]
	v_mad_u64_u32 v[70:71], s[16:17], v77, s10, v[12:13]
	v_mad_u64_u32 v[72:73], s[16:17], v80, s10, v[12:13]
	v_mad_u64_u32 v[74:75], s[16:17], v79, s10, v[12:13]
	s_waitcnt vmcnt(15)
	ds_write_b32 v4, v81
	s_waitcnt vmcnt(14)
	ds_write_b32 v34, v82
	s_waitcnt vmcnt(13)
	ds_write_b32 v48, v83
	s_waitcnt vmcnt(12)
	ds_write_b32 v50, v84
	s_waitcnt vmcnt(11)
	ds_write_b32 v52, v85
	s_waitcnt vmcnt(10)
	ds_write_b32 v54, v86
	s_waitcnt vmcnt(9)
	ds_write_b32 v56, v87
	s_waitcnt vmcnt(8)
	ds_write_b32 v58, v88
	s_waitcnt vmcnt(7)
	ds_write_b32 v60, v89
	s_waitcnt vmcnt(6)
	ds_write_b32 v62, v90
	s_waitcnt vmcnt(5)
	ds_write_b32 v64, v91
	s_waitcnt vmcnt(4)
	ds_write_b32 v66, v92
	s_waitcnt vmcnt(3)
	ds_write_b32 v68, v8
	s_waitcnt vmcnt(2)
	ds_write_b32 v70, v93
	s_waitcnt vmcnt(1)
	ds_write_b32 v72, v94
	s_waitcnt vmcnt(0)
	ds_write_b32 v74, v95
	s_cbranch_scc1 .LBB0_34
; #define LAS __attribute__((address_space(3)))
; __device__ __forceinline__ unsigned pk2(float lo, float hi) { unsigned r; asm("v_cvt_pk_bf16_f32 %0, %1, %2" : "=v"(r) : "v"(lo), "v"(hi)); return r; }
; __device__ __forceinline__ void tr_item(const float* W, int K, int N, bf16_t* WT, int ldt, LAS float* scr, int item, int lane, int mapmode, int p0, int p1) {
;     ...
;     const int c = lane & 7;
; #pragma unroll
;     for (int j = 0; j < 4; ++j) { const int n = (lane >> 3) + 8 * j; const LAS float* s = scr + (8 * c) * 33 + n;
;         u32x4 o; o.x = pk2(s[0 * 33], s[1 * 33]); o.y = pk2(s[2 * 33], s[3 * 33]); o.z = pk2(s[4 * 33], s[5 * 33]); o.w = pk2(s[6 * 33], s[7 * 33]);
;         const int ns = n0 + n; int dst;
;         if (mapmode == 0) dst = p0 + (ns & ~255) + 128 * ((ns >> 5) & 1) + 32 * ((ns >> 6) & 3) + (ns & 31);
;         else if (mapmode == 1) dst = (ns >= p0 && ns < p1) ? ((ns & ~127) + il128(ns & 127)) : ns;
;         else dst = 256 * (ns >> 7) + 128 * ((ns >> 2) & 1) + 32 * ((ns >> 5) & 3) + 8 * ((ns >> 3) & 3) + 4 * p0 + (ns & 3);
;         *(u32x4*)(WT + (size_t)dst * ldt + k0 + 8 * c) = o; }
	s_lshl_b32 s2, s7, 1
	s_waitcnt lgkmcnt(0)
	v_lshl_add_u64 v[62:63], v[24:25], 0, s[2:3]
	s_and_b32 s0, s0, 0x700
	s_and_b32 s1, s1, 0x80
	s_lshl_b32 s2, s14, 4
	ds_read2_b32 v[34:35], v13 offset0:33 offset1:41
	ds_read2_b32 v[48:49], v13 offset1:8
	ds_read2_b32 v[50:51], v13 offset0:66 offset1:74
	ds_read2_b32 v[52:53], v13 offset0:99 offset1:107
	ds_read2_b32 v[54:55], v13 offset0:132 offset1:140
	ds_read2_b32 v[56:57], v13 offset0:165 offset1:173
	ds_read2_b32 v[58:59], v13 offset0:198 offset1:206
	ds_read2_b32 v[60:61], v13 offset0:231 offset1:239
	s_and_b32 s2, s2, 0x60
	s_or_b32 s0, s1, s0
	s_or_b32 s0, s0, s2
	v_or_b32_e32 v8, s0, v7
	v_mul_u32_u24_e32 v8, 0x1080, v8
	v_lshl_add_u64 v[64:65], v[62:63], 0, v[8:9]
	s_waitcnt lgkmcnt(6)
	v_cvt_pk_bf16_f32 v2, v48, v34
	s_waitcnt lgkmcnt(4)
	v_cvt_pk_bf16_f32 v3, v50, v52
	s_waitcnt lgkmcnt(2)
	v_cvt_pk_bf16_f32 v4, v54, v56
	s_waitcnt lgkmcnt(0)
	v_cvt_pk_bf16_f32 v5, v58, v60
	global_store_dwordx4 v[64:65], v[2:5], off sc0 sc1
	v_or_b32_e32 v8, s0, v36
	v_mul_u32_u24_e32 v8, 0x1080, v8
	v_cvt_pk_bf16_f32 v2, v49, v35
	v_cvt_pk_bf16_f32 v3, v51, v53
	v_cvt_pk_bf16_f32 v4, v55, v57
	v_cvt_pk_bf16_f32 v5, v59, v61
	ds_read2_b32 v[48:49], v13 offset0:16 offset1:24
	ds_read2_b32 v[50:51], v13 offset0:49 offset1:57
	ds_read2_b32 v[52:53], v13 offset0:82 offset1:90
	ds_read2_b32 v[54:55], v13 offset0:115 offset1:123
	ds_read2_b32 v[56:57], v13 offset0:148 offset1:156
	ds_read2_b32 v[58:59], v13 offset0:181 offset1:189
	ds_read2_b32 v[60:61], v13 offset0:214 offset1:222
	ds_read2_b32 v[64:65], v13 offset0:247 offset1:255
	v_lshl_add_u64 v[34:35], v[62:63], 0, v[8:9]
	v_or_b32_e32 v8, s0, v37
	v_mul_u32_u24_e32 v8, 0x1080, v8
	global_store_dwordx4 v[34:35], v[2:5], off sc0 sc1
	v_lshl_add_u64 v[34:35], v[62:63], 0, v[8:9]
	v_or_b32_e32 v8, s0, v38
	v_mul_u32_u24_e32 v8, 0x1080, v8
	s_waitcnt lgkmcnt(6)
	v_cvt_pk_bf16_f32 v2, v48, v50
	s_waitcnt lgkmcnt(4)
	v_cvt_pk_bf16_f32 v3, v52, v54
	s_waitcnt lgkmcnt(2)
	v_cvt_pk_bf16_f32 v4, v56, v58
	s_waitcnt lgkmcnt(0)
	v_cvt_pk_bf16_f32 v5, v60, v64
	global_store_dwordx4 v[34:35], v[2:5], off sc0 sc1
	v_lshl_add_u64 v[34:35], v[62:63], 0, v[8:9]
	s_nop 0
	v_cvt_pk_bf16_f32 v2, v49, v51
	v_cvt_pk_bf16_f32 v3, v53, v55
	v_cvt_pk_bf16_f32 v4, v57, v59
	v_cvt_pk_bf16_f32 v5, v61, v65
	global_store_dwordx4 v[34:35], v[2:5], off sc0 sc1
	s_waitcnt lgkmcnt(0)

; __device__ __forceinline__ void tr_item(const float* W, int K, int N, bf16_t* WT, int ldt, LAS float* scr, int item, int lane, int mapmode, int p0, int p1) {
;     ...
; #pragma unroll 8
;     for (int i = 0; i < 32; ++i) { const int kk = 2 * i + (lane >> 5); scr[kk * 33 + (lane & 31)] = W[(size_t)(k0 + kk) * N + n0 + (lane & 31)]; }
.LBB0_39:
	s_lshl_b32 s15, s7, 1
	s_lshl_b32 s16, s8, 1
	v_or_b32_e32 v66, s16, v6
	s_add_i32 s17, s15, 4
	s_add_i32 s18, s16, 4
	s_add_i32 s20, s16, 8
	v_add_u32_e32 v8, s2, v66
	v_or_b32_e32 v67, s17, v1
	v_or_b32_e32 v68, s18, v6
	v_mov_b32_e32 v35, v9
	v_or_b32_e32 v33, s15, v1
	s_add_i32 s22, s16, 12
	v_or_b32_e32 v70, s20, v6
	v_lshlrev_b64 v[60:61], 10, v[8:9]
	v_add_u32_e32 v34, s6, v67
	v_add_u32_e32 v8, s2, v68
	v_mov_b32_e32 v5, v9
	s_add_i32 s19, s15, 8
	s_add_i32 s21, s15, 12
	s_add_i32 s25, s16, 16
	v_add_u32_e32 v4, s6, v33
	v_or_b32_e32 v72, s22, v6
	v_lshlrev_b64 v[34:35], 10, v[34:35]
	v_lshlrev_b64 v[62:63], 10, v[8:9]
	v_add_u32_e32 v8, s2, v70
	s_add_i32 s33, s16, 20
	v_or_b32_e32 v69, s19, v1
	v_or_b32_e32 v71, s21, v1
	v_or_b32_e32 v74, s25, v6
	v_lshlrev_b64 v[4:5], 10, v[4:5]
	v_lshl_add_u64 v[60:61], v[2:3], 0, v[60:61]
	v_lshl_add_u64 v[34:35], v[2:3], 0, v[34:35]
	v_lshlrev_b64 v[64:65], 10, v[8:9]
	v_add_u32_e32 v8, s2, v72
	v_mov_b32_e32 v49, v9
	v_mov_b32_e32 v51, v9
	s_add_i32 s23, s15, 16
	s_add_i32 s27, s15, 20
	s_add_i32 s36, s16, 24
	v_or_b32_e32 v76, s33, v6
	v_add_u32_e32 v48, s6, v69
	v_add_u32_e32 v50, s6, v71
	v_lshl_add_u64 v[4:5], v[2:3], 0, v[4:5]
	v_lshl_add_u64 v[62:63], v[2:3], 0, v[62:63]
	global_load_dword v81, v[60:61], off
	global_load_dword v82, v[4:5], off
	global_load_dword v83, v[62:63], off
	global_load_dword v84, v[34:35], off
	v_lshlrev_b64 v[34:35], 10, v[8:9]
	v_add_u32_e32 v8, s2, v74
	s_add_i32 s35, s15, 24
	s_add_i32 s15, s15, 28
	s_add_i32 s16, s16, 28
	v_or_b32_e32 v73, s23, v1
	v_or_b32_e32 v75, s27, v1
	v_or_b32_e32 v78, s36, v6
	v_lshlrev_b64 v[48:49], 10, v[48:49]
	v_lshlrev_b64 v[50:51], 10, v[50:51]
	v_lshl_add_u64 v[4:5], v[2:3], 0, v[64:65]
	v_lshl_add_u64 v[34:35], v[2:3], 0, v[34:35]
	v_lshlrev_b64 v[60:61], 10, v[8:9]
	v_add_u32_e32 v8, s2, v76
	v_mov_b32_e32 v53, v9
	v_mov_b32_e32 v55, v9
	v_or_b32_e32 v77, s35, v1
	v_or_b32_e32 v79, s15, v1
	v_or_b32_e32 v80, s16, v6
	v_add_u32_e32 v52, s6, v73
	v_add_u32_e32 v54, s6, v75
	v_lshl_add_u64 v[48:49], v[2:3], 0, v[48:49]
	v_lshl_add_u64 v[50:51], v[2:3], 0, v[50:51]
	global_load_dword v85, v[4:5], off
	global_load_dword v86, v[48:49], off
	global_load_dword v87, v[34:35], off
	global_load_dword v88, v[50:51], off
	v_lshlrev_b64 v[34:35], 10, v[8:9]
	v_add_u32_e32 v8, s2, v78
	v_mov_b32_e32 v57, v9
	v_mov_b32_e32 v59, v9
	v_add_u32_e32 v56, s6, v77
	v_add_u32_e32 v58, s6, v79
	v_lshlrev_b64 v[52:53], 10, v[52:53]
	v_lshlrev_b64 v[54:55], 10, v[54:55]
	v_lshl_add_u64 v[4:5], v[2:3], 0, v[60:61]
	v_lshl_add_u64 v[34:35], v[2:3], 0, v[34:35]
	v_lshlrev_b64 v[48:49], 10, v[8:9]
	v_add_u32_e32 v8, s2, v80
	v_lshlrev_b64 v[56:57], 10, v[56:57]
	v_lshlrev_b64 v[58:59], 10, v[58:59]
	v_lshl_add_u64 v[52:53], v[2:3], 0, v[52:53]
	v_lshl_add_u64 v[54:55], v[2:3], 0, v[54:55]
	global_load_dword v89, v[4:5], off
	global_load_dword v90, v[52:53], off
	global_load_dword v91, v[34:35], off
	global_load_dword v92, v[54:55], off
	v_lshl_add_u64 v[4:5], v[2:3], 0, v[48:49]
	v_lshlrev_b64 v[34:35], 10, v[8:9]
	v_lshl_add_u64 v[56:57], v[2:3], 0, v[56:57]
	v_lshl_add_u64 v[58:59], v[2:3], 0, v[58:59]
	v_lshl_add_u64 v[34:35], v[2:3], 0, v[34:35]
	global_load_dword v8, v[4:5], off
	global_load_dword v93, v[56:57], off
	global_load_dword v94, v[34:35], off
	global_load_dword v95, v[58:59], off
	s_add_i32 s8, s8, 16
	s_add_i32 s7, s7, 16
	s_add_i32 s9, s9, -16
	v_mad_u64_u32 v[4:5], s[16:17], v66, s10, v[12:13]
	s_cmp_lg_u32 s9, 0
	v_mad_u64_u32 v[34:35], s[16:17], v33, s10, v[12:13]
	v_mad_u64_u32 v[48:49], s[16:17], v68, s10, v[12:13]
	v_mad_u64_u32 v[50:51], s[16:17], v67, s10, v[12:13]
	v_mad_u64_u32 v[52:53], s[16:17], v70, s10, v[12:13]
	v_mad_u64_u32 v[54:55], s[16:17], v69, s10, v[12:13]
	v_mad_u64_u32 v[56:57], s[16:17], v72, s10, v[12:13]
	v_mad_u64_u32 v[58:59], s[16:17], v71, s10, v[12:13]
	v_mad_u64_u32 v[60:61], s[16:17], v74, s10, v[12:13]
	v_mad_u64_u32 v[62:63], s[16:17], v73, s10, v[12:13]
	v_mad_u64_u32 v[64:65], s[16:17], v76, s10, v[12:13]
	v_mad_u64_u32 v[66:67], s[16:17], v75, s10, v[12:13]
	v_mad_u64_u32 v[68:69], s[16:17], v78, s10, v[12:13]
	v_mad_u64_u32 v[70:71], s[16:17], v77, s10, v[12:13]
	v_mad_u64_u32 v[72:73], s[16:17], v80, s10, v[12:13]
	v_mad_u64_u32 v[74:75], s[16:17], v79, s10, v[12:13]
	s_waitcnt vmcnt(15)
	ds_write_b32 v4, v81
	s_waitcnt vmcnt(14)
	ds_write_b32 v34, v82
	s_waitcnt vmcnt(13)
	ds_write_b32 v48, v83
	s_waitcnt vmcnt(12)
	ds_write_b32 v50, v84
	s_waitcnt vmcnt(11)
	ds_write_b32 v52, v85
	s_waitcnt vmcnt(10)
	ds_write_b32 v54, v86
	s_waitcnt vmcnt(9)
	ds_write_b32 v56, v87
	s_waitcnt vmcnt(8)
	ds_write_b32 v58, v88
	s_waitcnt vmcnt(7)
	ds_write_b32 v60, v89
	s_waitcnt vmcnt(6)
	ds_write_b32 v62, v90
	s_waitcnt vmcnt(5)
	ds_write_b32 v64, v91
	s_waitcnt vmcnt(4)
	ds_write_b32 v66, v92
	s_waitcnt vmcnt(3)
	ds_write_b32 v68, v8
	s_waitcnt vmcnt(2)
	ds_write_b32 v70, v93
	s_waitcnt vmcnt(1)
	ds_write_b32 v72, v94
	s_waitcnt vmcnt(0)
	ds_write_b32 v74, v95
	s_cbranch_scc1 .LBB0_39
; #define LAS __attribute__((address_space(3)))
; __device__ __forceinline__ unsigned pk2(float lo, float hi) { unsigned r; asm("v_cvt_pk_bf16_f32 %0, %1, %2" : "=v"(r) : "v"(lo), "v"(hi)); return r; }
; __device__ __forceinline__ void tr_item(const float* W, int K, int N, bf16_t* WT, int ldt, LAS float* scr, int item, int lane, int mapmode, int p0, int p1) {
;     ...
;     const int c = lane & 7;
; #pragma unroll
;     for (int j = 0; j < 4; ++j) { const int n = (lane >> 3) + 8 * j; const LAS float* s = scr + (8 * c) * 33 + n;
;         u32x4 o; o.x = pk2(s[0 * 33], s[1 * 33]); o.y = pk2(s[2 * 33], s[3 * 33]); o.z = pk2(s[4 * 33], s[5 * 33]); o.w = pk2(s[6 * 33], s[7 * 33]);
;         const int ns = n0 + n; int dst;
;         if (mapmode == 0) dst = p0 + (ns & ~255) + 128 * ((ns >> 5) & 1) + 32 * ((ns >> 6) & 3) + (ns & 31);
;         else if (mapmode == 1) dst = (ns >= p0 && ns < p1) ? ((ns & ~127) + il128(ns & 127)) : ns;
;         else dst = 256 * (ns >> 7) + 128 * ((ns >> 2) & 1) + 32 * ((ns >> 5) & 3) + 8 * ((ns >> 3) & 3) + 4 * p0 + (ns & 3);
;         *(u32x4*)(WT + (size_t)dst * ldt + k0 + 8 * c) = o; }
	s_lshl_b32 s2, s2, 1
	v_lshl_add_u64 v[62:63], v[26:27], 0, s[2:3]
	s_lshl_b32 s2, s14, 4
	s_and_b32 s0, s0, 0x80
	s_and_b32 s2, s2, 0x60
	s_or_b32 s0, s2, s0
	s_lshl_b32 s1, s1, 8
	s_waitcnt lgkmcnt(0)
	v_or_b32_e32 v8, s0, v7
	ds_read2_b32 v[34:35], v13 offset0:33 offset1:41
	ds_read2_b32 v[48:49], v13 offset1:8
	ds_read2_b32 v[50:51], v13 offset0:66 offset1:74
	ds_read2_b32 v[52:53], v13 offset0:99 offset1:107
	ds_read2_b32 v[54:55], v13 offset0:132 offset1:140
	ds_read2_b32 v[56:57], v13 offset0:165 offset1:173
	ds_read2_b32 v[58:59], v13 offset0:198 offset1:206
	ds_read2_b32 v[60:61], v13 offset0:231 offset1:239
	v_or_b32_e32 v8, s1, v8
	v_lshlrev_b32_e32 v8, 9, v8
	v_lshl_add_u64 v[64:65], v[62:63], 0, v[8:9]
	v_or_b32_e32 v8, s0, v36
	v_or_b32_e32 v8, s1, v8
	s_waitcnt lgkmcnt(6)
	v_cvt_pk_bf16_f32 v2, v48, v34
	v_lshlrev_b32_e32 v8, 9, v8
	s_waitcnt lgkmcnt(4)
	v_cvt_pk_bf16_f32 v3, v50, v52
	s_waitcnt lgkmcnt(2)
	v_cvt_pk_bf16_f32 v4, v54, v56
	s_waitcnt lgkmcnt(0)
	v_cvt_pk_bf16_f32 v5, v58, v60
	global_store_dwordx4 v[64:65], v[2:5], off sc0 sc1
	s_nop 1
	v_cvt_pk_bf16_f32 v2, v49, v35
	v_lshl_add_u64 v[34:35], v[62:63], 0, v[8:9]
	v_or_b32_e32 v8, s0, v37
	v_cvt_pk_bf16_f32 v3, v51, v53
	v_cvt_pk_bf16_f32 v4, v55, v57
	v_cvt_pk_bf16_f32 v5, v59, v61
	ds_read2_b32 v[48:49], v13 offset0:16 offset1:24
	ds_read2_b32 v[50:51], v13 offset0:49 offset1:57
	ds_read2_b32 v[52:53], v13 offset0:82 offset1:90
	ds_read2_b32 v[54:55], v13 offset0:115 offset1:123
	ds_read2_b32 v[56:57], v13 offset0:148 offset1:156
	ds_read2_b32 v[58:59], v13 offset0:181 offset1:189
	ds_read2_b32 v[60:61], v13 offset0:214 offset1:222
	ds_read2_b32 v[64:65], v13 offset0:247 offset1:255
	v_or_b32_e32 v8, s1, v8
	v_lshlrev_b32_e32 v8, 9, v8
	global_store_dwordx4 v[34:35], v[2:5], off sc0 sc1
	v_lshl_add_u64 v[34:35], v[62:63], 0, v[8:9]
	v_or_b32_e32 v8, s0, v38
	v_or_b32_e32 v8, s1, v8
	v_lshlrev_b32_e32 v8, 9, v8
	s_waitcnt lgkmcnt(6)
	v_cvt_pk_bf16_f32 v2, v48, v50
	s_waitcnt lgkmcnt(4)
	v_cvt_pk_bf16_f32 v3, v52, v54
	s_waitcnt lgkmcnt(2)
	v_cvt_pk_bf16_f32 v4, v56, v58
	s_waitcnt lgkmcnt(0)
	v_cvt_pk_bf16_f32 v5, v60, v64
	global_store_dwordx4 v[34:35], v[2:5], off sc0 sc1
	v_lshl_add_u64 v[34:35], v[62:63], 0, v[8:9]
	s_nop 0
	v_cvt_pk_bf16_f32 v2, v49, v51
	v_cvt_pk_bf16_f32 v3, v53, v55
	v_cvt_pk_bf16_f32 v4, v57, v59
	v_cvt_pk_bf16_f32 v5, v61, v65
	global_store_dwordx4 v[34:35], v[2:5], off sc0 sc1
	s_waitcnt lgkmcnt(0)

; __device__ __forceinline__ void tr_item(const float* W, int K, int N, bf16_t* WT, int ldt, LAS float* scr, int item, int lane, int mapmode, int p0, int p1) {
;     ...
;         const int ns = n0 + n; int dst;
;         if (mapmode == 0) dst = p0 + (ns & ~255) + 128 * ((ns >> 5) & 1) + 32 * ((ns >> 6) & 3) + (ns & 31);
;         else if (mapmode == 1) dst = (ns >= p0 && ns < p1) ? ((ns & ~127) + il128(ns & 127)) : ns;
;         else dst = 256 * (ns >> 7) + 128 * ((ns >> 2) & 1) + 32 * ((ns >> 5) & 3) + 8 * ((ns >> 3) & 3) + 4 * p0 + (ns & 3);
;         *(u32x4*)(WT + (size_t)dst * ldt + k0 + 8 * c) = o; }
.LBB0_46:
	ds_read2_b32 v[50:51], v13 offset0:8 offset1:41
	ds_read2_b32 v[52:53], v13 offset0:74 offset1:107
	ds_read2_b32 v[54:55], v13 offset0:140 offset1:173
	ds_read2_b32 v[56:57], v13 offset0:206 offset1:239
	s_ashr_i32 s1, s0, 31
	v_mul_lo_u32 v48, v8, s12
	v_lshl_add_u64 v[34:35], s[0:1], 1, v[30:31]
	v_ashrrev_i32_e32 v49, 31, v48
	v_cndmask_b32_e64 v8, 0, 1, s[8:9]
	v_lshl_add_u64 v[48:49], v[34:35], 0, v[48:49]
	v_cmp_ne_u32_e64 s[0:1], 1, v8
	s_andn2_b64 vcc, exec, s[8:9]
	v_or_b32_e32 v8, s6, v36
	global_store_dwordx4 v[48:49], v[2:5], off sc0 sc1
	s_waitcnt lgkmcnt(3)
	s_nop 0
	v_cvt_pk_bf16_f32 v2, v50, v51
	s_waitcnt lgkmcnt(2)
	v_cvt_pk_bf16_f32 v3, v52, v53
	s_waitcnt lgkmcnt(1)
	v_cvt_pk_bf16_f32 v4, v54, v55
	s_waitcnt lgkmcnt(0)
	v_cvt_pk_bf16_f32 v5, v56, v57
	s_cbranch_vccnz .LBB0_48
	s_lshr_b32 s7, s6, 4
	s_and_b32 s2, s6, 0x1f80
	v_lshlrev_b32_e32 v8, 1, v8
	s_and_b32 s7, s7, 4
	v_and_b32_e32 v8, 0x58, v8
	s_or_b32 s2, s2, s7
	v_or3_b32 v8, s2, v8, v39
.LBB0_48:
	ds_read2_b32 v[50:51], v13 offset0:16 offset1:49
	ds_read2_b32 v[52:53], v13 offset0:82 offset1:115
	ds_read2_b32 v[54:55], v13 offset0:148 offset1:181
	ds_read2_b32 v[56:57], v13 offset0:214 offset1:247
	v_mul_lo_u32 v48, v8, s12
	v_ashrrev_i32_e32 v49, 31, v48
	v_lshl_add_u64 v[48:49], v[34:35], 0, v[48:49]
	s_and_b64 vcc, exec, s[0:1]
	v_or_b32_e32 v8, s6, v37
	global_store_dwordx4 v[48:49], v[2:5], off sc0 sc1
	s_waitcnt lgkmcnt(3)
	s_nop 0
	v_cvt_pk_bf16_f32 v2, v50, v51
	s_waitcnt lgkmcnt(2)
	v_cvt_pk_bf16_f32 v3, v52, v53
	s_waitcnt lgkmcnt(1)
	v_cvt_pk_bf16_f32 v4, v54, v55
	s_waitcnt lgkmcnt(0)
	v_cvt_pk_bf16_f32 v5, v56, v57
	s_cbranch_vccnz .LBB0_50
	s_lshr_b32 s7, s6, 4
	s_and_b32 s2, s6, 0x1f80
	v_lshlrev_b32_e32 v8, 1, v8
	s_and_b32 s7, s7, 4
	v_and_b32_e32 v8, 0x68, v8
	s_or_b32 s2, s2, s7
	v_or3_b32 v8, s2, v8, v39
.LBB0_50:
	ds_read2_b32 v[50:51], v13 offset0:24 offset1:57
	ds_read2_b32 v[52:53], v13 offset0:90 offset1:123
	ds_read2_b32 v[54:55], v13 offset0:156 offset1:189
	ds_read2_b32 v[56:57], v13 offset0:222 offset1:255
	v_mul_lo_u32 v48, v8, s12
	v_ashrrev_i32_e32 v49, 31, v48
	v_lshl_add_u64 v[48:49], v[34:35], 0, v[48:49]
	s_and_b64 vcc, exec, s[0:1]
	v_or_b32_e32 v8, s6, v38
	global_store_dwordx4 v[48:49], v[2:5], off sc0 sc1
	s_waitcnt lgkmcnt(3)
	s_nop 0
	v_cvt_pk_bf16_f32 v2, v50, v51
	s_waitcnt lgkmcnt(2)
	v_cvt_pk_bf16_f32 v3, v52, v53
	s_waitcnt lgkmcnt(1)
	v_cvt_pk_bf16_f32 v4, v54, v55
	s_waitcnt lgkmcnt(0)
	v_cvt_pk_bf16_f32 v5, v56, v57
	s_cbranch_vccnz .LBB0_11
	s_lshr_b32 s1, s6, 4
	s_and_b32 s0, s6, 0x1f80
	v_lshlrev_b32_e32 v8, 1, v8
	s_and_b32 s1, s1, 4
	v_and_b32_e32 v8, 0x78, v8
	s_or_b32 s0, s0, s1
	v_or3_b32 v8, s0, v8, v39
	s_branch .LBB0_11

; __device__ __forceinline__ void p_prologue(const Args& a, LAS unsigned char* lds, const Ctx& c) {
;     ...
;         const int t = i >> 6, e = i & 63; double pw = 1.0; for (int k = 0; k < e; ++k) pw *= 1.1547819846894583;
;         const float inv = 1.0f / (float)pw; const double ang = (double)((float)t * inv);
;         const double kq = rint(ang * 0.6366197723675814); const double r = (ang - kq * 1.5707963267948966) - kq * 6.123233995736766e-17; const double r2 = r * r;
;         const double sn = r * (1.0 + r2 * (-1.0 / 6 + r2 * (1.0 / 120 + r2 * (-1.0 / 5040 + r2 * (1.0 / 362880 + r2 * (-1.0 / 39916800 + r2 * (1.0 / 6227020800.0)))))));
;         const double cs = 1.0 + r2 * (-0.5 + r2 * (1.0 / 24 + r2 * (-1.0 / 720 + r2 * (1.0 / 40320 + r2 * (-1.0 / 3628800 + r2 * (1.0 / 479001600 + r2 * (-1.0 / 87178291200.0)))))));
;         const int qd = ((int)kq) & 3; const double cc = (qd == 0) ? cs : (qd == 1) ? -sn : (qd == 2) ? -cs : sn; const double ss = (qd == 0) ? sn : (qd == 1) ? cs : (qd == 2) ? -sn : -cs;
;         cosT[i] = (float)cc; sinT[i] = (float)ss; }
.LBB0_55:
	s_or_b64 exec, exec, s[42:43]
	v_cmp_eq_u32_e64 s[2:3], 2, v1
	s_nop 1
	v_cndmask_b32_e64 v23, v26, v24, s[2:3]
	v_cndmask_b32_e64 v30, -v27, -v25, s[2:3]
	v_cmp_eq_u32_e64 s[2:3], 1, v1
	s_nop 1
	v_cndmask_b32_e64 v1, v23, v26, s[2:3]
	v_cndmask_b32_e64 v23, v30, v27, s[2:3]
	v_cndmask_b32_e32 v25, v23, v25, vcc
	v_ashrrev_i32_e32 v23, 31, v22
	v_lshlrev_b64 v[26:27], 2, v[22:23]
	v_add_u32_e32 v22, s24, v22
	v_cndmask_b32_e32 v24, v1, v24, vcc
	v_cvt_f32_f64_e32 v1, v[28:29]
	v_lshl_add_u64 v[28:29], s[8:9], 0, v[26:27]
	v_cmp_lt_i32_e32 vcc, s25, v22
	global_store_dword v[28:29], v1, off sc0 sc1
	v_cvt_f32_f64_e32 v1, v[24:25]
	v_lshl_add_u64 v[24:25], s[10:11], 0, v[26:27]
	s_or_b64 s[12:13], vcc, s[12:13]
	global_store_dword v[24:25], v1, off sc0 sc1
	s_andn2_b64 exec, exec, s[12:13]
	s_cbranch_execz .LBB0_63

; __device__ __forceinline__ void p_prologue(const Args& a, LAS unsigned char* lds, const Ctx& c) {
;     ...
;     for (int i = c.gt; i < BATCH * 8 * 16 * 128; i += c.NGT) kmean[i] = 0.f;
.LBB0_66:
	v_add_u32_e32 v6, -2, v6
	v_ashrrev_i32_e32 v9, 31, v3
	v_mov_b32_e32 v8, v3
	v_ashrrev_i32_e32 v11, 31, v2
	v_mov_b32_e32 v10, v2
	v_cmp_eq_u32_e32 vcc, 0, v6
	v_add_u32_e32 v3, s11, v3
	v_add_u32_e32 v2, s10, v2
	v_lshl_add_u64 v[10:11], v[10:11], 2, s[6:7]
	v_lshl_add_u64 v[8:9], v[8:9], 2, s[6:7]
	s_or_b64 s[8:9], vcc, s[8:9]
	global_store_dword v[10:11], v5, off sc0 sc1
	global_store_dword v[8:9], v5, off sc0 sc1
	s_andn2_b64 exec, exec, s[8:9]
	s_cbranch_execnz .LBB0_66
	s_or_b64 exec, exec, s[8:9]
	v_mad_u64_u32 v[2:3], s[6:7], v4, s24, v[144:145]
	v_cmp_ne_u32_e32 vcc, v1, v4
	s_orn2_b64 s[6:7], vcc, exec

; __device__ __forceinline__ void p_prologue(const Args& a, LAS unsigned char* lds, const Ctx& c) {
;     ...
;     for (int i = c.gt; i < BATCH * 8 * 16 * 128; i += c.NGT) kmean[i] = 0.f;
.LBB0_70:
	v_add_u32_e32 v2, s24, v2
	v_cmp_lt_i32_e32 vcc, s8, v2
	global_store_dword v[4:5], v1, off sc0 sc1
	s_or_b64 s[6:7], vcc, s[6:7]
	v_lshl_add_u64 v[4:5], v[4:5], 0, s[0:1]
	s_andn2_b64 exec, exec, s[6:7]
	s_cbranch_execnz .LBB0_70

; __device__ __forceinline__ unsigned pk2(float lo, float hi) { unsigned r; asm("v_cvt_pk_bf16_f32 %0, %1, %2" : "=v"(r) : "v"(lo), "v"(hi)); return r; }
; __device__ __forceinline__ void row_norm_store(const f32x4 (&v)[8], const float* gain, bf16_t* orow, int lane) {
;     float s = 0.f;
; #pragma unroll
;     for (int j = 0; j < 8; ++j) s += (v[j][0] * v[j][0] + v[j][1] * v[j][1]) + (v[j][2] * v[j][2] + v[j][3] * v[j][3]);
;     const float rs = 1.0f / sqrtf(wave_sum(s) * (1.0f / D_MODEL) + EPS);
; #pragma unroll
;     for (int j = 0; j < 8; ++j) { const f32x4 gv = *(const f32x4*)(gain + 4 * lane + 256 * j); const f32x4 y = v[j] * rs * gv;
;         u32x2 w; w.x = pk2(y[0], y[1]); w.y = pk2(y[2], y[3]); *(u32x2*)(orow + 4 * lane + 256 * j) = w; }
; }
; __device__ __forceinline__ void p_prologue(const Args& a, LAS unsigned char* lds, const Ctx& c) {
;     ...
;     for (int m = c.gw; m < MTOK; m += c.NGW) { f32x4 v[8];
; #pragma unroll
;         for (int j = 0; j < 8; ++j) v[j] = *(const f32x4*)(a.x + (size_t)m * D_MODEL + 4 * c.lane + 256 * j);
;         row_norm_store(v, a.gains, HN0 + (size_t)m * LDH, c.lane); }
.LBB0_73:
	global_load_dwordx4 v[48:51], v[36:37], off offset:-4096
	global_load_dwordx4 v[52:55], v[36:37], off offset:-3072
	global_load_dwordx4 v[22:25], v[36:37], off offset:-2048
	global_load_dwordx4 v[18:21], v[36:37], off offset:-1024
	global_load_dwordx4 v[10:13], v[36:37], off offset:1024
	global_load_dwordx4 v[6:9], v[36:37], off offset:2048
	global_load_dwordx4 v[14:17], v[36:37], off
	global_load_dwordx4 v[2:5], v[36:37], off offset:3072
	global_load_dwordx4 v[56:59], v[26:27], off
	s_add_i32 s7, s7, s60
	v_lshl_add_u64 v[36:37], v[36:37], 0, s[2:3]
	s_cmpk_lt_i32 s7, 0x4000
	s_waitcnt vmcnt(8)
	v_mov_b32_e32 v62, v49
	s_waitcnt vmcnt(7)
	v_mov_b32_e32 v63, v53
	v_mov_b32_e32 v66, v51
	v_mov_b32_e32 v67, v55
	v_mov_b32_e32 v60, v48
	v_mov_b32_e32 v61, v52
	v_mov_b32_e32 v64, v50
	v_mov_b32_e32 v65, v54
	s_waitcnt vmcnt(6)
	v_pk_mul_f32 v[68:69], v[24:25], v[24:25]
	v_pk_mul_f32 v[70:71], v[22:23], v[22:23]
	v_pk_mul_f32 v[62:63], v[62:63], v[62:63]
	v_pk_mul_f32 v[66:67], v[66:67], v[66:67]
	v_pk_mov_b32 v[84:85], v[70:71], v[68:69] op_sel:[1,0]
	v_mov_b32_e32 v71, v69
	v_pk_fma_f32 v[60:61], v[60:61], v[60:61], v[62:63]
	v_pk_fma_f32 v[62:63], v[64:65], v[64:65], v[66:67]
	s_waitcnt vmcnt(5)
	v_mul_f32_e32 v72, v18, v18
	v_mul_f32_e32 v74, v20, v20
	v_pk_add_f32 v[64:65], v[84:85], v[70:71]
	v_pk_add_f32 v[60:61], v[60:61], v[62:63]
	v_pk_fma_f32 v[68:69], v[18:19], v[18:19], v[72:73] op_sel_hi:[1,1,0]
	v_pk_fma_f32 v[72:73], v[20:21], v[20:21], v[74:75] op_sel_hi:[1,1,0]
	v_pk_add_f32 v[62:63], v[64:65], v[64:65] op_sel_hi:[0,1]
	v_pk_add_f32 v[60:61], v[60:61], v[60:61] op_sel_hi:[0,1]
	s_waitcnt vmcnt(4)
	v_pk_mul_f32 v[76:77], v[12:13], v[12:13]
	v_pk_mul_f32 v[78:79], v[10:11], v[10:11]
	s_waitcnt vmcnt(2)
	v_mul_f32_e32 v68, v14, v14
	v_mul_f32_e32 v72, v15, v15
	v_mul_f32_e32 v62, v16, v16
	v_mul_f32_e32 v60, v17, v17
	v_pk_mov_b32 v[74:75], v[78:79], v[76:77] op_sel:[1,0]
	v_mov_b32_e32 v79, v77
	v_pk_add_f32 v[64:65], v[68:69], v[72:73]
	v_pk_add_f32 v[60:61], v[62:63], v[60:61]
	v_mul_f32_e32 v80, v6, v6
	v_mul_f32_e32 v82, v8, v8
	v_pk_add_f32 v[66:67], v[74:75], v[78:79]
	v_pk_add_f32 v[60:61], v[64:65], v[60:61]
	v_pk_fma_f32 v[76:77], v[6:7], v[6:7], v[80:81] op_sel_hi:[1,1,0]
	v_pk_fma_f32 v[80:81], v[8:9], v[8:9], v[82:83] op_sel_hi:[1,1,0]
	v_pk_add_f32 v[66:67], v[66:67], v[66:67] op_sel_hi:[0,1]
	v_pk_add_f32 v[60:61], v[60:61], v[60:61] op_sel_hi:[0,1]
	s_waitcnt vmcnt(1)
	v_mul_f32_e32 v76, v2, v2
	v_mul_f32_e32 v80, v3, v3
	v_mul_f32_e32 v66, v4, v4
	v_mul_f32_e32 v60, v5, v5
	v_pk_add_f32 v[68:69], v[76:77], v[80:81]
	v_pk_add_f32 v[60:61], v[66:67], v[60:61]
	s_nop 0
	v_pk_add_f32 v[60:61], v[68:69], v[60:61]
	s_nop 0
	v_add_f32_e32 v47, v60, v61
	ds_bpermute_b32 v60, v1, v47
	s_waitcnt lgkmcnt(0)
	v_add_f32_e32 v47, v47, v60
	ds_bpermute_b32 v60, v40, v47
	s_waitcnt lgkmcnt(0)
	v_add_f32_e32 v47, v47, v60
	ds_bpermute_b32 v60, v41, v47
	s_waitcnt lgkmcnt(0)
	v_add_f32_e32 v47, v47, v60
	ds_bpermute_b32 v60, v42, v47
	s_waitcnt lgkmcnt(0)
	v_add_f32_e32 v47, v47, v60
	ds_bpermute_b32 v60, v43, v47
	s_waitcnt lgkmcnt(0)
	v_add_f32_e32 v47, v47, v60
	ds_bpermute_b32 v60, v44, v47
	s_waitcnt lgkmcnt(0)
	v_add_f32_e32 v47, v47, v60
	v_fmamk_f32 v47, v47, 0x3a000000, v45
	v_mul_f32_e32 v60, 0x4f800000, v47
	v_cmp_gt_f32_e32 vcc, s6, v47
	s_nop 1
	v_cndmask_b32_e32 v47, v47, v60, vcc
	v_sqrt_f32_e32 v60, v47
	s_nop 0
	v_add_u32_e32 v61, -1, v60
	v_add_u32_e32 v62, 1, v60
	v_fma_f32 v63, -v61, v60, v47
	v_fma_f32 v64, -v62, v60, v47
	v_cmp_ge_f32_e64 s[0:1], 0, v63
	s_nop 1
	v_cndmask_b32_e64 v60, v60, v61, s[0:1]
	v_cmp_lt_f32_e64 s[0:1], 0, v64
	s_nop 1
	v_cndmask_b32_e64 v60, v60, v62, s[0:1]
	v_mul_f32_e32 v61, 0x37800000, v60
	v_cndmask_b32_e32 v60, v60, v61, vcc
	v_cmp_class_f32_e32 vcc, v47, v46
	s_nop 1
	v_cndmask_b32_e32 v47, v60, v47, vcc
	v_div_scale_f32 v60, s[0:1], v47, v47, 1.0
	v_rcp_f32_e32 v62, v60
	v_div_scale_f32 v61, vcc, 1.0, v47, 1.0
	v_fma_f32 v63, -v60, v62, 1.0
	v_fmac_f32_e32 v62, v63, v62
	v_mul_f32_e32 v63, v61, v62
	v_fma_f32 v64, -v60, v63, v61
	v_fmac_f32_e32 v63, v64, v62
	v_fma_f32 v60, -v60, v63, v61
	v_div_fmas_f32 v60, v60, v62, v63
	v_div_fixup_f32 v60, v60, v47, 1.0
	v_pk_mul_f32 v[48:49], v[48:49], v[60:61] op_sel_hi:[1,0]
	v_pk_mul_f32 v[50:51], v[50:51], v[60:61] op_sel_hi:[1,0]
	s_waitcnt vmcnt(0)
	v_pk_mul_f32 v[48:49], v[56:57], v[48:49]
	v_pk_mul_f32 v[50:51], v[58:59], v[50:51]
	v_cvt_pk_bf16_f32 v48, v48, v49
	v_pk_mul_f32 v[52:53], v[52:53], v[60:61] op_sel_hi:[1,0]
	v_cvt_pk_bf16_f32 v49, v50, v51
	global_store_dwordx2 v[38:39], v[48:49], off sc0 sc1
	v_pk_mul_f32 v[54:55], v[54:55], v[60:61] op_sel_hi:[1,0]
	v_pk_mul_f32 v[22:23], v[22:23], v[60:61] op_sel_hi:[1,0]
	v_pk_mul_f32 v[24:25], v[24:25], v[60:61] op_sel_hi:[1,0]
	v_pk_mul_f32 v[18:19], v[18:19], v[60:61] op_sel_hi:[1,0]
	v_pk_mul_f32 v[20:21], v[20:21], v[60:61] op_sel_hi:[1,0]
	v_pk_mul_f32 v[14:15], v[14:15], v[60:61] op_sel_hi:[1,0]
	v_pk_mul_f32 v[16:17], v[16:17], v[60:61] op_sel_hi:[1,0]
	v_pk_mul_f32 v[10:11], v[10:11], v[60:61] op_sel_hi:[1,0]
	v_pk_mul_f32 v[12:13], v[12:13], v[60:61] op_sel_hi:[1,0]
	v_pk_mul_f32 v[6:7], v[6:7], v[60:61] op_sel_hi:[1,0]
	v_pk_mul_f32 v[8:9], v[8:9], v[60:61] op_sel_hi:[1,0]
	v_pk_mul_f32 v[2:3], v[2:3], v[60:61] op_sel_hi:[1,0]
	v_pk_mul_f32 v[4:5], v[4:5], v[60:61] op_sel_hi:[1,0]
	v_pk_mul_f32 v[48:49], v[176:177], v[52:53]
	v_pk_mul_f32 v[50:51], v[178:179], v[54:55]
	v_cvt_pk_bf16_f32 v48, v48, v49
	s_nop 0
	v_cvt_pk_bf16_f32 v49, v50, v51
	global_store_dwordx2 v[38:39], v[48:49], off offset:512 sc0 sc1
	v_pk_mul_f32 v[22:23], v[180:181], v[22:23]
	v_pk_mul_f32 v[24:25], v[182:183], v[24:25]
	v_cvt_pk_bf16_f32 v22, v22, v23
	s_nop 0
	v_cvt_pk_bf16_f32 v23, v24, v25
	global_store_dwordx2 v[38:39], v[22:23], off offset:1024 sc0 sc1
	v_pk_mul_f32 v[18:19], v[18:19], v[184:185]
	v_pk_mul_f32 v[20:21], v[20:21], v[186:187]
	v_cvt_pk_bf16_f32 v18, v18, v19
	s_nop 0
	v_cvt_pk_bf16_f32 v19, v20, v21
	global_store_dwordx2 v[38:39], v[18:19], off offset:1536 sc0 sc1
	v_pk_mul_f32 v[14:15], v[14:15], v[188:189]
	v_pk_mul_f32 v[16:17], v[16:17], v[190:191]
	v_cvt_pk_bf16_f32 v14, v14, v15
	s_nop 0
	v_cvt_pk_bf16_f32 v15, v16, v17
	global_store_dwordx2 v[38:39], v[14:15], off offset:2048 sc0 sc1
	v_pk_mul_f32 v[10:11], v[10:11], v[192:193]
	v_pk_mul_f32 v[12:13], v[12:13], v[194:195]
	v_cvt_pk_bf16_f32 v10, v10, v11
	s_nop 0
	v_cvt_pk_bf16_f32 v11, v12, v13
	global_store_dwordx2 v[38:39], v[10:11], off offset:2560 sc0 sc1
	v_pk_mul_f32 v[6:7], v[6:7], v[196:197]
	v_pk_mul_f32 v[8:9], v[8:9], v[198:199]
	v_cvt_pk_bf16_f32 v6, v6, v7
	s_nop 0
	v_cvt_pk_bf16_f32 v7, v8, v9
	global_store_dwordx2 v[38:39], v[6:7], off offset:3072 sc0 sc1
	v_pk_mul_f32 v[2:3], v[2:3], v[200:201]
	v_pk_mul_f32 v[4:5], v[4:5], v[202:203]
	v_cvt_pk_bf16_f32 v2, v2, v3
	s_nop 0
	v_cvt_pk_bf16_f32 v3, v4, v5
	global_store_dwordx2 v[38:39], v[2:3], off offset:3584 sc0 sc1
	v_lshl_add_u64 v[38:39], v[38:39], 0, s[82:83]
	s_cbranch_scc1 .LBB0_73

; __device__ __forceinline__ unsigned cvt_pk_bf16(float lo, float hi) { unsigned r; asm volatile("v_cvt_pk_bf16_f32 %0, %1, %2" : "=v"(r) : "v"(lo), "v"(hi)); return r; }
;     __device__ __forceinline__ void operator()(const f32x4 (&acc)[2][2][4][2], const Unit& u, int wr, int wc, int fr, int fq) const {
;     ...
;         if (!rope) {
; #pragma unroll
;             for (int ai = 0; ai < 2; ++ai)
; #pragma unroll
;                 for (int m = 0; m < 4; ++m) { bf16_t* rowp = O + (size_t)(row0 + ai * HALF + m * 16) * ldc + colt + cin;
; #pragma unroll
;                     for (int bj = 0; bj < 2; ++bj) { const f32x4 v0 = acc[ai][bj][m][0], v1 = acc[ai][bj][m][1];
;                         u32x4 w; w.x = cvt_pk_bf16(v0[0], v0[1]); w.y = cvt_pk_bf16(v0[2], v0[3]); w.z = cvt_pk_bf16(v1[0], v1[1]); w.w = cvt_pk_bf16(v1[2], v1[3]);
;                         *(u32x4*)(rowp + bj * HALF) = w; } }
.LBB0_103:
	v_lshl_add_u32 v172, s49, 8, v143
	s_lshl_b32 s16, s50, 8
	s_add_i32 s17, s50, -4
	s_mov_b64 s[18:19], -1
	s_cmp_lt_u32 s17, 24
	v_or_b32_e32 v171, 16, v172
	v_or_b32_e32 v170, 32, v172
	v_or_b32_e32 v169, 48, v172
	v_add_u32_e32 v167, 0x80, v172
	v_add_u32_e32 v166, 0x90, v172
	v_add_u32_e32 v165, 0xa0, v172
	v_add_u32_e32 v163, 0xb0, v172
	v_lshlrev_b32_e32 v140, 1, v142
	s_cbranch_scc1 .LBB0_105
	v_mov_b64_e32 v[128:129], s[8:9]
	s_ashr_i32 s17, s16, 31
	v_mad_i64_i32 v[130:131], s[18:19], v172, s45, v[128:129]
	s_lshl_b64 s[18:19], s[16:17], 1
	s_nop 0
	v_lshl_add_u64 v[130:131], v[130:131], 0, s[18:19]
	v_lshl_add_u64 v[130:131], v[130:131], 0, v[140:141]
	v_cvt_pk_bf16_f32 v174, v124, v125
	v_cvt_pk_bf16_f32 v175, v126, v127
	v_cvt_pk_bf16_f32 v176, v120, v121
	v_cvt_pk_bf16_f32 v177, v122, v123
	global_store_dwordx4 v[130:131], v[174:177], off sc0 sc1
	s_nop 1
	v_cvt_pk_bf16_f32 v174, v116, v117
	v_cvt_pk_bf16_f32 v175, v118, v119
	v_cvt_pk_bf16_f32 v176, v112, v113
	v_cvt_pk_bf16_f32 v177, v114, v115
	global_store_dwordx4 v[130:131], v[174:177], off offset:256 sc0 sc1
	v_mad_i64_i32 v[130:131], s[20:21], v171, s45, v[128:129]
	v_lshl_add_u64 v[130:131], v[130:131], 0, s[18:19]
	v_lshl_add_u64 v[130:131], v[130:131], 0, v[140:141]
	v_cvt_pk_bf16_f32 v174, v108, v109
	v_cvt_pk_bf16_f32 v175, v110, v111
	v_cvt_pk_bf16_f32 v176, v104, v105
	v_cvt_pk_bf16_f32 v177, v106, v107
	global_store_dwordx4 v[130:131], v[174:177], off sc0 sc1
	s_nop 1
	v_cvt_pk_bf16_f32 v174, v100, v101
	v_cvt_pk_bf16_f32 v175, v102, v103
	v_cvt_pk_bf16_f32 v176, v96, v97
	v_cvt_pk_bf16_f32 v177, v98, v99
	global_store_dwordx4 v[130:131], v[174:177], off offset:256 sc0 sc1
	v_mad_i64_i32 v[130:131], s[20:21], v170, s45, v[128:129]
	v_lshl_add_u64 v[130:131], v[130:131], 0, s[18:19]
	v_lshl_add_u64 v[130:131], v[130:131], 0, v[140:141]
	v_cvt_pk_bf16_f32 v174, v92, v93
	v_cvt_pk_bf16_f32 v175, v94, v95
	v_cvt_pk_bf16_f32 v176, v88, v89
	v_cvt_pk_bf16_f32 v177, v90, v91
	global_store_dwordx4 v[130:131], v[174:177], off sc0 sc1
	s_nop 1
	v_cvt_pk_bf16_f32 v174, v84, v85
	v_cvt_pk_bf16_f32 v175, v86, v87
	v_cvt_pk_bf16_f32 v176, v80, v81
	v_cvt_pk_bf16_f32 v177, v82, v83
	global_store_dwordx4 v[130:131], v[174:177], off offset:256 sc0 sc1
	v_mad_i64_i32 v[130:131], s[20:21], v169, s45, v[128:129]
	v_lshl_add_u64 v[130:131], v[130:131], 0, s[18:19]
	v_lshl_add_u64 v[130:131], v[130:131], 0, v[140:141]
	v_cvt_pk_bf16_f32 v174, v76, v77
	v_cvt_pk_bf16_f32 v175, v78, v79
	v_cvt_pk_bf16_f32 v176, v72, v73
	v_cvt_pk_bf16_f32 v177, v74, v75
	global_store_dwordx4 v[130:131], v[174:177], off sc0 sc1
	s_nop 1
	v_cvt_pk_bf16_f32 v174, v68, v69
	v_cvt_pk_bf16_f32 v175, v70, v71
	v_cvt_pk_bf16_f32 v176, v64, v65
	v_cvt_pk_bf16_f32 v177, v66, v67
	global_store_dwordx4 v[130:131], v[174:177], off offset:256 sc0 sc1
	v_mad_i64_i32 v[130:131], s[20:21], v167, s45, v[128:129]
	v_lshl_add_u64 v[130:131], v[130:131], 0, s[18:19]
	v_lshl_add_u64 v[130:131], v[130:131], 0, v[140:141]
	v_cvt_pk_bf16_f32 v174, v60, v61
	v_cvt_pk_bf16_f32 v175, v62, v63
	v_cvt_pk_bf16_f32 v176, v56, v57
	v_cvt_pk_bf16_f32 v177, v58, v59
	global_store_dwordx4 v[130:131], v[174:177], off sc0 sc1
	s_nop 1
	v_cvt_pk_bf16_f32 v174, v52, v53
	v_cvt_pk_bf16_f32 v175, v54, v55
	v_cvt_pk_bf16_f32 v176, v48, v49
	v_cvt_pk_bf16_f32 v177, v50, v51
	global_store_dwordx4 v[130:131], v[174:177], off offset:256 sc0 sc1
	v_mad_i64_i32 v[130:131], s[20:21], v166, s45, v[128:129]
	v_lshl_add_u64 v[130:131], v[130:131], 0, s[18:19]
	v_lshl_add_u64 v[130:131], v[130:131], 0, v[140:141]
	v_cvt_pk_bf16_f32 v174, v44, v45
	v_cvt_pk_bf16_f32 v175, v46, v47
	v_cvt_pk_bf16_f32 v176, v40, v41
	v_cvt_pk_bf16_f32 v177, v42, v43
	global_store_dwordx4 v[130:131], v[174:177], off sc0 sc1
	s_nop 1
	v_cvt_pk_bf16_f32 v174, v36, v37
	v_cvt_pk_bf16_f32 v175, v38, v39
	v_cvt_pk_bf16_f32 v176, v32, v33
	v_cvt_pk_bf16_f32 v177, v34, v35
	global_store_dwordx4 v[130:131], v[174:177], off offset:256 sc0 sc1
	v_mad_i64_i32 v[130:131], s[20:21], v165, s45, v[128:129]
	v_lshl_add_u64 v[130:131], v[130:131], 0, s[18:19]
	v_lshl_add_u64 v[130:131], v[130:131], 0, v[140:141]
	v_cvt_pk_bf16_f32 v174, v28, v29
	v_cvt_pk_bf16_f32 v175, v30, v31
	v_mad_i64_i32 v[128:129], s[20:21], v163, s45, v[128:129]
	v_cvt_pk_bf16_f32 v176, v24, v25
	v_cvt_pk_bf16_f32 v177, v26, v27
	global_store_dwordx4 v[130:131], v[174:177], off sc0 sc1
	v_lshl_add_u64 v[158:159], v[128:129], 0, s[18:19]
	s_mov_b64 s[18:19], 0
	v_cvt_pk_bf16_f32 v174, v20, v21
	v_cvt_pk_bf16_f32 v175, v22, v23
	v_cvt_pk_bf16_f32 v176, v16, v17
	v_cvt_pk_bf16_f32 v177, v18, v19
	global_store_dwordx4 v[130:131], v[174:177], off offset:256 sc0 sc1
	v_cvt_pk_bf16_f32 v128, v12, v13
	v_cvt_pk_bf16_f32 v129, v14, v15
	v_cvt_pk_bf16_f32 v130, v8, v9
	v_cvt_pk_bf16_f32 v131, v10, v11
	s_nop 1
	v_lshl_add_u64 v[174:175], v[158:159], 0, v[140:141]
	global_store_dwordx4 v[174:175], v[128:131], off sc0 sc1
	s_nop 1
	v_cvt_pk_bf16_f32 v128, v4, v5
	v_cvt_pk_bf16_f32 v129, v6, v7
	v_cvt_pk_bf16_f32 v130, v0, v1
	v_cvt_pk_bf16_f32 v131, v2, v3
; __device__ __forceinline__ unsigned cvt_pk_bf16(float lo, float hi) { unsigned r; asm volatile("v_cvt_pk_bf16_f32 %0, %1, %2" : "=v"(r) : "v"(lo), "v"(hi)); return r; }
;     __device__ __forceinline__ void operator()(const f32x4 (&acc)[2][2][4][2], const Unit& u, int wr, int wc, int fr, int fq) const {
;     ...
;             for (int ai = 0; ai < 2; ++ai)
; #pragma unroll
;                 for (int m = 0; m < 4; ++m) { const int row = row0 + ai * HALF + m * 16, t = row & (SEQ - 1);
;                     const f32x4 c4 = *(const f32x4*)(cosT + t * 64 + e0), s4 = *(const f32x4*)(sinT + t * 64 + e0);
;                     bf16_t* rowp = O + (size_t)row * ldc + colt + cin;
; #pragma unroll
;                     for (int bj = 0; bj < 2; ++bj) { const f32x4 x1 = acc[ai][bj][m][0], x2 = acc[ai][bj][m][1];
;                         const f32x4 o1 = x1 * c4 - x2 * s4, o2 = x2 * c4 + x1 * s4;
;                         ks[bj][0] += o1; ks[bj][1] += o2;
;                         u32x4 w; w.x = cvt_pk_bf16(o1[0], o1[1]); w.y = cvt_pk_bf16(o1[2], o1[3]); w.z = cvt_pk_bf16(o2[0], o2[1]); w.w = cvt_pk_bf16(o2[2], o2[3]);
;                         *(u32x4*)(rowp + bj * HALF) = w; } }
.LBB0_105:
	s_andn2_b64 vcc, exec, s[18:19]
	s_cbranch_vccnz .LBB0_107
	v_lshlrev_b32_e32 v128, 8, v172
	v_and_b32_e32 v128, 0xfcf00, v128
	v_mov_b32_e32 v129, v141
	v_lshl_add_u64 v[130:131], v[148:149], 0, v[128:129]
	global_load_dwordx4 v[174:177], v[130:131], off
	v_lshl_add_u64 v[128:129], v[146:147], 0, v[128:129]
	global_load_dwordx4 v[178:181], v[128:129], off
	s_mov_b32 s17, s39
	v_mov_b64_e32 v[128:129], s[8:9]
	v_mad_i64_i32 v[158:159], s[18:19], v172, s45, v[128:129]
	s_lshl_b64 s[16:17], s[16:17], 1
	v_lshlrev_b32_e32 v130, 8, v171
	v_lshl_add_u64 v[158:159], v[158:159], 0, s[16:17]
	v_mov_b32_e32 v131, v141
	v_and_b32_e32 v130, 0xfdf00, v130
	v_lshl_add_u64 v[158:159], v[158:159], 0, v[140:141]
	v_lshl_add_u64 v[172:173], v[148:149], 0, v[130:131]
	s_waitcnt vmcnt(0)
	v_pk_mul_f32 v[182:183], v[122:123], v[176:177]
	v_pk_mul_f32 v[184:185], v[120:121], v[174:175]
	v_pk_mul_f32 v[186:187], v[126:127], v[176:177]
	v_pk_mul_f32 v[188:189], v[124:125], v[174:175]
	v_pk_mul_f32 v[190:191], v[114:115], v[176:177]
	v_pk_mul_f32 v[192:193], v[112:113], v[174:175]
	v_pk_mul_f32 v[176:177], v[118:119], v[176:177]
	v_pk_mul_f32 v[174:175], v[116:117], v[174:175]
	v_pk_fma_f32 v[126:127], v[126:127], v[180:181], v[182:183] neg_lo:[0,0,1] neg_hi:[0,0,1]
	v_pk_fma_f32 v[124:125], v[124:125], v[178:179], v[184:185] neg_lo:[0,0,1] neg_hi:[0,0,1]
	v_pk_fma_f32 v[122:123], v[122:123], v[180:181], v[186:187]
	v_pk_fma_f32 v[120:121], v[120:121], v[178:179], v[188:189]
	v_pk_fma_f32 v[176:177], v[114:115], v[180:181], v[176:177]
	v_pk_fma_f32 v[174:175], v[112:113], v[178:179], v[174:175]
	v_cvt_pk_bf16_f32 v112, v124, v125
	v_cvt_pk_bf16_f32 v113, v126, v127
	v_cvt_pk_bf16_f32 v114, v120, v121
	v_cvt_pk_bf16_f32 v115, v122, v123
	v_pk_fma_f32 v[118:119], v[118:119], v[180:181], v[190:191] neg_lo:[0,0,1] neg_hi:[0,0,1]
	v_pk_fma_f32 v[116:117], v[116:117], v[178:179], v[192:193] neg_lo:[0,0,1] neg_hi:[0,0,1]
	global_store_dwordx4 v[158:159], v[112:115], off sc0 sc1
	v_mad_i64_i32 v[122:123], s[18:19], v171, s45, v[128:129]
	s_nop 0
	v_cvt_pk_bf16_f32 v112, v116, v117
	v_cvt_pk_bf16_f32 v113, v118, v119
	v_cvt_pk_bf16_f32 v114, v174, v175
	v_cvt_pk_bf16_f32 v115, v176, v177
	global_store_dwordx4 v[158:159], v[112:115], off offset:256 sc0 sc1
	global_load_dwordx4 v[112:115], v[172:173], off
	v_lshl_add_u64 v[116:117], v[146:147], 0, v[130:131]
	global_load_dwordx4 v[116:119], v[116:117], off
	v_lshlrev_b32_e32 v120, 8, v170
	v_lshl_add_u64 v[122:123], v[122:123], 0, s[16:17]
	v_mov_b32_e32 v121, v141
	v_and_b32_e32 v120, 0xfef00, v120
	v_lshl_add_u64 v[122:123], v[122:123], 0, v[140:141]
	v_lshl_add_u64 v[124:125], v[148:149], 0, v[120:121]
	s_waitcnt vmcnt(1)
	v_pk_mul_f32 v[126:127], v[106:107], v[114:115]
	v_pk_mul_f32 v[130:131], v[104:105], v[112:113]
	v_pk_mul_f32 v[158:159], v[110:111], v[114:115]
	v_pk_mul_f32 v[172:173], v[108:109], v[112:113]
	v_pk_mul_f32 v[174:175], v[98:99], v[114:115]
	v_pk_mul_f32 v[176:177], v[96:97], v[112:113]
	v_pk_mul_f32 v[114:115], v[102:103], v[114:115]
	v_pk_mul_f32 v[112:113], v[100:101], v[112:113]
	s_waitcnt vmcnt(0)
	v_pk_fma_f32 v[110:111], v[110:111], v[118:119], v[126:127] neg_lo:[0,0,1] neg_hi:[0,0,1]
	v_pk_fma_f32 v[108:109], v[108:109], v[116:117], v[130:131] neg_lo:[0,0,1] neg_hi:[0,0,1]
	v_pk_fma_f32 v[106:107], v[106:107], v[118:119], v[158:159]
	v_pk_fma_f32 v[104:105], v[104:105], v[116:117], v[172:173]
	v_pk_fma_f32 v[114:115], v[98:99], v[118:119], v[114:115]
	v_pk_fma_f32 v[112:113], v[96:97], v[116:117], v[112:113]
	v_cvt_pk_bf16_f32 v96, v108, v109
	v_cvt_pk_bf16_f32 v97, v110, v111
	v_cvt_pk_bf16_f32 v98, v104, v105
	v_cvt_pk_bf16_f32 v99, v106, v107
	v_pk_fma_f32 v[102:103], v[102:103], v[118:119], v[174:175] neg_lo:[0,0,1] neg_hi:[0,0,1]
	v_pk_fma_f32 v[100:101], v[100:101], v[116:117], v[176:177] neg_lo:[0,0,1] neg_hi:[0,0,1]
	global_store_dwordx4 v[122:123], v[96:99], off sc0 sc1
	v_mad_i64_i32 v[106:107], s[18:19], v170, s45, v[128:129]
	s_nop 0
	v_cvt_pk_bf16_f32 v96, v100, v101
	v_cvt_pk_bf16_f32 v97, v102, v103
	v_cvt_pk_bf16_f32 v98, v112, v113
	v_cvt_pk_bf16_f32 v99, v114, v115
	global_store_dwordx4 v[122:123], v[96:99], off offset:256 sc0 sc1
	global_load_dwordx4 v[96:99], v[124:125], off
	v_lshl_add_u64 v[100:101], v[146:147], 0, v[120:121]
	global_load_dwordx4 v[100:103], v[100:101], off
	v_lshlrev_b32_e32 v104, 8, v169
	v_lshl_add_u64 v[106:107], v[106:107], 0, s[16:17]
	v_mov_b32_e32 v105, v141
	v_and_b32_e32 v104, 0xfff00, v104
	v_lshl_add_u64 v[106:107], v[106:107], 0, v[140:141]
	v_lshl_add_u64 v[108:109], v[148:149], 0, v[104:105]
	s_waitcnt vmcnt(1)
	v_pk_mul_f32 v[110:111], v[90:91], v[98:99]
	v_pk_mul_f32 v[112:113], v[88:89], v[96:97]
	v_pk_mul_f32 v[114:115], v[94:95], v[98:99]
	v_pk_mul_f32 v[116:117], v[92:93], v[96:97]
	v_pk_mul_f32 v[118:119], v[82:83], v[98:99]
	v_pk_mul_f32 v[120:121], v[80:81], v[96:97]
	v_pk_mul_f32 v[98:99], v[86:87], v[98:99]
	v_pk_mul_f32 v[96:97], v[84:85], v[96:97]
	s_waitcnt vmcnt(0)
; __device__ __forceinline__ unsigned cvt_pk_bf16(float lo, float hi) { unsigned r; asm volatile("v_cvt_pk_bf16_f32 %0, %1, %2" : "=v"(r) : "v"(lo), "v"(hi)); return r; }
;     __device__ __forceinline__ void operator()(const f32x4 (&acc)[2][2][4][2], const Unit& u, int wr, int wc, int fr, int fq) const {
;     ...
;             for (int ai = 0; ai < 2; ++ai)
; #pragma unroll
;                 for (int m = 0; m < 4; ++m) { const int row = row0 + ai * HALF + m * 16, t = row & (SEQ - 1);
;                     const f32x4 c4 = *(const f32x4*)(cosT + t * 64 + e0), s4 = *(const f32x4*)(sinT + t * 64 + e0);
;                     bf16_t* rowp = O + (size_t)row * ldc + colt + cin;
; #pragma unroll
;                     for (int bj = 0; bj < 2; ++bj) { const f32x4 x1 = acc[ai][bj][m][0], x2 = acc[ai][bj][m][1];
;                         const f32x4 o1 = x1 * c4 - x2 * s4, o2 = x2 * c4 + x1 * s4;
;                         ks[bj][0] += o1; ks[bj][1] += o2;
;                         u32x4 w; w.x = cvt_pk_bf16(o1[0], o1[1]); w.y = cvt_pk_bf16(o1[2], o1[3]); w.z = cvt_pk_bf16(o2[0], o2[1]); w.w = cvt_pk_bf16(o2[2], o2[3]);
;                         *(u32x4*)(rowp + bj * HALF) = w; } }
	v_pk_fma_f32 v[94:95], v[94:95], v[102:103], v[110:111] neg_lo:[0,0,1] neg_hi:[0,0,1]
	v_pk_fma_f32 v[92:93], v[92:93], v[100:101], v[112:113] neg_lo:[0,0,1] neg_hi:[0,0,1]
	v_pk_fma_f32 v[90:91], v[90:91], v[102:103], v[114:115]
	v_pk_fma_f32 v[88:89], v[88:89], v[100:101], v[116:117]
	v_pk_fma_f32 v[98:99], v[82:83], v[102:103], v[98:99]
	v_pk_fma_f32 v[96:97], v[80:81], v[100:101], v[96:97]
	v_cvt_pk_bf16_f32 v80, v92, v93
	v_cvt_pk_bf16_f32 v81, v94, v95
	v_cvt_pk_bf16_f32 v82, v88, v89
	v_cvt_pk_bf16_f32 v83, v90, v91
	v_pk_fma_f32 v[86:87], v[86:87], v[102:103], v[118:119] neg_lo:[0,0,1] neg_hi:[0,0,1]
	v_pk_fma_f32 v[84:85], v[84:85], v[100:101], v[120:121] neg_lo:[0,0,1] neg_hi:[0,0,1]
	global_store_dwordx4 v[106:107], v[80:83], off sc0 sc1
	v_mad_i64_i32 v[90:91], s[18:19], v169, s45, v[128:129]
	s_nop 0
	v_cvt_pk_bf16_f32 v80, v84, v85
	v_cvt_pk_bf16_f32 v81, v86, v87
	v_cvt_pk_bf16_f32 v82, v96, v97
	v_cvt_pk_bf16_f32 v83, v98, v99
	global_store_dwordx4 v[106:107], v[80:83], off offset:256 sc0 sc1
	global_load_dwordx4 v[80:83], v[108:109], off
	v_lshl_add_u64 v[84:85], v[146:147], 0, v[104:105]
	global_load_dwordx4 v[84:87], v[84:85], off
	v_lshlrev_b32_e32 v88, 8, v167
	v_lshl_add_u64 v[90:91], v[90:91], 0, s[16:17]
	v_mov_b32_e32 v89, v141
	v_and_b32_e32 v88, 0xfcf00, v88
	v_lshl_add_u64 v[90:91], v[90:91], 0, v[140:141]
	v_lshl_add_u64 v[92:93], v[148:149], 0, v[88:89]
	s_waitcnt vmcnt(1)
	v_pk_mul_f32 v[94:95], v[74:75], v[82:83]
	v_pk_mul_f32 v[96:97], v[72:73], v[80:81]
	v_pk_mul_f32 v[98:99], v[78:79], v[82:83]
	v_pk_mul_f32 v[100:101], v[76:77], v[80:81]
	v_pk_mul_f32 v[102:103], v[66:67], v[82:83]
	v_pk_mul_f32 v[104:105], v[64:65], v[80:81]
	v_pk_mul_f32 v[82:83], v[70:71], v[82:83]
	v_pk_mul_f32 v[80:81], v[68:69], v[80:81]
	s_waitcnt vmcnt(0)
	v_pk_fma_f32 v[78:79], v[78:79], v[86:87], v[94:95] neg_lo:[0,0,1] neg_hi:[0,0,1]
	v_pk_fma_f32 v[76:77], v[76:77], v[84:85], v[96:97] neg_lo:[0,0,1] neg_hi:[0,0,1]
	v_pk_fma_f32 v[74:75], v[74:75], v[86:87], v[98:99]
	v_pk_fma_f32 v[72:73], v[72:73], v[84:85], v[100:101]
	v_pk_fma_f32 v[82:83], v[66:67], v[86:87], v[82:83]
	v_pk_fma_f32 v[80:81], v[64:65], v[84:85], v[80:81]
	v_cvt_pk_bf16_f32 v64, v76, v77
	v_cvt_pk_bf16_f32 v65, v78, v79
	v_cvt_pk_bf16_f32 v66, v72, v73
	v_cvt_pk_bf16_f32 v67, v74, v75
	v_pk_fma_f32 v[70:71], v[70:71], v[86:87], v[102:103] neg_lo:[0,0,1] neg_hi:[0,0,1]
	v_pk_fma_f32 v[68:69], v[68:69], v[84:85], v[104:105] neg_lo:[0,0,1] neg_hi:[0,0,1]
	global_store_dwordx4 v[90:91], v[64:67], off sc0 sc1
	v_mad_i64_i32 v[74:75], s[18:19], v167, s45, v[128:129]
	s_nop 0
	v_cvt_pk_bf16_f32 v64, v68, v69
	v_cvt_pk_bf16_f32 v65, v70, v71
	v_cvt_pk_bf16_f32 v66, v80, v81
	v_cvt_pk_bf16_f32 v67, v82, v83
	global_store_dwordx4 v[90:91], v[64:67], off offset:256 sc0 sc1
	global_load_dwordx4 v[64:67], v[92:93], off
	v_lshl_add_u64 v[68:69], v[146:147], 0, v[88:89]
	global_load_dwordx4 v[68:71], v[68:69], off
	v_lshlrev_b32_e32 v72, 8, v166
	v_lshl_add_u64 v[74:75], v[74:75], 0, s[16:17]
	v_mov_b32_e32 v73, v141
	v_and_b32_e32 v72, 0xfdf00, v72
	v_lshl_add_u64 v[74:75], v[74:75], 0, v[140:141]
	v_lshl_add_u64 v[76:77], v[148:149], 0, v[72:73]
	s_waitcnt vmcnt(1)
	v_pk_mul_f32 v[78:79], v[58:59], v[66:67]
	v_pk_mul_f32 v[80:81], v[56:57], v[64:65]
	v_pk_mul_f32 v[82:83], v[62:63], v[66:67]
	v_pk_mul_f32 v[84:85], v[60:61], v[64:65]
	v_pk_mul_f32 v[86:87], v[50:51], v[66:67]
	v_pk_mul_f32 v[88:89], v[48:49], v[64:65]
	v_pk_mul_f32 v[66:67], v[54:55], v[66:67]
	v_pk_mul_f32 v[64:65], v[52:53], v[64:65]
	s_waitcnt vmcnt(0)
	v_pk_fma_f32 v[62:63], v[62:63], v[70:71], v[78:79] neg_lo:[0,0,1] neg_hi:[0,0,1]
	v_pk_fma_f32 v[60:61], v[60:61], v[68:69], v[80:81] neg_lo:[0,0,1] neg_hi:[0,0,1]
	v_pk_fma_f32 v[58:59], v[58:59], v[70:71], v[82:83]
	v_pk_fma_f32 v[56:57], v[56:57], v[68:69], v[84:85]
	v_pk_fma_f32 v[66:67], v[50:51], v[70:71], v[66:67]
	v_pk_fma_f32 v[64:65], v[48:49], v[68:69], v[64:65]
	v_cvt_pk_bf16_f32 v48, v60, v61
	v_cvt_pk_bf16_f32 v49, v62, v63
	v_cvt_pk_bf16_f32 v50, v56, v57
	v_cvt_pk_bf16_f32 v51, v58, v59
	v_pk_fma_f32 v[54:55], v[54:55], v[70:71], v[86:87] neg_lo:[0,0,1] neg_hi:[0,0,1]
	v_pk_fma_f32 v[52:53], v[52:53], v[68:69], v[88:89] neg_lo:[0,0,1] neg_hi:[0,0,1]
	global_store_dwordx4 v[74:75], v[48:51], off sc0 sc1
	v_mad_i64_i32 v[58:59], s[18:19], v166, s45, v[128:129]
	s_nop 0
	v_cvt_pk_bf16_f32 v48, v52, v53
	v_cvt_pk_bf16_f32 v49, v54, v55
	v_cvt_pk_bf16_f32 v50, v64, v65
	v_cvt_pk_bf16_f32 v51, v66, v67
	global_store_dwordx4 v[74:75], v[48:51], off offset:256 sc0 sc1
	global_load_dwordx4 v[48:51], v[76:77], off
	v_lshl_add_u64 v[52:53], v[146:147], 0, v[72:73]
	global_load_dwordx4 v[52:55], v[52:53], off
	v_lshlrev_b32_e32 v56, 8, v165
	v_lshl_add_u64 v[58:59], v[58:59], 0, s[16:17]
	v_mov_b32_e32 v57, v141
	v_and_b32_e32 v56, 0xfef00, v56
	v_lshl_add_u64 v[58:59], v[58:59], 0, v[140:141]
	v_lshl_add_u64 v[60:61], v[148:149], 0, v[56:57]
	s_waitcnt vmcnt(1)
; __device__ __forceinline__ unsigned cvt_pk_bf16(float lo, float hi) { unsigned r; asm volatile("v_cvt_pk_bf16_f32 %0, %1, %2" : "=v"(r) : "v"(lo), "v"(hi)); return r; }
; #define PG8_BAR __builtin_amdgcn_s_barrier()
;     __device__ __forceinline__ void operator()(const f32x4 (&acc)[2][2][4][2], const Unit& u, int wr, int wc, int fr, int fq) const {
;     ...
;             for (int ai = 0; ai < 2; ++ai)
; #pragma unroll
;                 for (int m = 0; m < 4; ++m) { const int row = row0 + ai * HALF + m * 16, t = row & (SEQ - 1);
;                     const f32x4 c4 = *(const f32x4*)(cosT + t * 64 + e0), s4 = *(const f32x4*)(sinT + t * 64 + e0);
;                     bf16_t* rowp = O + (size_t)row * ldc + colt + cin;
; #pragma unroll
;                     for (int bj = 0; bj < 2; ++bj) { const f32x4 x1 = acc[ai][bj][m][0], x2 = acc[ai][bj][m][1];
;                         const f32x4 o1 = x1 * c4 - x2 * s4, o2 = x2 * c4 + x1 * s4;
;                         ks[bj][0] += o1; ks[bj][1] += o2;
;                         u32x4 w; w.x = cvt_pk_bf16(o1[0], o1[1]); w.y = cvt_pk_bf16(o1[2], o1[3]); w.z = cvt_pk_bf16(o2[0], o2[1]); w.w = cvt_pk_bf16(o2[2], o2[3]);
;                         *(u32x4*)(rowp + bj * HALF) = w; } }
; template <class EpiT>
; __device__ __forceinline__ void gemm_phase(LAS unsigned char* lds, const Gemm g, const StaticOrder& S, const EpiT& E) {
;     ...
;         if (wr == 0) PG8_BAR;
;         E(acc, cur, wr, wc, fr, fq);
;         if (!has_next) break;
; #pragma unroll
;         for (int a = 0; a < 2; ++a)
; #pragma unroll
;             for (int b = 0; b < 2; ++b)
; #pragma unroll
;                 for (int m = 0; m < 4; ++m)
; #pragma unroll
;                     for (int n = 0; n < 2; ++n) acc[a][b][m][n] = (f32x4){0.f, 0.f, 0.f, 0.f};
;         cur = nxt; cA = nA; cB = nB; ++ui;
;         if (wr == 1) PG8_BAR;
	v_pk_mul_f32 v[62:63], v[42:43], v[50:51]
	v_pk_mul_f32 v[64:65], v[40:41], v[48:49]
	v_pk_mul_f32 v[66:67], v[46:47], v[50:51]
	v_pk_mul_f32 v[68:69], v[44:45], v[48:49]
	v_pk_mul_f32 v[70:71], v[34:35], v[50:51]
	v_pk_mul_f32 v[72:73], v[32:33], v[48:49]
	v_pk_mul_f32 v[50:51], v[38:39], v[50:51]
	v_pk_mul_f32 v[48:49], v[36:37], v[48:49]
	s_waitcnt vmcnt(0)
	v_pk_fma_f32 v[46:47], v[46:47], v[54:55], v[62:63] neg_lo:[0,0,1] neg_hi:[0,0,1]
	v_pk_fma_f32 v[44:45], v[44:45], v[52:53], v[64:65] neg_lo:[0,0,1] neg_hi:[0,0,1]
	v_pk_fma_f32 v[42:43], v[42:43], v[54:55], v[66:67]
	v_pk_fma_f32 v[40:41], v[40:41], v[52:53], v[68:69]
	v_pk_fma_f32 v[50:51], v[34:35], v[54:55], v[50:51]
	v_pk_fma_f32 v[48:49], v[32:33], v[52:53], v[48:49]
	v_cvt_pk_bf16_f32 v32, v44, v45
	v_cvt_pk_bf16_f32 v33, v46, v47
	v_cvt_pk_bf16_f32 v34, v40, v41
	v_cvt_pk_bf16_f32 v35, v42, v43
	v_pk_fma_f32 v[38:39], v[38:39], v[54:55], v[70:71] neg_lo:[0,0,1] neg_hi:[0,0,1]
	v_pk_fma_f32 v[36:37], v[36:37], v[52:53], v[72:73] neg_lo:[0,0,1] neg_hi:[0,0,1]
	global_store_dwordx4 v[58:59], v[32:35], off sc0 sc1
	v_mad_i64_i32 v[42:43], s[18:19], v165, s45, v[128:129]
	s_nop 0
	v_cvt_pk_bf16_f32 v32, v36, v37
	v_cvt_pk_bf16_f32 v33, v38, v39
	v_cvt_pk_bf16_f32 v34, v48, v49
	v_cvt_pk_bf16_f32 v35, v50, v51
	global_store_dwordx4 v[58:59], v[32:35], off offset:256 sc0 sc1
	global_load_dwordx4 v[32:35], v[60:61], off
	v_lshl_add_u64 v[36:37], v[146:147], 0, v[56:57]
	global_load_dwordx4 v[36:39], v[36:37], off
	v_lshlrev_b32_e32 v40, 8, v163
	v_lshl_add_u64 v[42:43], v[42:43], 0, s[16:17]
	v_mov_b32_e32 v41, v141
	v_and_b32_e32 v40, 0xfff00, v40
	v_lshl_add_u64 v[42:43], v[42:43], 0, v[140:141]
	v_lshl_add_u64 v[44:45], v[148:149], 0, v[40:41]
	s_waitcnt vmcnt(1)
	v_pk_mul_f32 v[46:47], v[26:27], v[34:35]
	v_pk_mul_f32 v[48:49], v[24:25], v[32:33]
	v_pk_mul_f32 v[50:51], v[30:31], v[34:35]
	v_pk_mul_f32 v[52:53], v[28:29], v[32:33]
	v_pk_mul_f32 v[54:55], v[18:19], v[34:35]
	v_pk_mul_f32 v[56:57], v[16:17], v[32:33]
	v_pk_mul_f32 v[34:35], v[22:23], v[34:35]
	v_pk_mul_f32 v[32:33], v[20:21], v[32:33]
	s_waitcnt vmcnt(0)
	v_pk_fma_f32 v[30:31], v[30:31], v[38:39], v[46:47] neg_lo:[0,0,1] neg_hi:[0,0,1]
	v_pk_fma_f32 v[28:29], v[28:29], v[36:37], v[48:49] neg_lo:[0,0,1] neg_hi:[0,0,1]
	v_pk_fma_f32 v[26:27], v[26:27], v[38:39], v[50:51]
	v_pk_fma_f32 v[24:25], v[24:25], v[36:37], v[52:53]
	v_pk_fma_f32 v[34:35], v[18:19], v[38:39], v[34:35]
	v_pk_fma_f32 v[32:33], v[16:17], v[36:37], v[32:33]
	v_cvt_pk_bf16_f32 v16, v28, v29
	v_cvt_pk_bf16_f32 v17, v30, v31
	v_cvt_pk_bf16_f32 v18, v24, v25
	v_cvt_pk_bf16_f32 v19, v26, v27
	v_pk_fma_f32 v[22:23], v[22:23], v[38:39], v[54:55] neg_lo:[0,0,1] neg_hi:[0,0,1]
	v_pk_fma_f32 v[20:21], v[20:21], v[36:37], v[56:57] neg_lo:[0,0,1] neg_hi:[0,0,1]
	global_store_dwordx4 v[42:43], v[16:19], off sc0 sc1
	v_mad_i64_i32 v[24:25], s[18:19], v163, s45, v[128:129]
	s_nop 0
	v_cvt_pk_bf16_f32 v16, v20, v21
	v_cvt_pk_bf16_f32 v17, v22, v23
	v_cvt_pk_bf16_f32 v18, v32, v33
	v_cvt_pk_bf16_f32 v19, v34, v35
	global_store_dwordx4 v[42:43], v[16:19], off offset:256 sc0 sc1
	global_load_dwordx4 v[16:19], v[44:45], off
	v_lshl_add_u64 v[20:21], v[146:147], 0, v[40:41]
	global_load_dwordx4 v[20:23], v[20:21], off
	v_lshl_add_u64 v[158:159], v[24:25], 0, s[16:17]
	v_lshl_add_u64 v[24:25], v[158:159], 0, v[140:141]
	s_waitcnt vmcnt(1)
	v_pk_mul_f32 v[26:27], v[10:11], v[18:19]
	v_pk_mul_f32 v[28:29], v[8:9], v[16:17]
	v_pk_mul_f32 v[30:31], v[14:15], v[18:19]
	v_pk_mul_f32 v[32:33], v[12:13], v[16:17]
	v_pk_mul_f32 v[34:35], v[2:3], v[18:19]
	v_pk_mul_f32 v[36:37], v[0:1], v[16:17]
	v_pk_mul_f32 v[18:19], v[6:7], v[18:19]
	v_pk_mul_f32 v[16:17], v[4:5], v[16:17]
	s_waitcnt vmcnt(0)
	v_pk_fma_f32 v[14:15], v[14:15], v[22:23], v[26:27] neg_lo:[0,0,1] neg_hi:[0,0,1]
	v_pk_fma_f32 v[12:13], v[12:13], v[20:21], v[28:29] neg_lo:[0,0,1] neg_hi:[0,0,1]
	v_pk_fma_f32 v[10:11], v[10:11], v[22:23], v[30:31]
	v_pk_fma_f32 v[8:9], v[8:9], v[20:21], v[32:33]
	v_pk_fma_f32 v[6:7], v[6:7], v[22:23], v[34:35] neg_lo:[0,0,1] neg_hi:[0,0,1]
	v_pk_fma_f32 v[4:5], v[4:5], v[20:21], v[36:37] neg_lo:[0,0,1] neg_hi:[0,0,1]
	v_pk_fma_f32 v[18:19], v[2:3], v[22:23], v[18:19]
	v_pk_fma_f32 v[16:17], v[0:1], v[20:21], v[16:17]
	v_cvt_pk_bf16_f32 v0, v12, v13
	v_cvt_pk_bf16_f32 v1, v14, v15
	v_cvt_pk_bf16_f32 v2, v8, v9
	v_cvt_pk_bf16_f32 v3, v10, v11
	global_store_dwordx4 v[24:25], v[0:3], off sc0 sc1
	v_cvt_pk_bf16_f32 v128, v4, v5
	v_cvt_pk_bf16_f32 v129, v6, v7
	v_cvt_pk_bf16_f32 v130, v16, v17
	v_cvt_pk_bf16_f32 v131, v18, v19
.LBB0_107:
	s_nop 1
	v_lshl_add_u64 v[0:1], v[158:159], 0, v[140:141]
	s_and_b64 vcc, exec, s[0:1]
	s_mov_b64 s[0:1], -1
	global_store_dwordx4 v[0:1], v[128:131], off offset:256 sc0 sc1
	s_cbranch_vccnz .LBB0_92
	s_andn2_b64 vcc, exec, s[6:7]
	s_cbranch_vccnz .LBB0_91
	s_barrier
	s_branch .LBB0_91

; __device__ __forceinline__ unsigned pk2(float lo, float hi) { unsigned r; asm("v_cvt_pk_bf16_f32 %0, %1, %2" : "=v"(r) : "v"(lo), "v"(hi)); return r; }
; template <int MODE> ...
;     ...
; #pragma unroll
;     for (int qt = 0; qt < 2; ++qt) {
;         const int orow = rowbase + (qw0 + 16 * qt + c15) * rowstride;
;         const float inv = (MODE == SB) ? 1.0f : 1.0f / lrun[qt];
; #pragma unroll
;         for (int dt = 0; dt < 8; ++dt) { const f32x4 v = o[qt][dt] * inv; u32x2 w; w.x = pk2(v[0], v[1]); w.y = pk2(v[2], v[3]);
;             *(u32x2*)(Op + (size_t)orow * ldo + 16 * dt + 4 * g) = w; }
;         if constexpr (MODE == DIL) { if (g == 0) lse_out[(size_t)orow * 8] = (mrun[qt] + __builtin_amdgcn_logf(lrun[qt])) * 0.6931471805599453f; }
;     }
.LBB0_215:
	s_ashr_i32 s67, s66, 31
	s_lshl_b64 s[0:1], s[66:67], 19
	s_add_u32 s0, s25, s0
	s_addc_u32 s1, s27, s1
	s_lshl_b32 s4, s87, 2
	s_add_u32 s4, s0, s4
	s_addc_u32 s5, s1, 0
	v_div_scale_f32 v82, s[0:1], v166, v166, 1.0
	v_rcp_f32_e32 v83, v82
	v_lshlrev_b32_e32 v146, 1, v167
	v_lshl_add_u64 v[80:81], s[68:69], 0, v[146:147]
	v_cmp_eq_u32_e64 s[0:1], 0, v165
	v_fma_f32 v84, -v82, v83, 1.0
	v_fmac_f32_e32 v83, v84, v83
	v_div_scale_f32 v84, vcc, 1.0, v166, 1.0
	v_mul_f32_e32 v86, v84, v83
	v_fma_f32 v87, -v82, v86, v84
	v_fmac_f32_e32 v86, v87, v83
	v_fma_f32 v82, -v82, v86, v84
	v_div_fmas_f32 v82, v82, v83, v86
	v_div_fixup_f32 v82, v82, v166, 1.0
	v_lshl_add_u64 v[86:87], v[80:81], 0, v[154:155]
	v_pk_mul_f32 v[76:77], v[82:83], v[76:77] op_sel_hi:[0,1]
	v_pk_mul_f32 v[72:73], v[82:83], v[72:73] op_sel_hi:[0,1]
	v_pk_mul_f32 v[68:69], v[82:83], v[68:69] op_sel_hi:[0,1]
	v_pk_mul_f32 v[64:65], v[82:83], v[64:65] op_sel_hi:[0,1]
	v_pk_mul_f32 v[60:61], v[82:83], v[60:61] op_sel_hi:[0,1]
	v_pk_mul_f32 v[56:57], v[82:83], v[56:57] op_sel_hi:[0,1]
	v_pk_mul_f32 v[52:53], v[82:83], v[52:53] op_sel_hi:[0,1]
	v_pk_mul_f32 v[48:49], v[82:83], v[48:49] op_sel_hi:[0,1]
	v_pk_mul_f32 v[78:79], v[82:83], v[78:79] op_sel_hi:[0,1]
	v_cvt_pk_bf16_f32 v76, v76, v77
	v_cvt_pk_bf16_f32 v77, v78, v79
	global_store_dwordx2 v[86:87], v[76:77], off offset:2048 sc0 sc1
	v_pk_mul_f32 v[74:75], v[82:83], v[74:75] op_sel_hi:[0,1]
	v_cvt_pk_bf16_f32 v72, v72, v73
	v_cvt_pk_bf16_f32 v73, v74, v75
	global_store_dwordx2 v[86:87], v[72:73], off offset:2080 sc0 sc1
	v_pk_mul_f32 v[70:71], v[82:83], v[70:71] op_sel_hi:[0,1]
	v_cvt_pk_bf16_f32 v68, v68, v69
	v_cvt_pk_bf16_f32 v69, v70, v71
	global_store_dwordx2 v[86:87], v[68:69], off offset:2112 sc0 sc1
	v_pk_mul_f32 v[66:67], v[82:83], v[66:67] op_sel_hi:[0,1]
	v_cvt_pk_bf16_f32 v64, v64, v65
	v_cvt_pk_bf16_f32 v65, v66, v67
	global_store_dwordx2 v[86:87], v[64:65], off offset:2144 sc0 sc1
	v_pk_mul_f32 v[62:63], v[82:83], v[62:63] op_sel_hi:[0,1]
	v_cvt_pk_bf16_f32 v60, v60, v61
	v_cvt_pk_bf16_f32 v61, v62, v63
	global_store_dwordx2 v[86:87], v[60:61], off offset:2176 sc0 sc1
	v_pk_mul_f32 v[58:59], v[82:83], v[58:59] op_sel_hi:[0,1]
	v_cvt_pk_bf16_f32 v56, v56, v57
	v_cvt_pk_bf16_f32 v57, v58, v59
	global_store_dwordx2 v[86:87], v[56:57], off offset:2208 sc0 sc1
	v_pk_mul_f32 v[54:55], v[82:83], v[54:55] op_sel_hi:[0,1]
	v_cvt_pk_bf16_f32 v52, v52, v53
	v_cvt_pk_bf16_f32 v53, v54, v55
	global_store_dwordx2 v[86:87], v[52:53], off offset:2240 sc0 sc1
	v_pk_mul_f32 v[50:51], v[82:83], v[50:51] op_sel_hi:[0,1]
	v_cvt_pk_bf16_f32 v48, v48, v49
	v_cvt_pk_bf16_f32 v49, v50, v51
	global_store_dwordx2 v[86:87], v[48:49], off offset:2272 sc0 sc1
	s_and_saveexec_b64 s[6:7], s[0:1]
	s_cbranch_execz .LBB0_217
	v_log_f32_e32 v50, v166
	v_lshlrev_b64 v[48:49], 5, v[150:151]
	v_lshl_add_u64 v[48:49], s[4:5], 0, v[48:49]
	v_add_f32_e32 v50, v128, v50
	v_mul_f32_e32 v50, 0x3f317218, v50
	global_store_dword v[48:49], v50, off sc0 sc1
.LBB0_217:
	s_or_b64 exec, exec, s[6:7]
	v_div_scale_f32 v48, s[6:7], v163, v163, 1.0
	v_rcp_f32_e32 v49, v48
	v_div_scale_f32 v50, vcc, 1.0, v163, 1.0
	v_fma_f32 v51, -v48, v49, 1.0
	v_fmac_f32_e32 v49, v51, v49
	v_mul_f32_e32 v51, v50, v49
	v_fma_f32 v52, -v48, v51, v50
	v_fmac_f32_e32 v51, v52, v49
	v_fma_f32 v48, -v48, v51, v50
	v_div_fmas_f32 v48, v48, v49, v51
	v_div_fixup_f32 v48, v48, v163, 1.0
	v_lshl_add_u64 v[50:51], v[80:81], 0, v[152:153]
	v_pk_mul_f32 v[44:45], v[48:49], v[44:45] op_sel_hi:[0,1]
	v_pk_mul_f32 v[40:41], v[48:49], v[40:41] op_sel_hi:[0,1]
	v_pk_mul_f32 v[36:37], v[48:49], v[36:37] op_sel_hi:[0,1]
	v_pk_mul_f32 v[32:33], v[48:49], v[32:33] op_sel_hi:[0,1]
	v_pk_mul_f32 v[28:29], v[48:49], v[28:29] op_sel_hi:[0,1]
	v_pk_mul_f32 v[24:25], v[48:49], v[24:25] op_sel_hi:[0,1]
	v_pk_mul_f32 v[20:21], v[48:49], v[20:21] op_sel_hi:[0,1]
	v_pk_mul_f32 v[16:17], v[48:49], v[16:17] op_sel_hi:[0,1]
	v_pk_mul_f32 v[46:47], v[48:49], v[46:47] op_sel_hi:[0,1]
	v_cvt_pk_bf16_f32 v44, v44, v45
	v_cvt_pk_bf16_f32 v45, v46, v47
	global_store_dwordx2 v[50:51], v[44:45], off offset:2048 sc0 sc1
	v_pk_mul_f32 v[42:43], v[48:49], v[42:43] op_sel_hi:[0,1]
	v_cvt_pk_bf16_f32 v40, v40, v41
	v_cvt_pk_bf16_f32 v41, v42, v43
	global_store_dwordx2 v[50:51], v[40:41], off offset:2080 sc0 sc1
	v_pk_mul_f32 v[38:39], v[48:49], v[38:39] op_sel_hi:[0,1]
	v_cvt_pk_bf16_f32 v36, v36, v37
	v_cvt_pk_bf16_f32 v37, v38, v39
	global_store_dwordx2 v[50:51], v[36:37], off offset:2112 sc0 sc1
	v_pk_mul_f32 v[34:35], v[48:49], v[34:35] op_sel_hi:[0,1]
	v_cvt_pk_bf16_f32 v32, v32, v33
	v_cvt_pk_bf16_f32 v33, v34, v35
	global_store_dwordx2 v[50:51], v[32:33], off offset:2144 sc0 sc1
	v_pk_mul_f32 v[30:31], v[48:49], v[30:31] op_sel_hi:[0,1]
	v_cvt_pk_bf16_f32 v28, v28, v29
	v_cvt_pk_bf16_f32 v29, v30, v31
	global_store_dwordx2 v[50:51], v[28:29], off offset:2176 sc0 sc1
	v_pk_mul_f32 v[26:27], v[48:49], v[26:27] op_sel_hi:[0,1]
	v_cvt_pk_bf16_f32 v24, v24, v25
	v_cvt_pk_bf16_f32 v25, v26, v27
	global_store_dwordx2 v[50:51], v[24:25], off offset:2208 sc0 sc1
	v_pk_mul_f32 v[22:23], v[48:49], v[22:23] op_sel_hi:[0,1]
	v_cvt_pk_bf16_f32 v20, v20, v21
	v_cvt_pk_bf16_f32 v21, v22, v23
	global_store_dwordx2 v[50:51], v[20:21], off offset:2240 sc0 sc1
	v_pk_mul_f32 v[18:19], v[48:49], v[18:19] op_sel_hi:[0,1]
	v_cvt_pk_bf16_f32 v16, v16, v17
	v_cvt_pk_bf16_f32 v17, v18, v19
	global_store_dwordx2 v[50:51], v[16:17], off offset:2272 sc0 sc1
	s_and_saveexec_b64 s[6:7], s[0:1]
	s_cbranch_execz .LBB0_165
	v_log_f32_e32 v18, v163
	v_lshlrev_b64 v[16:17], 5, v[148:149]
	v_lshl_add_u64 v[16:17], s[4:5], 0, v[16:17]
	v_add_f32_e32 v18, v85, v18
	v_mul_f32_e32 v18, 0x3f317218, v18
	global_store_dword v[16:17], v18, off sc0 sc1
	s_branch .LBB0_165

; __device__ __forceinline__ unsigned pk2(float lo, float hi) { unsigned r; asm("v_cvt_pk_bf16_f32 %0, %1, %2" : "=v"(r) : "v"(lo), "v"(hi)); return r; }
; __device__ __forceinline__ void p_dilated(const Args& a, LAS unsigned char* lds, const Ctx& c) {
;     ...
;         for (int k = 0; k < cnt; ++k) { const u32x4 v = *(const u32x4*)(PROJ + (size_t)(row - k) * LDP0 + ch8 * 8);
;             const float f[8] = {bflo(v.x), bfhi(v.x), bflo(v.y), bfhi(v.y), bflo(v.z), bfhi(v.z), bflo(v.w), bfhi(v.w)};
; #pragma unroll
;             for (int j = 0; j < 8; ++j) { s[j] += f[j]; u0[j] = (k == 0) ? f[j] : u0[j]; } }
;         const float ic = 1.0f / (float)cnt; u32x4 o;
;         o.x = pk2(s[0] * ic - u0[0], s[1] * ic - u0[1]); o.y = pk2(s[2] * ic - u0[2], s[3] * ic - u0[3]); o.z = pk2(s[4] * ic - u0[4], s[5] * ic - u0[5]); o.w = pk2(s[6] * ic - u0[6], s[7] * ic - u0[7]);
;         *(u32x4*)(POOLED + (size_t)row * 1024 + ch8 * 8) = o; }
.LBB0_221:
	s_or_b64 exec, exec, s[6:7]
	v_cvt_f32_ubyte0_e32 v24, v28
	v_div_scale_f32 v25, s[6:7], v24, v24, 1.0
	v_rcp_f32_e32 v28, v25
	v_div_scale_f32 v29, vcc, 1.0, v24, 1.0
	v_ashrrev_i32_e32 v7, 31, v6
	v_fma_f32 v30, -v25, v28, 1.0
	v_fmac_f32_e32 v28, v30, v28
	v_mul_f32_e32 v30, v29, v28
	v_fma_f32 v31, -v25, v30, v29
	v_fmac_f32_e32 v30, v31, v28
	v_fma_f32 v25, -v25, v30, v29
	v_div_fmas_f32 v25, v25, v28, v30
	v_div_fixup_f32 v24, v25, v24, 1.0
	v_fma_f32 v8, v24, v22, -v8
	v_fma_f32 v9, v24, v23, -v9
	v_cvt_pk_bf16_f32 v8, v8, v9
	v_fma_f32 v9, v24, v20, -v10
	v_fma_f32 v10, v24, v21, -v11
	v_add_u32_e32 v27, s24, v27
	v_cvt_pk_bf16_f32 v9, v9, v10
	v_fma_f32 v10, v24, v18, -v12
	v_fma_f32 v11, v24, v19, -v13
	v_lshlrev_b64 v[6:7], 11, v[6:7]
	v_cmp_lt_i32_e32 vcc, s11, v27
	v_cvt_pk_bf16_f32 v10, v10, v11
	v_fma_f32 v11, v24, v16, -v14
	v_lshl_add_u64 v[6:7], v[2:3], 0, v[6:7]
	s_or_b64 s[2:3], vcc, s[2:3]
	v_fma_f32 v12, v24, v17, -v15
	v_cvt_pk_bf16_f32 v11, v11, v12
	global_store_dwordx4 v[6:7], v[8:11], off sc0 sc1
	s_andn2_b64 exec, exec, s[2:3]
	s_cbranch_execz .LBB0_226

; __device__ __forceinline__ unsigned cvt_pk_bf16(float lo, float hi) { unsigned r; asm volatile("v_cvt_pk_bf16_f32 %0, %1, %2" : "=v"(r) : "v"(lo), "v"(hi)); return r; }
;     __device__ __forceinline__ void operator()(const f32x4 (&acc)[2][2][4][2], const Unit& u, int wr, int wc, int fr, int fq) const {
;     ...
;         if constexpr (MODE == 0) {
;             const int colo = colt + 64 * wc + 8 * fq; const bool low = fr < 8;
;             f32x4 sc[2][2];
; #pragma unroll
;             for (int bj = 0; bj < 2; ++bj)
; #pragma unroll
;                 for (int n = 0; n < 2; ++n) sc[bj][n] = colscale ? *(const f32x4*)(colscale + colo + 32 * bj + 4 * n) : (f32x4){1.f, 1.f, 1.f, 1.f};
; #pragma unroll
;             for (int ai = 0; ai < 2; ++ai)
; #pragma unroll
;                 for (int m = 0; m < 4; ++m) {
;                     u32x4 w[2];
; #pragma unroll
;                     for (int bj = 0; bj < 2; ++bj) { const f32x4 v0 = acc[ai][bj][m][0] * sc[bj][0], v1 = acc[ai][bj][m][1] * sc[bj][1];
;                         w[bj].x = cvt_pk_bf16(v0[0], v0[1]); w[bj].y = cvt_pk_bf16(v0[2], v0[3]); w[bj].z = cvt_pk_bf16(v1[0], v1[1]); w[bj].w = cvt_pk_bf16(v1[2], v1[3]); }
;                     u32x4 snd, rcv;
;                     snd.x = low ? w[1].x : w[0].x; snd.y = low ? w[1].y : w[0].y; snd.z = low ? w[1].z : w[0].z; snd.w = low ? w[1].w : w[0].w;
;                     rcv.x = (unsigned)__shfl_xor((int)snd.x, 8); rcv.y = (unsigned)__shfl_xor((int)snd.y, 8); rcv.z = (unsigned)__shfl_xor((int)snd.z, 8); rcv.w = (unsigned)__shfl_xor((int)snd.w, 8);
;                     u32x4 dA, dB;
;                     dA.x = low ? w[0].x : rcv.x; dA.y = low ? w[0].y : rcv.y; dA.z = low ? w[0].z : rcv.z; dA.w = low ? w[0].w : rcv.w;
;                     dB.x = low ? rcv.x : w[1].x; dB.y = low ? rcv.y : w[1].y; dB.z = low ? rcv.z : w[1].z; dB.w = low ? rcv.w : w[1].w;
;                     bf16_t* pA = O + (size_t)(u.pm * BM + wr * 64 + ai * HALF + m * 16 + (fr & 7)) * ldc + colo + (low ? 0 : 32);
;                     __builtin_nontemporal_store(dA, (u32x4*)pA); __builtin_nontemporal_store(dB, (u32x4*)(pA + (size_t)8 * ldc)); }
.LBB0_307:
	s_waitcnt vmcnt(0)
	v_pk_mul_f32 v[124:125], v[124:125], v[132:133]
	v_pk_mul_f32 v[122:123], v[122:123], v[130:131]
	v_pk_mul_f32 v[120:121], v[120:121], v[128:129]
	v_pk_mul_f32 v[118:119], v[118:119], v[142:143]
	v_pk_mul_f32 v[126:127], v[126:127], v[134:135]
	v_cvt_pk_bf16_f32 v124, v124, v125
	v_pk_mul_f32 v[116:117], v[116:117], v[140:141]
	v_cvt_pk_bf16_f32 v125, v126, v127
	v_cvt_pk_bf16_f32 v120, v120, v121
	v_cvt_pk_bf16_f32 v121, v122, v123
	v_pk_mul_f32 v[114:115], v[114:115], v[138:139]
	v_cvt_pk_bf16_f32 v122, v116, v117
	v_cvt_pk_bf16_f32 v123, v118, v119
	v_and_b32_e32 v119, 64, v171
	v_xor_b32_e32 v117, 8, v171
	v_add_u32_e32 v119, 64, v119
	v_cmp_lt_i32_e32 vcc, v117, v119
	v_pk_mul_f32 v[112:113], v[112:113], v[136:137]
	v_pk_mul_f32 v[108:109], v[108:109], v[132:133]
	v_cndmask_b32_e32 v117, v171, v117, vcc
	v_cvt_pk_bf16_f32 v112, v112, v113
	v_cvt_pk_bf16_f32 v113, v114, v115
	v_cndmask_b32_e64 v114, v124, v122, s[0:1]
	v_cndmask_b32_e64 v115, v125, v123, s[0:1]
	v_cndmask_b32_e64 v116, v120, v112, s[0:1]
	v_cndmask_b32_e64 v118, v121, v113, s[0:1]
	v_lshlrev_b32_e32 v117, 2, v117
	ds_bpermute_b32 v114, v117, v114
	ds_bpermute_b32 v115, v117, v115
	ds_bpermute_b32 v126, v117, v116
	ds_bpermute_b32 v127, v117, v118
	v_lshl_add_u32 v116, s40, 8, v165
	s_waitcnt lgkmcnt(3)
	v_cndmask_b32_e64 v118, v114, v124, s[0:1]
	s_waitcnt lgkmcnt(2)
	v_cndmask_b32_e64 v119, v115, v125, s[0:1]
	s_waitcnt lgkmcnt(1)
	v_cndmask_b32_e64 v124, v112, v126, s[0:1]
	s_waitcnt lgkmcnt(0)
	v_cndmask_b32_e64 v125, v113, v127, s[0:1]
	v_mov_b64_e32 v[112:113], s[94:95]
	v_cndmask_b32_e64 v120, v126, v120, s[0:1]
	v_cndmask_b32_e64 v121, v127, v121, s[0:1]
	v_cndmask_b32_e64 v122, v122, v114, s[0:1]
	v_cndmask_b32_e64 v123, v123, v115, s[0:1]
	v_mad_i64_i32 v[126:127], s[4:5], v116, s53, v[112:113]
	v_lshlrev_b64 v[114:115], 1, v[160:161]
	v_lshl_add_u64 v[126:127], v[126:127], 0, v[114:115]
	v_lshl_add_u64 v[126:127], v[126:127], 0, v[154:155]
	global_store_dwordx4 v[126:127], v[118:121], off sc0 sc1 nt
	v_pk_mul_f32 v[104:105], v[104:105], v[128:129]
	v_pk_mul_f32 v[102:103], v[102:103], v[142:143]
	v_add_co_u32_e32 v118, vcc, s48, v126
	v_pk_mul_f32 v[100:101], v[100:101], v[140:141]
	s_nop 0
	v_addc_co_u32_e32 v119, vcc, 0, v127, vcc
	v_pk_mul_f32 v[98:99], v[98:99], v[138:139]
	global_store_dwordx4 v[118:119], v[122:125], off offset:1024 sc0 sc1 nt
	v_pk_mul_f32 v[110:111], v[110:111], v[134:135]
	v_pk_mul_f32 v[106:107], v[106:107], v[130:131]
	v_cvt_pk_bf16_f32 v108, v108, v109
	v_cvt_pk_bf16_f32 v109, v110, v111
	v_cvt_pk_bf16_f32 v104, v104, v105
	v_pk_mul_f32 v[96:97], v[96:97], v[136:137]
	v_cvt_pk_bf16_f32 v105, v106, v107
	v_cvt_pk_bf16_f32 v100, v100, v101
	v_cvt_pk_bf16_f32 v101, v102, v103
	v_pk_mul_f32 v[92:93], v[92:93], v[132:133]
	v_cvt_pk_bf16_f32 v102, v96, v97
	v_cvt_pk_bf16_f32 v103, v98, v99
	v_cndmask_b32_e64 v96, v108, v100, s[0:1]
	v_cndmask_b32_e64 v98, v104, v102, s[0:1]
	v_cndmask_b32_e64 v99, v105, v103, s[0:1]
	ds_bpermute_b32 v110, v117, v98
	ds_bpermute_b32 v111, v117, v99
	v_cndmask_b32_e64 v97, v109, v101, s[0:1]
	ds_bpermute_b32 v106, v117, v96
	ds_bpermute_b32 v107, v117, v97
	s_waitcnt lgkmcnt(3)
	v_cndmask_b32_e64 v98, v110, v104, s[0:1]
	v_or_b32_e32 v104, 16, v116
	s_waitcnt lgkmcnt(2)
	v_cndmask_b32_e64 v99, v111, v105, s[0:1]
	v_mad_i64_i32 v[104:105], s[4:5], v104, s53, v[112:113]
	v_lshl_add_u64 v[104:105], v[104:105], 0, v[114:115]
	s_waitcnt lgkmcnt(1)
	v_cndmask_b32_e64 v96, v106, v108, s[0:1]
	s_waitcnt lgkmcnt(0)
	v_cndmask_b32_e64 v97, v107, v109, s[0:1]
	v_lshl_add_u64 v[104:105], v[104:105], 0, v[154:155]
	global_store_dwordx4 v[104:105], v[96:99], off sc0 sc1 nt
	v_cndmask_b32_e64 v100, v100, v106, s[0:1]
	v_cndmask_b32_e64 v101, v101, v107, s[0:1]
	v_add_co_u32_e32 v96, vcc, s48, v104
	v_cndmask_b32_e64 v102, v102, v110, s[0:1]
	v_cndmask_b32_e64 v103, v103, v111, s[0:1]
	v_addc_co_u32_e32 v97, vcc, 0, v105, vcc
	v_pk_mul_f32 v[88:89], v[88:89], v[128:129]
	v_pk_mul_f32 v[86:87], v[86:87], v[142:143]
	v_pk_mul_f32 v[84:85], v[84:85], v[140:141]
	v_pk_mul_f32 v[82:83], v[82:83], v[138:139]
	global_store_dwordx4 v[96:97], v[100:103], off offset:1024 sc0 sc1 nt
	v_pk_mul_f32 v[94:95], v[94:95], v[134:135]
	v_pk_mul_f32 v[90:91], v[90:91], v[130:131]
	v_cvt_pk_bf16_f32 v92, v92, v93
	v_cvt_pk_bf16_f32 v93, v94, v95
	v_cvt_pk_bf16_f32 v88, v88, v89
	v_pk_mul_f32 v[80:81], v[80:81], v[136:137]
	v_cvt_pk_bf16_f32 v89, v90, v91
	v_cvt_pk_bf16_f32 v84, v84, v85
	v_cvt_pk_bf16_f32 v85, v86, v87
	v_pk_mul_f32 v[76:77], v[76:77], v[132:133]
	v_cvt_pk_bf16_f32 v86, v80, v81
	v_cvt_pk_bf16_f32 v87, v82, v83
	v_cndmask_b32_e64 v80, v92, v84, s[0:1]
	v_cndmask_b32_e64 v82, v88, v86, s[0:1]
	v_cndmask_b32_e64 v83, v89, v87, s[0:1]
	ds_bpermute_b32 v94, v117, v82
	ds_bpermute_b32 v95, v117, v83
	v_cndmask_b32_e64 v81, v93, v85, s[0:1]
	ds_bpermute_b32 v90, v117, v80
	ds_bpermute_b32 v91, v117, v81
	s_waitcnt lgkmcnt(3)
	v_cndmask_b32_e64 v82, v94, v88, s[0:1]
	v_or_b32_e32 v88, 32, v116
	s_waitcnt lgkmcnt(2)
	v_cndmask_b32_e64 v83, v95, v89, s[0:1]
	v_mad_i64_i32 v[88:89], s[4:5], v88, s53, v[112:113]
	v_lshl_add_u64 v[88:89], v[88:89], 0, v[114:115]
	s_waitcnt lgkmcnt(1)
	v_cndmask_b32_e64 v80, v90, v92, s[0:1]
	s_waitcnt lgkmcnt(0)
; __device__ __forceinline__ unsigned cvt_pk_bf16(float lo, float hi) { unsigned r; asm volatile("v_cvt_pk_bf16_f32 %0, %1, %2" : "=v"(r) : "v"(lo), "v"(hi)); return r; }
;     __device__ __forceinline__ void operator()(const f32x4 (&acc)[2][2][4][2], const Unit& u, int wr, int wc, int fr, int fq) const {
;     ...
;         if constexpr (MODE == 0) {
;             const int colo = colt + 64 * wc + 8 * fq; const bool low = fr < 8;
;             f32x4 sc[2][2];
; #pragma unroll
;             for (int bj = 0; bj < 2; ++bj)
; #pragma unroll
;                 for (int n = 0; n < 2; ++n) sc[bj][n] = colscale ? *(const f32x4*)(colscale + colo + 32 * bj + 4 * n) : (f32x4){1.f, 1.f, 1.f, 1.f};
; #pragma unroll
;             for (int ai = 0; ai < 2; ++ai)
; #pragma unroll
;                 for (int m = 0; m < 4; ++m) {
;                     u32x4 w[2];
; #pragma unroll
;                     for (int bj = 0; bj < 2; ++bj) { const f32x4 v0 = acc[ai][bj][m][0] * sc[bj][0], v1 = acc[ai][bj][m][1] * sc[bj][1];
;                         w[bj].x = cvt_pk_bf16(v0[0], v0[1]); w[bj].y = cvt_pk_bf16(v0[2], v0[3]); w[bj].z = cvt_pk_bf16(v1[0], v1[1]); w[bj].w = cvt_pk_bf16(v1[2], v1[3]); }
;                     u32x4 snd, rcv;
;                     snd.x = low ? w[1].x : w[0].x; snd.y = low ? w[1].y : w[0].y; snd.z = low ? w[1].z : w[0].z; snd.w = low ? w[1].w : w[0].w;
;                     rcv.x = (unsigned)__shfl_xor((int)snd.x, 8); rcv.y = (unsigned)__shfl_xor((int)snd.y, 8); rcv.z = (unsigned)__shfl_xor((int)snd.z, 8); rcv.w = (unsigned)__shfl_xor((int)snd.w, 8);
;                     u32x4 dA, dB;
;                     dA.x = low ? w[0].x : rcv.x; dA.y = low ? w[0].y : rcv.y; dA.z = low ? w[0].z : rcv.z; dA.w = low ? w[0].w : rcv.w;
;                     dB.x = low ? rcv.x : w[1].x; dB.y = low ? rcv.y : w[1].y; dB.z = low ? rcv.z : w[1].z; dB.w = low ? rcv.w : w[1].w;
;                     bf16_t* pA = O + (size_t)(u.pm * BM + wr * 64 + ai * HALF + m * 16 + (fr & 7)) * ldc + colo + (low ? 0 : 32);
;                     __builtin_nontemporal_store(dA, (u32x4*)pA); __builtin_nontemporal_store(dB, (u32x4*)(pA + (size_t)8 * ldc)); }
	v_cndmask_b32_e64 v81, v91, v93, s[0:1]
	v_lshl_add_u64 v[88:89], v[88:89], 0, v[154:155]
	global_store_dwordx4 v[88:89], v[80:83], off sc0 sc1 nt
	v_cndmask_b32_e64 v84, v84, v90, s[0:1]
	v_cndmask_b32_e64 v85, v85, v91, s[0:1]
	v_add_co_u32_e32 v80, vcc, s48, v88
	v_cndmask_b32_e64 v86, v86, v94, s[0:1]
	v_cndmask_b32_e64 v87, v87, v95, s[0:1]
	v_addc_co_u32_e32 v81, vcc, 0, v89, vcc
	v_pk_mul_f32 v[72:73], v[72:73], v[128:129]
	v_pk_mul_f32 v[70:71], v[70:71], v[142:143]
	v_pk_mul_f32 v[68:69], v[68:69], v[140:141]
	v_pk_mul_f32 v[66:67], v[66:67], v[138:139]
	global_store_dwordx4 v[80:81], v[84:87], off offset:1024 sc0 sc1 nt
	v_pk_mul_f32 v[78:79], v[78:79], v[134:135]
	v_pk_mul_f32 v[74:75], v[74:75], v[130:131]
	v_cvt_pk_bf16_f32 v76, v76, v77
	v_cvt_pk_bf16_f32 v77, v78, v79
	v_cvt_pk_bf16_f32 v72, v72, v73
	v_pk_mul_f32 v[64:65], v[64:65], v[136:137]
	v_cvt_pk_bf16_f32 v73, v74, v75
	v_cvt_pk_bf16_f32 v68, v68, v69
	v_cvt_pk_bf16_f32 v69, v70, v71
	v_pk_mul_f32 v[60:61], v[60:61], v[132:133]
	v_cvt_pk_bf16_f32 v70, v64, v65
	v_cvt_pk_bf16_f32 v71, v66, v67
	v_cndmask_b32_e64 v64, v76, v68, s[0:1]
	v_cndmask_b32_e64 v66, v72, v70, s[0:1]
	v_cndmask_b32_e64 v67, v73, v71, s[0:1]
	ds_bpermute_b32 v78, v117, v66
	ds_bpermute_b32 v79, v117, v67
	v_cndmask_b32_e64 v65, v77, v69, s[0:1]
	ds_bpermute_b32 v74, v117, v64
	ds_bpermute_b32 v75, v117, v65
	s_waitcnt lgkmcnt(3)
	v_cndmask_b32_e64 v66, v78, v72, s[0:1]
	v_or_b32_e32 v72, 48, v116
	s_waitcnt lgkmcnt(2)
	v_cndmask_b32_e64 v67, v79, v73, s[0:1]
	v_mad_i64_i32 v[72:73], s[4:5], v72, s53, v[112:113]
	v_lshl_add_u64 v[72:73], v[72:73], 0, v[114:115]
	s_waitcnt lgkmcnt(1)
	v_cndmask_b32_e64 v64, v74, v76, s[0:1]
	s_waitcnt lgkmcnt(0)
	v_cndmask_b32_e64 v65, v75, v77, s[0:1]
	v_lshl_add_u64 v[72:73], v[72:73], 0, v[154:155]
	global_store_dwordx4 v[72:73], v[64:67], off sc0 sc1 nt
	v_cndmask_b32_e64 v68, v68, v74, s[0:1]
	v_cndmask_b32_e64 v69, v69, v75, s[0:1]
	v_add_co_u32_e32 v64, vcc, s48, v72
	v_cndmask_b32_e64 v70, v70, v78, s[0:1]
	v_cndmask_b32_e64 v71, v71, v79, s[0:1]
	v_addc_co_u32_e32 v65, vcc, 0, v73, vcc
	v_pk_mul_f32 v[56:57], v[56:57], v[128:129]
	v_pk_mul_f32 v[54:55], v[54:55], v[142:143]
	v_pk_mul_f32 v[52:53], v[52:53], v[140:141]
	v_pk_mul_f32 v[50:51], v[50:51], v[138:139]
	global_store_dwordx4 v[64:65], v[68:71], off offset:1024 sc0 sc1 nt
	v_pk_mul_f32 v[62:63], v[62:63], v[134:135]
	v_pk_mul_f32 v[58:59], v[58:59], v[130:131]
	v_cvt_pk_bf16_f32 v60, v60, v61
	v_cvt_pk_bf16_f32 v61, v62, v63
	v_cvt_pk_bf16_f32 v56, v56, v57
	v_pk_mul_f32 v[48:49], v[48:49], v[136:137]
	v_cvt_pk_bf16_f32 v57, v58, v59
	v_cvt_pk_bf16_f32 v52, v52, v53
	v_cvt_pk_bf16_f32 v53, v54, v55
	v_add_u32_e32 v64, 0x80, v116
	v_cvt_pk_bf16_f32 v54, v48, v49
	v_cvt_pk_bf16_f32 v55, v50, v51
	v_cndmask_b32_e64 v48, v60, v52, s[0:1]
	v_cndmask_b32_e64 v50, v56, v54, s[0:1]
	v_cndmask_b32_e64 v51, v57, v55, s[0:1]
	ds_bpermute_b32 v62, v117, v50
	ds_bpermute_b32 v63, v117, v51
	v_cndmask_b32_e64 v49, v61, v53, s[0:1]
	ds_bpermute_b32 v58, v117, v48
	ds_bpermute_b32 v59, v117, v49
	s_waitcnt lgkmcnt(3)
	v_cndmask_b32_e64 v50, v62, v56, s[0:1]
	s_waitcnt lgkmcnt(2)
	v_cndmask_b32_e64 v51, v63, v57, s[0:1]
	v_mad_i64_i32 v[56:57], s[4:5], v64, s53, v[112:113]
	v_lshl_add_u64 v[56:57], v[56:57], 0, v[114:115]
	s_waitcnt lgkmcnt(1)
	v_cndmask_b32_e64 v48, v58, v60, s[0:1]
	s_waitcnt lgkmcnt(0)
	v_cndmask_b32_e64 v49, v59, v61, s[0:1]
	v_lshl_add_u64 v[56:57], v[56:57], 0, v[154:155]
	global_store_dwordx4 v[56:57], v[48:51], off sc0 sc1 nt
	v_cndmask_b32_e64 v52, v52, v58, s[0:1]
	v_cndmask_b32_e64 v53, v53, v59, s[0:1]
	v_add_co_u32_e32 v48, vcc, s48, v56
	v_cndmask_b32_e64 v54, v54, v62, s[0:1]
	v_cndmask_b32_e64 v55, v55, v63, s[0:1]
	v_addc_co_u32_e32 v49, vcc, 0, v57, vcc
	v_pk_mul_f32 v[44:45], v[44:45], v[132:133]
	v_pk_mul_f32 v[40:41], v[40:41], v[128:129]
	v_pk_mul_f32 v[38:39], v[38:39], v[142:143]
	v_pk_mul_f32 v[36:37], v[36:37], v[140:141]
	v_pk_mul_f32 v[34:35], v[34:35], v[138:139]
	global_store_dwordx4 v[48:49], v[52:55], off offset:1024 sc0 sc1 nt
	v_pk_mul_f32 v[46:47], v[46:47], v[134:135]
	v_pk_mul_f32 v[42:43], v[42:43], v[130:131]
	v_cvt_pk_bf16_f32 v44, v44, v45
	v_cvt_pk_bf16_f32 v45, v46, v47
	v_cvt_pk_bf16_f32 v40, v40, v41
	v_pk_mul_f32 v[32:33], v[32:33], v[136:137]
	v_cvt_pk_bf16_f32 v41, v42, v43
	v_cvt_pk_bf16_f32 v36, v36, v37
	v_cvt_pk_bf16_f32 v37, v38, v39
	v_pk_mul_f32 v[28:29], v[28:29], v[132:133]
	v_cvt_pk_bf16_f32 v38, v32, v33
	v_cvt_pk_bf16_f32 v39, v34, v35
	v_cndmask_b32_e64 v32, v44, v36, s[0:1]
	v_cndmask_b32_e64 v34, v40, v38, s[0:1]
	v_cndmask_b32_e64 v35, v41, v39, s[0:1]
	ds_bpermute_b32 v46, v117, v34
	ds_bpermute_b32 v47, v117, v35
	v_cndmask_b32_e64 v33, v45, v37, s[0:1]
	ds_bpermute_b32 v42, v117, v32
	ds_bpermute_b32 v43, v117, v33
	s_waitcnt lgkmcnt(3)
;     __device__ __forceinline__ void operator()(const f32x4 (&acc)[2][2][4][2], const Unit& u, int wr, int wc, int fr, int fq) const {
;     ...
;         if constexpr (MODE == 0) {
;             const int colo = colt + 64 * wc + 8 * fq; const bool low = fr < 8;
;             f32x4 sc[2][2];
; #pragma unroll
;             for (int bj = 0; bj < 2; ++bj)
; #pragma unroll
;                 for (int n = 0; n < 2; ++n) sc[bj][n] = colscale ? *(const f32x4*)(colscale + colo + 32 * bj + 4 * n) : (f32x4){1.f, 1.f, 1.f, 1.f};
; #pragma unroll
;             for (int ai = 0; ai < 2; ++ai)
; #pragma unroll
;                 for (int m = 0; m < 4; ++m) {
;                     u32x4 w[2];
; #pragma unroll
;                     for (int bj = 0; bj < 2; ++bj) { const f32x4 v0 = acc[ai][bj][m][0] * sc[bj][0], v1 = acc[ai][bj][m][1] * sc[bj][1];
;                         w[bj].x = cvt_pk_bf16(v0[0], v0[1]); w[bj].y = cvt_pk_bf16(v0[2], v0[3]); w[bj].z = cvt_pk_bf16(v1[0], v1[1]); w[bj].w = cvt_pk_bf16(v1[2], v1[3]); }
;                     u32x4 snd, rcv;
;                     snd.x = low ? w[1].x : w[0].x; snd.y = low ? w[1].y : w[0].y; snd.z = low ? w[1].z : w[0].z; snd.w = low ? w[1].w : w[0].w;
;                     rcv.x = (unsigned)__shfl_xor((int)snd.x, 8); rcv.y = (unsigned)__shfl_xor((int)snd.y, 8); rcv.z = (unsigned)__shfl_xor((int)snd.z, 8); rcv.w = (unsigned)__shfl_xor((int)snd.w, 8);
;                     u32x4 dA, dB;
;                     dA.x = low ? w[0].x : rcv.x; dA.y = low ? w[0].y : rcv.y; dA.z = low ? w[0].z : rcv.z; dA.w = low ? w[0].w : rcv.w;
;                     dB.x = low ? rcv.x : w[1].x; dB.y = low ? rcv.y : w[1].y; dB.z = low ? rcv.z : w[1].z; dB.w = low ? rcv.w : w[1].w;
;                     bf16_t* pA = O + (size_t)(u.pm * BM + wr * 64 + ai * HALF + m * 16 + (fr & 7)) * ldc + colo + (low ? 0 : 32);
;                     __builtin_nontemporal_store(dA, (u32x4*)pA); __builtin_nontemporal_store(dB, (u32x4*)(pA + (size_t)8 * ldc)); }
; template <class EpiT>
; __device__ __forceinline__ void gemm_phase(LAS unsigned char* lds, const Gemm g, const StaticOrder& S, const EpiT& E) {
;     ...
;         if (!has_next) break;
; #pragma unroll
;         for (int a = 0; a < 2; ++a)
; #pragma unroll
;             for (int b = 0; b < 2; ++b)
; #pragma unroll
;                 for (int m = 0; m < 4; ++m)
; #pragma unroll
	v_cndmask_b32_e64 v34, v46, v40, s[0:1]
	v_add_u32_e32 v40, 0x90, v116
	s_waitcnt lgkmcnt(2)
	v_cndmask_b32_e64 v35, v47, v41, s[0:1]
	v_mad_i64_i32 v[40:41], s[4:5], v40, s53, v[112:113]
	v_lshl_add_u64 v[40:41], v[40:41], 0, v[114:115]
	s_waitcnt lgkmcnt(1)
	v_cndmask_b32_e64 v32, v42, v44, s[0:1]
	s_waitcnt lgkmcnt(0)
	v_cndmask_b32_e64 v33, v43, v45, s[0:1]
	v_lshl_add_u64 v[40:41], v[40:41], 0, v[154:155]
	global_store_dwordx4 v[40:41], v[32:35], off sc0 sc1 nt
	v_cndmask_b32_e64 v36, v36, v42, s[0:1]
	v_cndmask_b32_e64 v37, v37, v43, s[0:1]
	v_add_co_u32_e32 v32, vcc, s48, v40
	v_cndmask_b32_e64 v38, v38, v46, s[0:1]
	v_cndmask_b32_e64 v39, v39, v47, s[0:1]
	v_addc_co_u32_e32 v33, vcc, 0, v41, vcc
	v_pk_mul_f32 v[24:25], v[24:25], v[128:129]
	v_pk_mul_f32 v[22:23], v[22:23], v[142:143]
	v_pk_mul_f32 v[20:21], v[20:21], v[140:141]
	v_pk_mul_f32 v[18:19], v[18:19], v[138:139]
	global_store_dwordx4 v[32:33], v[36:39], off offset:1024 sc0 sc1 nt
	v_pk_mul_f32 v[30:31], v[30:31], v[134:135]
	v_pk_mul_f32 v[26:27], v[26:27], v[130:131]
	v_cvt_pk_bf16_f32 v28, v28, v29
	v_cvt_pk_bf16_f32 v29, v30, v31
	v_cvt_pk_bf16_f32 v24, v24, v25
	v_pk_mul_f32 v[16:17], v[16:17], v[136:137]
	v_cvt_pk_bf16_f32 v25, v26, v27
	v_cvt_pk_bf16_f32 v20, v20, v21
	v_cvt_pk_bf16_f32 v21, v22, v23
	v_pk_mul_f32 v[12:13], v[12:13], v[132:133]
	v_cvt_pk_bf16_f32 v22, v16, v17
	v_cvt_pk_bf16_f32 v23, v18, v19
	v_cndmask_b32_e64 v16, v28, v20, s[0:1]
	v_cndmask_b32_e64 v18, v24, v22, s[0:1]
	v_cndmask_b32_e64 v19, v25, v23, s[0:1]
	ds_bpermute_b32 v30, v117, v18
	ds_bpermute_b32 v31, v117, v19
	v_cndmask_b32_e64 v17, v29, v21, s[0:1]
	ds_bpermute_b32 v26, v117, v16
	ds_bpermute_b32 v27, v117, v17
	s_waitcnt lgkmcnt(3)
	v_cndmask_b32_e64 v18, v30, v24, s[0:1]
	v_add_u32_e32 v24, 0xa0, v116
	s_waitcnt lgkmcnt(2)
	v_cndmask_b32_e64 v19, v31, v25, s[0:1]
	v_mad_i64_i32 v[24:25], s[4:5], v24, s53, v[112:113]
	v_lshl_add_u64 v[24:25], v[24:25], 0, v[114:115]
	s_waitcnt lgkmcnt(1)
	v_cndmask_b32_e64 v16, v26, v28, s[0:1]
	s_waitcnt lgkmcnt(0)
	v_cndmask_b32_e64 v17, v27, v29, s[0:1]
	v_lshl_add_u64 v[24:25], v[24:25], 0, v[154:155]
	global_store_dwordx4 v[24:25], v[16:19], off sc0 sc1 nt
	v_cndmask_b32_e64 v20, v20, v26, s[0:1]
	v_cndmask_b32_e64 v21, v21, v27, s[0:1]
	v_add_co_u32_e32 v16, vcc, s48, v24
	v_cndmask_b32_e64 v22, v22, v30, s[0:1]
	v_cndmask_b32_e64 v23, v23, v31, s[0:1]
	v_addc_co_u32_e32 v17, vcc, 0, v25, vcc
	v_pk_mul_f32 v[8:9], v[8:9], v[128:129]
	v_pk_mul_f32 v[6:7], v[6:7], v[142:143]
	v_pk_mul_f32 v[4:5], v[4:5], v[140:141]
	v_pk_mul_f32 v[2:3], v[2:3], v[138:139]
	global_store_dwordx4 v[16:17], v[20:23], off offset:1024 sc0 sc1 nt
	v_pk_mul_f32 v[14:15], v[14:15], v[134:135]
	v_pk_mul_f32 v[10:11], v[10:11], v[130:131]
	v_cvt_pk_bf16_f32 v12, v12, v13
	v_cvt_pk_bf16_f32 v13, v14, v15
	v_cvt_pk_bf16_f32 v8, v8, v9
	v_pk_mul_f32 v[0:1], v[0:1], v[136:137]
	v_cvt_pk_bf16_f32 v9, v10, v11
	v_cvt_pk_bf16_f32 v4, v4, v5
	v_cvt_pk_bf16_f32 v5, v6, v7
	s_nop 0
	v_cvt_pk_bf16_f32 v6, v0, v1
	v_cvt_pk_bf16_f32 v7, v2, v3
	v_cndmask_b32_e64 v0, v12, v4, s[0:1]
	v_cndmask_b32_e64 v2, v8, v6, s[0:1]
	v_cndmask_b32_e64 v3, v9, v7, s[0:1]
	ds_bpermute_b32 v14, v117, v2
	ds_bpermute_b32 v15, v117, v3
	v_cndmask_b32_e64 v1, v13, v5, s[0:1]
	ds_bpermute_b32 v10, v117, v0
	ds_bpermute_b32 v11, v117, v1
	s_waitcnt lgkmcnt(3)
	v_cndmask_b32_e64 v2, v14, v8, s[0:1]
	v_add_u32_e32 v8, 0xb0, v116
	s_waitcnt lgkmcnt(2)
	v_cndmask_b32_e64 v3, v15, v9, s[0:1]
	v_mad_i64_i32 v[8:9], s[4:5], v8, s53, v[112:113]
	v_lshl_add_u64 v[8:9], v[8:9], 0, v[114:115]
	s_waitcnt lgkmcnt(1)
	v_cndmask_b32_e64 v0, v10, v12, s[0:1]
	s_waitcnt lgkmcnt(0)
	v_cndmask_b32_e64 v1, v11, v13, s[0:1]
	v_lshl_add_u64 v[8:9], v[8:9], 0, v[154:155]
	global_store_dwordx4 v[8:9], v[0:3], off sc0 sc1 nt
	v_cndmask_b32_e64 v4, v4, v10, s[0:1]
	v_cndmask_b32_e64 v5, v5, v11, s[0:1]
	v_add_co_u32_e32 v0, vcc, 0x8000, v8
	v_cndmask_b32_e64 v6, v6, v14, s[0:1]
	s_nop 0
	v_addc_co_u32_e32 v1, vcc, 0, v9, vcc
	v_cndmask_b32_e64 v7, v7, v15, s[0:1]
	s_andn2_b64 vcc, exec, s[2:3]
	s_mov_b64 s[2:3], -1
	global_store_dwordx4 v[0:1], v[4:7], off offset:1024 sc0 sc1 nt
	s_cbranch_vccnz .LBB0_290
	s_andn2_b64 vcc, exec, s[8:9]
	s_cbranch_vccnz .LBB0_289
	s_barrier
	s_branch .LBB0_289

; __device__ __forceinline__ unsigned pk2(float lo, float hi) { unsigned r; asm("v_cvt_pk_bf16_f32 %0, %1, %2" : "=v"(r) : "v"(lo), "v"(hi)); return r; }
; __device__ __forceinline__ void p_merge(const Args& a, const Ctx& c) {
;     ...
;     for (int i = c.gt; i < MTOK * 128; i += c.NGT) {
;         const int row = i >> 7, h = (i >> 4) & 7, cc = i & 15;
;         const float l0 = lse[((size_t)0 * MTOK + row) * 8 + h], l1 = lse[((size_t)1 * MTOK + row) * 8 + h], l2 = lse[((size_t)2 * MTOK + row) * 8 + h];
;         const float mx = fmaxf(l0, fmaxf(l1, l2)); float w0 = __expf(l0 - mx), w1 = __expf(l1 - mx), w2 = __expf(l2 - mx); const float iw = 1.0f / (w0 + w1 + w2); w0 *= iw; w1 *= iw; w2 *= iw;
;         const bf16_t* base = PROJ + (size_t)row * LDP0 + 1024 + h * 128 + cc * 8;
;         const u32x4 v0 = *(const u32x4*)base, v1 = *(const u32x4*)(base + 1024), v2 = *(const u32x4*)(base + 2048);
;         u32x4 o;
;         o.x = pk2(w0 * bflo(v0.x) + w1 * bflo(v1.x) + w2 * bflo(v2.x), w0 * bfhi(v0.x) + w1 * bfhi(v1.x) + w2 * bfhi(v2.x));
;         o.y = pk2(w0 * bflo(v0.y) + w1 * bflo(v1.y) + w2 * bflo(v2.y), w0 * bfhi(v0.y) + w1 * bfhi(v1.y) + w2 * bfhi(v2.y));
;         o.z = pk2(w0 * bflo(v0.z) + w1 * bflo(v1.z) + w2 * bflo(v2.z), w0 * bfhi(v0.z) + w1 * bfhi(v1.z) + w2 * bfhi(v2.z));
;         o.w = pk2(w0 * bflo(v0.w) + w1 * bflo(v1.w) + w2 * bflo(v2.w), w0 * bfhi(v0.w) + w1 * bfhi(v1.w) + w2 * bfhi(v2.w));
;         *(u32x4*)(MIX + (size_t)row * LDH + 1024 + h * 128 + cc * 8) = o; }
.LBB0_318:
	v_ashrrev_i32_e32 v8, 7, v144
	v_ashrrev_i32_e32 v9, 31, v8
	v_bfe_u32 v7, v144, 4, 3
	v_mad_i64_i32 v[12:13], s[16:17], v8, s11, v[2:3]
	v_mad_i64_i32 v[14:15], s[16:17], v8, s14, v[4:5]
	v_lshlrev_b64 v[8:9], 5, v[8:9]
	v_add_u32_e32 v144, s24, v144
	v_lshlrev_b32_e32 v0, 2, v7
	v_lshl_add_u64 v[8:9], s[2:3], 0, v[8:9]
	v_cmp_lt_i32_e32 vcc, s15, v144
	v_lshl_add_u64 v[8:9], v[8:9], 0, v[0:1]
	s_or_b64 s[4:5], vcc, s[4:5]
	v_add_co_u32_e32 v16, vcc, 0x80000, v8
	v_and_b32_e32 v10, 0x78, v6
	v_lshlrev_b32_e32 v0, 8, v7
	v_addc_co_u32_e32 v17, vcc, 0, v9, vcc
	v_mov_b32_e32 v11, v1
	v_lshlrev_b32_e32 v10, 1, v10
	global_load_dword v7, v[8:9], off
	v_lshl_add_u64 v[12:13], v[12:13], 0, v[0:1]
	v_add_co_u32_e32 v8, vcc, 0x100000, v8
	v_lshl_add_u64 v[14:15], v[14:15], 0, v[0:1]
	v_lshl_add_u64 v[12:13], v[12:13], 0, v[10:11]
	v_addc_co_u32_e32 v9, vcc, 0, v9, vcc
	v_lshl_add_u64 v[20:21], v[14:15], 0, v[10:11]
	v_add_co_u32_e32 v14, vcc, s12, v12
	v_lshl_add_u64 v[10:11], v[12:13], 0, s[8:9]
	s_nop 0
	v_addc_co_u32_e32 v15, vcc, 0, v13, vcc
	v_add_co_u32_e32 v18, vcc, s13, v12
	v_add_u32_e32 v6, s10, v6
	s_nop 0
	v_addc_co_u32_e32 v19, vcc, 0, v13, vcc
	global_load_dword v0, v[16:17], off
	global_load_dword v30, v[8:9], off
	s_nop 0
	global_load_dwordx4 v[8:11], v[10:11], off offset:2048
	s_nop 0
	global_load_dwordx4 v[12:15], v[14:15], off offset:2048
	s_nop 0
	global_load_dwordx4 v[16:19], v[18:19], off offset:2048
	s_waitcnt vmcnt(3)
	v_max3_f32 v31, v7, v0, v30
	v_sub_f32_e32 v7, v7, v31
	v_sub_f32_e32 v0, v0, v31
	s_waitcnt vmcnt(2)
	v_lshlrev_b32_e32 v34, 16, v9
	v_and_b32_e32 v35, 0xffff0000, v9
	s_waitcnt vmcnt(1)
	v_lshlrev_b32_e32 v9, 16, v12
	v_and_b32_e32 v23, 0xffff0000, v12
	s_waitcnt vmcnt(0)
	v_lshlrev_b32_e32 v24, 16, v17
	v_and_b32_e32 v12, 0xffff0000, v17
	v_lshlrev_b32_e32 v17, 16, v14
	v_and_b32_e32 v27, 0xffff0000, v14
	v_sub_f32_e32 v14, v30, v31
	v_mul_f32_e32 v7, 0x3fb8aa3b, v7
	v_mul_f32_e32 v0, 0x3fb8aa3b, v0
	v_lshlrev_b32_e32 v38, 16, v11
	v_lshlrev_b32_e32 v29, 16, v15
	v_and_b32_e32 v39, 0xffff0000, v11
	v_and_b32_e32 v11, 0xffff0000, v15
	v_mul_f32_e32 v14, 0x3fb8aa3b, v14
	v_exp_f32_e32 v15, v7
	v_exp_f32_e32 v7, v0
	v_exp_f32_e32 v14, v14
	v_lshlrev_b32_e32 v32, 16, v8
	v_and_b32_e32 v33, 0xffff0000, v8
	v_add_f32_e32 v0, v15, v7
	v_add_f32_e32 v0, v14, v0
	v_lshlrev_b32_e32 v8, 16, v16
	v_and_b32_e32 v22, 0xffff0000, v16
	v_lshlrev_b32_e32 v16, 16, v18
	v_and_b32_e32 v26, 0xffff0000, v18
	v_div_scale_f32 v18, s[16:17], v0, v0, 1.0
	v_rcp_f32_e32 v30, v18
	v_lshlrev_b32_e32 v36, 16, v10
	v_and_b32_e32 v37, 0xffff0000, v10
	v_lshlrev_b32_e32 v28, 16, v19
	v_fma_f32 v31, -v18, v30, 1.0
	v_and_b32_e32 v10, 0xffff0000, v19
	v_div_scale_f32 v19, vcc, 1.0, v0, 1.0
	v_fmac_f32_e32 v30, v31, v30
	v_mul_f32_e32 v31, v19, v30
	v_fma_f32 v40, -v18, v31, v19
	v_fmac_f32_e32 v31, v40, v30
	v_fma_f32 v18, -v18, v31, v19
	v_div_fmas_f32 v18, v18, v30, v31
	v_div_fixup_f32 v0, v18, v0, 1.0
	v_lshlrev_b32_e32 v25, 16, v13
	v_and_b32_e32 v13, 0xffff0000, v13
	v_pk_mul_f32 v[14:15], v[14:15], v[0:1] op_sel_hi:[1,0]
	v_mul_f32_e32 v7, v7, v0
	v_pk_mul_f32 v[8:9], v[14:15], v[8:9]
	v_pk_mul_f32 v[18:19], v[14:15], v[22:23]
	v_pk_mul_f32 v[22:23], v[14:15], v[24:25]
	v_pk_mul_f32 v[12:13], v[14:15], v[12:13]
	v_pk_mul_f32 v[16:17], v[14:15], v[16:17]
	v_pk_mul_f32 v[24:25], v[14:15], v[26:27]
	v_pk_mul_f32 v[26:27], v[14:15], v[28:29]
	v_pk_mul_f32 v[10:11], v[14:15], v[10:11]
	v_fma_f32 v0, v7, v32, v9
	v_fma_f32 v9, v7, v33, v19
	v_fma_f32 v14, v7, v34, v23
	v_fma_f32 v13, v7, v35, v13
	v_fma_f32 v15, v7, v36, v17
	v_fma_f32 v17, v7, v37, v25
	v_fma_f32 v19, v7, v38, v27
	v_fma_f32 v7, v7, v39, v11
	v_add_f32_e32 v0, v8, v0
	v_add_f32_e32 v8, v18, v9
	v_add_f32_e32 v9, v22, v14
	v_add_f32_e32 v11, v12, v13
	v_add_f32_e32 v12, v16, v15
	v_add_f32_e32 v13, v24, v17
	v_add_f32_e32 v14, v26, v19
	v_add_f32_e32 v7, v10, v7
	v_cvt_pk_bf16_f32 v8, v0, v8
	v_cvt_pk_bf16_f32 v9, v9, v11
	v_cvt_pk_bf16_f32 v10, v12, v13
	v_cvt_pk_bf16_f32 v11, v14, v7
	global_store_dwordx4 v[20:21], v[8:11], off offset:2048 sc0 sc1
	s_andn2_b64 exec, exec, s[4:5]
	s_cbranch_execnz .LBB0_318

; __device__ __forceinline__ unsigned cvt_pk_bf16(float lo, float hi) { unsigned r; asm volatile("v_cvt_pk_bf16_f32 %0, %1, %2" : "=v"(r) : "v"(lo), "v"(hi)); return r; }
;     __device__ __forceinline__ void operator()(const f32x4 (&acc)[2][2][4][2], const Unit& u, int wr, int wc, int fr, int fq) const {
;     ...
;                     u32x4 w[2];
; #pragma unroll
;                     for (int bj = 0; bj < 2; ++bj) { const f32x4 v0 = acc[ai][bj][m][0] * sc[bj][0], v1 = acc[ai][bj][m][1] * sc[bj][1];
;                         w[bj].x = cvt_pk_bf16(v0[0], v0[1]); w[bj].y = cvt_pk_bf16(v0[2], v0[3]); w[bj].z = cvt_pk_bf16(v1[0], v1[1]); w[bj].w = cvt_pk_bf16(v1[2], v1[3]); }
;                     u32x4 snd, rcv;
;                     snd.x = low ? w[1].x : w[0].x; snd.y = low ? w[1].y : w[0].y; snd.z = low ? w[1].z : w[0].z; snd.w = low ? w[1].w : w[0].w;
;                     rcv.x = (unsigned)__shfl_xor((int)snd.x, 8); rcv.y = (unsigned)__shfl_xor((int)snd.y, 8); rcv.z = (unsigned)__shfl_xor((int)snd.z, 8); rcv.w = (unsigned)__shfl_xor((int)snd.w, 8);
;                     u32x4 dA, dB;
;                     dA.x = low ? w[0].x : rcv.x; dA.y = low ? w[0].y : rcv.y; dA.z = low ? w[0].z : rcv.z; dA.w = low ? w[0].w : rcv.w;
;                     dB.x = low ? rcv.x : w[1].x; dB.y = low ? rcv.y : w[1].y; dB.z = low ? rcv.z : w[1].z; dB.w = low ? rcv.w : w[1].w;
;                     bf16_t* pA = O + (size_t)(u.pm * BM + wr * 64 + ai * HALF + m * 16 + (fr & 7)) * ldc + colo + (low ? 0 : 32);
;                     __builtin_nontemporal_store(dA, (u32x4*)pA); __builtin_nontemporal_store(dB, (u32x4*)(pA + (size_t)8 * ldc)); }
.LBB0_395:
	v_cvt_pk_bf16_f32 v124, v124, v125
	v_cvt_pk_bf16_f32 v125, v126, v127
	v_cvt_pk_bf16_f32 v120, v120, v121
	v_cvt_pk_bf16_f32 v121, v122, v123
	v_cvt_pk_bf16_f32 v122, v116, v117
	v_cvt_pk_bf16_f32 v123, v118, v119
	v_and_b32_e32 v119, 64, v152
	v_xor_b32_e32 v118, 8, v152
	v_add_u32_e32 v119, 64, v119
	v_cmp_lt_i32_e32 vcc, v118, v119
	v_cvt_pk_bf16_f32 v112, v112, v113
	v_cvt_pk_bf16_f32 v113, v114, v115
	v_cndmask_b32_e64 v114, v124, v122, s[0:1]
	v_cndmask_b32_e64 v115, v125, v123, s[0:1]
	v_cndmask_b32_e32 v118, v152, v118, vcc
	v_cndmask_b32_e64 v116, v120, v112, s[0:1]
	v_cndmask_b32_e64 v117, v121, v113, s[0:1]
	v_lshlrev_b32_e32 v126, 2, v118
	ds_bpermute_b32 v114, v126, v114
	ds_bpermute_b32 v115, v126, v115
	ds_bpermute_b32 v127, v126, v116
	ds_bpermute_b32 v153, v126, v117
	v_lshl_or_b32 v154, s50, 8, v148
	v_ashrrev_i32_e32 v155, 31, v154
	v_lshl_add_u32 v156, s49, 8, v147
	s_waitcnt lgkmcnt(0)
	v_cndmask_b32_e64 v118, v127, v120, s[0:1]
	v_cndmask_b32_e64 v119, v153, v121, s[0:1]
	v_cndmask_b32_e64 v120, v122, v114, s[0:1]
	v_cndmask_b32_e64 v121, v123, v115, s[0:1]
	v_cndmask_b32_e64 v122, v112, v127, s[0:1]
	v_cndmask_b32_e64 v123, v113, v153, s[0:1]
	v_mov_b64_e32 v[112:113], s[10:11]
	v_cndmask_b32_e64 v116, v114, v124, s[0:1]
	v_cndmask_b32_e64 v117, v115, v125, s[0:1]
	v_mad_i64_i32 v[124:125], s[18:19], v156, s46, v[112:113]
	v_lshlrev_b64 v[114:115], 1, v[154:155]
	v_lshl_add_u64 v[124:125], v[124:125], 0, v[114:115]
	v_lshl_add_u64 v[124:125], v[124:125], 0, v[136:137]
	global_store_dwordx4 v[124:125], v[116:119], off sc0 sc1 nt
	s_nop 1
	v_add_co_u32_e32 v116, vcc, s42, v124
	s_nop 1
	v_addc_co_u32_e32 v117, vcc, 0, v125, vcc
	global_store_dwordx4 v[116:117], v[120:123], off offset:1024 sc0 sc1 nt
	v_cvt_pk_bf16_f32 v108, v108, v109
	v_cvt_pk_bf16_f32 v109, v110, v111
	v_cvt_pk_bf16_f32 v104, v104, v105
	v_cvt_pk_bf16_f32 v105, v106, v107
	v_cvt_pk_bf16_f32 v100, v100, v101
	v_cvt_pk_bf16_f32 v101, v102, v103
	v_cvt_pk_bf16_f32 v102, v96, v97
	v_cvt_pk_bf16_f32 v103, v98, v99
	s_nop 0
	v_cndmask_b32_e64 v98, v104, v102, s[0:1]
	v_cndmask_b32_e64 v99, v105, v103, s[0:1]
	ds_bpermute_b32 v110, v126, v98
	ds_bpermute_b32 v111, v126, v99
	v_cndmask_b32_e64 v96, v108, v100, s[0:1]
	v_cndmask_b32_e64 v97, v109, v101, s[0:1]
	ds_bpermute_b32 v106, v126, v96
	ds_bpermute_b32 v107, v126, v97
	s_waitcnt lgkmcnt(0)
	v_cndmask_b32_e64 v98, v110, v104, s[0:1]
	v_or_b32_e32 v104, 16, v156
	v_cndmask_b32_e64 v99, v111, v105, s[0:1]
	v_mad_i64_i32 v[104:105], s[18:19], v104, s46, v[112:113]
	v_lshl_add_u64 v[104:105], v[104:105], 0, v[114:115]
	v_cndmask_b32_e64 v96, v106, v108, s[0:1]
	v_cndmask_b32_e64 v97, v107, v109, s[0:1]
	v_lshl_add_u64 v[104:105], v[104:105], 0, v[136:137]
	global_store_dwordx4 v[104:105], v[96:99], off sc0 sc1 nt
	v_cndmask_b32_e64 v100, v100, v106, s[0:1]
	v_cndmask_b32_e64 v101, v101, v107, s[0:1]
	v_add_co_u32_e32 v96, vcc, s42, v104
	v_cndmask_b32_e64 v102, v102, v110, s[0:1]
	v_cndmask_b32_e64 v103, v103, v111, s[0:1]
	v_addc_co_u32_e32 v97, vcc, 0, v105, vcc
	global_store_dwordx4 v[96:97], v[100:103], off offset:1024 sc0 sc1 nt
	v_cvt_pk_bf16_f32 v92, v92, v93
	v_cvt_pk_bf16_f32 v93, v94, v95
	v_cvt_pk_bf16_f32 v88, v88, v89
	v_cvt_pk_bf16_f32 v89, v90, v91
	v_cvt_pk_bf16_f32 v84, v84, v85
	v_cvt_pk_bf16_f32 v85, v86, v87
	v_cvt_pk_bf16_f32 v86, v80, v81
	v_cvt_pk_bf16_f32 v87, v82, v83
	s_nop 0
	v_cndmask_b32_e64 v82, v88, v86, s[0:1]
	v_cndmask_b32_e64 v83, v89, v87, s[0:1]
	ds_bpermute_b32 v94, v126, v82
	ds_bpermute_b32 v95, v126, v83
	v_cndmask_b32_e64 v80, v92, v84, s[0:1]
	v_cndmask_b32_e64 v81, v93, v85, s[0:1]
	ds_bpermute_b32 v90, v126, v80
	ds_bpermute_b32 v91, v126, v81
	s_waitcnt lgkmcnt(0)
	v_cndmask_b32_e64 v82, v94, v88, s[0:1]
	v_or_b32_e32 v88, 32, v156
	v_cndmask_b32_e64 v83, v95, v89, s[0:1]
	v_mad_i64_i32 v[88:89], s[18:19], v88, s46, v[112:113]
	v_lshl_add_u64 v[88:89], v[88:89], 0, v[114:115]
	v_cndmask_b32_e64 v80, v90, v92, s[0:1]
	v_cndmask_b32_e64 v81, v91, v93, s[0:1]
	v_lshl_add_u64 v[88:89], v[88:89], 0, v[136:137]
	global_store_dwordx4 v[88:89], v[80:83], off sc0 sc1 nt
	v_cndmask_b32_e64 v84, v84, v90, s[0:1]
	v_cndmask_b32_e64 v85, v85, v91, s[0:1]
	v_add_co_u32_e32 v80, vcc, s42, v88
	v_cndmask_b32_e64 v86, v86, v94, s[0:1]
	v_cndmask_b32_e64 v87, v87, v95, s[0:1]
	v_addc_co_u32_e32 v81, vcc, 0, v89, vcc
	global_store_dwordx4 v[80:81], v[84:87], off offset:1024 sc0 sc1 nt
	v_cvt_pk_bf16_f32 v76, v76, v77
	v_cvt_pk_bf16_f32 v77, v78, v79
	v_cvt_pk_bf16_f32 v72, v72, v73
	v_cvt_pk_bf16_f32 v73, v74, v75
	v_cvt_pk_bf16_f32 v68, v68, v69
	v_cvt_pk_bf16_f32 v69, v70, v71
	v_cvt_pk_bf16_f32 v70, v64, v65
	v_cvt_pk_bf16_f32 v71, v66, v67
	s_nop 0
	v_cndmask_b32_e64 v66, v72, v70, s[0:1]
	v_cndmask_b32_e64 v67, v73, v71, s[0:1]
	ds_bpermute_b32 v78, v126, v66
	ds_bpermute_b32 v79, v126, v67
	v_cndmask_b32_e64 v64, v76, v68, s[0:1]
	v_cndmask_b32_e64 v65, v77, v69, s[0:1]
	ds_bpermute_b32 v74, v126, v64
	ds_bpermute_b32 v75, v126, v65
	s_waitcnt lgkmcnt(0)
; __device__ __forceinline__ unsigned cvt_pk_bf16(float lo, float hi) { unsigned r; asm volatile("v_cvt_pk_bf16_f32 %0, %1, %2" : "=v"(r) : "v"(lo), "v"(hi)); return r; }
; #define PG8_BAR __builtin_amdgcn_s_barrier()
;     __device__ __forceinline__ void operator()(const f32x4 (&acc)[2][2][4][2], const Unit& u, int wr, int wc, int fr, int fq) const {
;     ...
;                     u32x4 w[2];
; #pragma unroll
;                     for (int bj = 0; bj < 2; ++bj) { const f32x4 v0 = acc[ai][bj][m][0] * sc[bj][0], v1 = acc[ai][bj][m][1] * sc[bj][1];
;                         w[bj].x = cvt_pk_bf16(v0[0], v0[1]); w[bj].y = cvt_pk_bf16(v0[2], v0[3]); w[bj].z = cvt_pk_bf16(v1[0], v1[1]); w[bj].w = cvt_pk_bf16(v1[2], v1[3]); }
;                     u32x4 snd, rcv;
;                     snd.x = low ? w[1].x : w[0].x; snd.y = low ? w[1].y : w[0].y; snd.z = low ? w[1].z : w[0].z; snd.w = low ? w[1].w : w[0].w;
;                     rcv.x = (unsigned)__shfl_xor((int)snd.x, 8); rcv.y = (unsigned)__shfl_xor((int)snd.y, 8); rcv.z = (unsigned)__shfl_xor((int)snd.z, 8); rcv.w = (unsigned)__shfl_xor((int)snd.w, 8);
;                     u32x4 dA, dB;
;                     dA.x = low ? w[0].x : rcv.x; dA.y = low ? w[0].y : rcv.y; dA.z = low ? w[0].z : rcv.z; dA.w = low ? w[0].w : rcv.w;
;                     dB.x = low ? rcv.x : w[1].x; dB.y = low ? rcv.y : w[1].y; dB.z = low ? rcv.z : w[1].z; dB.w = low ? rcv.w : w[1].w;
;                     bf16_t* pA = O + (size_t)(u.pm * BM + wr * 64 + ai * HALF + m * 16 + (fr & 7)) * ldc + colo + (low ? 0 : 32);
;                     __builtin_nontemporal_store(dA, (u32x4*)pA); __builtin_nontemporal_store(dB, (u32x4*)(pA + (size_t)8 * ldc)); }
; template <class EpiT>
; __device__ __forceinline__ void gemm_phase(LAS unsigned char* lds, const Gemm g, const StaticOrder& S, const EpiT& E) {
;     ...
;         if (wr == 0) PG8_BAR;
;         E(acc, cur, wr, wc, fr, fq);
;         if (!has_next) break;
; #pragma unroll
;         for (int a = 0; a < 2; ++a)
; #pragma unroll
;             for (int b = 0; b < 2; ++b)
; #pragma unroll
;                 for (int m = 0; m < 4; ++m)
; #pragma unroll
;                     for (int n = 0; n < 2; ++n) acc[a][b][m][n] = (f32x4){0.f, 0.f, 0.f, 0.f};
;         cur = nxt; cA = nA; cB = nB; ++ui;
;         if (wr == 1) PG8_BAR;
	v_cndmask_b32_e64 v66, v78, v72, s[0:1]
	v_or_b32_e32 v72, 48, v156
	v_cndmask_b32_e64 v67, v79, v73, s[0:1]
	v_mad_i64_i32 v[72:73], s[18:19], v72, s46, v[112:113]
	v_lshl_add_u64 v[72:73], v[72:73], 0, v[114:115]
	v_cndmask_b32_e64 v64, v74, v76, s[0:1]
	v_cndmask_b32_e64 v65, v75, v77, s[0:1]
	v_lshl_add_u64 v[72:73], v[72:73], 0, v[136:137]
	global_store_dwordx4 v[72:73], v[64:67], off sc0 sc1 nt
	v_cndmask_b32_e64 v68, v68, v74, s[0:1]
	v_cndmask_b32_e64 v69, v69, v75, s[0:1]
	v_add_co_u32_e32 v64, vcc, s42, v72
	v_cndmask_b32_e64 v70, v70, v78, s[0:1]
	v_cndmask_b32_e64 v71, v71, v79, s[0:1]
	v_addc_co_u32_e32 v65, vcc, 0, v73, vcc
	global_store_dwordx4 v[64:65], v[68:71], off offset:1024 sc0 sc1 nt
	v_cvt_pk_bf16_f32 v60, v60, v61
	v_cvt_pk_bf16_f32 v61, v62, v63
	v_cvt_pk_bf16_f32 v56, v56, v57
	v_cvt_pk_bf16_f32 v57, v58, v59
	v_cvt_pk_bf16_f32 v52, v52, v53
	v_cvt_pk_bf16_f32 v53, v54, v55
	v_cvt_pk_bf16_f32 v54, v48, v49
	v_cvt_pk_bf16_f32 v55, v50, v51
	v_add_u32_e32 v64, 0x80, v156
	v_cndmask_b32_e64 v50, v56, v54, s[0:1]
	v_cndmask_b32_e64 v51, v57, v55, s[0:1]
	ds_bpermute_b32 v62, v126, v50
	ds_bpermute_b32 v63, v126, v51
	v_cndmask_b32_e64 v48, v60, v52, s[0:1]
	v_cndmask_b32_e64 v49, v61, v53, s[0:1]
	ds_bpermute_b32 v58, v126, v48
	ds_bpermute_b32 v59, v126, v49
	s_waitcnt lgkmcnt(0)
	v_cndmask_b32_e64 v50, v62, v56, s[0:1]
	v_cndmask_b32_e64 v51, v63, v57, s[0:1]
	v_mad_i64_i32 v[56:57], s[18:19], v64, s46, v[112:113]
	v_lshl_add_u64 v[56:57], v[56:57], 0, v[114:115]
	v_cndmask_b32_e64 v48, v58, v60, s[0:1]
	v_cndmask_b32_e64 v49, v59, v61, s[0:1]
	v_lshl_add_u64 v[56:57], v[56:57], 0, v[136:137]
	global_store_dwordx4 v[56:57], v[48:51], off sc0 sc1 nt
	v_cndmask_b32_e64 v52, v52, v58, s[0:1]
	v_cndmask_b32_e64 v53, v53, v59, s[0:1]
	v_add_co_u32_e32 v48, vcc, s42, v56
	v_cndmask_b32_e64 v54, v54, v62, s[0:1]
	v_cndmask_b32_e64 v55, v55, v63, s[0:1]
	v_addc_co_u32_e32 v49, vcc, 0, v57, vcc
	global_store_dwordx4 v[48:49], v[52:55], off offset:1024 sc0 sc1 nt
	v_cvt_pk_bf16_f32 v44, v44, v45
	v_cvt_pk_bf16_f32 v45, v46, v47
	v_cvt_pk_bf16_f32 v40, v40, v41
	v_cvt_pk_bf16_f32 v41, v42, v43
	v_cvt_pk_bf16_f32 v36, v36, v37
	v_cvt_pk_bf16_f32 v37, v38, v39
	v_cvt_pk_bf16_f32 v38, v32, v33
	v_cvt_pk_bf16_f32 v39, v34, v35
	s_nop 0
	v_cndmask_b32_e64 v34, v40, v38, s[0:1]
	v_cndmask_b32_e64 v35, v41, v39, s[0:1]
	ds_bpermute_b32 v46, v126, v34
	ds_bpermute_b32 v47, v126, v35
	v_cndmask_b32_e64 v32, v44, v36, s[0:1]
	v_cndmask_b32_e64 v33, v45, v37, s[0:1]
	ds_bpermute_b32 v42, v126, v32
	ds_bpermute_b32 v43, v126, v33
	s_waitcnt lgkmcnt(0)
	v_cndmask_b32_e64 v34, v46, v40, s[0:1]
	v_add_u32_e32 v40, 0x90, v156
	v_cndmask_b32_e64 v35, v47, v41, s[0:1]
	v_mad_i64_i32 v[40:41], s[18:19], v40, s46, v[112:113]
	v_lshl_add_u64 v[40:41], v[40:41], 0, v[114:115]
	v_cndmask_b32_e64 v32, v42, v44, s[0:1]
	v_cndmask_b32_e64 v33, v43, v45, s[0:1]
	v_lshl_add_u64 v[40:41], v[40:41], 0, v[136:137]
	global_store_dwordx4 v[40:41], v[32:35], off sc0 sc1 nt
	v_cndmask_b32_e64 v36, v36, v42, s[0:1]
	v_cndmask_b32_e64 v37, v37, v43, s[0:1]
	v_add_co_u32_e32 v32, vcc, s42, v40
	v_cndmask_b32_e64 v38, v38, v46, s[0:1]
	v_cndmask_b32_e64 v39, v39, v47, s[0:1]
	v_addc_co_u32_e32 v33, vcc, 0, v41, vcc
	global_store_dwordx4 v[32:33], v[36:39], off offset:1024 sc0 sc1 nt
	v_cvt_pk_bf16_f32 v28, v28, v29
	v_cvt_pk_bf16_f32 v29, v30, v31
	v_cvt_pk_bf16_f32 v24, v24, v25
	v_cvt_pk_bf16_f32 v25, v26, v27
	v_cvt_pk_bf16_f32 v20, v20, v21
	v_cvt_pk_bf16_f32 v21, v22, v23
	v_cvt_pk_bf16_f32 v22, v16, v17
	v_cvt_pk_bf16_f32 v23, v18, v19
	s_nop 0
	v_cndmask_b32_e64 v18, v24, v22, s[0:1]
	v_cndmask_b32_e64 v19, v25, v23, s[0:1]
	ds_bpermute_b32 v30, v126, v18
	ds_bpermute_b32 v31, v126, v19
	v_cndmask_b32_e64 v16, v28, v20, s[0:1]
	v_cndmask_b32_e64 v17, v29, v21, s[0:1]
	ds_bpermute_b32 v26, v126, v16
	ds_bpermute_b32 v27, v126, v17
	s_waitcnt lgkmcnt(0)
	v_cndmask_b32_e64 v18, v30, v24, s[0:1]
	v_add_u32_e32 v24, 0xa0, v156
	v_cndmask_b32_e64 v19, v31, v25, s[0:1]
	v_mad_i64_i32 v[24:25], s[18:19], v24, s46, v[112:113]
	v_lshl_add_u64 v[24:25], v[24:25], 0, v[114:115]
	v_cndmask_b32_e64 v16, v26, v28, s[0:1]
	v_cndmask_b32_e64 v17, v27, v29, s[0:1]
	v_lshl_add_u64 v[24:25], v[24:25], 0, v[136:137]
	global_store_dwordx4 v[24:25], v[16:19], off sc0 sc1 nt
	v_cndmask_b32_e64 v20, v20, v26, s[0:1]
	v_cndmask_b32_e64 v21, v21, v27, s[0:1]
	v_add_co_u32_e32 v16, vcc, s42, v24
	v_cndmask_b32_e64 v22, v22, v30, s[0:1]
	v_cndmask_b32_e64 v23, v23, v31, s[0:1]
	v_addc_co_u32_e32 v17, vcc, 0, v25, vcc
	global_store_dwordx4 v[16:17], v[20:23], off offset:1024 sc0 sc1 nt
	v_cvt_pk_bf16_f32 v12, v12, v13
	v_cvt_pk_bf16_f32 v13, v14, v15
	v_cvt_pk_bf16_f32 v8, v8, v9
	v_cvt_pk_bf16_f32 v9, v10, v11
	v_cvt_pk_bf16_f32 v4, v4, v5
	v_cvt_pk_bf16_f32 v5, v6, v7
	v_cvt_pk_bf16_f32 v6, v0, v1
	v_cvt_pk_bf16_f32 v7, v2, v3
	s_nop 0
	v_cndmask_b32_e64 v2, v8, v6, s[0:1]
	v_cndmask_b32_e64 v3, v9, v7, s[0:1]
	ds_bpermute_b32 v14, v126, v2
	ds_bpermute_b32 v15, v126, v3
	v_cndmask_b32_e64 v0, v12, v4, s[0:1]
	v_cndmask_b32_e64 v1, v13, v5, s[0:1]
	ds_bpermute_b32 v10, v126, v0
	ds_bpermute_b32 v11, v126, v1
	s_waitcnt lgkmcnt(0)
	v_cndmask_b32_e64 v2, v14, v8, s[0:1]
	v_add_u32_e32 v8, 0xb0, v156
	v_cndmask_b32_e64 v3, v15, v9, s[0:1]
	v_mad_i64_i32 v[8:9], s[18:19], v8, s46, v[112:113]
	v_lshl_add_u64 v[8:9], v[8:9], 0, v[114:115]
	v_cndmask_b32_e64 v0, v10, v12, s[0:1]
	v_cndmask_b32_e64 v1, v11, v13, s[0:1]
	v_lshl_add_u64 v[8:9], v[8:9], 0, v[136:137]
	global_store_dwordx4 v[8:9], v[0:3], off sc0 sc1 nt
	v_cndmask_b32_e64 v4, v4, v10, s[0:1]
	v_cndmask_b32_e64 v5, v5, v11, s[0:1]
	v_add_co_u32_e32 v0, vcc, 0x8000, v8
	v_cndmask_b32_e64 v6, v6, v14, s[0:1]
	s_nop 0
	v_addc_co_u32_e32 v1, vcc, 0, v9, vcc
	v_cndmask_b32_e64 v7, v7, v15, s[0:1]
	s_and_b64 vcc, exec, s[2:3]
	s_mov_b64 s[2:3], -1
	global_store_dwordx4 v[0:1], v[4:7], off offset:1024 sc0 sc1 nt
	s_cbranch_vccnz .LBB0_380
	s_andn2_b64 vcc, exec, s[8:9]
	s_cbranch_vccnz .LBB0_379
	s_barrier
	s_branch .LBB0_379

; __device__ __forceinline__ void resid_rows(const float* prev, const bf16_t* Y, const float* ga, const bf16_t* F, const float* gc, float* xout, const float* gb, bf16_t* hn, int gw, int NGW, int lane) {
;     for (int m = gw; m < MTOK; m += NGW) {
;         f32x4 y[8]; float s = 0.f;
; #pragma unroll
;         for (int j = 0; j < 8; ++j) { const u32x2 w = *(const u32x2*)(Y + (size_t)m * LDH + 4 * lane + 256 * j); y[j] = (f32x4){bflo(w.x), bfhi(w.x), bflo(w.y), bfhi(w.y)};
;             s += (y[j][0] * y[j][0] + y[j][1] * y[j][1]) + (y[j][2] * y[j][2] + y[j][3] * y[j][3]); }
;         const float rs = 1.0f / sqrtf(wave_sum(s) * (1.0f / D_MODEL) + EPS);
.LBB0_451:
	global_load_dwordx2 v[92:93], v[90:91], off
	global_load_dwordx2 v[94:95], v[90:91], off offset:512
	global_load_dwordx2 v[96:97], v[90:91], off offset:1024
	global_load_dwordx2 v[98:99], v[90:91], off offset:1536
	global_load_dwordx2 v[102:103], v[90:91], off offset:2048
	global_load_dwordx2 v[104:105], v[90:91], off offset:2560
	global_load_dwordx2 v[106:107], v[90:91], off offset:3072
	global_load_dwordx2 v[108:109], v[90:91], off offset:3584
	global_load_dwordx4 v[0:3], v[88:89], off offset:-4096
	global_load_dwordx4 v[4:7], v[88:89], off offset:-3072
	global_load_dwordx4 v[12:15], v[68:69], off
	global_load_dwordx4 v[8:11], v[68:69], off offset:1024
	global_load_dwordx4 v[16:19], v[88:89], off offset:-2048
	global_load_dwordx4 v[20:23], v[88:89], off offset:-1024
	global_load_dwordx4 v[28:31], v[68:69], off offset:2048
	global_load_dwordx4 v[24:27], v[68:69], off offset:3072
	global_load_dwordx4 v[32:35], v[88:89], off
	global_load_dwordx4 v[36:39], v[88:89], off offset:1024
	global_load_dwordx4 v[40:43], v[82:83], off
	global_load_dwordx4 v[44:47], v[84:85], off
	global_load_dwordx4 v[48:51], v[88:89], off offset:2048
	global_load_dwordx4 v[52:55], v[88:89], off offset:3072
	global_load_dwordx4 v[56:59], v[86:87], off
	global_load_dwordx4 v[60:63], v[80:81], off
	global_load_dwordx4 v[64:67], v[70:71], off
	v_add_co_u32_e32 v100, vcc, s7, v90
	s_add_i32 s8, s8, s60
	s_nop 0
	v_addc_co_u32_e32 v101, vcc, 0, v91, vcc
	v_lshl_add_u64 v[88:89], v[88:89], 0, s[4:5]
	v_lshl_add_u64 v[90:91], v[90:91], 0, s[82:83]
	s_cmpk_lt_i32 s8, 0x4000
	s_waitcnt vmcnt(24)
	v_lshlrev_b32_e32 v118, 16, v92
	v_and_b32_e32 v119, 0xffff0000, v92
	v_lshlrev_b32_e32 v92, 16, v93
	v_and_b32_e32 v93, 0xffff0000, v93
	s_waitcnt vmcnt(23)
	v_lshlrev_b32_e32 v121, 16, v95
	v_lshlrev_b32_e32 v120, 16, v94
	v_and_b32_e32 v95, 0xffff0000, v95
	v_and_b32_e32 v94, 0xffff0000, v94
	s_waitcnt vmcnt(22)
	v_and_b32_e32 v123, 0xffff0000, v96
	s_waitcnt vmcnt(21)
	v_lshlrev_b32_e32 v125, 16, v98
	s_waitcnt vmcnt(17)
	v_lshlrev_b32_e32 v135, 16, v108
	v_mul_f32_e32 v124, v93, v93
	v_pk_mul_f32 v[138:139], v[94:95], v[94:95]
	v_mul_f32_e32 v134, v119, v119
	v_lshlrev_b32_e32 v122, 16, v96
	v_lshlrev_b32_e32 v96, 16, v97
	v_and_b32_e32 v97, 0xffff0000, v97
	v_lshlrev_b32_e32 v129, 16, v103
	v_lshlrev_b32_e32 v128, 16, v102
	v_and_b32_e32 v103, 0xffff0000, v103
	v_and_b32_e32 v102, 0xffff0000, v102
	v_lshlrev_b32_e32 v131, 16, v105
	v_lshlrev_b32_e32 v130, 16, v104
	v_and_b32_e32 v105, 0xffff0000, v105
	v_and_b32_e32 v104, 0xffff0000, v104
	v_mov_b32_e32 v141, v125
	v_mul_f32_e32 v140, v123, v123
	v_mov_b32_e32 v154, v120
	v_mov_b32_e32 v155, v94
	v_mov_b32_e32 v94, v121
	v_pk_fma_f32 v[160:161], v[92:93], v[92:93], v[124:125] op_sel_hi:[1,1,0]
	v_pk_fma_f32 v[120:121], v[120:121], v[120:121], v[138:139]
	v_pk_fma_f32 v[138:139], v[118:119], v[118:119], v[134:135] op_sel_hi:[1,1,0]
	v_and_b32_e32 v127, 0xffff0000, v98
	v_lshlrev_b32_e32 v98, 16, v99
	v_and_b32_e32 v99, 0xffff0000, v99
	v_mul_f32_e32 v142, v97, v97
	v_pk_mul_f32 v[144:145], v[102:103], v[102:103]
	v_pk_mul_f32 v[146:147], v[104:105], v[104:105]
	v_mov_b32_e32 v143, v135
	v_pk_fma_f32 v[162:163], v[122:123], v[122:123], v[140:141] op_sel_hi:[1,1,0]
	v_mov_b32_e32 v124, v138
	v_mov_b32_e32 v140, v160
	v_mul_f32_e32 v149, v127, v127
	v_mul_f32_e32 v153, v98, v98
	v_mul_f32_e32 v165, v99, v99
	v_mov_b32_e32 v126, v125
	v_mov_b32_e32 v156, v128
	v_mov_b32_e32 v157, v102
	v_mov_b32_e32 v102, v129
	v_mov_b32_e32 v158, v131
	v_mov_b32_e32 v159, v105
	v_pk_fma_f32 v[166:167], v[96:97], v[96:97], v[142:143] op_sel_hi:[1,1,0]
	v_pk_fma_f32 v[128:129], v[128:129], v[128:129], v[144:145]
	v_pk_fma_f32 v[144:145], v[130:131], v[130:131], v[146:147]
	v_mov_b32_e32 v131, v104
	v_pk_add_f32 v[104:105], v[138:139], v[160:161]
	v_pk_add_f32 v[120:121], v[120:121], v[120:121] op_sel:[0,1] op_sel_hi:[1,0]
	v_pk_mul_f32 v[124:125], v[124:125], v[140:141]
	v_mov_b32_e32 v163, v153
	v_mov_b32_e32 v167, v165
	v_mov_b32_e32 v121, v149
	v_mov_b32_e32 v105, v125
	v_pk_add_f32 v[140:141], v[162:163], v[166:167]
	v_pk_add_f32 v[104:105], v[104:105], v[120:121]
	v_lshlrev_b32_e32 v132, 16, v106
	v_pk_add_f32 v[104:105], v[104:105], v[140:141]
	v_and_b32_e32 v133, 0xffff0000, v106
	v_lshlrev_b32_e32 v106, 16, v107
	v_and_b32_e32 v107, 0xffff0000, v107
	v_pk_add_f32 v[128:129], v[128:129], v[128:129] op_sel:[0,1] op_sel_hi:[1,0]
	v_pk_add_f32 v[104:105], v[104:105], v[104:105] op_sel:[0,1] op_sel_hi:[1,0]
	v_and_b32_e32 v137, 0xffff0000, v108
	v_lshlrev_b32_e32 v108, 16, v109
	v_and_b32_e32 v109, 0xffff0000, v109
	v_mul_f32_e32 v150, v133, v133
	v_mul_f32_e32 v152, v107, v107
	v_mov_b32_e32 v142, v128
	v_mov_b32_e32 v134, v104
	v_mul_f32_e32 v170, v137, v137
	v_mul_f32_e32 v171, v108, v108
	v_mul_f32_e32 v172, v109, v109
	v_pk_fma_f32 v[146:147], v[132:133], v[132:133], v[150:151] op_sel_hi:[1,1,0]
	v_pk_fma_f32 v[150:151], v[106:107], v[106:107], v[152:153] op_sel_hi:[1,1,0]
	v_pk_add_f32 v[138:139], v[144:145], v[144:145] op_sel:[0,1] op_sel_hi:[1,0]
	v_pk_add_f32 v[104:105], v[104:105], v[128:129]
	v_pk_mul_f32 v[120:121], v[134:135], v[142:143]
	v_mov_b32_e32 v147, v171
	v_mov_b32_e32 v151, v172
	v_mov_b32_e32 v139, v170
	v_mov_b32_e32 v105, v121
	v_pk_add_f32 v[144:145], v[146:147], v[150:151]
	v_pk_add_f32 v[104:105], v[104:105], v[138:139]
	v_mov_b32_e32 v136, v135
	v_pk_add_f32 v[104:105], v[104:105], v[144:145]
	s_nop 0
	v_add_f32_e32 v104, v104, v105
	ds_bpermute_b32 v105, v110, v104
	s_waitcnt lgkmcnt(0)
	v_add_f32_e32 v104, v104, v105
	ds_bpermute_b32 v105, v111, v104
	s_waitcnt lgkmcnt(0)
; __device__ __forceinline__ void row_norm_store(const f32x4 (&v)[8], const float* gain, bf16_t* orow, int lane) {
;     float s = 0.f;
; #pragma unroll
;     for (int j = 0; j < 8; ++j) s += (v[j][0] * v[j][0] + v[j][1] * v[j][1]) + (v[j][2] * v[j][2] + v[j][3] * v[j][3]);
;     const float rs = 1.0f / sqrtf(wave_sum(s) * (1.0f / D_MODEL) + EPS);
; __device__ __forceinline__ void resid_rows(const float* prev, const bf16_t* Y, const float* ga, const bf16_t* F, const float* gc, float* xout, const float* gb, bf16_t* hn, int gw, int NGW, int lane) {
;     ...
;         const float rs = 1.0f / sqrtf(wave_sum(s) * (1.0f / D_MODEL) + EPS);
;         f32x4 x1[8];
; #pragma unroll
;         for (int j = 0; j < 8; ++j) { const f32x4 pv = *(const f32x4*)(prev + (size_t)m * D_MODEL + 4 * lane + 256 * j); const f32x4 gv = *(const f32x4*)(ga + 4 * lane + 256 * j);
;             x1[j] = pv + y[j] * rs * gv; }
	v_add_f32_e32 v104, v104, v105
	ds_bpermute_b32 v105, v112, v104
	s_waitcnt lgkmcnt(0)
	v_add_f32_e32 v104, v104, v105
	ds_bpermute_b32 v105, v113, v104
	s_waitcnt lgkmcnt(0)
	v_add_f32_e32 v104, v104, v105
	ds_bpermute_b32 v105, v114, v104
	s_waitcnt lgkmcnt(0)
	v_add_f32_e32 v104, v104, v105
	ds_bpermute_b32 v105, v115, v104
	s_waitcnt lgkmcnt(0)
	v_add_f32_e32 v104, v104, v105
	v_fmamk_f32 v104, v104, 0x3a000000, v116
	v_mul_f32_e32 v105, 0x4f800000, v104
	v_cmp_gt_f32_e32 vcc, s6, v104
	s_nop 1
	v_cndmask_b32_e32 v104, v104, v105, vcc
	v_sqrt_f32_e32 v105, v104
	s_nop 0
	v_add_u32_e32 v120, -1, v105
	v_add_u32_e32 v121, 1, v105
	v_fma_f32 v124, -v120, v105, v104
	v_fma_f32 v125, -v121, v105, v104
	v_cmp_ge_f32_e64 s[0:1], 0, v124
	s_nop 1
	v_cndmask_b32_e64 v105, v105, v120, s[0:1]
	v_cmp_lt_f32_e64 s[0:1], 0, v125
	s_nop 1
	v_cndmask_b32_e64 v105, v105, v121, s[0:1]
	v_mul_f32_e32 v120, 0x37800000, v105
	v_cndmask_b32_e32 v105, v105, v120, vcc
	v_cmp_class_f32_e32 vcc, v104, v117
	s_nop 1
	v_cndmask_b32_e32 v104, v105, v104, vcc
	v_div_scale_f32 v105, s[0:1], v104, v104, 1.0
	v_rcp_f32_e32 v121, v105
	v_div_scale_f32 v120, vcc, 1.0, v104, 1.0
	v_fma_f32 v124, -v105, v121, 1.0
	v_fmac_f32_e32 v121, v124, v121
	v_mul_f32_e32 v124, v120, v121
	v_fma_f32 v125, -v105, v124, v120
	v_fmac_f32_e32 v124, v125, v121
	v_fma_f32 v105, -v105, v124, v120
	v_div_fmas_f32 v105, v105, v121, v124
	v_div_fixup_f32 v104, v105, v104, 1.0
	v_pk_mul_f32 v[118:119], v[104:105], v[118:119] op_sel_hi:[0,1]
	v_pk_mul_f32 v[92:93], v[104:105], v[92:93] op_sel_hi:[0,1]
	v_pk_mul_f32 v[120:121], v[104:105], v[154:155] op_sel_hi:[0,1]
	v_pk_mul_f32 v[94:95], v[104:105], v[94:95] op_sel_hi:[0,1]
	v_pk_mul_f32 v[96:97], v[104:105], v[96:97] op_sel_hi:[0,1]
	v_pk_mul_f32 v[122:123], v[104:105], v[122:123] op_sel_hi:[0,1]
	v_pk_mul_f32 v[98:99], v[98:99], v[104:105] op_sel_hi:[1,0]
	v_pk_mul_f32 v[102:103], v[104:105], v[102:103] op_sel_hi:[0,1]
	v_pk_mul_f32 v[128:129], v[104:105], v[158:159] op_sel_hi:[0,1]
	s_waitcnt vmcnt(14)
	v_pk_fma_f32 v[2:3], v[14:15], v[92:93], v[2:3]
	v_pk_fma_f32 v[0:1], v[12:13], v[118:119], v[0:1]
	s_waitcnt vmcnt(13)
	v_pk_fma_f32 v[6:7], v[10:11], v[94:95], v[6:7]
	v_pk_fma_f32 v[4:5], v[8:9], v[120:121], v[4:5]
	v_pk_mul_f32 v[124:125], v[126:127], v[104:105] op_sel_hi:[1,0]
	v_pk_mul_f32 v[126:127], v[104:105], v[156:157] op_sel_hi:[0,1]
	v_pk_mul_f32 v[130:131], v[104:105], v[130:131] op_sel_hi:[0,1]
	s_waitcnt vmcnt(10)
	v_pk_fma_f32 v[8:9], v[28:29], v[122:123], v[16:17]
	v_pk_fma_f32 v[10:11], v[30:31], v[96:97], v[18:19]
	s_waitcnt vmcnt(9)
	v_pk_fma_f32 v[12:13], v[26:27], v[98:99], v[22:23]
	s_waitcnt vmcnt(1)
	v_pk_fma_f32 v[16:17], v[62:63], v[102:103], v[34:35]
	v_pk_fma_f32 v[22:23], v[42:43], v[128:129], v[38:39]
	v_mov_b32_e32 v34, v1
	v_mov_b32_e32 v35, v5
	v_mov_b32_e32 v38, v3
	v_mov_b32_e32 v39, v7
	v_pk_mul_f32 v[134:135], v[136:137], v[104:105] op_sel_hi:[1,0]
	v_pk_fma_f32 v[14:15], v[24:25], v[124:125], v[20:21]
	v_pk_fma_f32 v[18:19], v[60:61], v[126:127], v[32:33]
	v_pk_fma_f32 v[20:21], v[40:41], v[130:131], v[36:37]
	v_mov_b32_e32 v32, v0
	v_mov_b32_e32 v33, v4
	v_mov_b32_e32 v36, v2
	v_mov_b32_e32 v37, v6
	v_pk_mul_f32 v[40:41], v[10:11], v[10:11]
	v_pk_mul_f32 v[42:43], v[8:9], v[8:9]
	v_pk_mul_f32 v[34:35], v[34:35], v[34:35]
	v_pk_mul_f32 v[38:39], v[38:39], v[38:39]
	v_pk_mul_f32 v[132:133], v[104:105], v[132:133] op_sel_hi:[0,1]
	v_pk_mul_f32 v[106:107], v[104:105], v[106:107] op_sel_hi:[0,1]
	v_pk_fma_f32 v[30:31], v[134:135], v[56:57], v[52:53]
	v_pk_mov_b32 v[56:57], v[42:43], v[40:41] op_sel:[1,0]
	v_mov_b32_e32 v43, v41
	v_pk_fma_f32 v[32:33], v[32:33], v[32:33], v[34:35]
	v_pk_fma_f32 v[34:35], v[36:37], v[36:37], v[38:39]
	v_pk_fma_f32 v[24:25], v[46:47], v[106:107], v[50:51]
	v_pk_fma_f32 v[26:27], v[44:45], v[132:133], v[48:49]
	v_mul_f32_e32 v44, v14, v14
	v_mul_f32_e32 v46, v12, v12
	v_pk_add_f32 v[36:37], v[56:57], v[42:43]
	v_pk_add_f32 v[32:33], v[32:33], v[34:35]
	v_pk_fma_f32 v[40:41], v[14:15], v[14:15], v[44:45] op_sel_hi:[1,1,0]
	v_pk_fma_f32 v[44:45], v[12:13], v[12:13], v[46:47] op_sel_hi:[1,1,0]
	v_pk_add_f32 v[34:35], v[36:37], v[36:37] op_sel_hi:[0,1]
	v_pk_add_f32 v[32:33], v[32:33], v[32:33] op_sel_hi:[0,1]
	v_pk_mul_f32 v[48:49], v[22:23], v[22:23]
	v_pk_mul_f32 v[50:51], v[20:21], v[20:21]
	v_mul_f32_e32 v40, v18, v18
	v_mul_f32_e32 v44, v19, v19
	v_mul_f32_e32 v34, v16, v16
	v_mul_f32_e32 v32, v17, v17
	v_pk_mul_f32 v[104:105], v[108:109], v[104:105] op_sel_hi:[1,0]
	v_pk_mov_b32 v[46:47], v[50:51], v[48:49] op_sel:[1,0]
	v_mov_b32_e32 v51, v49
	v_pk_add_f32 v[36:37], v[40:41], v[44:45]
	v_pk_add_f32 v[32:33], v[34:35], v[32:33]
	v_pk_fma_f32 v[28:29], v[104:105], v[58:59], v[54:55]
	v_mul_f32_e32 v52, v26, v26
	v_mul_f32_e32 v54, v24, v24
	v_pk_add_f32 v[38:39], v[46:47], v[50:51]
	v_pk_add_f32 v[32:33], v[36:37], v[32:33]
	v_pk_fma_f32 v[48:49], v[26:27], v[26:27], v[52:53] op_sel_hi:[1,1,0]
	v_pk_fma_f32 v[52:53], v[24:25], v[24:25], v[54:55] op_sel_hi:[1,1,0]
	v_pk_add_f32 v[38:39], v[38:39], v[38:39] op_sel_hi:[0,1]
	v_pk_add_f32 v[32:33], v[32:33], v[32:33] op_sel_hi:[0,1]
	v_mul_f32_e32 v48, v30, v30
	v_mul_f32_e32 v52, v31, v31
	v_mul_f32_e32 v38, v28, v28
	v_mul_f32_e32 v32, v29, v29
	v_pk_add_f32 v[40:41], v[48:49], v[52:53]
	v_pk_add_f32 v[32:33], v[38:39], v[32:33]
	s_nop 0
	v_pk_add_f32 v[32:33], v[40:41], v[32:33]
	s_nop 0
	v_add_f32_e32 v32, v32, v33
	ds_bpermute_b32 v33, v110, v32
	s_waitcnt lgkmcnt(0)
; __device__ __forceinline__ unsigned pk2(float lo, float hi) { unsigned r; asm("v_cvt_pk_bf16_f32 %0, %1, %2" : "=v"(r) : "v"(lo), "v"(hi)); return r; }
; __device__ __forceinline__ void row_norm_store(const f32x4 (&v)[8], const float* gain, bf16_t* orow, int lane) {
;     ...
;     const float rs = 1.0f / sqrtf(wave_sum(s) * (1.0f / D_MODEL) + EPS);
; #pragma unroll
;     for (int j = 0; j < 8; ++j) { const f32x4 gv = *(const f32x4*)(gain + 4 * lane + 256 * j); const f32x4 y = v[j] * rs * gv;
;         u32x2 w; w.x = pk2(y[0], y[1]); w.y = pk2(y[2], y[3]); *(u32x2*)(orow + 4 * lane + 256 * j) = w; }
	v_add_f32_e32 v32, v32, v33
	ds_bpermute_b32 v33, v111, v32
	s_waitcnt lgkmcnt(0)
	v_add_f32_e32 v32, v32, v33
	ds_bpermute_b32 v33, v112, v32
	s_waitcnt lgkmcnt(0)
	v_add_f32_e32 v32, v32, v33
	ds_bpermute_b32 v33, v113, v32
	s_waitcnt lgkmcnt(0)
	v_add_f32_e32 v32, v32, v33
	ds_bpermute_b32 v33, v114, v32
	s_waitcnt lgkmcnt(0)
	v_add_f32_e32 v32, v32, v33
	ds_bpermute_b32 v33, v115, v32
	s_waitcnt lgkmcnt(0)
	v_add_f32_e32 v32, v32, v33
	v_fmamk_f32 v32, v32, 0x3a000000, v116
	v_mul_f32_e32 v33, 0x4f800000, v32
	v_cmp_gt_f32_e32 vcc, s6, v32
	s_nop 1
	v_cndmask_b32_e32 v32, v32, v33, vcc
	v_sqrt_f32_e32 v33, v32
	s_nop 0
	v_add_u32_e32 v34, -1, v33
	v_add_u32_e32 v35, 1, v33
	v_fma_f32 v36, -v34, v33, v32
	v_fma_f32 v37, -v35, v33, v32
	v_cmp_ge_f32_e64 s[0:1], 0, v36
	s_nop 1
	v_cndmask_b32_e64 v33, v33, v34, s[0:1]
	v_cmp_lt_f32_e64 s[0:1], 0, v37
	s_nop 1
	v_cndmask_b32_e64 v33, v33, v35, s[0:1]
	v_mul_f32_e32 v34, 0x37800000, v33
	v_cndmask_b32_e32 v33, v33, v34, vcc
	v_cmp_class_f32_e32 vcc, v32, v117
	s_nop 1
	v_cndmask_b32_e32 v32, v33, v32, vcc
	v_div_scale_f32 v33, s[0:1], v32, v32, 1.0
	v_rcp_f32_e32 v35, v33
	v_div_scale_f32 v34, vcc, 1.0, v32, 1.0
	v_fma_f32 v36, -v33, v35, 1.0
	v_fmac_f32_e32 v35, v36, v35
	v_mul_f32_e32 v36, v34, v35
	v_fma_f32 v37, -v33, v36, v34
	v_fmac_f32_e32 v36, v37, v35
	v_fma_f32 v33, -v33, v36, v34
	v_div_fmas_f32 v33, v33, v35, v36
	v_div_fixup_f32 v32, v33, v32, 1.0
	v_pk_mul_f32 v[0:1], v[0:1], v[32:33] op_sel_hi:[1,0]
	v_pk_mul_f32 v[2:3], v[2:3], v[32:33] op_sel_hi:[1,0]
	s_waitcnt vmcnt(0)
	v_pk_mul_f32 v[0:1], v[64:65], v[0:1]
	v_pk_mul_f32 v[2:3], v[66:67], v[2:3]
	v_cvt_pk_bf16_f32 v0, v0, v1
	v_pk_mul_f32 v[4:5], v[4:5], v[32:33] op_sel_hi:[1,0]
	v_cvt_pk_bf16_f32 v1, v2, v3
	global_store_dwordx2 v[100:101], v[0:1], off sc0 sc1
	v_pk_mul_f32 v[6:7], v[6:7], v[32:33] op_sel_hi:[1,0]
	v_pk_mul_f32 v[0:1], v[176:177], v[4:5]
	v_pk_mul_f32 v[2:3], v[178:179], v[6:7]
	v_cvt_pk_bf16_f32 v0, v0, v1
	v_pk_mul_f32 v[4:5], v[8:9], v[32:33] op_sel_hi:[1,0]
	v_cvt_pk_bf16_f32 v1, v2, v3
	global_store_dwordx2 v[100:101], v[0:1], off offset:512 sc0 sc1
	v_pk_mul_f32 v[6:7], v[10:11], v[32:33] op_sel_hi:[1,0]
	v_pk_mul_f32 v[0:1], v[180:181], v[4:5]
	v_pk_mul_f32 v[2:3], v[182:183], v[6:7]
	v_cvt_pk_bf16_f32 v0, v0, v1
	v_pk_mul_f32 v[4:5], v[14:15], v[32:33] op_sel_hi:[1,0]
	v_cvt_pk_bf16_f32 v1, v2, v3
	global_store_dwordx2 v[100:101], v[0:1], off offset:1024 sc0 sc1
	v_pk_mul_f32 v[6:7], v[12:13], v[32:33] op_sel_hi:[1,0]
	v_pk_mul_f32 v[0:1], v[184:185], v[4:5]
	v_pk_mul_f32 v[2:3], v[186:187], v[6:7]
	v_cvt_pk_bf16_f32 v0, v0, v1
	v_pk_mul_f32 v[4:5], v[18:19], v[32:33] op_sel_hi:[1,0]
	v_cvt_pk_bf16_f32 v1, v2, v3
	global_store_dwordx2 v[100:101], v[0:1], off offset:1536 sc0 sc1
	v_pk_mul_f32 v[6:7], v[16:17], v[32:33] op_sel_hi:[1,0]
	v_pk_mul_f32 v[0:1], v[188:189], v[4:5]
	v_pk_mul_f32 v[2:3], v[190:191], v[6:7]
	v_cvt_pk_bf16_f32 v0, v0, v1
	v_pk_mul_f32 v[4:5], v[20:21], v[32:33] op_sel_hi:[1,0]
	v_cvt_pk_bf16_f32 v1, v2, v3
	global_store_dwordx2 v[100:101], v[0:1], off offset:2048 sc0 sc1
	v_pk_mul_f32 v[6:7], v[22:23], v[32:33] op_sel_hi:[1,0]
	v_pk_mul_f32 v[0:1], v[4:5], v[192:193]
	v_pk_mul_f32 v[2:3], v[6:7], v[194:195]
	v_cvt_pk_bf16_f32 v0, v0, v1
	v_pk_mul_f32 v[4:5], v[26:27], v[32:33] op_sel_hi:[1,0]
	v_cvt_pk_bf16_f32 v1, v2, v3
	global_store_dwordx2 v[100:101], v[0:1], off offset:2560 sc0 sc1
	v_pk_mul_f32 v[6:7], v[24:25], v[32:33] op_sel_hi:[1,0]
	v_pk_mul_f32 v[0:1], v[4:5], v[196:197]
	v_pk_mul_f32 v[2:3], v[6:7], v[198:199]
	v_cvt_pk_bf16_f32 v0, v0, v1
	v_pk_mul_f32 v[4:5], v[30:31], v[32:33] op_sel_hi:[1,0]
	v_cvt_pk_bf16_f32 v1, v2, v3
	global_store_dwordx2 v[100:101], v[0:1], off offset:3072 sc0 sc1
	v_pk_mul_f32 v[6:7], v[28:29], v[32:33] op_sel_hi:[1,0]
	v_pk_mul_f32 v[0:1], v[4:5], v[200:201]
	v_pk_mul_f32 v[2:3], v[6:7], v[202:203]
	v_cvt_pk_bf16_f32 v0, v0, v1
	s_nop 0
	v_cvt_pk_bf16_f32 v1, v2, v3
	global_store_dwordx2 v[100:101], v[0:1], off offset:3584 sc0 sc1
	s_cbranch_scc1 .LBB0_451

; __device__ __forceinline__ unsigned cvt_pk_bf16(float lo, float hi) { unsigned r; asm volatile("v_cvt_pk_bf16_f32 %0, %1, %2" : "=v"(r) : "v"(lo), "v"(hi)); return r; }
;     __device__ __forceinline__ void operator()(const f32x4 (&acc)[2][2][4][2], const Unit& u, int wr, int wc, int fr, int fq) const {
;     ...
;                 for (int m = 0; m < 4; ++m) { bf16_t* rowp = O + (size_t)(row0 + ai * HALF + m * 16) * ldc + col0; float h[2][4];
; #pragma unroll
;                     for (int bj = 0; bj < 2; ++bj) { const f32x4 g = acc[ai][bj][m][0], up = acc[ai][bj][m][1];
; #pragma unroll
;                         for (int j = 0; j < 4; ++j) h[bj][j] = g[j] * __builtin_amdgcn_rcpf(1.0f + __builtin_amdgcn_exp2f(-1.4426950408889634f * g[j])) * up[j]; }
;                     u32x4 w; w.x = cvt_pk_bf16(h[0][0], h[0][1]); w.y = cvt_pk_bf16(h[0][2], h[0][3]); w.z = cvt_pk_bf16(h[1][0], h[1][1]); w.w = cvt_pk_bf16(h[1][2], h[1][3]);
;                     *(u32x4*)rowp = w; }
.LBB0_519:
	v_mul_f32_e32 v144, 0xbfb8aa3b, v124
	v_exp_f32_e32 v156, v144
	v_mul_f32_e32 v144, 0xbfb8aa3b, v125
	v_exp_f32_e32 v157, v144
	v_lshl_or_b32 v154, s50, 7, v149
	v_add_f32_e32 v156, 1.0, v156
	v_rcp_f32_e32 v158, v156
	v_add_f32_e32 v156, 1.0, v157
	v_rcp_f32_e32 v159, v156
	v_lshl_add_u32 v153, s49, 8, v146
	v_mul_f32_e32 v124, v124, v158
	v_mul_f32_e32 v120, v120, v124
	v_mul_f32_e32 v124, v125, v159
	v_mul_f32_e32 v125, 0xbfb8aa3b, v126
	v_exp_f32_e32 v125, v125
	v_mul_f32_e32 v158, 0xbfb8aa3b, v127
	v_exp_f32_e32 v158, v158
	v_mul_f32_e32 v121, v121, v124
	v_add_f32_e32 v124, 1.0, v125
	v_rcp_f32_e32 v124, v124
	v_add_f32_e32 v125, 1.0, v158
	v_mul_f32_e32 v158, 0xbfb8aa3b, v116
	v_rcp_f32_e32 v125, v125
	v_exp_f32_e32 v158, v158
	v_mul_f32_e32 v124, v126, v124
	v_mul_f32_e32 v122, v122, v124
	v_mul_f32_e32 v124, v127, v125
	v_add_f32_e32 v125, 1.0, v158
	v_rcp_f32_e32 v125, v125
	v_mul_f32_e32 v126, 0xbfb8aa3b, v117
	v_exp_f32_e32 v126, v126
	v_mul_f32_e32 v123, v123, v124
	v_mul_f32_e32 v116, v116, v125
	v_mul_f32_e32 v116, v112, v116
	v_add_f32_e32 v112, 1.0, v126
	v_mul_f32_e32 v124, 0xbfb8aa3b, v118
	v_rcp_f32_e32 v112, v112
	v_exp_f32_e32 v124, v124
	v_mul_f32_e32 v125, 0xbfb8aa3b, v119
	v_exp_f32_e32 v125, v125
	v_mul_f32_e32 v112, v117, v112
	v_add_f32_e32 v117, 1.0, v124
	v_rcp_f32_e32 v117, v117
	v_add_f32_e32 v124, 1.0, v125
	v_rcp_f32_e32 v124, v124
	v_mul_f32_e32 v125, v113, v112
	v_mul_f32_e32 v112, v118, v117
	v_ashrrev_i32_e32 v155, 31, v154
	v_mov_b64_e32 v[144:145], s[8:9]
	v_mul_f32_e32 v117, v114, v112
	v_mul_f32_e32 v112, v119, v124
	v_mad_i64_i32 v[156:157], s[16:17], v153, s46, v[144:145]
	v_mul_f32_e32 v124, v115, v112
	v_lshlrev_b64 v[112:113], 1, v[154:155]
	v_lshl_add_u64 v[118:119], v[156:157], 0, v[112:113]
	v_cvt_pk_bf16_f32 v114, v120, v121
	v_cvt_pk_bf16_f32 v115, v122, v123
	v_cvt_pk_bf16_f32 v116, v116, v125
	v_cvt_pk_bf16_f32 v117, v117, v124
	global_store_dwordx4 v[118:119], v[114:117], off sc0 sc1
	s_and_b64 vcc, exec, s[0:1]
	s_mov_b64 s[0:1], -1
	v_mul_f32_e32 v114, 0xbfb8aa3b, v108
	v_exp_f32_e32 v114, v114
	v_mul_f32_e32 v115, 0xbfb8aa3b, v109
	v_exp_f32_e32 v115, v115
	v_or_b32_e32 v116, 16, v153
	v_add_f32_e32 v114, 1.0, v114
	v_rcp_f32_e32 v117, v114
	v_add_f32_e32 v114, 1.0, v115
	v_rcp_f32_e32 v118, v114
	v_mad_i64_i32 v[114:115], s[16:17], v116, s46, v[144:145]
	v_mul_f32_e32 v108, v108, v117
	v_mul_f32_e32 v104, v104, v108
	v_mul_f32_e32 v108, v109, v118
	v_mul_f32_e32 v109, 0xbfb8aa3b, v110
	v_exp_f32_e32 v109, v109
	v_mul_f32_e32 v116, 0xbfb8aa3b, v111
	v_exp_f32_e32 v116, v116
	v_mul_f32_e32 v105, v105, v108
	v_add_f32_e32 v108, 1.0, v109
	v_rcp_f32_e32 v108, v108
	v_add_f32_e32 v109, 1.0, v116
	v_mul_f32_e32 v116, 0xbfb8aa3b, v100
	v_rcp_f32_e32 v109, v109
	v_exp_f32_e32 v116, v116
	v_mul_f32_e32 v108, v110, v108
	v_mul_f32_e32 v106, v106, v108
	v_mul_f32_e32 v108, v111, v109
	v_add_f32_e32 v109, 1.0, v116
	v_rcp_f32_e32 v109, v109
	v_mul_f32_e32 v110, 0xbfb8aa3b, v101
	v_exp_f32_e32 v110, v110
	v_mul_f32_e32 v107, v107, v108
	v_mul_f32_e32 v100, v100, v109
	v_mul_f32_e32 v108, v96, v100
	v_mul_f32_e32 v100, 0xbfb8aa3b, v102
	v_add_f32_e32 v96, 1.0, v110
	v_exp_f32_e32 v100, v100
	v_mul_f32_e32 v109, 0xbfb8aa3b, v103
	v_rcp_f32_e32 v96, v96
	v_exp_f32_e32 v109, v109
	v_add_f32_e32 v100, 1.0, v100
	v_rcp_f32_e32 v100, v100
	v_mul_f32_e32 v96, v101, v96
	v_add_f32_e32 v101, 1.0, v109
	v_rcp_f32_e32 v101, v101
	v_mul_f32_e32 v109, v97, v96
	v_mul_f32_e32 v96, v102, v100
	v_mul_f32_e32 v102, v98, v96
	v_mul_f32_e32 v96, v103, v101
	v_mul_f32_e32 v99, v99, v96
	v_lshl_add_u64 v[100:101], v[114:115], 0, v[112:113]
	v_cvt_pk_bf16_f32 v96, v104, v105
	v_cvt_pk_bf16_f32 v97, v106, v107
	v_cvt_pk_bf16_f32 v98, v108, v109
	v_cvt_pk_bf16_f32 v99, v102, v99
	global_store_dwordx4 v[100:101], v[96:99], off sc0 sc1
	s_nop 1
	v_mul_f32_e32 v96, 0xbfb8aa3b, v92
	v_exp_f32_e32 v96, v96
	v_mul_f32_e32 v97, 0xbfb8aa3b, v93
	v_exp_f32_e32 v97, v97
	v_or_b32_e32 v98, 32, v153
	v_add_f32_e32 v96, 1.0, v96
	v_rcp_f32_e32 v99, v96
	v_add_f32_e32 v96, 1.0, v97
	v_rcp_f32_e32 v100, v96
	v_mad_i64_i32 v[96:97], s[16:17], v98, s46, v[144:145]
	v_mul_f32_e32 v92, v92, v99
	v_mul_f32_e32 v88, v88, v92
	v_mul_f32_e32 v92, v93, v100
	v_mul_f32_e32 v93, 0xbfb8aa3b, v94
	v_exp_f32_e32 v93, v93
	v_mul_f32_e32 v98, 0xbfb8aa3b, v95
	v_exp_f32_e32 v98, v98
	v_mul_f32_e32 v89, v89, v92
	v_add_f32_e32 v92, 1.0, v93
	v_rcp_f32_e32 v92, v92
	v_add_f32_e32 v93, 1.0, v98
	v_mul_f32_e32 v98, 0xbfb8aa3b, v84
	v_rcp_f32_e32 v93, v93
	v_exp_f32_e32 v98, v98
	v_mul_f32_e32 v92, v94, v92
	v_mul_f32_e32 v90, v90, v92
	v_mul_f32_e32 v92, v95, v93
	v_add_f32_e32 v93, 1.0, v98
	v_rcp_f32_e32 v93, v93
	v_mul_f32_e32 v94, 0xbfb8aa3b, v85
	v_exp_f32_e32 v94, v94
	v_mul_f32_e32 v91, v91, v92
	v_mul_f32_e32 v84, v84, v93
	v_mul_f32_e32 v92, v80, v84
	v_mul_f32_e32 v84, 0xbfb8aa3b, v86
	v_add_f32_e32 v80, 1.0, v94
	v_exp_f32_e32 v84, v84
	v_mul_f32_e32 v93, 0xbfb8aa3b, v87
	v_rcp_f32_e32 v80, v80
	v_exp_f32_e32 v93, v93
	v_add_f32_e32 v84, 1.0, v84
	v_rcp_f32_e32 v84, v84
	v_mul_f32_e32 v80, v85, v80
	v_add_f32_e32 v85, 1.0, v93
	v_rcp_f32_e32 v85, v85
	v_mul_f32_e32 v93, v81, v80
	v_mul_f32_e32 v80, v86, v84
	v_mul_f32_e32 v86, v82, v80
	v_mul_f32_e32 v80, v87, v85
	v_mul_f32_e32 v83, v83, v80
	v_lshl_add_u64 v[84:85], v[96:97], 0, v[112:113]
	v_cvt_pk_bf16_f32 v80, v88, v89
	v_cvt_pk_bf16_f32 v81, v90, v91
	v_cvt_pk_bf16_f32 v82, v92, v93
	v_cvt_pk_bf16_f32 v83, v86, v83
	global_store_dwordx4 v[84:85], v[80:83], off sc0 sc1
	s_nop 1
	v_mul_f32_e32 v80, 0xbfb8aa3b, v76
	v_exp_f32_e32 v80, v80
	v_mul_f32_e32 v81, 0xbfb8aa3b, v77
; __device__ __forceinline__ unsigned cvt_pk_bf16(float lo, float hi) { unsigned r; asm volatile("v_cvt_pk_bf16_f32 %0, %1, %2" : "=v"(r) : "v"(lo), "v"(hi)); return r; }
;     __device__ __forceinline__ void operator()(const f32x4 (&acc)[2][2][4][2], const Unit& u, int wr, int wc, int fr, int fq) const {
;     ...
;                 for (int m = 0; m < 4; ++m) { bf16_t* rowp = O + (size_t)(row0 + ai * HALF + m * 16) * ldc + col0; float h[2][4];
; #pragma unroll
;                     for (int bj = 0; bj < 2; ++bj) { const f32x4 g = acc[ai][bj][m][0], up = acc[ai][bj][m][1];
; #pragma unroll
;                         for (int j = 0; j < 4; ++j) h[bj][j] = g[j] * __builtin_amdgcn_rcpf(1.0f + __builtin_amdgcn_exp2f(-1.4426950408889634f * g[j])) * up[j]; }
;                     u32x4 w; w.x = cvt_pk_bf16(h[0][0], h[0][1]); w.y = cvt_pk_bf16(h[0][2], h[0][3]); w.z = cvt_pk_bf16(h[1][0], h[1][1]); w.w = cvt_pk_bf16(h[1][2], h[1][3]);
;                     *(u32x4*)rowp = w; }
	v_exp_f32_e32 v81, v81
	v_or_b32_e32 v82, 48, v153
	v_add_f32_e32 v80, 1.0, v80
	v_rcp_f32_e32 v83, v80
	v_add_f32_e32 v80, 1.0, v81
	v_rcp_f32_e32 v84, v80
	v_mad_i64_i32 v[80:81], s[16:17], v82, s46, v[144:145]
	v_mul_f32_e32 v76, v76, v83
	v_mul_f32_e32 v72, v72, v76
	v_mul_f32_e32 v76, v77, v84
	v_mul_f32_e32 v77, 0xbfb8aa3b, v78
	v_exp_f32_e32 v77, v77
	v_mul_f32_e32 v82, 0xbfb8aa3b, v79
	v_exp_f32_e32 v82, v82
	v_mul_f32_e32 v73, v73, v76
	v_add_f32_e32 v76, 1.0, v77
	v_rcp_f32_e32 v76, v76
	v_add_f32_e32 v77, 1.0, v82
	v_mul_f32_e32 v82, 0xbfb8aa3b, v68
	v_rcp_f32_e32 v77, v77
	v_exp_f32_e32 v82, v82
	v_mul_f32_e32 v76, v78, v76
	v_mul_f32_e32 v74, v74, v76
	v_mul_f32_e32 v76, v79, v77
	v_add_f32_e32 v77, 1.0, v82
	v_rcp_f32_e32 v77, v77
	v_mul_f32_e32 v78, 0xbfb8aa3b, v69
	v_exp_f32_e32 v78, v78
	v_mul_f32_e32 v75, v75, v76
	v_mul_f32_e32 v68, v68, v77
	v_mul_f32_e32 v76, v64, v68
	v_mul_f32_e32 v68, 0xbfb8aa3b, v70
	v_add_f32_e32 v64, 1.0, v78
	v_exp_f32_e32 v68, v68
	v_mul_f32_e32 v77, 0xbfb8aa3b, v71
	v_rcp_f32_e32 v64, v64
	v_exp_f32_e32 v77, v77
	v_add_f32_e32 v68, 1.0, v68
	v_rcp_f32_e32 v68, v68
	v_mul_f32_e32 v64, v69, v64
	v_add_f32_e32 v69, 1.0, v77
	v_rcp_f32_e32 v69, v69
	v_mul_f32_e32 v77, v65, v64
	v_mul_f32_e32 v64, v70, v68
	v_mul_f32_e32 v70, v66, v64
	v_mul_f32_e32 v64, v71, v69
	v_mul_f32_e32 v67, v67, v64
	v_lshl_add_u64 v[68:69], v[80:81], 0, v[112:113]
	v_cvt_pk_bf16_f32 v64, v72, v73
	v_cvt_pk_bf16_f32 v65, v74, v75
	v_cvt_pk_bf16_f32 v66, v76, v77
	v_cvt_pk_bf16_f32 v67, v70, v67
	global_store_dwordx4 v[68:69], v[64:67], off sc0 sc1
	s_nop 1
	v_mul_f32_e32 v64, 0xbfb8aa3b, v60
	v_exp_f32_e32 v64, v64
	v_mul_f32_e32 v65, 0xbfb8aa3b, v61
	v_exp_f32_e32 v65, v65
	v_add_u32_e32 v66, 0x80, v153
	v_add_f32_e32 v64, 1.0, v64
	v_rcp_f32_e32 v67, v64
	v_add_f32_e32 v64, 1.0, v65
	v_rcp_f32_e32 v68, v64
	v_mad_i64_i32 v[64:65], s[16:17], v66, s46, v[144:145]
	v_mul_f32_e32 v60, v60, v67
	v_mul_f32_e32 v56, v56, v60
	v_mul_f32_e32 v60, v61, v68
	v_mul_f32_e32 v61, 0xbfb8aa3b, v62
	v_exp_f32_e32 v61, v61
	v_mul_f32_e32 v66, 0xbfb8aa3b, v63
	v_exp_f32_e32 v66, v66
	v_mul_f32_e32 v57, v57, v60
	v_add_f32_e32 v60, 1.0, v61
	v_rcp_f32_e32 v60, v60
	v_add_f32_e32 v61, 1.0, v66
	v_mul_f32_e32 v66, 0xbfb8aa3b, v52
	v_rcp_f32_e32 v61, v61
	v_exp_f32_e32 v66, v66
	v_mul_f32_e32 v60, v62, v60
	v_mul_f32_e32 v58, v58, v60
	v_mul_f32_e32 v60, v63, v61
	v_add_f32_e32 v61, 1.0, v66
	v_rcp_f32_e32 v61, v61
	v_mul_f32_e32 v62, 0xbfb8aa3b, v53
	v_exp_f32_e32 v62, v62
	v_mul_f32_e32 v59, v59, v60
	v_mul_f32_e32 v52, v52, v61
	v_mul_f32_e32 v60, v48, v52
	v_mul_f32_e32 v52, 0xbfb8aa3b, v54
	v_add_f32_e32 v48, 1.0, v62
	v_exp_f32_e32 v52, v52
	v_mul_f32_e32 v61, 0xbfb8aa3b, v55
	v_rcp_f32_e32 v48, v48
	v_exp_f32_e32 v61, v61
	v_add_f32_e32 v52, 1.0, v52
	v_rcp_f32_e32 v52, v52
	v_mul_f32_e32 v48, v53, v48
	v_add_f32_e32 v53, 1.0, v61
	v_rcp_f32_e32 v53, v53
	v_mul_f32_e32 v61, v49, v48
	v_mul_f32_e32 v48, v54, v52
	v_mul_f32_e32 v54, v50, v48
	v_mul_f32_e32 v48, v55, v53
	v_mul_f32_e32 v51, v51, v48
	v_lshl_add_u64 v[52:53], v[64:65], 0, v[112:113]
	v_cvt_pk_bf16_f32 v48, v56, v57
	v_cvt_pk_bf16_f32 v49, v58, v59
	v_cvt_pk_bf16_f32 v50, v60, v61
	v_cvt_pk_bf16_f32 v51, v54, v51
	global_store_dwordx4 v[52:53], v[48:51], off sc0 sc1
	s_nop 1
	v_mul_f32_e32 v48, 0xbfb8aa3b, v44
	v_exp_f32_e32 v48, v48
	v_mul_f32_e32 v49, 0xbfb8aa3b, v45
	v_exp_f32_e32 v49, v49
	v_add_u32_e32 v50, 0x90, v153
	v_add_f32_e32 v48, 1.0, v48
	v_rcp_f32_e32 v51, v48
	v_add_f32_e32 v48, 1.0, v49
	v_rcp_f32_e32 v52, v48
	v_mad_i64_i32 v[48:49], s[16:17], v50, s46, v[144:145]
	v_mul_f32_e32 v44, v44, v51
	v_mul_f32_e32 v40, v40, v44
	v_mul_f32_e32 v44, v45, v52
	v_mul_f32_e32 v45, 0xbfb8aa3b, v46
	v_exp_f32_e32 v45, v45
	v_mul_f32_e32 v50, 0xbfb8aa3b, v47
	v_exp_f32_e32 v50, v50
	v_mul_f32_e32 v41, v41, v44
	v_add_f32_e32 v44, 1.0, v45
	v_rcp_f32_e32 v44, v44
	v_add_f32_e32 v45, 1.0, v50
	v_mul_f32_e32 v50, 0xbfb8aa3b, v36
	v_rcp_f32_e32 v45, v45
	v_exp_f32_e32 v50, v50
	v_mul_f32_e32 v44, v46, v44
	v_mul_f32_e32 v42, v42, v44
	v_mul_f32_e32 v44, v47, v45
	v_add_f32_e32 v45, 1.0, v50
	v_rcp_f32_e32 v45, v45
	v_mul_f32_e32 v46, 0xbfb8aa3b, v37
	v_exp_f32_e32 v46, v46
; __device__ __forceinline__ unsigned cvt_pk_bf16(float lo, float hi) { unsigned r; asm volatile("v_cvt_pk_bf16_f32 %0, %1, %2" : "=v"(r) : "v"(lo), "v"(hi)); return r; }
; #define PG8_BAR __builtin_amdgcn_s_barrier()
;     __device__ __forceinline__ void operator()(const f32x4 (&acc)[2][2][4][2], const Unit& u, int wr, int wc, int fr, int fq) const {
;     ...
;                 for (int m = 0; m < 4; ++m) { bf16_t* rowp = O + (size_t)(row0 + ai * HALF + m * 16) * ldc + col0; float h[2][4];
; #pragma unroll
;                     for (int bj = 0; bj < 2; ++bj) { const f32x4 g = acc[ai][bj][m][0], up = acc[ai][bj][m][1];
; #pragma unroll
;                         for (int j = 0; j < 4; ++j) h[bj][j] = g[j] * __builtin_amdgcn_rcpf(1.0f + __builtin_amdgcn_exp2f(-1.4426950408889634f * g[j])) * up[j]; }
;                     u32x4 w; w.x = cvt_pk_bf16(h[0][0], h[0][1]); w.y = cvt_pk_bf16(h[0][2], h[0][3]); w.z = cvt_pk_bf16(h[1][0], h[1][1]); w.w = cvt_pk_bf16(h[1][2], h[1][3]);
;                     *(u32x4*)rowp = w; }
; template <class EpiT>
; __device__ __forceinline__ void gemm_phase(LAS unsigned char* lds, const Gemm g, const StaticOrder& S, const EpiT& E) {
;     ...
;         if (!has_next) break;
; #pragma unroll
;         for (int a = 0; a < 2; ++a)
; #pragma unroll
;             for (int b = 0; b < 2; ++b)
; #pragma unroll
;                 for (int m = 0; m < 4; ++m)
; #pragma unroll
;                     for (int n = 0; n < 2; ++n) acc[a][b][m][n] = (f32x4){0.f, 0.f, 0.f, 0.f};
;         cur = nxt; cA = nA; cB = nB; ++ui;
;         if (wr == 1) PG8_BAR;
	v_mul_f32_e32 v43, v43, v44
	v_mul_f32_e32 v36, v36, v45
	v_mul_f32_e32 v44, v32, v36
	v_mul_f32_e32 v36, 0xbfb8aa3b, v38
	v_add_f32_e32 v32, 1.0, v46
	v_exp_f32_e32 v36, v36
	v_mul_f32_e32 v45, 0xbfb8aa3b, v39
	v_rcp_f32_e32 v32, v32
	v_exp_f32_e32 v45, v45
	v_add_f32_e32 v36, 1.0, v36
	v_rcp_f32_e32 v36, v36
	v_mul_f32_e32 v32, v37, v32
	v_add_f32_e32 v37, 1.0, v45
	v_rcp_f32_e32 v37, v37
	v_mul_f32_e32 v45, v33, v32
	v_mul_f32_e32 v32, v38, v36
	v_mul_f32_e32 v38, v34, v32
	v_mul_f32_e32 v32, v39, v37
	v_mul_f32_e32 v35, v35, v32
	v_lshl_add_u64 v[36:37], v[48:49], 0, v[112:113]
	v_cvt_pk_bf16_f32 v32, v40, v41
	v_cvt_pk_bf16_f32 v33, v42, v43
	v_cvt_pk_bf16_f32 v34, v44, v45
	v_cvt_pk_bf16_f32 v35, v38, v35
	global_store_dwordx4 v[36:37], v[32:35], off sc0 sc1
	s_nop 1
	v_mul_f32_e32 v32, 0xbfb8aa3b, v28
	v_exp_f32_e32 v32, v32
	v_mul_f32_e32 v33, 0xbfb8aa3b, v29
	v_exp_f32_e32 v33, v33
	v_add_u32_e32 v34, 0xa0, v153
	v_add_f32_e32 v32, 1.0, v32
	v_rcp_f32_e32 v35, v32
	v_add_f32_e32 v32, 1.0, v33
	v_rcp_f32_e32 v36, v32
	v_mad_i64_i32 v[32:33], s[16:17], v34, s46, v[144:145]
	v_mul_f32_e32 v28, v28, v35
	v_mul_f32_e32 v24, v24, v28
	v_mul_f32_e32 v28, v29, v36
	v_mul_f32_e32 v29, 0xbfb8aa3b, v30
	v_exp_f32_e32 v29, v29
	v_mul_f32_e32 v34, 0xbfb8aa3b, v31
	v_exp_f32_e32 v34, v34
	v_mul_f32_e32 v25, v25, v28
	v_add_f32_e32 v28, 1.0, v29
	v_rcp_f32_e32 v28, v28
	v_add_f32_e32 v29, 1.0, v34
	v_mul_f32_e32 v34, 0xbfb8aa3b, v20
	v_rcp_f32_e32 v29, v29
	v_exp_f32_e32 v34, v34
	v_mul_f32_e32 v28, v30, v28
	v_mul_f32_e32 v26, v26, v28
	v_mul_f32_e32 v28, v31, v29
	v_add_f32_e32 v29, 1.0, v34
	v_rcp_f32_e32 v29, v29
	v_mul_f32_e32 v30, 0xbfb8aa3b, v21
	v_exp_f32_e32 v30, v30
	v_mul_f32_e32 v27, v27, v28
	v_mul_f32_e32 v20, v20, v29
	v_mul_f32_e32 v28, v16, v20
	v_mul_f32_e32 v20, 0xbfb8aa3b, v22
	v_add_f32_e32 v16, 1.0, v30
	v_exp_f32_e32 v20, v20
	v_mul_f32_e32 v29, 0xbfb8aa3b, v23
	v_rcp_f32_e32 v16, v16
	v_exp_f32_e32 v29, v29
	v_add_f32_e32 v20, 1.0, v20
	v_rcp_f32_e32 v20, v20
	v_mul_f32_e32 v16, v21, v16
	v_add_f32_e32 v21, 1.0, v29
	v_rcp_f32_e32 v21, v21
	v_mul_f32_e32 v29, v17, v16
	v_mul_f32_e32 v16, v22, v20
	v_mul_f32_e32 v22, v18, v16
	v_mul_f32_e32 v16, v23, v21
	v_mul_f32_e32 v19, v19, v16
	v_lshl_add_u64 v[20:21], v[32:33], 0, v[112:113]
	v_cvt_pk_bf16_f32 v16, v24, v25
	v_cvt_pk_bf16_f32 v17, v26, v27
	v_cvt_pk_bf16_f32 v18, v28, v29
	v_cvt_pk_bf16_f32 v19, v22, v19
	global_store_dwordx4 v[20:21], v[16:19], off sc0 sc1
	s_nop 1
	v_mul_f32_e32 v16, 0xbfb8aa3b, v12
	v_exp_f32_e32 v16, v16
	v_mul_f32_e32 v17, 0xbfb8aa3b, v13
	v_exp_f32_e32 v17, v17
	v_add_u32_e32 v18, 0xb0, v153
	v_add_f32_e32 v16, 1.0, v16
	v_rcp_f32_e32 v19, v16
	v_add_f32_e32 v16, 1.0, v17
	v_rcp_f32_e32 v20, v16
	v_mad_i64_i32 v[16:17], s[16:17], v18, s46, v[144:145]
	v_mul_f32_e32 v12, v12, v19
	v_mul_f32_e32 v8, v8, v12
	v_mul_f32_e32 v12, v13, v20
	v_mul_f32_e32 v13, 0xbfb8aa3b, v14
	v_exp_f32_e32 v13, v13
	v_mul_f32_e32 v18, 0xbfb8aa3b, v15
	v_exp_f32_e32 v18, v18
	v_mul_f32_e32 v9, v9, v12
	v_add_f32_e32 v12, 1.0, v13
	v_rcp_f32_e32 v12, v12
	v_add_f32_e32 v13, 1.0, v18
	v_mul_f32_e32 v18, 0xbfb8aa3b, v4
	v_rcp_f32_e32 v13, v13
	v_exp_f32_e32 v18, v18
	v_mul_f32_e32 v12, v14, v12
	v_mul_f32_e32 v10, v10, v12
	v_mul_f32_e32 v12, v15, v13
	v_add_f32_e32 v13, 1.0, v18
	v_rcp_f32_e32 v13, v13
	v_mul_f32_e32 v14, 0xbfb8aa3b, v5
	v_exp_f32_e32 v14, v14
	v_mul_f32_e32 v11, v11, v12
	v_mul_f32_e32 v4, v4, v13
	v_mul_f32_e32 v12, v0, v4
	v_mul_f32_e32 v4, 0xbfb8aa3b, v6
	v_add_f32_e32 v0, 1.0, v14
	v_exp_f32_e32 v4, v4
	v_mul_f32_e32 v13, 0xbfb8aa3b, v7
	v_rcp_f32_e32 v0, v0
	v_exp_f32_e32 v13, v13
	v_add_f32_e32 v4, 1.0, v4
	v_rcp_f32_e32 v4, v4
	v_mul_f32_e32 v0, v5, v0
	v_add_f32_e32 v5, 1.0, v13
	v_rcp_f32_e32 v5, v5
	v_mul_f32_e32 v13, v1, v0
	v_mul_f32_e32 v0, v6, v4
	v_mul_f32_e32 v6, v2, v0
	v_mul_f32_e32 v0, v7, v5
	v_mul_f32_e32 v3, v3, v0
	v_lshl_add_u64 v[4:5], v[16:17], 0, v[112:113]
	v_cvt_pk_bf16_f32 v0, v8, v9
	v_cvt_pk_bf16_f32 v1, v10, v11
	v_cvt_pk_bf16_f32 v2, v12, v13
	v_cvt_pk_bf16_f32 v3, v6, v3
	global_store_dwordx4 v[4:5], v[0:3], off sc0 sc1
	s_cbranch_vccnz .LBB0_508
	s_andn2_b64 vcc, exec, s[6:7]
	s_cbranch_vccnz .LBB0_507
	s_barrier
	s_branch .LBB0_507

; __device__ __forceinline__ unsigned cvt_pk_bf16(float lo, float hi) { unsigned r; asm volatile("v_cvt_pk_bf16_f32 %0, %1, %2" : "=v"(r) : "v"(lo), "v"(hi)); return r; }
;     __device__ __forceinline__ void operator()(const f32x4 (&acc)[2][2][4][2], const Unit& u, int wr, int wc, int fr, int fq) const {
;     ...
;                     u32x4 w[2];
; #pragma unroll
;                     for (int bj = 0; bj < 2; ++bj) { const f32x4 v0 = acc[ai][bj][m][0] * sc[bj][0], v1 = acc[ai][bj][m][1] * sc[bj][1];
;                         w[bj].x = cvt_pk_bf16(v0[0], v0[1]); w[bj].y = cvt_pk_bf16(v0[2], v0[3]); w[bj].z = cvt_pk_bf16(v1[0], v1[1]); w[bj].w = cvt_pk_bf16(v1[2], v1[3]); }
;                     u32x4 snd, rcv;
;                     snd.x = low ? w[1].x : w[0].x; snd.y = low ? w[1].y : w[0].y; snd.z = low ? w[1].z : w[0].z; snd.w = low ? w[1].w : w[0].w;
;                     rcv.x = (unsigned)__shfl_xor((int)snd.x, 8); rcv.y = (unsigned)__shfl_xor((int)snd.y, 8); rcv.z = (unsigned)__shfl_xor((int)snd.z, 8); rcv.w = (unsigned)__shfl_xor((int)snd.w, 8);
;                     u32x4 dA, dB;
;                     dA.x = low ? w[0].x : rcv.x; dA.y = low ? w[0].y : rcv.y; dA.z = low ? w[0].z : rcv.z; dA.w = low ? w[0].w : rcv.w;
;                     dB.x = low ? rcv.x : w[1].x; dB.y = low ? rcv.y : w[1].y; dB.z = low ? rcv.z : w[1].z; dB.w = low ? rcv.w : w[1].w;
;                     bf16_t* pA = O + (size_t)(u.pm * BM + wr * 64 + ai * HALF + m * 16 + (fr & 7)) * ldc + colo + (low ? 0 : 32);
;                     __builtin_nontemporal_store(dA, (u32x4*)pA); __builtin_nontemporal_store(dB, (u32x4*)(pA + (size_t)8 * ldc)); }
.LBB0_598:
	v_cvt_pk_bf16_f32 v124, v124, v125
	v_cvt_pk_bf16_f32 v125, v126, v127
	v_cvt_pk_bf16_f32 v120, v120, v121
	v_cvt_pk_bf16_f32 v121, v122, v123
	v_cvt_pk_bf16_f32 v122, v116, v117
	v_cvt_pk_bf16_f32 v123, v118, v119
	v_and_b32_e32 v119, 64, v153
	v_xor_b32_e32 v118, 8, v153
	v_add_u32_e32 v119, 64, v119
	v_cmp_lt_i32_e32 vcc, v118, v119
	v_cvt_pk_bf16_f32 v112, v112, v113
	v_cvt_pk_bf16_f32 v113, v114, v115
	v_cndmask_b32_e64 v114, v124, v122, s[0:1]
	v_cndmask_b32_e64 v115, v125, v123, s[0:1]
	v_cndmask_b32_e32 v118, v153, v118, vcc
	v_cndmask_b32_e64 v116, v120, v112, s[0:1]
	v_cndmask_b32_e64 v117, v121, v113, s[0:1]
	v_lshlrev_b32_e32 v126, 2, v118
	ds_bpermute_b32 v114, v126, v114
	ds_bpermute_b32 v115, v126, v115
	ds_bpermute_b32 v127, v126, v116
	ds_bpermute_b32 v156, v126, v117
	v_lshl_or_b32 v154, s52, 8, v149
	v_ashrrev_i32_e32 v155, 31, v154
	v_lshl_add_u32 v157, s51, 8, v147
	s_waitcnt lgkmcnt(0)
	v_cndmask_b32_e64 v118, v127, v120, s[0:1]
	v_cndmask_b32_e64 v119, v156, v121, s[0:1]
	v_cndmask_b32_e64 v120, v122, v114, s[0:1]
	v_cndmask_b32_e64 v121, v123, v115, s[0:1]
	v_cndmask_b32_e64 v122, v112, v127, s[0:1]
	v_cndmask_b32_e64 v123, v113, v156, s[0:1]
	v_mov_b64_e32 v[112:113], s[10:11]
	v_cndmask_b32_e64 v116, v114, v124, s[0:1]
	v_cndmask_b32_e64 v117, v115, v125, s[0:1]
	v_mad_i64_i32 v[124:125], s[18:19], v157, s48, v[112:113]
	v_lshlrev_b64 v[114:115], 1, v[154:155]
	v_lshl_add_u64 v[124:125], v[124:125], 0, v[114:115]
	v_lshl_add_u64 v[124:125], v[124:125], 0, v[136:137]
	global_store_dwordx4 v[124:125], v[116:119], off sc0 sc1 nt
	s_nop 1
	v_add_co_u32_e32 v116, vcc, s44, v124
	s_nop 1
	v_addc_co_u32_e32 v117, vcc, 0, v125, vcc
	global_store_dwordx4 v[116:117], v[120:123], off offset:1024 sc0 sc1 nt
	v_cvt_pk_bf16_f32 v108, v108, v109
	v_cvt_pk_bf16_f32 v109, v110, v111
	v_cvt_pk_bf16_f32 v104, v104, v105
	v_cvt_pk_bf16_f32 v105, v106, v107
	v_cvt_pk_bf16_f32 v100, v100, v101
	v_cvt_pk_bf16_f32 v101, v102, v103
	v_cvt_pk_bf16_f32 v102, v96, v97
	v_cvt_pk_bf16_f32 v103, v98, v99
	s_nop 0
	v_cndmask_b32_e64 v98, v104, v102, s[0:1]
	v_cndmask_b32_e64 v99, v105, v103, s[0:1]
	ds_bpermute_b32 v110, v126, v98
	ds_bpermute_b32 v111, v126, v99
	v_cndmask_b32_e64 v96, v108, v100, s[0:1]
	v_cndmask_b32_e64 v97, v109, v101, s[0:1]
	ds_bpermute_b32 v106, v126, v96
	ds_bpermute_b32 v107, v126, v97
	s_waitcnt lgkmcnt(0)
	v_cndmask_b32_e64 v98, v110, v104, s[0:1]
	v_or_b32_e32 v104, 16, v157
	v_cndmask_b32_e64 v99, v111, v105, s[0:1]
	v_mad_i64_i32 v[104:105], s[18:19], v104, s48, v[112:113]
	v_lshl_add_u64 v[104:105], v[104:105], 0, v[114:115]
	v_cndmask_b32_e64 v96, v106, v108, s[0:1]
	v_cndmask_b32_e64 v97, v107, v109, s[0:1]
	v_lshl_add_u64 v[104:105], v[104:105], 0, v[136:137]
	global_store_dwordx4 v[104:105], v[96:99], off sc0 sc1 nt
	v_cndmask_b32_e64 v100, v100, v106, s[0:1]
	v_cndmask_b32_e64 v101, v101, v107, s[0:1]
	v_add_co_u32_e32 v96, vcc, s44, v104
	v_cndmask_b32_e64 v102, v102, v110, s[0:1]
	v_cndmask_b32_e64 v103, v103, v111, s[0:1]
	v_addc_co_u32_e32 v97, vcc, 0, v105, vcc
	global_store_dwordx4 v[96:97], v[100:103], off offset:1024 sc0 sc1 nt
	v_cvt_pk_bf16_f32 v92, v92, v93
	v_cvt_pk_bf16_f32 v93, v94, v95
	v_cvt_pk_bf16_f32 v88, v88, v89
	v_cvt_pk_bf16_f32 v89, v90, v91
	v_cvt_pk_bf16_f32 v84, v84, v85
	v_cvt_pk_bf16_f32 v85, v86, v87
	v_cvt_pk_bf16_f32 v86, v80, v81
	v_cvt_pk_bf16_f32 v87, v82, v83
	s_nop 0
	v_cndmask_b32_e64 v82, v88, v86, s[0:1]
	v_cndmask_b32_e64 v83, v89, v87, s[0:1]
	ds_bpermute_b32 v94, v126, v82
	ds_bpermute_b32 v95, v126, v83
	v_cndmask_b32_e64 v80, v92, v84, s[0:1]
	v_cndmask_b32_e64 v81, v93, v85, s[0:1]
	ds_bpermute_b32 v90, v126, v80
	ds_bpermute_b32 v91, v126, v81
	s_waitcnt lgkmcnt(0)
	v_cndmask_b32_e64 v82, v94, v88, s[0:1]
	v_or_b32_e32 v88, 32, v157
	v_cndmask_b32_e64 v83, v95, v89, s[0:1]
	v_mad_i64_i32 v[88:89], s[18:19], v88, s48, v[112:113]
	v_lshl_add_u64 v[88:89], v[88:89], 0, v[114:115]
	v_cndmask_b32_e64 v80, v90, v92, s[0:1]
	v_cndmask_b32_e64 v81, v91, v93, s[0:1]
	v_lshl_add_u64 v[88:89], v[88:89], 0, v[136:137]
	global_store_dwordx4 v[88:89], v[80:83], off sc0 sc1 nt
	v_cndmask_b32_e64 v84, v84, v90, s[0:1]
	v_cndmask_b32_e64 v85, v85, v91, s[0:1]
	v_add_co_u32_e32 v80, vcc, s44, v88
	v_cndmask_b32_e64 v86, v86, v94, s[0:1]
	v_cndmask_b32_e64 v87, v87, v95, s[0:1]
	v_addc_co_u32_e32 v81, vcc, 0, v89, vcc
	global_store_dwordx4 v[80:81], v[84:87], off offset:1024 sc0 sc1 nt
	v_cvt_pk_bf16_f32 v76, v76, v77
	v_cvt_pk_bf16_f32 v77, v78, v79
	v_cvt_pk_bf16_f32 v72, v72, v73
	v_cvt_pk_bf16_f32 v73, v74, v75
	v_cvt_pk_bf16_f32 v68, v68, v69
	v_cvt_pk_bf16_f32 v69, v70, v71
	v_cvt_pk_bf16_f32 v70, v64, v65
	v_cvt_pk_bf16_f32 v71, v66, v67
	s_nop 0
	v_cndmask_b32_e64 v66, v72, v70, s[0:1]
	v_cndmask_b32_e64 v67, v73, v71, s[0:1]
	ds_bpermute_b32 v78, v126, v66
	ds_bpermute_b32 v79, v126, v67
	v_cndmask_b32_e64 v64, v76, v68, s[0:1]
	v_cndmask_b32_e64 v65, v77, v69, s[0:1]
	ds_bpermute_b32 v74, v126, v64
	ds_bpermute_b32 v75, v126, v65
	s_waitcnt lgkmcnt(0)
; __device__ __forceinline__ unsigned cvt_pk_bf16(float lo, float hi) { unsigned r; asm volatile("v_cvt_pk_bf16_f32 %0, %1, %2" : "=v"(r) : "v"(lo), "v"(hi)); return r; }
; #define PG8_BAR __builtin_amdgcn_s_barrier()
;     __device__ __forceinline__ void operator()(const f32x4 (&acc)[2][2][4][2], const Unit& u, int wr, int wc, int fr, int fq) const {
;     ...
;                     u32x4 w[2];
; #pragma unroll
;                     for (int bj = 0; bj < 2; ++bj) { const f32x4 v0 = acc[ai][bj][m][0] * sc[bj][0], v1 = acc[ai][bj][m][1] * sc[bj][1];
;                         w[bj].x = cvt_pk_bf16(v0[0], v0[1]); w[bj].y = cvt_pk_bf16(v0[2], v0[3]); w[bj].z = cvt_pk_bf16(v1[0], v1[1]); w[bj].w = cvt_pk_bf16(v1[2], v1[3]); }
;                     u32x4 snd, rcv;
;                     snd.x = low ? w[1].x : w[0].x; snd.y = low ? w[1].y : w[0].y; snd.z = low ? w[1].z : w[0].z; snd.w = low ? w[1].w : w[0].w;
;                     rcv.x = (unsigned)__shfl_xor((int)snd.x, 8); rcv.y = (unsigned)__shfl_xor((int)snd.y, 8); rcv.z = (unsigned)__shfl_xor((int)snd.z, 8); rcv.w = (unsigned)__shfl_xor((int)snd.w, 8);
;                     u32x4 dA, dB;
;                     dA.x = low ? w[0].x : rcv.x; dA.y = low ? w[0].y : rcv.y; dA.z = low ? w[0].z : rcv.z; dA.w = low ? w[0].w : rcv.w;
;                     dB.x = low ? rcv.x : w[1].x; dB.y = low ? rcv.y : w[1].y; dB.z = low ? rcv.z : w[1].z; dB.w = low ? rcv.w : w[1].w;
;                     bf16_t* pA = O + (size_t)(u.pm * BM + wr * 64 + ai * HALF + m * 16 + (fr & 7)) * ldc + colo + (low ? 0 : 32);
;                     __builtin_nontemporal_store(dA, (u32x4*)pA); __builtin_nontemporal_store(dB, (u32x4*)(pA + (size_t)8 * ldc)); }
; template <class EpiT>
; __device__ __forceinline__ void gemm_phase(LAS unsigned char* lds, const Gemm g, const StaticOrder& S, const EpiT& E) {
;     ...
;         if (!has_next) break;
; #pragma unroll
;         for (int a = 0; a < 2; ++a)
; #pragma unroll
;             for (int b = 0; b < 2; ++b)
; #pragma unroll
;                 for (int m = 0; m < 4; ++m)
; #pragma unroll
;                     for (int n = 0; n < 2; ++n) acc[a][b][m][n] = (f32x4){0.f, 0.f, 0.f, 0.f};
;         cur = nxt; cA = nA; cB = nB; ++ui;
;         if (wr == 1) PG8_BAR;
	v_cndmask_b32_e64 v66, v78, v72, s[0:1]
	v_or_b32_e32 v72, 48, v157
	v_cndmask_b32_e64 v67, v79, v73, s[0:1]
	v_mad_i64_i32 v[72:73], s[18:19], v72, s48, v[112:113]
	v_lshl_add_u64 v[72:73], v[72:73], 0, v[114:115]
	v_cndmask_b32_e64 v64, v74, v76, s[0:1]
	v_cndmask_b32_e64 v65, v75, v77, s[0:1]
	v_lshl_add_u64 v[72:73], v[72:73], 0, v[136:137]
	global_store_dwordx4 v[72:73], v[64:67], off sc0 sc1 nt
	v_cndmask_b32_e64 v68, v68, v74, s[0:1]
	v_cndmask_b32_e64 v69, v69, v75, s[0:1]
	v_add_co_u32_e32 v64, vcc, s44, v72
	v_cndmask_b32_e64 v70, v70, v78, s[0:1]
	v_cndmask_b32_e64 v71, v71, v79, s[0:1]
	v_addc_co_u32_e32 v65, vcc, 0, v73, vcc
	global_store_dwordx4 v[64:65], v[68:71], off offset:1024 sc0 sc1 nt
	v_cvt_pk_bf16_f32 v60, v60, v61
	v_cvt_pk_bf16_f32 v61, v62, v63
	v_cvt_pk_bf16_f32 v56, v56, v57
	v_cvt_pk_bf16_f32 v57, v58, v59
	v_cvt_pk_bf16_f32 v52, v52, v53
	v_cvt_pk_bf16_f32 v53, v54, v55
	v_cvt_pk_bf16_f32 v54, v48, v49
	v_cvt_pk_bf16_f32 v55, v50, v51
	v_add_u32_e32 v64, 0x80, v157
	v_cndmask_b32_e64 v50, v56, v54, s[0:1]
	v_cndmask_b32_e64 v51, v57, v55, s[0:1]
	ds_bpermute_b32 v62, v126, v50
	ds_bpermute_b32 v63, v126, v51
	v_cndmask_b32_e64 v48, v60, v52, s[0:1]
	v_cndmask_b32_e64 v49, v61, v53, s[0:1]
	ds_bpermute_b32 v58, v126, v48
	ds_bpermute_b32 v59, v126, v49
	s_waitcnt lgkmcnt(0)
	v_cndmask_b32_e64 v50, v62, v56, s[0:1]
	v_cndmask_b32_e64 v51, v63, v57, s[0:1]
	v_mad_i64_i32 v[56:57], s[18:19], v64, s48, v[112:113]
	v_lshl_add_u64 v[56:57], v[56:57], 0, v[114:115]
	v_cndmask_b32_e64 v48, v58, v60, s[0:1]
	v_cndmask_b32_e64 v49, v59, v61, s[0:1]
	v_lshl_add_u64 v[56:57], v[56:57], 0, v[136:137]
	global_store_dwordx4 v[56:57], v[48:51], off sc0 sc1 nt
	v_cndmask_b32_e64 v52, v52, v58, s[0:1]
	v_cndmask_b32_e64 v53, v53, v59, s[0:1]
	v_add_co_u32_e32 v48, vcc, s44, v56
	v_cndmask_b32_e64 v54, v54, v62, s[0:1]
	v_cndmask_b32_e64 v55, v55, v63, s[0:1]
	v_addc_co_u32_e32 v49, vcc, 0, v57, vcc
	global_store_dwordx4 v[48:49], v[52:55], off offset:1024 sc0 sc1 nt
	v_cvt_pk_bf16_f32 v44, v44, v45
	v_cvt_pk_bf16_f32 v45, v46, v47
	v_cvt_pk_bf16_f32 v40, v40, v41
	v_cvt_pk_bf16_f32 v41, v42, v43
	v_cvt_pk_bf16_f32 v36, v36, v37
	v_cvt_pk_bf16_f32 v37, v38, v39
	v_cvt_pk_bf16_f32 v38, v32, v33
	v_cvt_pk_bf16_f32 v39, v34, v35
	s_nop 0
	v_cndmask_b32_e64 v34, v40, v38, s[0:1]
	v_cndmask_b32_e64 v35, v41, v39, s[0:1]
	ds_bpermute_b32 v46, v126, v34
	ds_bpermute_b32 v47, v126, v35
	v_cndmask_b32_e64 v32, v44, v36, s[0:1]
	v_cndmask_b32_e64 v33, v45, v37, s[0:1]
	ds_bpermute_b32 v42, v126, v32
	ds_bpermute_b32 v43, v126, v33
	s_waitcnt lgkmcnt(0)
	v_cndmask_b32_e64 v34, v46, v40, s[0:1]
	v_add_u32_e32 v40, 0x90, v157
	v_cndmask_b32_e64 v35, v47, v41, s[0:1]
	v_mad_i64_i32 v[40:41], s[18:19], v40, s48, v[112:113]
	v_lshl_add_u64 v[40:41], v[40:41], 0, v[114:115]
	v_cndmask_b32_e64 v32, v42, v44, s[0:1]
	v_cndmask_b32_e64 v33, v43, v45, s[0:1]
	v_lshl_add_u64 v[40:41], v[40:41], 0, v[136:137]
	global_store_dwordx4 v[40:41], v[32:35], off sc0 sc1 nt
	v_cndmask_b32_e64 v36, v36, v42, s[0:1]
	v_cndmask_b32_e64 v37, v37, v43, s[0:1]
	v_add_co_u32_e32 v32, vcc, s44, v40
	v_cndmask_b32_e64 v38, v38, v46, s[0:1]
	v_cndmask_b32_e64 v39, v39, v47, s[0:1]
	v_addc_co_u32_e32 v33, vcc, 0, v41, vcc
	global_store_dwordx4 v[32:33], v[36:39], off offset:1024 sc0 sc1 nt
	v_cvt_pk_bf16_f32 v28, v28, v29
	v_cvt_pk_bf16_f32 v29, v30, v31
	v_cvt_pk_bf16_f32 v24, v24, v25
	v_cvt_pk_bf16_f32 v25, v26, v27
	v_cvt_pk_bf16_f32 v20, v20, v21
	v_cvt_pk_bf16_f32 v21, v22, v23
	v_cvt_pk_bf16_f32 v22, v16, v17
	v_cvt_pk_bf16_f32 v23, v18, v19
	s_nop 0
	v_cndmask_b32_e64 v18, v24, v22, s[0:1]
	v_cndmask_b32_e64 v19, v25, v23, s[0:1]
	ds_bpermute_b32 v30, v126, v18
	ds_bpermute_b32 v31, v126, v19
	v_cndmask_b32_e64 v16, v28, v20, s[0:1]
	v_cndmask_b32_e64 v17, v29, v21, s[0:1]
	ds_bpermute_b32 v26, v126, v16
	ds_bpermute_b32 v27, v126, v17
	s_waitcnt lgkmcnt(0)
	v_cndmask_b32_e64 v18, v30, v24, s[0:1]
	v_add_u32_e32 v24, 0xa0, v157
	v_cndmask_b32_e64 v19, v31, v25, s[0:1]
	v_mad_i64_i32 v[24:25], s[18:19], v24, s48, v[112:113]
	v_lshl_add_u64 v[24:25], v[24:25], 0, v[114:115]
	v_cndmask_b32_e64 v16, v26, v28, s[0:1]
	v_cndmask_b32_e64 v17, v27, v29, s[0:1]
	v_lshl_add_u64 v[24:25], v[24:25], 0, v[136:137]
	global_store_dwordx4 v[24:25], v[16:19], off sc0 sc1 nt
	v_cndmask_b32_e64 v20, v20, v26, s[0:1]
	v_cndmask_b32_e64 v21, v21, v27, s[0:1]
	v_add_co_u32_e32 v16, vcc, s44, v24
	v_cndmask_b32_e64 v22, v22, v30, s[0:1]
	v_cndmask_b32_e64 v23, v23, v31, s[0:1]
	v_addc_co_u32_e32 v17, vcc, 0, v25, vcc
	global_store_dwordx4 v[16:17], v[20:23], off offset:1024 sc0 sc1 nt
	v_cvt_pk_bf16_f32 v12, v12, v13
	v_cvt_pk_bf16_f32 v13, v14, v15
	v_cvt_pk_bf16_f32 v8, v8, v9
	v_cvt_pk_bf16_f32 v9, v10, v11
	v_cvt_pk_bf16_f32 v4, v4, v5
	v_cvt_pk_bf16_f32 v5, v6, v7
	v_cvt_pk_bf16_f32 v6, v0, v1
	v_cvt_pk_bf16_f32 v7, v2, v3
	s_nop 0
	v_cndmask_b32_e64 v2, v8, v6, s[0:1]
	v_cndmask_b32_e64 v3, v9, v7, s[0:1]
	ds_bpermute_b32 v14, v126, v2
	ds_bpermute_b32 v15, v126, v3
	v_cndmask_b32_e64 v0, v12, v4, s[0:1]
	v_cndmask_b32_e64 v1, v13, v5, s[0:1]
	ds_bpermute_b32 v10, v126, v0
	ds_bpermute_b32 v11, v126, v1
	s_waitcnt lgkmcnt(0)
	v_cndmask_b32_e64 v2, v14, v8, s[0:1]
	v_add_u32_e32 v8, 0xb0, v157
	v_cndmask_b32_e64 v3, v15, v9, s[0:1]
	v_mad_i64_i32 v[8:9], s[18:19], v8, s48, v[112:113]
	v_lshl_add_u64 v[8:9], v[8:9], 0, v[114:115]
	v_cndmask_b32_e64 v0, v10, v12, s[0:1]
	v_cndmask_b32_e64 v1, v11, v13, s[0:1]
	v_lshl_add_u64 v[8:9], v[8:9], 0, v[136:137]
	global_store_dwordx4 v[8:9], v[0:3], off sc0 sc1 nt
	v_cndmask_b32_e64 v4, v4, v10, s[0:1]
	v_cndmask_b32_e64 v5, v5, v11, s[0:1]
	v_add_co_u32_e32 v0, vcc, 0x8000, v8
	v_cndmask_b32_e64 v6, v6, v14, s[0:1]
	s_nop 0
	v_addc_co_u32_e32 v1, vcc, 0, v9, vcc
	v_cndmask_b32_e64 v7, v7, v15, s[0:1]
	s_and_b64 vcc, exec, s[2:3]
	s_mov_b64 s[2:3], -1
	global_store_dwordx4 v[0:1], v[4:7], off offset:1024 sc0 sc1 nt
	s_cbranch_vccnz .LBB0_583
	s_andn2_b64 vcc, exec, s[8:9]
	s_cbranch_vccnz .LBB0_582
	s_barrier
	s_branch .LBB0_582

; __device__ __forceinline__ unsigned pk2(float lo, float hi) { unsigned r; asm("v_cvt_pk_bf16_f32 %0, %1, %2" : "=v"(r) : "v"(lo), "v"(hi)); return r; }
; __device__ __forceinline__ void row_norm_store(const f32x4 (&v)[8], const float* gain, bf16_t* orow, int lane) {
;     float s = 0.f;
; #pragma unroll
;     for (int j = 0; j < 8; ++j) s += (v[j][0] * v[j][0] + v[j][1] * v[j][1]) + (v[j][2] * v[j][2] + v[j][3] * v[j][3]);
;     const float rs = 1.0f / sqrtf(wave_sum(s) * (1.0f / D_MODEL) + EPS);
; #pragma unroll
;     for (int j = 0; j < 8; ++j) { const f32x4 gv = *(const f32x4*)(gain + 4 * lane + 256 * j); const f32x4 y = v[j] * rs * gv;
;         u32x2 w; w.x = pk2(y[0], y[1]); w.y = pk2(y[2], y[3]); *(u32x2*)(orow + 4 * lane + 256 * j) = w; }
; }
.LBB0_655:
	v_mov_b32_e32 v68, v29
	v_mov_b32_e32 v69, v25
	v_mov_b32_e32 v66, v28
	v_mov_b32_e32 v67, v24
	v_pk_mul_f32 v[68:69], v[68:69], v[68:69]
	v_mov_b32_e32 v70, v31
	v_mov_b32_e32 v71, v27
	v_pk_fma_f32 v[66:67], v[66:67], v[66:67], v[68:69]
	v_mov_b32_e32 v68, v30
	v_mov_b32_e32 v69, v26
	v_pk_mul_f32 v[70:71], v[70:71], v[70:71]
	s_add_i32 s15, s15, s60
	v_pk_fma_f32 v[68:69], v[68:69], v[68:69], v[70:71]
	v_pk_mul_f32 v[70:71], v[20:21], v[20:21]
	v_pk_add_f32 v[66:67], v[66:67], v[68:69]
	v_pk_mul_f32 v[68:69], v[22:23], v[22:23]
	v_pk_add_f32 v[66:67], v[66:67], v[66:67] op_sel_hi:[0,1]
	v_pk_mov_b32 v[72:73], v[70:71], v[68:69] op_sel:[1,0]
	v_mov_b32_e32 v71, v69
	v_mul_f32_e32 v66, v16, v16
	v_pk_add_f32 v[68:69], v[72:73], v[70:71]
	v_pk_fma_f32 v[70:71], v[16:17], v[16:17], v[66:67] op_sel_hi:[1,1,0]
	v_mul_f32_e32 v66, v18, v18
	v_pk_add_f32 v[68:69], v[68:69], v[68:69] op_sel_hi:[0,1]
	v_pk_fma_f32 v[72:73], v[18:19], v[18:19], v[66:67] op_sel_hi:[1,1,0]
	v_mul_f32_e32 v70, v12, v12
	v_mul_f32_e32 v72, v13, v13
	v_mul_f32_e32 v68, v14, v14
	v_mul_f32_e32 v66, v15, v15
	v_pk_add_f32 v[70:71], v[70:71], v[72:73]
	v_pk_add_f32 v[66:67], v[68:69], v[66:67]
	v_pk_mul_f32 v[68:69], v[8:9], v[8:9]
	v_pk_add_f32 v[66:67], v[70:71], v[66:67]
	s_add_u32 s6, s6, s8
	v_pk_add_f32 v[70:71], v[66:67], v[66:67] op_sel_hi:[0,1]
	v_pk_mul_f32 v[66:67], v[10:11], v[10:11]
	v_mul_f32_e32 v70, v3, v3
	v_pk_mov_b32 v[72:73], v[68:69], v[66:67] op_sel:[1,0]
	v_mov_b32_e32 v69, v67
	v_pk_add_f32 v[66:67], v[72:73], v[68:69]
	s_addc_u32 s7, s7, s9
	v_pk_add_f32 v[72:73], v[66:67], v[66:67] op_sel_hi:[0,1]
	v_mul_f32_e32 v66, v4, v4
	v_pk_fma_f32 v[74:75], v[4:5], v[4:5], v[66:67] op_sel_hi:[1,1,0]
	v_mul_f32_e32 v66, v6, v6
	v_pk_fma_f32 v[76:77], v[6:7], v[6:7], v[66:67] op_sel_hi:[1,1,0]
	global_load_dwordx4 v[66:69], v[36:37], off
	v_mul_f32_e32 v74, v0, v0
	v_mul_f32_e32 v76, v1, v1
	v_mul_f32_e32 v72, v2, v2
	v_pk_add_f32 v[74:75], v[74:75], v[76:77]
	v_pk_add_f32 v[70:71], v[72:73], v[70:71]
	s_add_u32 s10, s10, s8
	v_pk_add_f32 v[70:71], v[74:75], v[70:71]
	s_addc_u32 s11, s11, s9
	v_add_f32_e32 v70, v70, v71
	ds_bpermute_b32 v71, v116, v70
	s_cmpk_lt_i32 s15, 0x4000
	s_waitcnt lgkmcnt(0)
	v_add_f32_e32 v70, v70, v71
	ds_bpermute_b32 v71, v117, v70
	s_waitcnt lgkmcnt(0)
	v_add_f32_e32 v70, v70, v71
	ds_bpermute_b32 v71, v118, v70
	s_waitcnt lgkmcnt(0)
	v_add_f32_e32 v70, v70, v71
	ds_bpermute_b32 v71, v119, v70
	s_waitcnt lgkmcnt(0)
	v_add_f32_e32 v70, v70, v71
	ds_bpermute_b32 v71, v120, v70
	s_waitcnt lgkmcnt(0)
	v_add_f32_e32 v70, v70, v71
	ds_bpermute_b32 v71, v121, v70
	s_waitcnt lgkmcnt(0)
	v_add_f32_e32 v70, v70, v71
	v_fmamk_f32 v70, v70, 0x3a000000, v122
	v_mul_f32_e32 v71, 0x4f800000, v70
	v_cmp_gt_f32_e32 vcc, s12, v70
	s_nop 1
	v_cndmask_b32_e32 v70, v70, v71, vcc
	v_sqrt_f32_e32 v71, v70
	s_nop 0
	v_add_u32_e32 v72, -1, v71
	v_fma_f32 v73, -v72, v71, v70
	v_cmp_ge_f32_e64 s[2:3], 0, v73
	v_add_u32_e32 v73, 1, v71
	s_nop 0
	v_cndmask_b32_e64 v72, v71, v72, s[2:3]
	v_fma_f32 v71, -v73, v71, v70
	v_cmp_lt_f32_e64 s[2:3], 0, v71
	s_nop 1
	v_cndmask_b32_e64 v71, v72, v73, s[2:3]
	v_mul_f32_e32 v72, 0x37800000, v71
	v_cndmask_b32_e32 v71, v71, v72, vcc
	v_cmp_class_f32_e32 vcc, v70, v123
	s_nop 1
	v_cndmask_b32_e32 v70, v71, v70, vcc
	v_div_scale_f32 v71, s[2:3], v70, v70, 1.0
	v_rcp_f32_e32 v72, v71
	s_nop 0
	v_fma_f32 v73, -v71, v72, 1.0
	v_fmac_f32_e32 v72, v73, v72
	v_div_scale_f32 v73, vcc, 1.0, v70, 1.0
	v_mul_f32_e32 v74, v73, v72
	v_fma_f32 v75, -v71, v74, v73
	v_fmac_f32_e32 v74, v75, v72
	v_fma_f32 v71, -v71, v74, v73
	v_div_fmas_f32 v71, v71, v72, v74
	v_div_fixup_f32 v70, v71, v70, 1.0
	v_pk_mul_f32 v[28:29], v[28:29], v[70:71] op_sel_hi:[1,0]
	v_pk_mul_f32 v[30:31], v[30:31], v[70:71] op_sel_hi:[1,0]
	s_waitcnt vmcnt(0)
	v_pk_mul_f32 v[28:29], v[66:67], v[28:29]
	v_pk_mul_f32 v[30:31], v[68:69], v[30:31]
	v_cvt_pk_bf16_f32 v28, v28, v29
	v_pk_mul_f32 v[24:25], v[24:25], v[70:71] op_sel_hi:[1,0]
	v_cvt_pk_bf16_f32 v29, v30, v31
	global_store_dwordx2 v[64:65], v[28:29], off sc0 sc1
	v_pk_mul_f32 v[26:27], v[26:27], v[70:71] op_sel_hi:[1,0]
	v_pk_mul_f32 v[20:21], v[20:21], v[70:71] op_sel_hi:[1,0]
	v_pk_mul_f32 v[22:23], v[22:23], v[70:71] op_sel_hi:[1,0]
	v_pk_mul_f32 v[16:17], v[16:17], v[70:71] op_sel_hi:[1,0]
	v_pk_mul_f32 v[18:19], v[18:19], v[70:71] op_sel_hi:[1,0]
	v_pk_mul_f32 v[12:13], v[12:13], v[70:71] op_sel_hi:[1,0]
	v_pk_mul_f32 v[14:15], v[14:15], v[70:71] op_sel_hi:[1,0]
	v_pk_mul_f32 v[8:9], v[8:9], v[70:71] op_sel_hi:[1,0]
	v_pk_mul_f32 v[10:11], v[10:11], v[70:71] op_sel_hi:[1,0]
	v_pk_mul_f32 v[4:5], v[4:5], v[70:71] op_sel_hi:[1,0]
	v_pk_mul_f32 v[6:7], v[6:7], v[70:71] op_sel_hi:[1,0]
	v_pk_mul_f32 v[0:1], v[0:1], v[70:71] op_sel_hi:[1,0]
	v_pk_mul_f32 v[2:3], v[2:3], v[70:71] op_sel_hi:[1,0]
	v_pk_mul_f32 v[24:25], v[176:177], v[24:25]
	v_pk_mul_f32 v[26:27], v[178:179], v[26:27]
	v_cvt_pk_bf16_f32 v24, v24, v25
	s_nop 0
	v_cvt_pk_bf16_f32 v25, v26, v27
	global_store_dwordx2 v[64:65], v[24:25], off offset:512 sc0 sc1
	v_pk_mul_f32 v[20:21], v[180:181], v[20:21]
	v_pk_mul_f32 v[22:23], v[182:183], v[22:23]
	v_cvt_pk_bf16_f32 v20, v20, v21
	s_nop 0
	v_cvt_pk_bf16_f32 v21, v22, v23
	global_store_dwordx2 v[64:65], v[20:21], off offset:1024 sc0 sc1
	v_pk_mul_f32 v[16:17], v[16:17], v[184:185]
	v_pk_mul_f32 v[18:19], v[18:19], v[186:187]
	v_cvt_pk_bf16_f32 v16, v16, v17
	s_nop 0
	v_cvt_pk_bf16_f32 v17, v18, v19
	global_store_dwordx2 v[64:65], v[16:17], off offset:1536 sc0 sc1
	v_pk_mul_f32 v[12:13], v[12:13], v[188:189]
	v_pk_mul_f32 v[14:15], v[14:15], v[190:191]
	v_cvt_pk_bf16_f32 v12, v12, v13
	s_nop 0
	v_cvt_pk_bf16_f32 v13, v14, v15
	global_store_dwordx2 v[64:65], v[12:13], off offset:2048 sc0 sc1
	v_pk_mul_f32 v[8:9], v[8:9], v[192:193]
	v_pk_mul_f32 v[10:11], v[10:11], v[194:195]
	v_cvt_pk_bf16_f32 v8, v8, v9
	s_nop 0
	v_cvt_pk_bf16_f32 v9, v10, v11
	global_store_dwordx2 v[64:65], v[8:9], off offset:2560 sc0 sc1
	v_pk_mul_f32 v[4:5], v[4:5], v[196:197]
	v_pk_mul_f32 v[6:7], v[6:7], v[198:199]
	v_cvt_pk_bf16_f32 v4, v4, v5
	s_nop 0
	v_cvt_pk_bf16_f32 v5, v6, v7
	global_store_dwordx2 v[64:65], v[4:5], off offset:3072 sc0 sc1
	v_pk_mul_f32 v[0:1], v[0:1], v[200:201]
	v_pk_mul_f32 v[2:3], v[2:3], v[202:203]
	v_cvt_pk_bf16_f32 v0, v0, v1
	s_nop 0
	v_cvt_pk_bf16_f32 v1, v2, v3
	global_store_dwordx2 v[64:65], v[0:1], off offset:3584 sc0 sc1
	v_lshl_add_u64 v[64:65], v[64:65], 0, s[82:83]
	s_cbranch_scc0 .LBB0_658
; __device__ __forceinline__ void resid_rows(const float* prev, const bf16_t* Y, const float* ga, const bf16_t* F, const float* gc, float* xout, const float* gb, bf16_t* hn, int gw, int NGW, int lane) {
;     for (int m = gw; m < MTOK; m += NGW) {
;         f32x4 y[8]; float s = 0.f;
; #pragma unroll
;         for (int j = 0; j < 8; ++j) { const u32x2 w = *(const u32x2*)(Y + (size_t)m * LDH + 4 * lane + 256 * j); y[j] = (f32x4){bflo(w.x), bfhi(w.x), bflo(w.y), bfhi(w.y)};
;             s += (y[j][0] * y[j][0] + y[j][1] * y[j][1]) + (y[j][2] * y[j][2] + y[j][3] * y[j][3]); }
;         const float rs = 1.0f / sqrtf(wave_sum(s) * (1.0f / D_MODEL) + EPS);
;         f32x4 x1[8];
; #pragma unroll
;         for (int j = 0; j < 8; ++j) { const f32x4 pv = *(const f32x4*)(prev + (size_t)m * D_MODEL + 4 * lane + 256 * j); const f32x4 gv = *(const f32x4*)(ga + 4 * lane + 256 * j);
;             x1[j] = pv + y[j] * rs * gv; }
;         if (F) {
;             float s2 = 0.f;
; #pragma unroll
;             for (int j = 0; j < 8; ++j) { const u32x2 w = *(const u32x2*)(F + (size_t)m * LDH + 4 * lane + 256 * j); y[j] = (f32x4){bflo(w.x), bfhi(w.x), bflo(w.y), bfhi(w.y)};
;                 s2 += (y[j][0] * y[j][0] + y[j][1] * y[j][1]) + (y[j][2] * y[j][2] + y[j][3] * y[j][3]); }
.LBB0_656:
	global_load_dwordx2 v[6:7], v[64:65], off
	global_load_dwordx2 v[8:9], v[64:65], off offset:512
	global_load_dwordx2 v[12:13], v[64:65], off offset:1024
	global_load_dwordx2 v[16:17], v[64:65], off offset:1536
	global_load_dwordx2 v[18:19], v[64:65], off offset:2048
	global_load_dwordx2 v[20:21], v[64:65], off offset:2560
	global_load_dwordx2 v[24:25], v[64:65], off offset:3072
	global_load_dwordx2 v[76:77], v[64:65], off offset:3584
	v_lshl_add_u64 v[4:5], s[6:7], 0, v[62:63]
	global_load_dwordx4 v[0:3], v[4:5], off
	s_waitcnt vmcnt(8)
	v_and_b32_e32 v69, 0xffff0000, v6
	v_and_b32_e32 v71, 0xffff0000, v7
	v_lshlrev_b32_e32 v68, 16, v6
	v_lshlrev_b32_e32 v70, 16, v7
	s_waitcnt vmcnt(7)
	v_lshlrev_b32_e32 v73, 16, v9
	v_lshlrev_b32_e32 v72, 16, v8
	v_and_b32_e32 v75, 0xffff0000, v9
	v_and_b32_e32 v74, 0xffff0000, v8
	s_waitcnt vmcnt(5)
	v_lshlrev_b32_e32 v9, 16, v16
	v_and_b32_e32 v7, 0xffff0000, v16
	s_waitcnt vmcnt(2)
	v_and_b32_e32 v23, 0xffff0000, v24
	v_mul_f32_e32 v6, v71, v71
	v_mul_f32_e32 v8, v69, v69
	v_lshlrev_b32_e32 v10, 16, v12
	v_and_b32_e32 v11, 0xffff0000, v12
	v_lshlrev_b32_e32 v14, 16, v13
	v_and_b32_e32 v15, 0xffff0000, v13
	v_lshlrev_b32_e32 v12, 16, v17
	v_and_b32_e32 v13, 0xffff0000, v17
	v_lshlrev_b32_e32 v31, 16, v19
	v_and_b32_e32 v67, 0xffff0000, v19
	v_lshlrev_b32_e32 v27, 16, v21
	v_lshlrev_b32_e32 v26, 16, v20
	v_and_b32_e32 v29, 0xffff0000, v21
	v_and_b32_e32 v28, 0xffff0000, v20
	v_lshlrev_b32_e32 v22, 16, v24
	s_waitcnt vmcnt(1)
	v_lshlrev_b32_e32 v19, 16, v76
	v_and_b32_e32 v17, 0xffff0000, v76
	v_lshlrev_b32_e32 v20, 16, v77
	v_and_b32_e32 v21, 0xffff0000, v77
	v_pk_mul_f32 v[76:77], v[74:75], v[74:75]
	v_mov_b32_e32 v79, v9
	v_mul_f32_e32 v78, v23, v23
	v_pk_fma_f32 v[86:87], v[70:71], v[70:71], v[6:7] op_sel_hi:[1,1,0]
	v_pk_fma_f32 v[88:89], v[68:69], v[68:69], v[8:9] op_sel_hi:[1,1,0]
	v_lshlrev_b32_e32 v30, 16, v18
	v_and_b32_e32 v66, 0xffff0000, v18
	v_mul_f32_e32 v16, v11, v11
	v_mul_f32_e32 v18, v15, v15
	v_pk_fma_f32 v[76:77], v[72:73], v[72:73], v[76:77]
	v_pk_fma_f32 v[94:95], v[22:23], v[22:23], v[78:79] op_sel_hi:[1,1,0]
	v_mov_b32_e32 v8, v88
	v_mov_b32_e32 v78, v86
	v_mul_f32_e32 v98, v7, v7
	v_mul_f32_e32 v99, v12, v12
	v_mul_f32_e32 v100, v13, v13
	v_pk_fma_f32 v[90:91], v[10:11], v[10:11], v[16:17] op_sel_hi:[1,1,0]
	v_pk_fma_f32 v[92:93], v[14:15], v[14:15], v[18:19] op_sel_hi:[1,1,0]
	v_pk_add_f32 v[86:87], v[88:89], v[86:87]
	v_pk_add_f32 v[76:77], v[76:77], v[76:77] op_sel:[0,1] op_sel_hi:[1,0]
	v_pk_mul_f32 v[78:79], v[8:9], v[78:79]
	v_mov_b32_e32 v91, v99
	v_mov_b32_e32 v93, v100
	v_mov_b32_e32 v77, v98
	v_mov_b32_e32 v87, v79
	v_pk_mul_f32 v[80:81], v[66:67], v[66:67]
	v_pk_add_f32 v[88:89], v[90:91], v[92:93]
	v_pk_add_f32 v[76:77], v[86:87], v[76:77]
	v_lshlrev_b32_e32 v24, 16, v25
	v_and_b32_e32 v25, 0xffff0000, v25
	v_pk_fma_f32 v[80:81], v[30:31], v[30:31], v[80:81]
	v_pk_add_f32 v[76:77], v[76:77], v[88:89]
	v_pk_mul_f32 v[82:83], v[28:29], v[28:29]
	v_mov_b32_e32 v85, v19
	v_mul_f32_e32 v84, v25, v25
	v_pk_add_f32 v[80:81], v[80:81], v[80:81] op_sel:[0,1] op_sel_hi:[1,0]
	v_pk_add_f32 v[76:77], v[76:77], v[76:77] op_sel:[0,1] op_sel_hi:[1,0]
	v_pk_fma_f32 v[82:83], v[26:27], v[26:27], v[82:83]
	v_pk_fma_f32 v[96:97], v[24:25], v[24:25], v[84:85] op_sel_hi:[1,1,0]
	v_mov_b32_e32 v84, v80
	v_mov_b32_e32 v18, v76
	v_mul_f32_e32 v101, v17, v17
	v_mul_f32_e32 v102, v20, v20
	v_mul_f32_e32 v103, v21, v21
	v_pk_add_f32 v[82:83], v[82:83], v[82:83] op_sel:[0,1] op_sel_hi:[1,0]
	v_pk_add_f32 v[76:77], v[76:77], v[80:81]
	v_pk_mul_f32 v[78:79], v[18:19], v[84:85]
	v_mov_b32_e32 v95, v102
	v_mov_b32_e32 v97, v103
	v_mov_b32_e32 v83, v101
	v_mov_b32_e32 v77, v79
	v_pk_add_f32 v[90:91], v[94:95], v[96:97]
	v_pk_add_f32 v[80:81], v[76:77], v[82:83]
	global_load_dwordx4 v[76:79], v[32:33], off
	v_pk_add_f32 v[80:81], v[80:81], v[90:91]
	v_add_co_u32_e32 v96, vcc, s14, v64
	v_add_f32_e32 v6, v80, v81
	global_load_dwordx4 v[80:83], v[4:5], off offset:1024
	global_load_dwordx4 v[84:87], v[32:33], off offset:1024
	global_load_dwordx4 v[88:91], v[32:33], off offset:2048
	global_load_dwordx4 v[92:95], v[4:5], off offset:2048
	ds_bpermute_b32 v8, v116, v6
	v_addc_co_u32_e32 v97, vcc, 0, v65, vcc
	global_load_dwordx2 v[98:99], v[96:97], off
	global_load_dwordx2 v[100:101], v[96:97], off offset:512
	s_waitcnt lgkmcnt(0)
	v_add_f32_e32 v6, v6, v8
	ds_bpermute_b32 v8, v117, v6
	global_load_dwordx2 v[102:103], v[96:97], off offset:1024
	global_load_dwordx2 v[104:105], v[96:97], off offset:1536
	v_mov_b32_e32 v108, v73
	global_load_dwordx2 v[106:107], v[96:97], off offset:2048
	global_load_dwordx2 v[110:111], v[96:97], off offset:2560
	global_load_dwordx2 v[114:115], v[96:97], off offset:3072
	global_load_dwordx2 v[150:151], v[96:97], off offset:3584
	s_waitcnt lgkmcnt(0)
	v_add_f32_e32 v6, v6, v8
	ds_bpermute_b32 v8, v118, v6
	global_load_dwordx4 v[124:127], v[4:5], off offset:3072
	global_load_dwordx4 v[128:131], v[32:33], off offset:3072
	s_waitcnt lgkmcnt(0)
	v_add_f32_e32 v6, v6, v8
	ds_bpermute_b32 v8, v119, v6
	s_waitcnt lgkmcnt(0)
	v_add_f32_e32 v6, v6, v8
	ds_bpermute_b32 v8, v120, v6
	s_waitcnt lgkmcnt(0)
	v_add_f32_e32 v6, v6, v8
	ds_bpermute_b32 v8, v121, v6
	s_waitcnt lgkmcnt(0)
	v_add_f32_e32 v6, v6, v8
	v_fmamk_f32 v6, v6, 0x3a000000, v122
	v_mul_f32_e32 v8, 0x4f800000, v6
	v_cmp_gt_f32_e32 vcc, s12, v6
	s_waitcnt vmcnt(7)
	v_lshlrev_b32_e32 v96, 16, v103
	v_cndmask_b32_e32 v6, v6, v8, vcc
	v_sqrt_f32_e32 v8, v6
	v_and_b32_e32 v97, 0xffff0000, v103
	s_waitcnt vmcnt(3)
; __device__ __forceinline__ void resid_rows(const float* prev, const bf16_t* Y, const float* ga, const bf16_t* F, const float* gc, float* xout, const float* gb, bf16_t* hn, int gw, int NGW, int lane) {
;     ...
;         for (int j = 0; j < 8; ++j) { const u32x2 w = *(const u32x2*)(Y + (size_t)m * LDH + 4 * lane + 256 * j); y[j] = (f32x4){bflo(w.x), bfhi(w.x), bflo(w.y), bfhi(w.y)};
;             s += (y[j][0] * y[j][0] + y[j][1] * y[j][1]) + (y[j][2] * y[j][2] + y[j][3] * y[j][3]); }
;         const float rs = 1.0f / sqrtf(wave_sum(s) * (1.0f / D_MODEL) + EPS);
;         f32x4 x1[8];
; #pragma unroll
;         for (int j = 0; j < 8; ++j) { const f32x4 pv = *(const f32x4*)(prev + (size_t)m * D_MODEL + 4 * lane + 256 * j); const f32x4 gv = *(const f32x4*)(ga + 4 * lane + 256 * j);
;             x1[j] = pv + y[j] * rs * gv; }
;         if (F) {
;             float s2 = 0.f;
; #pragma unroll
;             for (int j = 0; j < 8; ++j) { const u32x2 w = *(const u32x2*)(F + (size_t)m * LDH + 4 * lane + 256 * j); y[j] = (f32x4){bflo(w.x), bfhi(w.x), bflo(w.y), bfhi(w.y)};
;                 s2 += (y[j][0] * y[j][0] + y[j][1] * y[j][1]) + (y[j][2] * y[j][2] + y[j][3] * y[j][3]); }
;             const float rs2 = 1.0f / sqrtf(wave_sum(s2) * (1.0f / D_MODEL) + EPS);
	v_and_b32_e32 v113, 0xffff0000, v114
	v_lshlrev_b32_e32 v112, 16, v114
	v_add_u32_e32 v16, -1, v8
	v_add_u32_e32 v18, 1, v8
	v_fma_f32 v73, -v16, v8, v6
	v_fma_f32 v109, -v18, v8, v6
	v_cmp_ge_f32_e64 s[2:3], 0, v73
	v_lshlrev_b32_e32 v114, 16, v115
	v_and_b32_e32 v115, 0xffff0000, v115
	v_cndmask_b32_e64 v8, v8, v16, s[2:3]
	v_cmp_lt_f32_e64 s[2:3], 0, v109
	v_mov_b32_e32 v109, v75
	s_nop 0
	v_cndmask_b32_e64 v8, v8, v18, s[2:3]
	v_mul_f32_e32 v16, 0x37800000, v8
	v_cndmask_b32_e32 v8, v8, v16, vcc
	v_cmp_class_f32_e32 vcc, v6, v123
	s_nop 1
	v_cndmask_b32_e32 v6, v8, v6, vcc
	v_div_scale_f32 v8, s[2:3], v6, v6, 1.0
	v_rcp_f32_e32 v16, v8
	v_div_scale_f32 v18, vcc, 1.0, v6, 1.0
	v_fma_f32 v73, -v8, v16, 1.0
	v_fmac_f32_e32 v16, v73, v16
	v_mul_f32_e32 v73, v18, v16
	v_fma_f32 v75, -v8, v73, v18
	v_fmac_f32_e32 v73, v75, v16
	v_fma_f32 v8, -v8, v73, v18
	v_div_fmas_f32 v8, v8, v16, v73
	v_div_fixup_f32 v18, v8, v6, 1.0
	v_pk_mul_f32 v[68:69], v[18:19], v[68:69] op_sel_hi:[0,1]
	v_mov_b32_e32 v73, v74
	v_pk_fma_f32 v[68:69], v[76:77], v[68:69], v[0:1]
	v_pk_mul_f32 v[0:1], v[18:19], v[72:73] op_sel_hi:[0,1]
	v_pk_mul_f32 v[70:71], v[18:19], v[70:71] op_sel_hi:[0,1]
	v_pk_fma_f32 v[72:73], v[84:85], v[0:1], v[80:81]
	v_pk_mul_f32 v[0:1], v[18:19], v[14:15] op_sel_hi:[0,1]
	v_pk_fma_f32 v[70:71], v[78:79], v[70:71], v[2:3]
	v_pk_fma_f32 v[78:79], v[90:91], v[0:1], v[94:95]
	v_add_co_u32_e32 v0, vcc, s13, v4
	v_pk_mul_f32 v[2:3], v[18:19], v[10:11] op_sel_hi:[0,1]
	v_mov_b32_e32 v6, v9
	v_addc_co_u32_e32 v1, vcc, 0, v5, vcc
	v_pk_fma_f32 v[76:77], v[88:89], v[2:3], v[92:93]
	v_pk_mul_f32 v[154:155], v[12:13], v[18:19] op_sel_hi:[1,0]
	v_pk_mul_f32 v[156:157], v[6:7], v[18:19] op_sel_hi:[1,0]
	global_load_dwordx4 v[132:135], v[0:1], off
	global_load_dwordx4 v[136:139], v[0:1], off offset:1024
	global_load_dwordx4 v[140:143], v[46:47], off
	global_load_dwordx4 v[144:147], v[48:49], off
	global_load_dwordx4 v[8:11], v[0:1], off offset:2048
	s_nop 0
	global_load_dwordx4 v[0:3], v[0:1], off offset:3072
	s_nop 0
	global_load_dwordx4 v[12:15], v[50:51], off
	global_load_dwordx4 v[4:7], v[52:53], off
	v_and_b32_e32 v95, 0xffff0000, v99
	v_pk_mul_f32 v[108:109], v[18:19], v[108:109] op_sel_hi:[0,1]
	v_and_b32_e32 v85, 0xffff0000, v98
	v_lshlrev_b32_e32 v94, 16, v99
	v_mul_f32_e32 v16, v95, v95
	v_pk_fma_f32 v[74:75], v[86:87], v[108:109], v[82:83]
	v_lshlrev_b32_e32 v84, 16, v98
	v_pk_fma_f32 v[98:99], v[94:95], v[94:95], v[16:17] op_sel_hi:[1,1,0]
	v_and_b32_e32 v83, 0xffff0000, v101
	v_and_b32_e32 v82, 0xffff0000, v100
	v_mul_f32_e32 v16, v85, v85
	v_lshlrev_b32_e32 v81, 16, v101
	v_lshlrev_b32_e32 v80, 16, v100
	v_pk_mul_f32 v[86:87], v[82:83], v[82:83]
	v_lshlrev_b32_e32 v92, 16, v102
	v_and_b32_e32 v93, 0xffff0000, v102
	v_lshlrev_b32_e32 v91, 16, v104
	v_pk_fma_f32 v[102:103], v[84:85], v[84:85], v[16:17] op_sel_hi:[1,1,0]
	v_pk_fma_f32 v[100:101], v[80:81], v[80:81], v[86:87]
	v_and_b32_e32 v89, 0xffff0000, v104
	v_lshlrev_b32_e32 v86, 16, v105
	v_and_b32_e32 v87, 0xffff0000, v105
	v_mov_b32_e32 v90, v102
	v_mov_b32_e32 v104, v98
	v_mov_b32_e32 v105, v91
	v_mul_f32_e32 v88, v89, v89
	v_pk_add_f32 v[98:99], v[102:103], v[98:99]
	v_pk_mul_f32 v[102:103], v[90:91], v[104:105]
	v_pk_add_f32 v[100:101], v[100:101], v[100:101] op_sel:[0,1] op_sel_hi:[1,0]
	v_mov_b32_e32 v99, v103
	v_mov_b32_e32 v101, v88
	v_mul_f32_e32 v16, v93, v93
	v_pk_add_f32 v[98:99], v[98:99], v[100:101]
	v_pk_fma_f32 v[100:101], v[92:93], v[92:93], v[16:17] op_sel_hi:[1,1,0]
	v_mul_f32_e32 v16, v97, v97
	v_mul_f32_e32 v108, v86, v86
	v_mul_f32_e32 v109, v87, v87
	v_pk_fma_f32 v[102:103], v[96:97], v[96:97], v[16:17] op_sel_hi:[1,1,0]
	v_mov_b32_e32 v101, v108
	v_mov_b32_e32 v103, v109
	v_pk_add_f32 v[100:101], v[100:101], v[102:103]
	v_and_b32_e32 v109, 0xffff0000, v107
	v_and_b32_e32 v108, 0xffff0000, v106
	v_pk_add_f32 v[152:153], v[98:99], v[100:101]
	v_lshlrev_b32_e32 v103, 16, v107
	v_lshlrev_b32_e32 v102, 16, v106
	v_pk_mul_f32 v[98:99], v[108:109], v[108:109]
	v_and_b32_e32 v107, 0xffff0000, v111
	v_pk_fma_f32 v[98:99], v[102:103], v[102:103], v[98:99]
	v_and_b32_e32 v106, 0xffff0000, v110
	v_pk_add_f32 v[158:159], v[98:99], v[98:99] op_sel:[0,1] op_sel_hi:[1,0]
	v_lshlrev_b32_e32 v101, 16, v111
	v_lshlrev_b32_e32 v100, 16, v110
	v_pk_mul_f32 v[98:99], v[106:107], v[106:107]
	s_waitcnt vmcnt(10)
	v_lshlrev_b32_e32 v111, 16, v150
	v_pk_fma_f32 v[160:161], v[100:101], v[100:101], v[98:99]
	v_and_b32_e32 v105, 0xffff0000, v150
	v_lshlrev_b32_e32 v98, 16, v151
	v_and_b32_e32 v99, 0xffff0000, v151
	v_pk_add_f32 v[150:151], v[152:153], v[152:153] op_sel:[0,1] op_sel_hi:[1,0]
	v_mov_b32_e32 v152, v158
	v_mov_b32_e32 v110, v150
	v_mov_b32_e32 v153, v111
	v_pk_add_f32 v[150:151], v[150:151], v[158:159]
	v_pk_mul_f32 v[152:153], v[110:111], v[152:153]
	v_mul_f32_e32 v16, v105, v105
	v_mov_b32_e32 v151, v153
	v_pk_add_f32 v[152:153], v[160:161], v[160:161] op_sel:[0,1] op_sel_hi:[1,0]
	v_mul_f32_e32 v88, v98, v98
	v_mov_b32_e32 v153, v16
	v_mul_f32_e32 v16, v113, v113
	v_pk_add_f32 v[158:159], v[150:151], v[152:153]
	v_pk_fma_f32 v[150:151], v[112:113], v[112:113], v[16:17] op_sel_hi:[1,1,0]
	v_mul_f32_e32 v16, v115, v115
	v_mul_f32_e32 v90, v99, v99
	v_pk_fma_f32 v[152:153], v[114:115], v[114:115], v[16:17] op_sel_hi:[1,1,0]
	v_mov_b32_e32 v151, v88
	v_mov_b32_e32 v153, v90
	v_pk_add_f32 v[160:161], v[150:151], v[152:153]
	global_load_dwordx4 v[150:153], v[34:35], off
	v_pk_add_f32 v[158:159], v[158:159], v[160:161]
	s_waitcnt vmcnt(9)
; __device__ __forceinline__ void resid_rows(const float* prev, const bf16_t* Y, const float* ga, const bf16_t* F, const float* gc, float* xout, const float* gb, bf16_t* hn, int gw, int NGW, int lane) {
;     ...
;             float s2 = 0.f;
; #pragma unroll
;             for (int j = 0; j < 8; ++j) { const u32x2 w = *(const u32x2*)(F + (size_t)m * LDH + 4 * lane + 256 * j); y[j] = (f32x4){bflo(w.x), bfhi(w.x), bflo(w.y), bfhi(w.y)};
;                 s2 += (y[j][0] * y[j][0] + y[j][1] * y[j][1]) + (y[j][2] * y[j][2] + y[j][3] * y[j][3]); }
;             const float rs2 = 1.0f / sqrtf(wave_sum(s2) * (1.0f / D_MODEL) + EPS);
; #pragma unroll
;             for (int j = 0; j < 8; ++j) { const f32x4 gv = *(const f32x4*)(gc + 4 * lane + 256 * j); x1[j] = x1[j] + y[j] * rs2 * gv; }
;         }
;         if (xout) {
; #pragma unroll
;             for (int j = 0; j < 8; ++j) *(f32x4*)(xout + (size_t)m * D_MODEL + 4 * lane + 256 * j) = x1[j]; }
	v_pk_fma_f32 v[160:161], v[130:131], v[154:155], v[126:127]
	v_add_f32_e32 v16, v158, v159
	v_pk_fma_f32 v[158:159], v[128:129], v[156:157], v[124:125]
	global_load_dwordx4 v[124:127], v[34:35], off offset:1024
	v_mov_b32_e32 v154, v31
	v_mov_b32_e32 v155, v67
	global_load_dwordx4 v[128:131], v[34:35], off offset:2048
	v_pk_mul_f32 v[162:163], v[18:19], v[154:155] op_sel_hi:[0,1]
	v_mov_b32_e32 v31, v66
	global_load_dwordx4 v[154:157], v[34:35], off offset:3072
	v_pk_mul_f32 v[30:31], v[18:19], v[30:31] op_sel_hi:[0,1]
	s_waitcnt vmcnt(9)
	v_pk_fma_f32 v[66:67], v[140:141], v[30:31], v[132:133]
	v_pk_fma_f32 v[162:163], v[142:143], v[162:163], v[134:135]
	global_load_dwordx4 v[132:135], v[54:55], off
	global_load_dwordx4 v[140:143], v[56:57], off
	v_mov_b32_e32 v30, v27
	v_mov_b32_e32 v31, v29
	v_mov_b32_e32 v27, v28
	v_pk_mul_f32 v[30:31], v[18:19], v[30:31] op_sel_hi:[0,1]
	v_pk_mul_f32 v[26:27], v[18:19], v[26:27] op_sel_hi:[0,1]
	s_waitcnt vmcnt(10)
	v_pk_fma_f32 v[166:167], v[144:145], v[26:27], v[136:137]
	v_pk_fma_f32 v[170:171], v[146:147], v[30:31], v[138:139]
	global_load_dwordx4 v[136:139], v[58:59], off
	global_load_dwordx4 v[144:147], v[60:61], off
	ds_bpermute_b32 v88, v116, v16
	v_pk_mul_f32 v[22:23], v[18:19], v[22:23] op_sel_hi:[0,1]
	s_waitcnt vmcnt(9)
	v_pk_fma_f32 v[172:173], v[12:13], v[22:23], v[8:9]
	v_pk_mul_f32 v[24:25], v[18:19], v[24:25] op_sel_hi:[0,1]
	v_pk_fma_f32 v[174:175], v[14:15], v[24:25], v[10:11]
	s_waitcnt lgkmcnt(0)
	v_add_f32_e32 v16, v16, v88
	ds_bpermute_b32 v88, v117, v16
	v_mov_b32_e32 v104, v111
	s_waitcnt lgkmcnt(0)
	v_add_f32_e32 v16, v16, v88
	ds_bpermute_b32 v88, v118, v16
	s_waitcnt lgkmcnt(0)
	v_add_f32_e32 v16, v16, v88
	ds_bpermute_b32 v88, v119, v16
	s_waitcnt lgkmcnt(0)
	v_add_f32_e32 v16, v16, v88
	ds_bpermute_b32 v28, v120, v16
	v_mov_b32_e32 v88, v91
	s_waitcnt lgkmcnt(0)
	v_add_f32_e32 v16, v16, v28
	ds_bpermute_b32 v26, v121, v16
	s_waitcnt lgkmcnt(0)
	v_add_f32_e32 v8, v16, v26
	v_fmamk_f32 v8, v8, 0x3a000000, v122
	v_mul_f32_e32 v9, 0x4f800000, v8
	v_cmp_gt_f32_e32 vcc, s12, v8
	v_mov_b32_e32 v16, v19
	s_nop 0
	v_cndmask_b32_e32 v12, v8, v9, vcc
	v_sqrt_f32_e32 v13, v12
	v_pk_mul_f32 v[8:9], v[20:21], v[18:19] op_sel_hi:[1,0]
	v_add_u32_e32 v10, -1, v13
	v_fma_f32 v11, -v10, v13, v12
	v_cmp_ge_f32_e64 s[2:3], 0, v11
	v_add_u32_e32 v11, 1, v13
	s_waitcnt vmcnt(8)
	v_pk_fma_f32 v[2:3], v[8:9], v[6:7], v[2:3]
	v_cndmask_b32_e64 v10, v13, v10, s[2:3]
	v_fma_f32 v13, -v11, v13, v12
	v_cmp_lt_f32_e64 s[2:3], 0, v13
	s_nop 1
	v_cndmask_b32_e64 v10, v10, v11, s[2:3]
	v_mul_f32_e32 v11, 0x37800000, v10
	v_cndmask_b32_e32 v10, v10, v11, vcc
	v_cmp_class_f32_e32 vcc, v12, v123
	s_nop 1
	v_cndmask_b32_e32 v12, v10, v12, vcc
	v_div_scale_f32 v13, s[2:3], v12, v12, 1.0
	v_rcp_f32_e32 v14, v13
	v_pk_mul_f32 v[10:11], v[16:17], v[18:19] op_sel_hi:[1,0]
	s_nop 0
	v_pk_fma_f32 v[0:1], v[10:11], v[4:5], v[0:1]
	v_fma_f32 v4, -v13, v14, 1.0
	v_fmac_f32_e32 v14, v4, v14
	v_div_scale_f32 v4, vcc, 1.0, v12, 1.0
	v_mul_f32_e32 v5, v4, v14
	v_fma_f32 v6, -v13, v5, v4
	v_fmac_f32_e32 v5, v6, v14
	v_fma_f32 v4, -v13, v5, v4
	v_div_fmas_f32 v4, v4, v14, v5
	v_div_fixup_f32 v90, v4, v12, 1.0
	v_pk_mul_f32 v[4:5], v[90:91], v[84:85] op_sel_hi:[0,1]
	s_waitcnt vmcnt(7)
	v_pk_fma_f32 v[28:29], v[150:151], v[4:5], v[68:69]
	v_mov_b32_e32 v4, v80
	v_mov_b32_e32 v5, v82
	v_pk_mul_f32 v[4:5], v[90:91], v[4:5] op_sel_hi:[0,1]
	v_pk_mul_f32 v[6:7], v[90:91], v[94:95] op_sel_hi:[0,1]
	v_mov_b32_e32 v82, v81
	s_waitcnt vmcnt(6)
	v_pk_fma_f32 v[24:25], v[124:125], v[4:5], v[72:73]
	v_pk_mul_f32 v[4:5], v[90:91], v[92:93] op_sel_hi:[0,1]
	v_pk_fma_f32 v[30:31], v[152:153], v[6:7], v[70:71]
	v_pk_mul_f32 v[6:7], v[90:91], v[82:83] op_sel_hi:[0,1]
	s_waitcnt vmcnt(5)
	v_pk_fma_f32 v[20:21], v[128:129], v[4:5], v[76:77]
	v_pk_mul_f32 v[4:5], v[88:89], v[90:91] op_sel_hi:[1,0]
	v_pk_fma_f32 v[26:27], v[126:127], v[6:7], v[74:75]
	v_pk_mul_f32 v[6:7], v[90:91], v[96:97] op_sel_hi:[0,1]
	s_waitcnt vmcnt(4)
	v_pk_fma_f32 v[16:17], v[154:155], v[4:5], v[158:159]
	v_mov_b32_e32 v4, v102
	v_mov_b32_e32 v5, v108
	v_pk_fma_f32 v[22:23], v[130:131], v[6:7], v[78:79]
	v_pk_mul_f32 v[6:7], v[86:87], v[90:91] op_sel_hi:[1,0]
	v_pk_mul_f32 v[4:5], v[90:91], v[4:5] op_sel_hi:[0,1]
	v_mov_b32_e32 v108, v103
	v_pk_fma_f32 v[18:19], v[156:157], v[6:7], v[160:161]
	v_pk_mul_f32 v[6:7], v[90:91], v[108:109] op_sel_hi:[0,1]
	s_waitcnt vmcnt(3)
	v_pk_fma_f32 v[12:13], v[132:133], v[4:5], v[66:67]
	v_mov_b32_e32 v4, v100
	v_mov_b32_e32 v5, v106
	v_mov_b32_e32 v106, v101
	v_pk_fma_f32 v[14:15], v[134:135], v[6:7], v[162:163]
	v_pk_mul_f32 v[4:5], v[90:91], v[4:5] op_sel_hi:[0,1]
	v_pk_mul_f32 v[6:7], v[90:91], v[106:107] op_sel_hi:[0,1]
	s_waitcnt vmcnt(2)
	v_pk_fma_f32 v[10:11], v[142:143], v[6:7], v[170:171]
	v_pk_fma_f32 v[8:9], v[140:141], v[4:5], v[166:167]
	v_pk_mul_f32 v[4:5], v[90:91], v[112:113] op_sel_hi:[0,1]
	v_pk_mul_f32 v[6:7], v[90:91], v[114:115] op_sel_hi:[0,1]
	v_pk_mul_f32 v[66:67], v[104:105], v[90:91] op_sel_hi:[1,0]
	v_pk_mul_f32 v[68:69], v[98:99], v[90:91] op_sel_hi:[1,0]
	s_waitcnt vmcnt(1)
	v_pk_fma_f32 v[6:7], v[138:139], v[6:7], v[174:175]
	v_pk_fma_f32 v[4:5], v[136:137], v[4:5], v[172:173]
	s_waitcnt vmcnt(0)
	v_pk_fma_f32 v[2:3], v[146:147], v[68:69], v[2:3]
	s_and_b64 vcc, exec, s[0:1]
	v_pk_fma_f32 v[0:1], v[144:145], v[66:67], v[0:1]
	s_cbranch_vccnz .LBB0_655
	v_lshl_add_u64 v[66:67], s[10:11], 0, v[62:63]
	global_store_dwordx4 v[66:67], v[28:31], off sc0 sc1
	global_store_dwordx4 v[66:67], v[24:27], off offset:1024 sc0 sc1
	global_store_dwordx4 v[66:67], v[20:23], off offset:2048 sc0 sc1
	global_store_dwordx4 v[66:67], v[16:19], off offset:3072 sc0 sc1
	v_add_co_u32_e32 v66, vcc, 0x1000, v66
	s_nop 1
	v_addc_co_u32_e32 v67, vcc, 0, v67, vcc
	global_store_dwordx4 v[66:67], v[12:15], off sc0 sc1
	global_store_dwordx4 v[66:67], v[8:11], off offset:1024 sc0 sc1
	global_store_dwordx4 v[66:67], v[4:7], off offset:2048 sc0 sc1
	global_store_dwordx4 v[66:67], v[0:3], off offset:3072 sc0 sc1
	s_branch .LBB0_655

; #define LAS __attribute__((address_space(3)))
; __device__ __forceinline__ unsigned pk2(float lo, float hi) { unsigned r; asm("v_cvt_pk_bf16_f32 %0, %1, %2" : "=v"(r) : "v"(lo), "v"(hi)); return r; }
; __device__ __forceinline__ void tr_item(const float* W, int K, int N, bf16_t* WT, int ldt, LAS float* scr, int item, int lane, int mapmode, int p0, int p1) {
;     ...
;     for (int j = 0; j < 4; ++j) { const int n = (lane >> 3) + 8 * j; const LAS float* s = scr + (8 * c) * 33 + n;
;         u32x4 o; o.x = pk2(s[0 * 33], s[1 * 33]); o.y = pk2(s[2 * 33], s[3 * 33]); o.z = pk2(s[4 * 33], s[5 * 33]); o.w = pk2(s[6 * 33], s[7 * 33]);
;         const int ns = n0 + n; int dst;
;         if (mapmode == 0) dst = p0 + (ns & ~255) + 128 * ((ns >> 5) & 1) + 32 * ((ns >> 6) & 3) + (ns & 31);
;         else if (mapmode == 1) dst = (ns >= p0 && ns < p1) ? ((ns & ~127) + il128(ns & 127)) : ns;
;         else dst = 256 * (ns >> 7) + 128 * ((ns >> 2) & 1) + 32 * ((ns >> 5) & 3) + 8 * ((ns >> 3) & 3) + 4 * p0 + (ns & 3);
;         *(u32x4*)(WT + (size_t)dst * ldt + k0 + 8 * c) = o; }
.LBB0_660:
	v_mul_lo_u32 v44, v6, s12
	v_ashrrev_i32_e32 v45, 31, v44
	v_lshl_add_u64 v[28:29], v[28:29], 0, v[44:45]
	global_store_dwordx4 v[28:29], v[0:3], off sc0 sc1
	s_waitcnt lgkmcnt(0)

; __device__ __forceinline__ void tr_item(const float* W, int K, int N, bf16_t* WT, int ldt, LAS float* scr, int item, int lane, int mapmode, int p0, int p1) {
;     const int nblk = N / 32, kb = item / nblk, nb = item % nblk, k0 = 64 * kb, n0 = 32 * nb;
; #pragma unroll 8
;     for (int i = 0; i < 32; ++i) { const int kk = 2 * i + (lane >> 5); scr[kk * 33 + (lane & 31)] = W[(size_t)(k0 + kk) * N + n0 + (lane & 31)]; }
.LBB0_668:
	s_lshl_b32 s16, s8, 1
	s_lshl_b32 s17, s9, 1
	v_or_b32_e32 v6, s16, v5
	v_or_b32_e32 v43, s17, v4
	s_add_i32 s18, s16, 4
	s_add_i32 s19, s17, 4
	s_add_i32 s20, s16, 8
	s_add_i32 s21, s17, 8
	s_add_i32 s22, s16, 12
	s_add_i32 s23, s17, 12
	s_add_i32 s24, s16, 16
	s_add_i32 s25, s17, 16
	s_add_i32 s27, s16, 20
	s_add_i32 s33, s17, 20
	s_add_i32 s35, s16, 24
	s_add_i32 s36, s17, 24
	s_add_i32 s16, s16, 28
	s_add_i32 s17, s17, 28
	v_add_u32_e32 v28, s0, v43
	v_or_b32_e32 v72, s18, v5
	v_or_b32_e32 v73, s19, v4
	v_or_b32_e32 v74, s20, v5
	v_or_b32_e32 v75, s21, v4
	v_or_b32_e32 v76, s22, v5
	v_or_b32_e32 v77, s23, v4
	v_or_b32_e32 v78, s24, v5
	v_or_b32_e32 v79, s25, v4
	v_or_b32_e32 v80, s27, v5
	v_or_b32_e32 v81, s33, v4
	v_or_b32_e32 v82, s35, v5
	v_or_b32_e32 v83, s36, v4
	v_or_b32_e32 v84, s16, v5
	v_or_b32_e32 v85, s17, v4
	v_add_u32_e32 v2, s1, v6
	v_ashrrev_i32_e32 v29, 31, v28
	v_add_u32_e32 v44, s1, v72
	v_add_u32_e32 v46, s0, v73
	v_add_u32_e32 v48, s1, v74
	v_add_u32_e32 v50, s0, v75
	v_add_u32_e32 v52, s1, v76
	v_add_u32_e32 v54, s0, v77
	v_add_u32_e32 v56, s1, v78
	v_add_u32_e32 v58, s0, v79
	v_add_u32_e32 v60, s1, v80
	v_add_u32_e32 v62, s0, v81
	v_add_u32_e32 v64, s1, v82
	v_add_u32_e32 v66, s0, v83
	v_add_u32_e32 v68, s1, v84
	v_add_u32_e32 v70, s0, v85
	v_ashrrev_i32_e32 v3, 31, v2
	v_lshlrev_b64 v[28:29], 13, v[28:29]
	v_ashrrev_i32_e32 v47, 31, v46
	v_ashrrev_i32_e32 v45, 31, v44
	v_ashrrev_i32_e32 v51, 31, v50
	v_ashrrev_i32_e32 v49, 31, v48
	v_ashrrev_i32_e32 v55, 31, v54
	v_ashrrev_i32_e32 v53, 31, v52
	v_ashrrev_i32_e32 v59, 31, v58
	v_ashrrev_i32_e32 v57, 31, v56
	v_ashrrev_i32_e32 v63, 31, v62
	v_ashrrev_i32_e32 v61, 31, v60
	v_ashrrev_i32_e32 v67, 31, v66
	v_ashrrev_i32_e32 v65, 31, v64
	v_ashrrev_i32_e32 v71, 31, v70
	v_ashrrev_i32_e32 v69, 31, v68
	v_lshlrev_b64 v[2:3], 13, v[2:3]
	v_lshl_add_u64 v[28:29], v[0:1], 0, v[28:29]
	v_lshlrev_b64 v[44:45], 13, v[44:45]
	v_lshlrev_b64 v[46:47], 13, v[46:47]
	v_lshlrev_b64 v[48:49], 13, v[48:49]
	v_lshlrev_b64 v[50:51], 13, v[50:51]
	v_lshlrev_b64 v[52:53], 13, v[52:53]
	v_lshlrev_b64 v[54:55], 13, v[54:55]
	v_lshlrev_b64 v[56:57], 13, v[56:57]
	v_lshlrev_b64 v[58:59], 13, v[58:59]
	v_lshlrev_b64 v[60:61], 13, v[60:61]
	v_lshlrev_b64 v[62:63], 13, v[62:63]
	v_lshlrev_b64 v[64:65], 13, v[64:65]
	v_lshlrev_b64 v[66:67], 13, v[66:67]
	v_lshlrev_b64 v[68:69], 13, v[68:69]
	v_lshlrev_b64 v[70:71], 13, v[70:71]
	v_lshl_add_u64 v[2:3], v[0:1], 0, v[2:3]
	v_lshl_add_u64 v[46:47], v[0:1], 0, v[46:47]
	v_lshl_add_u64 v[44:45], v[0:1], 0, v[44:45]
	v_lshl_add_u64 v[50:51], v[0:1], 0, v[50:51]
	v_lshl_add_u64 v[48:49], v[0:1], 0, v[48:49]
	v_lshl_add_u64 v[54:55], v[0:1], 0, v[54:55]
	v_lshl_add_u64 v[52:53], v[0:1], 0, v[52:53]
	v_lshl_add_u64 v[58:59], v[0:1], 0, v[58:59]
	v_lshl_add_u64 v[56:57], v[0:1], 0, v[56:57]
	v_lshl_add_u64 v[62:63], v[0:1], 0, v[62:63]
	v_lshl_add_u64 v[60:61], v[0:1], 0, v[60:61]
	v_lshl_add_u64 v[66:67], v[0:1], 0, v[66:67]
	v_lshl_add_u64 v[64:65], v[0:1], 0, v[64:65]
	v_lshl_add_u64 v[70:71], v[0:1], 0, v[70:71]
	v_lshl_add_u64 v[68:69], v[0:1], 0, v[68:69]
	global_load_dword v86, v[28:29], off
	global_load_dword v87, v[2:3], off
	global_load_dword v88, v[46:47], off
	global_load_dword v89, v[44:45], off
	global_load_dword v90, v[50:51], off
	global_load_dword v91, v[48:49], off
	global_load_dword v92, v[54:55], off
	global_load_dword v93, v[52:53], off
	global_load_dword v94, v[58:59], off
	global_load_dword v95, v[56:57], off
	global_load_dword v96, v[62:63], off
	global_load_dword v97, v[60:61], off
	global_load_dword v98, v[66:67], off
	global_load_dword v99, v[64:65], off
	global_load_dword v100, v[70:71], off
	global_load_dword v101, v[68:69], off
	s_add_i32 s9, s9, 16
	s_add_i32 s8, s8, 16
	s_add_i32 s15, s15, -16
	v_mad_u64_u32 v[2:3], s[16:17], v43, s10, v[10:11]
	s_cmp_lg_u32 s15, 0
	v_mad_u64_u32 v[28:29], s[16:17], v6, s10, v[10:11]
	v_mad_u64_u32 v[44:45], s[16:17], v73, s10, v[10:11]
	v_mad_u64_u32 v[46:47], s[16:17], v72, s10, v[10:11]
	v_mad_u64_u32 v[48:49], s[16:17], v75, s10, v[10:11]
	v_mad_u64_u32 v[50:51], s[16:17], v74, s10, v[10:11]
	v_mad_u64_u32 v[52:53], s[16:17], v77, s10, v[10:11]
	v_mad_u64_u32 v[54:55], s[16:17], v76, s10, v[10:11]
	v_mad_u64_u32 v[56:57], s[16:17], v79, s10, v[10:11]
	v_mad_u64_u32 v[58:59], s[16:17], v78, s10, v[10:11]
	v_mad_u64_u32 v[60:61], s[16:17], v81, s10, v[10:11]
	v_mad_u64_u32 v[62:63], s[16:17], v80, s10, v[10:11]
	v_mad_u64_u32 v[64:65], s[16:17], v83, s10, v[10:11]
	v_mad_u64_u32 v[66:67], s[16:17], v82, s10, v[10:11]
	v_mad_u64_u32 v[68:69], s[16:17], v85, s10, v[10:11]
	v_mad_u64_u32 v[70:71], s[16:17], v84, s10, v[10:11]
	s_waitcnt vmcnt(15)
	ds_write_b32 v2, v86
	s_waitcnt vmcnt(14)
	ds_write_b32 v28, v87
	s_waitcnt vmcnt(13)
	ds_write_b32 v44, v88
	s_waitcnt vmcnt(12)
	ds_write_b32 v46, v89
	s_waitcnt vmcnt(11)
	ds_write_b32 v48, v90
	s_waitcnt vmcnt(10)
	ds_write_b32 v50, v91
	s_waitcnt vmcnt(9)
	ds_write_b32 v52, v92
	s_waitcnt vmcnt(8)
	ds_write_b32 v54, v93
	s_waitcnt vmcnt(7)
	ds_write_b32 v56, v94
	s_waitcnt vmcnt(6)
	ds_write_b32 v58, v95
	s_waitcnt vmcnt(5)
	ds_write_b32 v60, v96
	s_waitcnt vmcnt(4)
	ds_write_b32 v62, v97
	s_waitcnt vmcnt(3)
	ds_write_b32 v64, v98
	s_waitcnt vmcnt(2)
	ds_write_b32 v66, v99
	s_waitcnt vmcnt(1)
	ds_write_b32 v68, v100
	s_waitcnt vmcnt(0)
	ds_write_b32 v70, v101
	s_cbranch_scc1 .LBB0_668
; #define LAS __attribute__((address_space(3)))
; __device__ __forceinline__ unsigned pk2(float lo, float hi) { unsigned r; asm("v_cvt_pk_bf16_f32 %0, %1, %2" : "=v"(r) : "v"(lo), "v"(hi)); return r; }
; __device__ __forceinline__ void tr_item(const float* W, int K, int N, bf16_t* WT, int ldt, LAS float* scr, int item, int lane, int mapmode, int p0, int p1) {
;     ...
;     asm volatile("s_waitcnt lgkmcnt(0)" ::: "memory");
;     const int c = lane & 7;
; #pragma unroll
;     for (int j = 0; j < 4; ++j) { const int n = (lane >> 3) + 8 * j; const LAS float* s = scr + (8 * c) * 33 + n;
;         u32x4 o; o.x = pk2(s[0 * 33], s[1 * 33]); o.y = pk2(s[2 * 33], s[3 * 33]); o.z = pk2(s[4 * 33], s[5 * 33]); o.w = pk2(s[6 * 33], s[7 * 33]);
;         const int ns = n0 + n; int dst;
;         if (mapmode == 0) dst = p0 + (ns & ~255) + 128 * ((ns >> 5) & 1) + 32 * ((ns >> 6) & 3) + (ns & 31);
;         else if (mapmode == 1) dst = (ns >= p0 && ns < p1) ? ((ns & ~127) + il128(ns & 127)) : ns;
;         else dst = 256 * (ns >> 7) + 128 * ((ns >> 2) & 1) + 32 * ((ns >> 5) & 3) + 8 * ((ns >> 3) & 3) + 4 * p0 + (ns & 3);
;         *(u32x4*)(WT + (size_t)dst * ldt + k0 + 8 * c) = o; }
;     asm volatile("s_waitcnt lgkmcnt(0)" ::: "memory");
	s_mov_b32 s1, s3
	v_lshl_add_u64 v[58:59], s[0:1], 1, v[12:13]
	s_and_b32 s1, s2, 0x80
	s_lshl_b32 s2, s14, 4
	s_waitcnt lgkmcnt(0)
	s_and_b32 s0, s7, 0x700
	s_and_b32 s2, s2, 0x60
	ds_read2_b32 v[28:29], v30 offset0:33 offset1:41
	ds_read2_b32 v[44:45], v30 offset1:8
	ds_read2_b32 v[46:47], v30 offset0:66 offset1:74
	ds_read2_b32 v[48:49], v30 offset0:99 offset1:107
	ds_read2_b32 v[50:51], v30 offset0:132 offset1:140
	ds_read2_b32 v[52:53], v30 offset0:165 offset1:173
	ds_read2_b32 v[54:55], v30 offset0:198 offset1:206
	ds_read2_b32 v[56:57], v30 offset0:231 offset1:239
	s_or_b32 s0, s0, s2
	s_or_b32 s0, s0, s1
	v_or_b32_e32 v6, s0, v11
	v_mul_u32_u24_e32 v6, 0x2c80, v6
	v_lshl_add_u64 v[60:61], v[58:59], 0, v[6:7]
	s_waitcnt lgkmcnt(6)
	v_cvt_pk_bf16_f32 v0, v44, v28
	s_waitcnt lgkmcnt(4)
	v_cvt_pk_bf16_f32 v1, v46, v48
	s_waitcnt lgkmcnt(2)
	v_cvt_pk_bf16_f32 v2, v50, v52
	s_waitcnt lgkmcnt(0)
	v_cvt_pk_bf16_f32 v3, v54, v56
	global_store_dwordx4 v[60:61], v[0:3], off sc0 sc1
	v_or_b32_e32 v6, s0, v31
	v_mul_u32_u24_e32 v6, 0x2c80, v6
	v_cvt_pk_bf16_f32 v0, v45, v29
	v_cvt_pk_bf16_f32 v1, v47, v49
	v_cvt_pk_bf16_f32 v2, v51, v53
	v_cvt_pk_bf16_f32 v3, v55, v57
	ds_read2_b32 v[44:45], v30 offset0:16 offset1:24
	ds_read2_b32 v[46:47], v30 offset0:49 offset1:57
	ds_read2_b32 v[48:49], v30 offset0:82 offset1:90
	ds_read2_b32 v[50:51], v30 offset0:115 offset1:123
	ds_read2_b32 v[52:53], v30 offset0:148 offset1:156
	ds_read2_b32 v[54:55], v30 offset0:181 offset1:189
	ds_read2_b32 v[56:57], v30 offset0:214 offset1:222
	ds_read2_b32 v[60:61], v30 offset0:247 offset1:255
	v_lshl_add_u64 v[28:29], v[58:59], 0, v[6:7]
	v_or_b32_e32 v6, s0, v32
	v_mul_u32_u24_e32 v6, 0x2c80, v6
	global_store_dwordx4 v[28:29], v[0:3], off sc0 sc1
	v_lshl_add_u64 v[28:29], v[58:59], 0, v[6:7]
	v_or_b32_e32 v6, s0, v33
	v_mul_u32_u24_e32 v6, 0x2c80, v6
	s_waitcnt lgkmcnt(6)
	v_cvt_pk_bf16_f32 v0, v44, v46
	s_waitcnt lgkmcnt(4)
	v_cvt_pk_bf16_f32 v1, v48, v50
	s_waitcnt lgkmcnt(2)
	v_cvt_pk_bf16_f32 v2, v52, v54
	s_waitcnt lgkmcnt(0)
	v_cvt_pk_bf16_f32 v3, v56, v60
	global_store_dwordx4 v[28:29], v[0:3], off sc0 sc1
	v_lshl_add_u64 v[28:29], v[58:59], 0, v[6:7]
	s_mov_b64 s[0:1], 0
	v_cvt_pk_bf16_f32 v0, v45, v47
	v_cvt_pk_bf16_f32 v1, v49, v51
	v_cvt_pk_bf16_f32 v2, v53, v55
	v_cvt_pk_bf16_f32 v3, v57, v61
	global_store_dwordx4 v[28:29], v[0:3], off sc0 sc1
	s_waitcnt lgkmcnt(0)

; #define LAS __attribute__((address_space(3)))
; __device__ __forceinline__ unsigned pk2(float lo, float hi) { unsigned r; asm("v_cvt_pk_bf16_f32 %0, %1, %2" : "=v"(r) : "v"(lo), "v"(hi)); return r; }
; __device__ __forceinline__ void tr_item(const float* W, int K, int N, bf16_t* WT, int ldt, LAS float* scr, int item, int lane, int mapmode, int p0, int p1) {
;     const int nblk = N / 32, kb = item / nblk, nb = item % nblk, k0 = 64 * kb, n0 = 32 * nb;
; #pragma unroll 8
;     for (int i = 0; i < 32; ++i) { const int kk = 2 * i + (lane >> 5); scr[kk * 33 + (lane & 31)] = W[(size_t)(k0 + kk) * N + n0 + (lane & 31)]; }
;     asm volatile("s_waitcnt lgkmcnt(0)" ::: "memory");
;     const int c = lane & 7;
; #pragma unroll
;     for (int j = 0; j < 4; ++j) { const int n = (lane >> 3) + 8 * j; const LAS float* s = scr + (8 * c) * 33 + n;
;         u32x4 o; o.x = pk2(s[0 * 33], s[1 * 33]); o.y = pk2(s[2 * 33], s[3 * 33]); o.z = pk2(s[4 * 33], s[5 * 33]); o.w = pk2(s[6 * 33], s[7 * 33]);
;         const int ns = n0 + n; int dst;
;         if (mapmode == 0) dst = p0 + (ns & ~255) + 128 * ((ns >> 5) & 1) + 32 * ((ns >> 6) & 3) + (ns & 31);
;         else if (mapmode == 1) dst = (ns >= p0 && ns < p1) ? ((ns & ~127) + il128(ns & 127)) : ns;
;         else dst = 256 * (ns >> 7) + 128 * ((ns >> 2) & 1) + 32 * ((ns >> 5) & 3) + 8 * ((ns >> 3) & 3) + 4 * p0 + (ns & 3);
;         *(u32x4*)(WT + (size_t)dst * ldt + k0 + 8 * c) = o; }
;     asm volatile("s_waitcnt lgkmcnt(0)" ::: "memory");
.LBB0_672:
	s_lshl_b32 s15, s7, 1
	s_lshl_b32 s16, s8, 1
	v_or_b32_e32 v6, s15, v5
	v_or_b32_e32 v43, s16, v4
	s_add_i32 s17, s15, 4
	s_add_i32 s18, s16, 4
	s_add_i32 s19, s15, 8
	s_add_i32 s20, s16, 8
	s_add_i32 s21, s15, 12
	s_add_i32 s22, s16, 12
	s_add_i32 s23, s15, 16
	s_add_i32 s24, s16, 16
	s_add_i32 s25, s15, 20
	s_add_i32 s27, s16, 20
	s_add_i32 s33, s15, 24
	s_add_i32 s35, s16, 24
	s_add_i32 s15, s15, 28
	s_add_i32 s16, s16, 28
	v_add_u32_e32 v2, s0, v43
	v_or_b32_e32 v72, s17, v5
	v_or_b32_e32 v73, s18, v4
	v_or_b32_e32 v74, s19, v5
	v_or_b32_e32 v75, s20, v4
	v_or_b32_e32 v76, s21, v5
	v_or_b32_e32 v77, s22, v4
	v_or_b32_e32 v78, s23, v5
	v_or_b32_e32 v79, s24, v4
	v_or_b32_e32 v80, s25, v5
	v_or_b32_e32 v81, s27, v4
	v_or_b32_e32 v82, s33, v5
	v_or_b32_e32 v83, s35, v4
	v_or_b32_e32 v84, s15, v5
	v_or_b32_e32 v85, s16, v4
	v_add_u32_e32 v28, s2, v6
	v_mad_u64_u32 v[2:3], s[16:17], v2, s11, v[0:1]
	v_add_u32_e32 v46, s2, v72
	v_add_u32_e32 v44, s0, v73
	v_add_u32_e32 v50, s2, v74
	v_add_u32_e32 v48, s0, v75
	v_add_u32_e32 v54, s2, v76
	v_add_u32_e32 v52, s0, v77
	v_add_u32_e32 v58, s2, v78
	v_add_u32_e32 v56, s0, v79
	v_add_u32_e32 v62, s2, v80
	v_add_u32_e32 v60, s0, v81
	v_add_u32_e32 v66, s2, v82
	v_add_u32_e32 v64, s0, v83
	v_add_u32_e32 v70, s2, v84
	v_add_u32_e32 v68, s0, v85
	v_mad_u64_u32 v[28:29], s[16:17], v28, s11, v[0:1]
	v_mad_u64_u32 v[44:45], s[16:17], v44, s11, v[0:1]
	v_mad_u64_u32 v[46:47], s[16:17], v46, s11, v[0:1]
	v_mad_u64_u32 v[48:49], s[16:17], v48, s11, v[0:1]
	v_mad_u64_u32 v[50:51], s[16:17], v50, s11, v[0:1]
	v_mad_u64_u32 v[52:53], s[16:17], v52, s11, v[0:1]
	v_mad_u64_u32 v[54:55], s[16:17], v54, s11, v[0:1]
	v_mad_u64_u32 v[56:57], s[16:17], v56, s11, v[0:1]
	v_mad_u64_u32 v[58:59], s[16:17], v58, s11, v[0:1]
	v_mad_u64_u32 v[60:61], s[16:17], v60, s11, v[0:1]
	v_mad_u64_u32 v[62:63], s[16:17], v62, s11, v[0:1]
	v_mad_u64_u32 v[64:65], s[16:17], v64, s11, v[0:1]
	v_mad_u64_u32 v[66:67], s[16:17], v66, s11, v[0:1]
	v_mad_u64_u32 v[68:69], s[16:17], v68, s11, v[0:1]
	v_mad_u64_u32 v[70:71], s[16:17], v70, s11, v[0:1]
	global_load_dword v86, v[2:3], off
	global_load_dword v87, v[28:29], off
	global_load_dword v88, v[44:45], off
	global_load_dword v89, v[46:47], off
	global_load_dword v90, v[48:49], off
	global_load_dword v91, v[50:51], off
	global_load_dword v92, v[52:53], off
	global_load_dword v93, v[54:55], off
	global_load_dword v94, v[56:57], off
	global_load_dword v95, v[58:59], off
	global_load_dword v96, v[60:61], off
	global_load_dword v97, v[62:63], off
	global_load_dword v98, v[64:65], off
	global_load_dword v99, v[66:67], off
	global_load_dword v100, v[68:69], off
	global_load_dword v101, v[70:71], off
	s_add_i32 s8, s8, 16
	s_add_i32 s7, s7, 16
	s_add_i32 s9, s9, -16
	v_mad_u64_u32 v[2:3], s[16:17], v43, s10, v[10:11]
	s_cmp_lg_u32 s9, 0
	v_mad_u64_u32 v[28:29], s[16:17], v6, s10, v[10:11]
	v_mad_u64_u32 v[44:45], s[16:17], v73, s10, v[10:11]
	v_mad_u64_u32 v[46:47], s[16:17], v72, s10, v[10:11]
	v_mad_u64_u32 v[48:49], s[16:17], v75, s10, v[10:11]
	v_mad_u64_u32 v[50:51], s[16:17], v74, s10, v[10:11]
	v_mad_u64_u32 v[52:53], s[16:17], v77, s10, v[10:11]
	v_mad_u64_u32 v[54:55], s[16:17], v76, s10, v[10:11]
	v_mad_u64_u32 v[56:57], s[16:17], v79, s10, v[10:11]
	v_mad_u64_u32 v[58:59], s[16:17], v78, s10, v[10:11]
	v_mad_u64_u32 v[60:61], s[16:17], v81, s10, v[10:11]
	v_mad_u64_u32 v[62:63], s[16:17], v80, s10, v[10:11]
	v_mad_u64_u32 v[64:65], s[16:17], v83, s10, v[10:11]
	v_mad_u64_u32 v[66:67], s[16:17], v82, s10, v[10:11]
	v_mad_u64_u32 v[68:69], s[16:17], v85, s10, v[10:11]
	v_mad_u64_u32 v[70:71], s[16:17], v84, s10, v[10:11]
	s_waitcnt vmcnt(15)
	ds_write_b32 v2, v86
	s_waitcnt vmcnt(14)
	ds_write_b32 v28, v87
	s_waitcnt vmcnt(13)
	ds_write_b32 v44, v88
	s_waitcnt vmcnt(12)
	ds_write_b32 v46, v89
	s_waitcnt vmcnt(11)
	ds_write_b32 v48, v90
	s_waitcnt vmcnt(10)
	ds_write_b32 v50, v91
	s_waitcnt vmcnt(9)
	ds_write_b32 v52, v92
	s_waitcnt vmcnt(8)
	ds_write_b32 v54, v93
	s_waitcnt vmcnt(7)
	ds_write_b32 v56, v94
	s_waitcnt vmcnt(6)
	ds_write_b32 v58, v95
	s_waitcnt vmcnt(5)
	ds_write_b32 v60, v96
	s_waitcnt vmcnt(4)
	ds_write_b32 v62, v97
	s_waitcnt vmcnt(3)
	ds_write_b32 v64, v98
	s_waitcnt vmcnt(2)
	ds_write_b32 v66, v99
	s_waitcnt vmcnt(1)
	ds_write_b32 v68, v100
	s_waitcnt vmcnt(0)
	ds_write_b32 v70, v101
	s_cbranch_scc1 .LBB0_672
	s_and_b32 s1, 0xffff, s1
	s_and_b32 s0, 0xffff, s0
	s_waitcnt lgkmcnt(0)
	s_lshl_b32 s2, s0, 1
	s_lshl_b32 s0, s1, 1
	ds_read2_b32 v[28:29], v30 offset0:33 offset1:41
	ds_read2_b32 v[44:45], v30 offset1:8
	ds_read2_b32 v[46:47], v30 offset0:66 offset1:74
	ds_read2_b32 v[48:49], v30 offset0:99 offset1:107
	ds_read2_b32 v[50:51], v30 offset0:132 offset1:140
	ds_read2_b32 v[52:53], v30 offset0:165 offset1:173
	ds_read2_b32 v[54:55], v30 offset0:198 offset1:206
	ds_read2_b32 v[56:57], v30 offset0:231 offset1:239
	s_and_b32 s0, s0, 0x3f00
	s_and_b32 s1, s1, 0x60
	s_or_b32 s0, s1, s0
	v_or_b32_e32 v6, s0, v36
	v_lshl_add_u64 v[58:59], v[16:17], 0, s[2:3]
	v_mul_u32_u24_e32 v6, 0x1080, v6
	v_lshl_add_u64 v[60:61], v[58:59], 0, v[6:7]
	s_waitcnt lgkmcnt(6)
	v_cvt_pk_bf16_f32 v0, v44, v28
	s_waitcnt lgkmcnt(4)
	v_cvt_pk_bf16_f32 v1, v46, v48
	s_waitcnt lgkmcnt(2)
	v_cvt_pk_bf16_f32 v2, v50, v52
	s_waitcnt lgkmcnt(0)
	v_cvt_pk_bf16_f32 v3, v54, v56
	global_store_dwordx4 v[60:61], v[0:3], off sc0 sc1
	v_or_b32_e32 v6, s0, v37
	v_mul_u32_u24_e32 v6, 0x1080, v6
	v_cvt_pk_bf16_f32 v0, v45, v29
	v_cvt_pk_bf16_f32 v1, v47, v49
	v_cvt_pk_bf16_f32 v2, v51, v53
	v_cvt_pk_bf16_f32 v3, v55, v57
	ds_read2_b32 v[44:45], v30 offset0:16 offset1:24
	ds_read2_b32 v[46:47], v30 offset0:49 offset1:57
	ds_read2_b32 v[48:49], v30 offset0:82 offset1:90
	ds_read2_b32 v[50:51], v30 offset0:115 offset1:123
	ds_read2_b32 v[52:53], v30 offset0:148 offset1:156
	ds_read2_b32 v[54:55], v30 offset0:181 offset1:189
	ds_read2_b32 v[56:57], v30 offset0:214 offset1:222
	ds_read2_b32 v[60:61], v30 offset0:247 offset1:255
	v_lshl_add_u64 v[28:29], v[58:59], 0, v[6:7]
	v_or_b32_e32 v6, s0, v38
	v_mul_u32_u24_e32 v6, 0x1080, v6
	global_store_dwordx4 v[28:29], v[0:3], off sc0 sc1
	v_lshl_add_u64 v[28:29], v[58:59], 0, v[6:7]
	v_or_b32_e32 v6, s0, v39
	v_mul_u32_u24_e32 v6, 0x1080, v6
	s_waitcnt lgkmcnt(6)
	v_cvt_pk_bf16_f32 v0, v44, v46
	s_waitcnt lgkmcnt(4)
	v_cvt_pk_bf16_f32 v1, v48, v50
	s_waitcnt lgkmcnt(2)
	v_cvt_pk_bf16_f32 v2, v52, v54
	s_waitcnt lgkmcnt(0)
	v_cvt_pk_bf16_f32 v3, v56, v60
	global_store_dwordx4 v[28:29], v[0:3], off sc0 sc1
	v_lshl_add_u64 v[28:29], v[58:59], 0, v[6:7]
	s_nop 0
	v_cvt_pk_bf16_f32 v0, v45, v47
	v_cvt_pk_bf16_f32 v1, v49, v51
	v_cvt_pk_bf16_f32 v2, v53, v55
	v_cvt_pk_bf16_f32 v3, v57, v61
	global_store_dwordx4 v[28:29], v[0:3], off sc0 sc1
	s_waitcnt lgkmcnt(0)

; #define LAS __attribute__((address_space(3)))
; __device__ __forceinline__ unsigned pk2(float lo, float hi) { unsigned r; asm("v_cvt_pk_bf16_f32 %0, %1, %2" : "=v"(r) : "v"(lo), "v"(hi)); return r; }
; __device__ __forceinline__ void tr_item(const float* W, int K, int N, bf16_t* WT, int ldt, LAS float* scr, int item, int lane, int mapmode, int p0, int p1) {
;     const int nblk = N / 32, kb = item / nblk, nb = item % nblk, k0 = 64 * kb, n0 = 32 * nb;
; #pragma unroll 8
;     for (int i = 0; i < 32; ++i) { const int kk = 2 * i + (lane >> 5); scr[kk * 33 + (lane & 31)] = W[(size_t)(k0 + kk) * N + n0 + (lane & 31)]; }
;     asm volatile("s_waitcnt lgkmcnt(0)" ::: "memory");
;     const int c = lane & 7;
; #pragma unroll
;     for (int j = 0; j < 4; ++j) { const int n = (lane >> 3) + 8 * j; const LAS float* s = scr + (8 * c) * 33 + n;
;         u32x4 o; o.x = pk2(s[0 * 33], s[1 * 33]); o.y = pk2(s[2 * 33], s[3 * 33]); o.z = pk2(s[4 * 33], s[5 * 33]); o.w = pk2(s[6 * 33], s[7 * 33]);
;         const int ns = n0 + n; int dst;
;         if (mapmode == 0) dst = p0 + (ns & ~255) + 128 * ((ns >> 5) & 1) + 32 * ((ns >> 6) & 3) + (ns & 31);
;         else if (mapmode == 1) dst = (ns >= p0 && ns < p1) ? ((ns & ~127) + il128(ns & 127)) : ns;
;         else dst = 256 * (ns >> 7) + 128 * ((ns >> 2) & 1) + 32 * ((ns >> 5) & 3) + 8 * ((ns >> 3) & 3) + 4 * p0 + (ns & 3);
;         *(u32x4*)(WT + (size_t)dst * ldt + k0 + 8 * c) = o; }
;     asm volatile("s_waitcnt lgkmcnt(0)" ::: "memory");
.LBB0_677:
	s_lshl_b32 s9, s6, 1
	s_lshl_b32 s15, s7, 1
	v_or_b32_e32 v6, s9, v5
	v_or_b32_e32 v43, s15, v4
	s_add_i32 s16, s9, 4
	s_add_i32 s17, s15, 4
	s_add_i32 s18, s9, 8
	s_add_i32 s19, s15, 8
	s_add_i32 s20, s9, 12
	s_add_i32 s21, s15, 12
	s_add_i32 s22, s9, 16
	s_add_i32 s23, s15, 16
	s_add_i32 s24, s9, 20
	s_add_i32 s25, s15, 20
	s_add_i32 s27, s9, 24
	s_add_i32 s33, s15, 24
	s_add_i32 s9, s9, 28
	s_add_i32 s15, s15, 28
	v_add_u32_e32 v2, s0, v43
	v_or_b32_e32 v72, s16, v5
	v_or_b32_e32 v73, s17, v4
	v_or_b32_e32 v74, s18, v5
	v_or_b32_e32 v75, s19, v4
	v_or_b32_e32 v76, s20, v5
	v_or_b32_e32 v77, s21, v4
	v_or_b32_e32 v78, s22, v5
	v_or_b32_e32 v79, s23, v4
	v_or_b32_e32 v80, s24, v5
	v_or_b32_e32 v81, s25, v4
	v_or_b32_e32 v82, s27, v5
	v_or_b32_e32 v83, s33, v4
	v_or_b32_e32 v84, s9, v5
	v_or_b32_e32 v85, s15, v4
	v_add_u32_e32 v28, s2, v6
	v_mad_u64_u32 v[2:3], s[16:17], v2, s11, v[0:1]
	v_add_u32_e32 v46, s2, v72
	v_add_u32_e32 v44, s0, v73
	v_add_u32_e32 v50, s2, v74
	v_add_u32_e32 v48, s0, v75
	v_add_u32_e32 v54, s2, v76
	v_add_u32_e32 v52, s0, v77
	v_add_u32_e32 v58, s2, v78
	v_add_u32_e32 v56, s0, v79
	v_add_u32_e32 v62, s2, v80
	v_add_u32_e32 v60, s0, v81
	v_add_u32_e32 v66, s2, v82
	v_add_u32_e32 v64, s0, v83
	v_add_u32_e32 v70, s2, v84
	v_add_u32_e32 v68, s0, v85
	v_mad_u64_u32 v[28:29], s[16:17], v28, s11, v[0:1]
	v_mad_u64_u32 v[44:45], s[16:17], v44, s11, v[0:1]
	v_mad_u64_u32 v[46:47], s[16:17], v46, s11, v[0:1]
	v_mad_u64_u32 v[48:49], s[16:17], v48, s11, v[0:1]
	v_mad_u64_u32 v[50:51], s[16:17], v50, s11, v[0:1]
	v_mad_u64_u32 v[52:53], s[16:17], v52, s11, v[0:1]
	v_mad_u64_u32 v[54:55], s[16:17], v54, s11, v[0:1]
	v_mad_u64_u32 v[56:57], s[16:17], v56, s11, v[0:1]
	v_mad_u64_u32 v[58:59], s[16:17], v58, s11, v[0:1]
	v_mad_u64_u32 v[60:61], s[16:17], v60, s11, v[0:1]
	v_mad_u64_u32 v[62:63], s[16:17], v62, s11, v[0:1]
	v_mad_u64_u32 v[64:65], s[16:17], v64, s11, v[0:1]
	v_mad_u64_u32 v[66:67], s[16:17], v66, s11, v[0:1]
	v_mad_u64_u32 v[68:69], s[16:17], v68, s11, v[0:1]
	v_mad_u64_u32 v[70:71], s[16:17], v70, s11, v[0:1]
	global_load_dword v86, v[2:3], off
	global_load_dword v87, v[28:29], off
	global_load_dword v88, v[44:45], off
	global_load_dword v89, v[46:47], off
	global_load_dword v90, v[48:49], off
	global_load_dword v91, v[50:51], off
	global_load_dword v92, v[52:53], off
	global_load_dword v93, v[54:55], off
	global_load_dword v94, v[56:57], off
	global_load_dword v95, v[58:59], off
	global_load_dword v96, v[60:61], off
	global_load_dword v97, v[62:63], off
	global_load_dword v98, v[64:65], off
	global_load_dword v99, v[66:67], off
	global_load_dword v100, v[68:69], off
	global_load_dword v101, v[70:71], off
	s_add_i32 s7, s7, 16
	s_add_i32 s6, s6, 16
	s_add_i32 s8, s8, -16
	v_mad_u64_u32 v[2:3], s[16:17], v43, s10, v[10:11]
	s_cmp_lg_u32 s8, 0
	v_mad_u64_u32 v[28:29], s[16:17], v6, s10, v[10:11]
	v_mad_u64_u32 v[44:45], s[16:17], v73, s10, v[10:11]
	v_mad_u64_u32 v[46:47], s[16:17], v72, s10, v[10:11]
	v_mad_u64_u32 v[48:49], s[16:17], v75, s10, v[10:11]
	v_mad_u64_u32 v[50:51], s[16:17], v74, s10, v[10:11]
	v_mad_u64_u32 v[52:53], s[16:17], v77, s10, v[10:11]
	v_mad_u64_u32 v[54:55], s[16:17], v76, s10, v[10:11]
	v_mad_u64_u32 v[56:57], s[16:17], v79, s10, v[10:11]
	v_mad_u64_u32 v[58:59], s[16:17], v78, s10, v[10:11]
	v_mad_u64_u32 v[60:61], s[16:17], v81, s10, v[10:11]
	v_mad_u64_u32 v[62:63], s[16:17], v80, s10, v[10:11]
	v_mad_u64_u32 v[64:65], s[16:17], v83, s10, v[10:11]
	v_mad_u64_u32 v[66:67], s[16:17], v82, s10, v[10:11]
	v_mad_u64_u32 v[68:69], s[16:17], v85, s10, v[10:11]
	v_mad_u64_u32 v[70:71], s[16:17], v84, s10, v[10:11]
	s_waitcnt vmcnt(15)
	ds_write_b32 v2, v86
	s_waitcnt vmcnt(14)
	ds_write_b32 v28, v87
	s_waitcnt vmcnt(13)
	ds_write_b32 v44, v88
	s_waitcnt vmcnt(12)
	ds_write_b32 v46, v89
	s_waitcnt vmcnt(11)
	ds_write_b32 v48, v90
	s_waitcnt vmcnt(10)
	ds_write_b32 v50, v91
	s_waitcnt vmcnt(9)
	ds_write_b32 v52, v92
	s_waitcnt vmcnt(8)
	ds_write_b32 v54, v93
	s_waitcnt vmcnt(7)
	ds_write_b32 v56, v94
	s_waitcnt vmcnt(6)
	ds_write_b32 v58, v95
	s_waitcnt vmcnt(5)
	ds_write_b32 v60, v96
	s_waitcnt vmcnt(4)
	ds_write_b32 v62, v97
	s_waitcnt vmcnt(3)
	ds_write_b32 v64, v98
	s_waitcnt vmcnt(2)
	ds_write_b32 v66, v99
	s_waitcnt vmcnt(1)
	ds_write_b32 v68, v100
	s_waitcnt vmcnt(0)
	ds_write_b32 v70, v101
	s_cbranch_scc1 .LBB0_677
	s_and_b32 s1, 0xffff, s1
	s_and_b32 s0, 0xffff, s0
	s_waitcnt lgkmcnt(0)
	s_lshl_b32 s2, s0, 1
	s_lshl_b32 s0, s1, 1
	ds_read2_b32 v[28:29], v30 offset0:33 offset1:41
	ds_read2_b32 v[44:45], v30 offset1:8
	ds_read2_b32 v[46:47], v30 offset0:66 offset1:74
	ds_read2_b32 v[48:49], v30 offset0:99 offset1:107
	ds_read2_b32 v[50:51], v30 offset0:132 offset1:140
	ds_read2_b32 v[52:53], v30 offset0:165 offset1:173
	ds_read2_b32 v[54:55], v30 offset0:198 offset1:206
	ds_read2_b32 v[56:57], v30 offset0:231 offset1:239
	s_and_b32 s0, s0, 0x3f00
	s_and_b32 s1, s1, 0x60
	s_or_b32 s0, s1, s0
	v_or_b32_e32 v6, s0, v35
	v_lshl_add_u64 v[58:59], v[16:17], 0, s[2:3]
	v_mul_u32_u24_e32 v6, 0x1080, v6
	v_lshl_add_u64 v[60:61], v[58:59], 0, v[6:7]
	s_waitcnt lgkmcnt(6)
	v_cvt_pk_bf16_f32 v0, v44, v28
	s_waitcnt lgkmcnt(4)
	v_cvt_pk_bf16_f32 v1, v46, v48
	s_waitcnt lgkmcnt(2)
	v_cvt_pk_bf16_f32 v2, v50, v52
	s_waitcnt lgkmcnt(0)
	v_cvt_pk_bf16_f32 v3, v54, v56
	global_store_dwordx4 v[60:61], v[0:3], off sc0 sc1
	v_or_b32_e32 v6, s0, v40
	v_mul_u32_u24_e32 v6, 0x1080, v6
	v_cvt_pk_bf16_f32 v0, v45, v29
	v_cvt_pk_bf16_f32 v1, v47, v49
	v_cvt_pk_bf16_f32 v2, v51, v53
	v_cvt_pk_bf16_f32 v3, v55, v57
	ds_read2_b32 v[44:45], v30 offset0:16 offset1:24
	ds_read2_b32 v[46:47], v30 offset0:49 offset1:57
	ds_read2_b32 v[48:49], v30 offset0:82 offset1:90
	ds_read2_b32 v[50:51], v30 offset0:115 offset1:123
	ds_read2_b32 v[52:53], v30 offset0:148 offset1:156
	ds_read2_b32 v[54:55], v30 offset0:181 offset1:189
	ds_read2_b32 v[56:57], v30 offset0:214 offset1:222
	ds_read2_b32 v[60:61], v30 offset0:247 offset1:255
	v_lshl_add_u64 v[28:29], v[58:59], 0, v[6:7]
	v_or_b32_e32 v6, s0, v41
	v_mul_u32_u24_e32 v6, 0x1080, v6
	global_store_dwordx4 v[28:29], v[0:3], off sc0 sc1
	v_lshl_add_u64 v[28:29], v[58:59], 0, v[6:7]
	v_or_b32_e32 v6, s0, v42
	v_mul_u32_u24_e32 v6, 0x1080, v6
	s_waitcnt lgkmcnt(6)
	v_cvt_pk_bf16_f32 v0, v44, v46
	s_waitcnt lgkmcnt(4)
	v_cvt_pk_bf16_f32 v1, v48, v50
	s_waitcnt lgkmcnt(2)
	v_cvt_pk_bf16_f32 v2, v52, v54
	s_waitcnt lgkmcnt(0)
	v_cvt_pk_bf16_f32 v3, v56, v60
	global_store_dwordx4 v[28:29], v[0:3], off sc0 sc1
	v_lshl_add_u64 v[28:29], v[58:59], 0, v[6:7]
	s_nop 0
	v_cvt_pk_bf16_f32 v0, v45, v47
	v_cvt_pk_bf16_f32 v1, v49, v51
	v_cvt_pk_bf16_f32 v2, v53, v55
	v_cvt_pk_bf16_f32 v3, v57, v61
	global_store_dwordx4 v[28:29], v[0:3], off sc0 sc1
	s_waitcnt lgkmcnt(0)

; __device__ __forceinline__ void tr_item(const float* W, int K, int N, bf16_t* WT, int ldt, LAS float* scr, int item, int lane, int mapmode, int p0, int p1) {
;     const int nblk = N / 32, kb = item / nblk, nb = item % nblk, k0 = 64 * kb, n0 = 32 * nb;
; #pragma unroll 8
;     for (int i = 0; i < 32; ++i) { const int kk = 2 * i + (lane >> 5); scr[kk * 33 + (lane & 31)] = W[(size_t)(k0 + kk) * N + n0 + (lane & 31)]; }
.LBB0_682:
	s_lshl_b32 s15, s7, 1
	s_lshl_b32 s16, s8, 1
	v_or_b32_e32 v62, s16, v4
	s_add_i32 s17, s15, 4
	s_add_i32 s18, s16, 4
	s_add_i32 s20, s16, 8
	v_add_u32_e32 v6, s6, v62
	v_or_b32_e32 v63, s17, v5
	v_or_b32_e32 v64, s18, v4
	v_mov_b32_e32 v29, v7
	v_or_b32_e32 v43, s15, v5
	s_add_i32 s22, s16, 12
	v_or_b32_e32 v66, s20, v4
	v_lshlrev_b64 v[56:57], 13, v[6:7]
	v_add_u32_e32 v28, s2, v63
	v_add_u32_e32 v6, s6, v64
	v_mov_b32_e32 v3, v7
	s_add_i32 s19, s15, 8
	s_add_i32 s21, s15, 12
	s_add_i32 s24, s16, 16
	v_add_u32_e32 v2, s2, v43
	v_or_b32_e32 v68, s22, v4
	v_lshlrev_b64 v[28:29], 13, v[28:29]
	v_lshlrev_b64 v[58:59], 13, v[6:7]
	v_add_u32_e32 v6, s6, v66
	s_add_i32 s27, s16, 20
	v_or_b32_e32 v65, s19, v5
	v_or_b32_e32 v67, s21, v5
	v_or_b32_e32 v70, s24, v4
	v_lshlrev_b64 v[2:3], 13, v[2:3]
	v_lshl_add_u64 v[56:57], v[0:1], 0, v[56:57]
	v_lshl_add_u64 v[28:29], v[0:1], 0, v[28:29]
	v_lshlrev_b64 v[60:61], 13, v[6:7]
	v_add_u32_e32 v6, s6, v68
	v_mov_b32_e32 v45, v7
	v_mov_b32_e32 v47, v7
	s_add_i32 s23, s15, 16
	s_add_i32 s25, s15, 20
	s_add_i32 s35, s16, 24
	v_or_b32_e32 v72, s27, v4
	v_add_u32_e32 v44, s2, v65
	v_add_u32_e32 v46, s2, v67
	v_lshl_add_u64 v[2:3], v[0:1], 0, v[2:3]
	v_lshl_add_u64 v[58:59], v[0:1], 0, v[58:59]
	global_load_dword v77, v[56:57], off
	global_load_dword v78, v[2:3], off
	global_load_dword v79, v[58:59], off
	global_load_dword v80, v[28:29], off
	v_lshlrev_b64 v[28:29], 13, v[6:7]
	v_add_u32_e32 v6, s6, v70
	s_add_i32 s33, s15, 24
	s_add_i32 s15, s15, 28
	s_add_i32 s16, s16, 28
	v_or_b32_e32 v69, s23, v5
	v_or_b32_e32 v71, s25, v5
	v_or_b32_e32 v74, s35, v4
	v_lshlrev_b64 v[44:45], 13, v[44:45]
	v_lshlrev_b64 v[46:47], 13, v[46:47]
	v_lshl_add_u64 v[2:3], v[0:1], 0, v[60:61]
	v_lshl_add_u64 v[28:29], v[0:1], 0, v[28:29]
	v_lshlrev_b64 v[56:57], 13, v[6:7]
	v_add_u32_e32 v6, s6, v72
	v_mov_b32_e32 v49, v7
	v_mov_b32_e32 v51, v7
	v_or_b32_e32 v73, s33, v5
	v_or_b32_e32 v75, s15, v5
	v_or_b32_e32 v76, s16, v4
	v_add_u32_e32 v48, s2, v69
	v_add_u32_e32 v50, s2, v71
	v_lshl_add_u64 v[44:45], v[0:1], 0, v[44:45]
	v_lshl_add_u64 v[46:47], v[0:1], 0, v[46:47]
	global_load_dword v81, v[2:3], off
	global_load_dword v82, v[44:45], off
	global_load_dword v83, v[28:29], off
	global_load_dword v84, v[46:47], off
	v_lshlrev_b64 v[28:29], 13, v[6:7]
	v_add_u32_e32 v6, s6, v74
	v_mov_b32_e32 v53, v7
	v_mov_b32_e32 v55, v7
	v_add_u32_e32 v52, s2, v73
	v_add_u32_e32 v54, s2, v75
	v_lshlrev_b64 v[48:49], 13, v[48:49]
	v_lshlrev_b64 v[50:51], 13, v[50:51]
	v_lshl_add_u64 v[2:3], v[0:1], 0, v[56:57]
	v_lshl_add_u64 v[28:29], v[0:1], 0, v[28:29]
	v_lshlrev_b64 v[44:45], 13, v[6:7]
	v_add_u32_e32 v6, s6, v76
	v_lshlrev_b64 v[52:53], 13, v[52:53]
	v_lshlrev_b64 v[54:55], 13, v[54:55]
	v_lshl_add_u64 v[48:49], v[0:1], 0, v[48:49]
	v_lshl_add_u64 v[50:51], v[0:1], 0, v[50:51]
	global_load_dword v85, v[2:3], off
	global_load_dword v86, v[48:49], off
	global_load_dword v87, v[28:29], off
	global_load_dword v88, v[50:51], off
	v_lshl_add_u64 v[2:3], v[0:1], 0, v[44:45]
	v_lshlrev_b64 v[28:29], 13, v[6:7]
	v_lshl_add_u64 v[52:53], v[0:1], 0, v[52:53]
	v_lshl_add_u64 v[54:55], v[0:1], 0, v[54:55]
	v_lshl_add_u64 v[28:29], v[0:1], 0, v[28:29]
	global_load_dword v6, v[2:3], off
	global_load_dword v89, v[52:53], off
	global_load_dword v90, v[28:29], off
	global_load_dword v91, v[54:55], off
	s_add_i32 s8, s8, 16
	s_add_i32 s7, s7, 16
	s_add_i32 s9, s9, -16
	v_mad_u64_u32 v[2:3], s[16:17], v62, s10, v[10:11]
	s_cmp_lg_u32 s9, 0
	v_mad_u64_u32 v[28:29], s[16:17], v43, s10, v[10:11]
	v_mad_u64_u32 v[44:45], s[16:17], v64, s10, v[10:11]
	v_mad_u64_u32 v[46:47], s[16:17], v63, s10, v[10:11]
	v_mad_u64_u32 v[48:49], s[16:17], v66, s10, v[10:11]
	v_mad_u64_u32 v[50:51], s[16:17], v65, s10, v[10:11]
	v_mad_u64_u32 v[52:53], s[16:17], v68, s10, v[10:11]
	v_mad_u64_u32 v[54:55], s[16:17], v67, s10, v[10:11]
	v_mad_u64_u32 v[56:57], s[16:17], v70, s10, v[10:11]
	v_mad_u64_u32 v[58:59], s[16:17], v69, s10, v[10:11]
	v_mad_u64_u32 v[60:61], s[16:17], v72, s10, v[10:11]
	v_mad_u64_u32 v[62:63], s[16:17], v71, s10, v[10:11]
	v_mad_u64_u32 v[64:65], s[16:17], v74, s10, v[10:11]
	v_mad_u64_u32 v[66:67], s[16:17], v73, s10, v[10:11]
	v_mad_u64_u32 v[68:69], s[16:17], v76, s10, v[10:11]
	v_mad_u64_u32 v[70:71], s[16:17], v75, s10, v[10:11]
	s_waitcnt vmcnt(15)
	ds_write_b32 v2, v77
	s_waitcnt vmcnt(14)
	ds_write_b32 v28, v78
	s_waitcnt vmcnt(13)
	ds_write_b32 v44, v79
	s_waitcnt vmcnt(12)
	ds_write_b32 v46, v80
	s_waitcnt vmcnt(11)
	ds_write_b32 v48, v81
	s_waitcnt vmcnt(10)
	ds_write_b32 v50, v82
	s_waitcnt vmcnt(9)
	ds_write_b32 v52, v83
	s_waitcnt vmcnt(8)
	ds_write_b32 v54, v84
	s_waitcnt vmcnt(7)
	ds_write_b32 v56, v85
	s_waitcnt vmcnt(6)
	ds_write_b32 v58, v86
	s_waitcnt vmcnt(5)
	ds_write_b32 v60, v87
	s_waitcnt vmcnt(4)
	ds_write_b32 v62, v88
	s_waitcnt vmcnt(3)
	ds_write_b32 v64, v6
	s_waitcnt vmcnt(2)
	ds_write_b32 v66, v89
	s_waitcnt vmcnt(1)
	ds_write_b32 v68, v90
	s_waitcnt vmcnt(0)
	ds_write_b32 v70, v91
	s_cbranch_scc1 .LBB0_682
; #define LAS __attribute__((address_space(3)))
; __device__ __forceinline__ unsigned pk2(float lo, float hi) { unsigned r; asm("v_cvt_pk_bf16_f32 %0, %1, %2" : "=v"(r) : "v"(lo), "v"(hi)); return r; }
; __device__ __forceinline__ void tr_item(const float* W, int K, int N, bf16_t* WT, int ldt, LAS float* scr, int item, int lane, int mapmode, int p0, int p1) {
;     ...
;     asm volatile("s_waitcnt lgkmcnt(0)" ::: "memory");
;     const int c = lane & 7;
; #pragma unroll
;     for (int j = 0; j < 4; ++j) { const int n = (lane >> 3) + 8 * j; const LAS float* s = scr + (8 * c) * 33 + n;
;         u32x4 o; o.x = pk2(s[0 * 33], s[1 * 33]); o.y = pk2(s[2 * 33], s[3 * 33]); o.z = pk2(s[4 * 33], s[5 * 33]); o.w = pk2(s[6 * 33], s[7 * 33]);
;         const int ns = n0 + n; int dst;
;         if (mapmode == 0) dst = p0 + (ns & ~255) + 128 * ((ns >> 5) & 1) + 32 * ((ns >> 6) & 3) + (ns & 31);
;         else if (mapmode == 1) dst = (ns >= p0 && ns < p1) ? ((ns & ~127) + il128(ns & 127)) : ns;
;         else dst = 256 * (ns >> 7) + 128 * ((ns >> 2) & 1) + 32 * ((ns >> 5) & 3) + 8 * ((ns >> 3) & 3) + 4 * p0 + (ns & 3);
;         *(u32x4*)(WT + (size_t)dst * ldt + k0 + 8 * c) = o; }
;     asm volatile("s_waitcnt lgkmcnt(0)" ::: "memory");
	s_lshl_b32 s2, s6, 1
	s_waitcnt lgkmcnt(0)
	v_lshl_add_u64 v[58:59], v[22:23], 0, s[2:3]
	s_and_b32 s0, s0, 0x700
	s_and_b32 s1, s1, 0x80
	s_lshl_b32 s2, s14, 4
	ds_read2_b32 v[28:29], v30 offset0:33 offset1:41
	ds_read2_b32 v[44:45], v30 offset1:8
	ds_read2_b32 v[46:47], v30 offset0:66 offset1:74
	ds_read2_b32 v[48:49], v30 offset0:99 offset1:107
	ds_read2_b32 v[50:51], v30 offset0:132 offset1:140
	ds_read2_b32 v[52:53], v30 offset0:165 offset1:173
	ds_read2_b32 v[54:55], v30 offset0:198 offset1:206
	ds_read2_b32 v[56:57], v30 offset0:231 offset1:239
	s_and_b32 s2, s2, 0x60
	s_or_b32 s0, s1, s0
	s_or_b32 s0, s0, s2
	v_or_b32_e32 v6, s0, v11
	v_mul_u32_u24_e32 v6, 0x1080, v6
	v_lshl_add_u64 v[60:61], v[58:59], 0, v[6:7]
	s_waitcnt lgkmcnt(6)
	v_cvt_pk_bf16_f32 v0, v44, v28
	s_waitcnt lgkmcnt(4)
	v_cvt_pk_bf16_f32 v1, v46, v48
	s_waitcnt lgkmcnt(2)
	v_cvt_pk_bf16_f32 v2, v50, v52
	s_waitcnt lgkmcnt(0)
	v_cvt_pk_bf16_f32 v3, v54, v56
	global_store_dwordx4 v[60:61], v[0:3], off sc0 sc1
	v_or_b32_e32 v6, s0, v31
	v_mul_u32_u24_e32 v6, 0x1080, v6
	v_cvt_pk_bf16_f32 v0, v45, v29
	v_cvt_pk_bf16_f32 v1, v47, v49
	v_cvt_pk_bf16_f32 v2, v51, v53
	v_cvt_pk_bf16_f32 v3, v55, v57
	ds_read2_b32 v[44:45], v30 offset0:16 offset1:24
	ds_read2_b32 v[46:47], v30 offset0:49 offset1:57
	ds_read2_b32 v[48:49], v30 offset0:82 offset1:90
	ds_read2_b32 v[50:51], v30 offset0:115 offset1:123
	ds_read2_b32 v[52:53], v30 offset0:148 offset1:156
	ds_read2_b32 v[54:55], v30 offset0:181 offset1:189
	ds_read2_b32 v[56:57], v30 offset0:214 offset1:222
	ds_read2_b32 v[60:61], v30 offset0:247 offset1:255
	v_lshl_add_u64 v[28:29], v[58:59], 0, v[6:7]
	v_or_b32_e32 v6, s0, v32
	v_mul_u32_u24_e32 v6, 0x1080, v6
	global_store_dwordx4 v[28:29], v[0:3], off sc0 sc1
	v_lshl_add_u64 v[28:29], v[58:59], 0, v[6:7]
	v_or_b32_e32 v6, s0, v33
	v_mul_u32_u24_e32 v6, 0x1080, v6
	s_waitcnt lgkmcnt(6)
	v_cvt_pk_bf16_f32 v0, v44, v46
	s_waitcnt lgkmcnt(4)
	v_cvt_pk_bf16_f32 v1, v48, v50
	s_waitcnt lgkmcnt(2)
	v_cvt_pk_bf16_f32 v2, v52, v54
	s_waitcnt lgkmcnt(0)
	v_cvt_pk_bf16_f32 v3, v56, v60
	global_store_dwordx4 v[28:29], v[0:3], off sc0 sc1
	v_lshl_add_u64 v[28:29], v[58:59], 0, v[6:7]
	s_nop 0
	v_cvt_pk_bf16_f32 v0, v45, v47
	v_cvt_pk_bf16_f32 v1, v49, v51
	v_cvt_pk_bf16_f32 v2, v53, v55
	v_cvt_pk_bf16_f32 v3, v57, v61
	global_store_dwordx4 v[28:29], v[0:3], off sc0 sc1
	s_waitcnt lgkmcnt(0)

; #define LAS __attribute__((address_space(3)))
; __device__ __forceinline__ unsigned pk2(float lo, float hi) { unsigned r; asm("v_cvt_pk_bf16_f32 %0, %1, %2" : "=v"(r) : "v"(lo), "v"(hi)); return r; }
; __device__ __forceinline__ void tr_item(const float* W, int K, int N, bf16_t* WT, int ldt, LAS float* scr, int item, int lane, int mapmode, int p0, int p1) {
;     ...
;     for (int j = 0; j < 4; ++j) { const int n = (lane >> 3) + 8 * j; const LAS float* s = scr + (8 * c) * 33 + n;
;         u32x4 o; o.x = pk2(s[0 * 33], s[1 * 33]); o.y = pk2(s[2 * 33], s[3 * 33]); o.z = pk2(s[4 * 33], s[5 * 33]); o.w = pk2(s[6 * 33], s[7 * 33]);
;         const int ns = n0 + n; int dst;
;         if (mapmode == 0) dst = p0 + (ns & ~255) + 128 * ((ns >> 5) & 1) + 32 * ((ns >> 6) & 3) + (ns & 31);
;         else if (mapmode == 1) dst = (ns >= p0 && ns < p1) ? ((ns & ~127) + il128(ns & 127)) : ns;
;         else dst = 256 * (ns >> 7) + 128 * ((ns >> 2) & 1) + 32 * ((ns >> 5) & 3) + 8 * ((ns >> 3) & 3) + 4 * p0 + (ns & 3);
;         *(u32x4*)(WT + (size_t)dst * ldt + k0 + 8 * c) = o; }
.LBB0_689:
	ds_read2_b32 v[46:47], v30 offset0:8 offset1:41
	ds_read2_b32 v[48:49], v30 offset0:74 offset1:107
	ds_read2_b32 v[50:51], v30 offset0:140 offset1:173
	ds_read2_b32 v[52:53], v30 offset0:206 offset1:239
	s_ashr_i32 s1, s0, 31
	v_mul_lo_u32 v44, v6, s12
	v_lshl_add_u64 v[28:29], s[0:1], 1, v[26:27]
	v_ashrrev_i32_e32 v45, 31, v44
	v_cndmask_b32_e64 v6, 0, 1, s[8:9]
	v_lshl_add_u64 v[44:45], v[28:29], 0, v[44:45]
	v_cmp_ne_u32_e64 s[0:1], 1, v6
	s_andn2_b64 vcc, exec, s[8:9]
	v_or_b32_e32 v6, s6, v31
	global_store_dwordx4 v[44:45], v[0:3], off sc0 sc1
	s_waitcnt lgkmcnt(3)
	s_nop 0
	v_cvt_pk_bf16_f32 v0, v46, v47
	s_waitcnt lgkmcnt(2)
	v_cvt_pk_bf16_f32 v1, v48, v49
	s_waitcnt lgkmcnt(1)
	v_cvt_pk_bf16_f32 v2, v50, v51
	s_waitcnt lgkmcnt(0)
	v_cvt_pk_bf16_f32 v3, v52, v53
	s_cbranch_vccnz .LBB0_691
	s_lshr_b32 s7, s6, 4
	s_and_b32 s2, s6, 0x1f80
	v_lshlrev_b32_e32 v6, 1, v6
	s_and_b32 s7, s7, 4
	v_and_b32_e32 v6, 0x58, v6
	s_or_b32 s2, s2, s7
	v_or3_b32 v6, s2, v6, v34
.LBB0_691:
	ds_read2_b32 v[46:47], v30 offset0:16 offset1:49
	ds_read2_b32 v[48:49], v30 offset0:82 offset1:115
	ds_read2_b32 v[50:51], v30 offset0:148 offset1:181
	ds_read2_b32 v[52:53], v30 offset0:214 offset1:247
	v_mul_lo_u32 v44, v6, s12
	v_ashrrev_i32_e32 v45, 31, v44
	v_lshl_add_u64 v[44:45], v[28:29], 0, v[44:45]
	s_and_b64 vcc, exec, s[0:1]
	v_or_b32_e32 v6, s6, v32
	global_store_dwordx4 v[44:45], v[0:3], off sc0 sc1
	s_waitcnt lgkmcnt(3)
	s_nop 0
	v_cvt_pk_bf16_f32 v0, v46, v47
	s_waitcnt lgkmcnt(2)
	v_cvt_pk_bf16_f32 v1, v48, v49
	s_waitcnt lgkmcnt(1)
	v_cvt_pk_bf16_f32 v2, v50, v51
	s_waitcnt lgkmcnt(0)
	v_cvt_pk_bf16_f32 v3, v52, v53
	s_cbranch_vccnz .LBB0_693
	s_lshr_b32 s7, s6, 4
	s_and_b32 s2, s6, 0x1f80
	v_lshlrev_b32_e32 v6, 1, v6
	s_and_b32 s7, s7, 4
	v_and_b32_e32 v6, 0x68, v6
	s_or_b32 s2, s2, s7
	v_or3_b32 v6, s2, v6, v34
.LBB0_693:
	ds_read2_b32 v[46:47], v30 offset0:24 offset1:57
	ds_read2_b32 v[48:49], v30 offset0:90 offset1:123
	ds_read2_b32 v[50:51], v30 offset0:156 offset1:189
	ds_read2_b32 v[52:53], v30 offset0:222 offset1:255
	v_mul_lo_u32 v44, v6, s12
	v_ashrrev_i32_e32 v45, 31, v44
	v_lshl_add_u64 v[44:45], v[28:29], 0, v[44:45]
	s_and_b64 vcc, exec, s[0:1]
	v_or_b32_e32 v6, s6, v33
	global_store_dwordx4 v[44:45], v[0:3], off sc0 sc1
	s_waitcnt lgkmcnt(3)
	s_nop 0
	v_cvt_pk_bf16_f32 v0, v46, v47
	s_waitcnt lgkmcnt(2)
	v_cvt_pk_bf16_f32 v1, v48, v49
	s_waitcnt lgkmcnt(1)
	v_cvt_pk_bf16_f32 v2, v50, v51
	s_waitcnt lgkmcnt(0)
	v_cvt_pk_bf16_f32 v3, v52, v53
	s_cbranch_vccnz .LBB0_660
	s_lshr_b32 s1, s6, 4
	s_and_b32 s0, s6, 0x1f80
	v_lshlrev_b32_e32 v6, 1, v6
	s_and_b32 s1, s1, 4
	v_and_b32_e32 v6, 0x78, v6
	s_or_b32 s0, s0, s1
	v_or3_b32 v6, s0, v6, v34
	s_branch .LBB0_660

; __device__ __forceinline__ unsigned cvt_pk_bf16(float lo, float hi) { unsigned r; asm volatile("v_cvt_pk_bf16_f32 %0, %1, %2" : "=v"(r) : "v"(lo), "v"(hi)); return r; }
;     __device__ __forceinline__ void operator()(const f32x4 (&acc)[2][2][4][2], const Unit& u, int wr, int wc, int fr, int fq) const {
;     ...
;         if (!rope) {
; #pragma unroll
;             for (int ai = 0; ai < 2; ++ai)
; #pragma unroll
;                 for (int m = 0; m < 4; ++m) { bf16_t* rowp = O + (size_t)(row0 + ai * HALF + m * 16) * ldc + colt + cin;
; #pragma unroll
;                     for (int bj = 0; bj < 2; ++bj) { const f32x4 v0 = acc[ai][bj][m][0], v1 = acc[ai][bj][m][1];
;                         u32x4 w; w.x = cvt_pk_bf16(v0[0], v0[1]); w.y = cvt_pk_bf16(v0[2], v0[3]); w.z = cvt_pk_bf16(v1[0], v1[1]); w.w = cvt_pk_bf16(v1[2], v1[3]);
;                         *(u32x4*)(rowp + bj * HALF) = w; } }
;             return;
.LBB0_764:
	v_lshl_add_u32 v173, s55, 8, v139
	s_lshl_b32 s8, s38, 8
	s_add_i32 s22, s38, -12
	s_mov_b64 s[20:21], -1
	s_cmp_lt_u32 s22, 8
	v_or_b32_e32 v172, 16, v173
	v_or_b32_e32 v171, 32, v173
	v_or_b32_e32 v170, 48, v173
	v_add_u32_e32 v167, 0x80, v173
	v_add_u32_e32 v166, 0x90, v173
	v_add_u32_e32 v165, 0xa0, v173
	v_add_u32_e32 v164, 0xb0, v173
	v_lshlrev_b32_e32 v156, 1, v138
	s_cbranch_scc1 .LBB0_766
	s_ashr_i32 s21, s8, 31
	s_mov_b32 s20, s8
	v_mov_b64_e32 v[158:159], s[12:13]
	v_mad_i64_i32 v[174:175], s[22:23], v173, s51, v[158:159]
	s_lshl_b64 s[20:21], s[20:21], 1
	v_lshl_add_u64 v[174:175], v[174:175], 0, s[20:21]
	v_mov_b32_e32 v157, v137
	v_lshl_add_u64 v[178:179], v[174:175], 0, v[156:157]
	v_cvt_pk_bf16_f32 v174, v124, v125
	v_cvt_pk_bf16_f32 v175, v126, v127
	v_cvt_pk_bf16_f32 v176, v120, v121
	v_cvt_pk_bf16_f32 v177, v122, v123
	global_store_dwordx4 v[178:179], v[174:177], off sc0 sc1
	s_nop 1
	v_cvt_pk_bf16_f32 v174, v116, v117
	v_cvt_pk_bf16_f32 v175, v118, v119
	v_cvt_pk_bf16_f32 v176, v112, v113
	v_cvt_pk_bf16_f32 v177, v114, v115
	global_store_dwordx4 v[178:179], v[174:177], off offset:256 sc0 sc1
	s_nop 1
	v_mad_i64_i32 v[174:175], s[22:23], v172, s51, v[158:159]
	v_lshl_add_u64 v[174:175], v[174:175], 0, s[20:21]
	v_lshl_add_u64 v[178:179], v[174:175], 0, v[156:157]
	v_cvt_pk_bf16_f32 v174, v108, v109
	v_cvt_pk_bf16_f32 v175, v110, v111
	v_cvt_pk_bf16_f32 v176, v104, v105
	v_cvt_pk_bf16_f32 v177, v106, v107
	global_store_dwordx4 v[178:179], v[174:177], off sc0 sc1
	s_nop 1
	v_cvt_pk_bf16_f32 v174, v100, v101
	v_cvt_pk_bf16_f32 v175, v102, v103
	v_cvt_pk_bf16_f32 v176, v96, v97
	v_cvt_pk_bf16_f32 v177, v98, v99
	global_store_dwordx4 v[178:179], v[174:177], off offset:256 sc0 sc1
	s_nop 1
	v_mad_i64_i32 v[174:175], s[22:23], v171, s51, v[158:159]
	v_lshl_add_u64 v[174:175], v[174:175], 0, s[20:21]
	v_lshl_add_u64 v[178:179], v[174:175], 0, v[156:157]
	v_cvt_pk_bf16_f32 v174, v92, v93
	v_cvt_pk_bf16_f32 v175, v94, v95
	v_cvt_pk_bf16_f32 v176, v88, v89
	v_cvt_pk_bf16_f32 v177, v90, v91
	global_store_dwordx4 v[178:179], v[174:177], off sc0 sc1
	s_nop 1
	v_cvt_pk_bf16_f32 v174, v84, v85
	v_cvt_pk_bf16_f32 v175, v86, v87
	v_cvt_pk_bf16_f32 v176, v80, v81
	v_cvt_pk_bf16_f32 v177, v82, v83
	global_store_dwordx4 v[178:179], v[174:177], off offset:256 sc0 sc1
	s_nop 1
	v_mad_i64_i32 v[174:175], s[22:23], v170, s51, v[158:159]
	v_lshl_add_u64 v[174:175], v[174:175], 0, s[20:21]
	v_lshl_add_u64 v[178:179], v[174:175], 0, v[156:157]
	v_cvt_pk_bf16_f32 v174, v76, v77
	v_cvt_pk_bf16_f32 v175, v78, v79
	v_cvt_pk_bf16_f32 v176, v72, v73
	v_cvt_pk_bf16_f32 v177, v74, v75
	global_store_dwordx4 v[178:179], v[174:177], off sc0 sc1
	s_nop 1
	v_cvt_pk_bf16_f32 v174, v68, v69
	v_cvt_pk_bf16_f32 v175, v70, v71
	v_cvt_pk_bf16_f32 v176, v64, v65
	v_cvt_pk_bf16_f32 v177, v66, v67
	global_store_dwordx4 v[178:179], v[174:177], off offset:256 sc0 sc1
	s_nop 1
	v_mad_i64_i32 v[174:175], s[22:23], v167, s51, v[158:159]
	v_lshl_add_u64 v[174:175], v[174:175], 0, s[20:21]
	v_lshl_add_u64 v[178:179], v[174:175], 0, v[156:157]
	v_cvt_pk_bf16_f32 v174, v60, v61
	v_cvt_pk_bf16_f32 v175, v62, v63
	v_cvt_pk_bf16_f32 v176, v56, v57
	v_cvt_pk_bf16_f32 v177, v58, v59
	global_store_dwordx4 v[178:179], v[174:177], off sc0 sc1
	s_nop 1
	v_cvt_pk_bf16_f32 v174, v52, v53
	v_cvt_pk_bf16_f32 v175, v54, v55
	v_cvt_pk_bf16_f32 v176, v48, v49
	v_cvt_pk_bf16_f32 v177, v50, v51
	global_store_dwordx4 v[178:179], v[174:177], off offset:256 sc0 sc1
	s_nop 1
	v_mad_i64_i32 v[174:175], s[22:23], v166, s51, v[158:159]
	v_lshl_add_u64 v[174:175], v[174:175], 0, s[20:21]
	v_lshl_add_u64 v[178:179], v[174:175], 0, v[156:157]
	v_cvt_pk_bf16_f32 v174, v44, v45
	v_cvt_pk_bf16_f32 v175, v46, v47
	v_cvt_pk_bf16_f32 v176, v40, v41
	v_cvt_pk_bf16_f32 v177, v42, v43
	global_store_dwordx4 v[178:179], v[174:177], off sc0 sc1
	s_nop 1
	v_cvt_pk_bf16_f32 v174, v36, v37
	v_cvt_pk_bf16_f32 v175, v38, v39
	v_cvt_pk_bf16_f32 v176, v32, v33
	v_cvt_pk_bf16_f32 v177, v34, v35
	global_store_dwordx4 v[178:179], v[174:177], off offset:256 sc0 sc1
	s_nop 1
	v_mad_i64_i32 v[174:175], s[22:23], v165, s51, v[158:159]
	v_lshl_add_u64 v[174:175], v[174:175], 0, s[20:21]
	v_lshl_add_u64 v[178:179], v[174:175], 0, v[156:157]
	v_cvt_pk_bf16_f32 v174, v28, v29
	v_cvt_pk_bf16_f32 v175, v30, v31
	v_cvt_pk_bf16_f32 v176, v24, v25
	v_cvt_pk_bf16_f32 v177, v26, v27
	v_mad_i64_i32 v[158:159], s[22:23], v164, s51, v[158:159]
	global_store_dwordx4 v[178:179], v[174:177], off sc0 sc1
	v_lshl_add_u64 v[158:159], v[158:159], 0, s[20:21]
	v_lshl_add_u64 v[158:159], v[158:159], 0, v[156:157]
	v_cvt_pk_bf16_f32 v174, v20, v21
	v_cvt_pk_bf16_f32 v175, v22, v23
	v_cvt_pk_bf16_f32 v176, v16, v17
	v_cvt_pk_bf16_f32 v177, v18, v19
	global_store_dwordx4 v[178:179], v[174:177], off offset:256 sc0 sc1
	s_mov_b64 s[20:21], 0
	s_nop 0
	v_cvt_pk_bf16_f32 v174, v12, v13
	v_cvt_pk_bf16_f32 v175, v14, v15
	v_cvt_pk_bf16_f32 v176, v8, v9
	v_cvt_pk_bf16_f32 v177, v10, v11
	global_store_dwordx4 v[158:159], v[174:177], off sc0 sc1
	s_nop 1
	v_cvt_pk_bf16_f32 v174, v4, v5
	v_cvt_pk_bf16_f32 v175, v6, v7
	v_cvt_pk_bf16_f32 v176, v0, v1
	v_cvt_pk_bf16_f32 v177, v2, v3
	global_store_dwordx4 v[158:159], v[174:177], off offset:256 sc0 sc1
; __device__ __forceinline__ unsigned cvt_pk_bf16(float lo, float hi) { unsigned r; asm volatile("v_cvt_pk_bf16_f32 %0, %1, %2" : "=v"(r) : "v"(lo), "v"(hi)); return r; }
;     __device__ __forceinline__ void operator()(const f32x4 (&acc)[2][2][4][2], const Unit& u, int wr, int wc, int fr, int fq) const {
;     ...
;                 for (int m = 0; m < 4; ++m) { const int row = row0 + ai * HALF + m * 16, t = row & (SEQ - 1);
;                     const f32x4 c4 = *(const f32x4*)(cosT + t * 64 + e0), s4 = *(const f32x4*)(sinT + t * 64 + e0);
;                     bf16_t* rowp = O + (size_t)row * ldc + colt + cin;
; #pragma unroll
;                     for (int bj = 0; bj < 2; ++bj) { const f32x4 x1 = acc[ai][bj][m][0], x2 = acc[ai][bj][m][1];
;                         const f32x4 o1 = x1 * c4 - x2 * s4, o2 = x2 * c4 + x1 * s4;
;                         ks[bj][0] += o1; ks[bj][1] += o2;
;                         u32x4 w; w.x = cvt_pk_bf16(o1[0], o1[1]); w.y = cvt_pk_bf16(o1[2], o1[3]); w.z = cvt_pk_bf16(o2[0], o2[1]); w.w = cvt_pk_bf16(o2[2], o2[3]);
;                         *(u32x4*)(rowp + bj * HALF) = w; } }
.LBB0_766:
	s_andn2_b64 vcc, exec, s[20:21]
	s_cbranch_vccnz .LBB0_801
	v_lshlrev_b32_e32 v136, 8, v173
	v_and_b32_e32 v136, 0xfcf00, v136
	v_lshl_add_u64 v[158:159], v[142:143], 0, v[136:137]
	global_load_dwordx4 v[174:177], v[158:159], off
	v_lshl_add_u64 v[158:159], v[140:141], 0, v[136:137]
	global_load_dwordx4 v[178:181], v[158:159], off
	v_mov_b64_e32 v[158:159], s[12:13]
	s_lshl_b64 s[20:21], s[8:9], 1
	v_mad_i64_i32 v[182:183], s[22:23], v173, s51, v[158:159]
	v_mov_b32_e32 v157, v137
	v_lshlrev_b32_e32 v136, 8, v172
	v_lshl_add_u64 v[182:183], v[182:183], 0, s[20:21]
	v_and_b32_e32 v136, 0xfdf00, v136
	v_lshl_add_u64 v[182:183], v[182:183], 0, v[156:157]
	v_lshl_add_u64 v[184:185], v[142:143], 0, v[136:137]
	v_mad_i64_i32 v[172:173], s[22:23], v172, s51, v[158:159]
	v_lshl_add_u64 v[172:173], v[172:173], 0, s[20:21]
	s_cmpk_lt_u32 s8, 0x1000
	s_waitcnt vmcnt(0)
	v_pk_mul_f32 v[186:187], v[122:123], v[176:177]
	v_pk_mul_f32 v[188:189], v[120:121], v[174:175]
	v_pk_mul_f32 v[190:191], v[126:127], v[176:177]
	v_pk_mul_f32 v[192:193], v[124:125], v[174:175]
	v_pk_mul_f32 v[194:195], v[114:115], v[176:177]
	v_pk_mul_f32 v[196:197], v[112:113], v[174:175]
	v_pk_mul_f32 v[176:177], v[118:119], v[176:177]
	v_pk_mul_f32 v[174:175], v[116:117], v[174:175]
	v_pk_fma_f32 v[126:127], v[126:127], v[180:181], v[186:187] neg_lo:[0,0,1] neg_hi:[0,0,1]
	v_pk_fma_f32 v[124:125], v[124:125], v[178:179], v[188:189] neg_lo:[0,0,1] neg_hi:[0,0,1]
	v_pk_fma_f32 v[122:123], v[122:123], v[180:181], v[190:191]
	v_pk_fma_f32 v[120:121], v[120:121], v[178:179], v[192:193]
	v_pk_fma_f32 v[114:115], v[114:115], v[180:181], v[176:177]
	v_pk_fma_f32 v[112:113], v[112:113], v[178:179], v[174:175]
	v_cvt_pk_bf16_f32 v174, v124, v125
	v_cvt_pk_bf16_f32 v175, v126, v127
	v_cvt_pk_bf16_f32 v176, v120, v121
	v_cvt_pk_bf16_f32 v177, v122, v123
	v_pk_fma_f32 v[118:119], v[118:119], v[180:181], v[194:195] neg_lo:[0,0,1] neg_hi:[0,0,1]
	v_pk_fma_f32 v[116:117], v[116:117], v[178:179], v[196:197] neg_lo:[0,0,1] neg_hi:[0,0,1]
	global_store_dwordx4 v[182:183], v[174:177], off sc0 sc1
	v_lshl_add_u64 v[178:179], v[140:141], 0, v[136:137]
	v_lshlrev_b32_e32 v136, 8, v171
	v_cvt_pk_bf16_f32 v174, v116, v117
	v_cvt_pk_bf16_f32 v175, v118, v119
	v_cvt_pk_bf16_f32 v176, v112, v113
	v_cvt_pk_bf16_f32 v177, v114, v115
	global_store_dwordx4 v[182:183], v[174:177], off offset:256 sc0 sc1
	global_load_dwordx4 v[174:177], v[184:185], off
	v_lshl_add_u64 v[182:183], v[172:173], 0, v[156:157]
	global_load_dwordx4 v[178:181], v[178:179], off
	v_and_b32_e32 v136, 0xfef00, v136
	v_lshl_add_u64 v[184:185], v[142:143], 0, v[136:137]
	s_waitcnt vmcnt(1)
	v_pk_mul_f32 v[172:173], v[106:107], v[176:177]
	v_pk_mul_f32 v[186:187], v[104:105], v[174:175]
	v_pk_mul_f32 v[188:189], v[110:111], v[176:177]
	v_pk_mul_f32 v[190:191], v[108:109], v[174:175]
	v_pk_mul_f32 v[194:195], v[96:97], v[174:175]
	v_pk_mul_f32 v[174:175], v[100:101], v[174:175]
	v_pk_mul_f32 v[192:193], v[98:99], v[176:177]
	v_pk_mul_f32 v[176:177], v[102:103], v[176:177]
	s_waitcnt vmcnt(0)
	v_pk_fma_f32 v[110:111], v[110:111], v[180:181], v[172:173] neg_lo:[0,0,1] neg_hi:[0,0,1]
	v_pk_fma_f32 v[108:109], v[108:109], v[178:179], v[186:187] neg_lo:[0,0,1] neg_hi:[0,0,1]
	v_pk_fma_f32 v[106:107], v[106:107], v[180:181], v[188:189]
	v_pk_fma_f32 v[104:105], v[104:105], v[178:179], v[190:191]
	v_pk_fma_f32 v[96:97], v[96:97], v[178:179], v[174:175]
	v_cvt_pk_bf16_f32 v172, v108, v109
	v_cvt_pk_bf16_f32 v173, v110, v111
	v_cvt_pk_bf16_f32 v174, v104, v105
	v_cvt_pk_bf16_f32 v175, v106, v107
	v_pk_fma_f32 v[102:103], v[102:103], v[180:181], v[192:193] neg_lo:[0,0,1] neg_hi:[0,0,1]
	v_pk_fma_f32 v[100:101], v[100:101], v[178:179], v[194:195] neg_lo:[0,0,1] neg_hi:[0,0,1]
	v_pk_fma_f32 v[98:99], v[98:99], v[180:181], v[176:177]
	global_store_dwordx4 v[182:183], v[172:175], off sc0 sc1
	v_lshl_add_u64 v[176:177], v[140:141], 0, v[136:137]
	v_mad_i64_i32 v[180:181], s[22:23], v171, s51, v[158:159]
	v_cvt_pk_bf16_f32 v172, v100, v101
	v_cvt_pk_bf16_f32 v173, v102, v103
	v_cvt_pk_bf16_f32 v174, v96, v97
	v_cvt_pk_bf16_f32 v175, v98, v99
	global_store_dwordx4 v[182:183], v[172:175], off offset:256 sc0 sc1
	global_load_dwordx4 v[172:175], v[184:185], off
	v_lshlrev_b32_e32 v136, 8, v170
	global_load_dwordx4 v[176:179], v[176:177], off
	v_lshl_add_u64 v[180:181], v[180:181], 0, s[20:21]
	v_lshl_add_u64 v[180:181], v[180:181], 0, v[156:157]
	v_and_b32_e32 v136, 0xfff00, v136
	v_lshl_add_u64 v[182:183], v[142:143], 0, v[136:137]
	v_mad_i64_i32 v[170:171], s[22:23], v170, s51, v[158:159]
	v_lshl_add_u64 v[170:171], v[170:171], 0, s[20:21]
	s_waitcnt vmcnt(1)
	v_pk_mul_f32 v[184:185], v[90:91], v[174:175]
	v_pk_mul_f32 v[186:187], v[88:89], v[172:173]
	v_pk_mul_f32 v[188:189], v[94:95], v[174:175]
	v_pk_mul_f32 v[190:191], v[92:93], v[172:173]
	v_pk_mul_f32 v[192:193], v[82:83], v[174:175]
	v_pk_mul_f32 v[194:195], v[80:81], v[172:173]
	v_pk_mul_f32 v[174:175], v[86:87], v[174:175]
	v_pk_mul_f32 v[172:173], v[84:85], v[172:173]
	s_waitcnt vmcnt(0)
; __device__ __forceinline__ unsigned cvt_pk_bf16(float lo, float hi) { unsigned r; asm volatile("v_cvt_pk_bf16_f32 %0, %1, %2" : "=v"(r) : "v"(lo), "v"(hi)); return r; }
;     __device__ __forceinline__ void operator()(const f32x4 (&acc)[2][2][4][2], const Unit& u, int wr, int wc, int fr, int fq) const {
;     ...
;                 for (int m = 0; m < 4; ++m) { const int row = row0 + ai * HALF + m * 16, t = row & (SEQ - 1);
;                     const f32x4 c4 = *(const f32x4*)(cosT + t * 64 + e0), s4 = *(const f32x4*)(sinT + t * 64 + e0);
;                     bf16_t* rowp = O + (size_t)row * ldc + colt + cin;
; #pragma unroll
;                     for (int bj = 0; bj < 2; ++bj) { const f32x4 x1 = acc[ai][bj][m][0], x2 = acc[ai][bj][m][1];
;                         const f32x4 o1 = x1 * c4 - x2 * s4, o2 = x2 * c4 + x1 * s4;
;                         ks[bj][0] += o1; ks[bj][1] += o2;
;                         u32x4 w; w.x = cvt_pk_bf16(o1[0], o1[1]); w.y = cvt_pk_bf16(o1[2], o1[3]); w.z = cvt_pk_bf16(o2[0], o2[1]); w.w = cvt_pk_bf16(o2[2], o2[3]);
;                         *(u32x4*)(rowp + bj * HALF) = w; } }
	v_pk_fma_f32 v[94:95], v[94:95], v[178:179], v[184:185] neg_lo:[0,0,1] neg_hi:[0,0,1]
	v_pk_fma_f32 v[92:93], v[92:93], v[176:177], v[186:187] neg_lo:[0,0,1] neg_hi:[0,0,1]
	v_pk_fma_f32 v[90:91], v[90:91], v[178:179], v[188:189]
	v_pk_fma_f32 v[88:89], v[88:89], v[176:177], v[190:191]
	v_pk_fma_f32 v[82:83], v[82:83], v[178:179], v[174:175]
	v_pk_fma_f32 v[80:81], v[80:81], v[176:177], v[172:173]
	v_cvt_pk_bf16_f32 v172, v92, v93
	v_cvt_pk_bf16_f32 v173, v94, v95
	v_cvt_pk_bf16_f32 v174, v88, v89
	v_cvt_pk_bf16_f32 v175, v90, v91
	v_pk_fma_f32 v[86:87], v[86:87], v[178:179], v[192:193] neg_lo:[0,0,1] neg_hi:[0,0,1]
	v_pk_fma_f32 v[84:85], v[84:85], v[176:177], v[194:195] neg_lo:[0,0,1] neg_hi:[0,0,1]
	global_store_dwordx4 v[180:181], v[172:175], off sc0 sc1
	v_lshl_add_u64 v[176:177], v[140:141], 0, v[136:137]
	v_lshlrev_b32_e32 v136, 8, v167
	v_cvt_pk_bf16_f32 v172, v84, v85
	v_cvt_pk_bf16_f32 v173, v86, v87
	v_cvt_pk_bf16_f32 v174, v80, v81
	v_cvt_pk_bf16_f32 v175, v82, v83
	global_store_dwordx4 v[180:181], v[172:175], off offset:256 sc0 sc1
	global_load_dwordx4 v[172:175], v[182:183], off
	v_lshl_add_u64 v[180:181], v[170:171], 0, v[156:157]
	global_load_dwordx4 v[176:179], v[176:177], off
	v_and_b32_e32 v136, 0xfcf00, v136
	v_lshl_add_u64 v[182:183], v[142:143], 0, v[136:137]
	s_waitcnt vmcnt(1)
	v_pk_mul_f32 v[170:171], v[74:75], v[174:175]
	v_pk_mul_f32 v[184:185], v[72:73], v[172:173]
	v_pk_mul_f32 v[186:187], v[78:79], v[174:175]
	v_pk_mul_f32 v[188:189], v[76:77], v[172:173]
	v_pk_mul_f32 v[192:193], v[64:65], v[172:173]
	v_pk_mul_f32 v[172:173], v[68:69], v[172:173]
	v_pk_mul_f32 v[190:191], v[66:67], v[174:175]
	v_pk_mul_f32 v[174:175], v[70:71], v[174:175]
	s_waitcnt vmcnt(0)
	v_pk_fma_f32 v[78:79], v[78:79], v[178:179], v[170:171] neg_lo:[0,0,1] neg_hi:[0,0,1]
	v_pk_fma_f32 v[76:77], v[76:77], v[176:177], v[184:185] neg_lo:[0,0,1] neg_hi:[0,0,1]
	v_pk_fma_f32 v[74:75], v[74:75], v[178:179], v[186:187]
	v_pk_fma_f32 v[72:73], v[72:73], v[176:177], v[188:189]
	v_pk_fma_f32 v[64:65], v[64:65], v[176:177], v[172:173]
	v_cvt_pk_bf16_f32 v170, v76, v77
	v_cvt_pk_bf16_f32 v171, v78, v79
	v_cvt_pk_bf16_f32 v172, v72, v73
	v_cvt_pk_bf16_f32 v173, v74, v75
	v_pk_fma_f32 v[70:71], v[70:71], v[178:179], v[190:191] neg_lo:[0,0,1] neg_hi:[0,0,1]
	v_pk_fma_f32 v[68:69], v[68:69], v[176:177], v[192:193] neg_lo:[0,0,1] neg_hi:[0,0,1]
	v_pk_fma_f32 v[66:67], v[66:67], v[178:179], v[174:175]
	global_store_dwordx4 v[180:181], v[170:173], off sc0 sc1
	v_lshl_add_u64 v[174:175], v[140:141], 0, v[136:137]
	v_mad_i64_i32 v[178:179], s[22:23], v167, s51, v[158:159]
	v_cvt_pk_bf16_f32 v170, v68, v69
	v_cvt_pk_bf16_f32 v171, v70, v71
	v_cvt_pk_bf16_f32 v172, v64, v65
	v_cvt_pk_bf16_f32 v173, v66, v67
	global_store_dwordx4 v[180:181], v[170:173], off offset:256 sc0 sc1
	global_load_dwordx4 v[170:173], v[182:183], off
	v_lshlrev_b32_e32 v136, 8, v166
	global_load_dwordx4 v[174:177], v[174:175], off
	v_lshl_add_u64 v[178:179], v[178:179], 0, s[20:21]
	v_lshl_add_u64 v[178:179], v[178:179], 0, v[156:157]
	v_and_b32_e32 v136, 0xfdf00, v136
	v_lshl_add_u64 v[180:181], v[142:143], 0, v[136:137]
	v_mad_i64_i32 v[166:167], s[22:23], v166, s51, v[158:159]
	v_lshl_add_u64 v[166:167], v[166:167], 0, s[20:21]
	v_lshl_add_u64 v[166:167], v[166:167], 0, v[156:157]
	s_waitcnt vmcnt(1)
	v_pk_mul_f32 v[182:183], v[58:59], v[172:173]
	v_pk_mul_f32 v[184:185], v[56:57], v[170:171]
	v_pk_mul_f32 v[186:187], v[62:63], v[172:173]
	v_pk_mul_f32 v[188:189], v[60:61], v[170:171]
	v_pk_mul_f32 v[190:191], v[50:51], v[172:173]
	v_pk_mul_f32 v[192:193], v[48:49], v[170:171]
	v_pk_mul_f32 v[172:173], v[54:55], v[172:173]
	v_pk_mul_f32 v[170:171], v[52:53], v[170:171]
	s_waitcnt vmcnt(0)
	v_pk_fma_f32 v[62:63], v[62:63], v[176:177], v[182:183] neg_lo:[0,0,1] neg_hi:[0,0,1]
	v_pk_fma_f32 v[60:61], v[60:61], v[174:175], v[184:185] neg_lo:[0,0,1] neg_hi:[0,0,1]
	v_pk_fma_f32 v[58:59], v[58:59], v[176:177], v[186:187]
	v_pk_fma_f32 v[56:57], v[56:57], v[174:175], v[188:189]
	v_pk_fma_f32 v[50:51], v[50:51], v[176:177], v[172:173]
	v_pk_fma_f32 v[48:49], v[48:49], v[174:175], v[170:171]
	v_cvt_pk_bf16_f32 v170, v60, v61
	v_cvt_pk_bf16_f32 v171, v62, v63
	v_cvt_pk_bf16_f32 v172, v56, v57
	v_cvt_pk_bf16_f32 v173, v58, v59
	v_pk_fma_f32 v[54:55], v[54:55], v[176:177], v[190:191] neg_lo:[0,0,1] neg_hi:[0,0,1]
	v_pk_fma_f32 v[52:53], v[52:53], v[174:175], v[192:193] neg_lo:[0,0,1] neg_hi:[0,0,1]
	global_store_dwordx4 v[178:179], v[170:173], off sc0 sc1
	v_lshl_add_u64 v[174:175], v[140:141], 0, v[136:137]
	v_lshlrev_b32_e32 v136, 8, v165
	v_cvt_pk_bf16_f32 v170, v52, v53
	v_cvt_pk_bf16_f32 v171, v54, v55
	v_cvt_pk_bf16_f32 v172, v48, v49
	v_cvt_pk_bf16_f32 v173, v50, v51
	global_store_dwordx4 v[178:179], v[170:173], off offset:256 sc0 sc1
	global_load_dwordx4 v[170:173], v[180:181], off
	v_and_b32_e32 v136, 0xfef00, v136
	global_load_dwordx4 v[174:177], v[174:175], off
	v_lshl_add_u64 v[178:179], v[142:143], 0, v[136:137]
	s_waitcnt vmcnt(1)
	v_pk_mul_f32 v[180:181], v[42:43], v[172:173]
	v_pk_mul_f32 v[182:183], v[40:41], v[170:171]
	v_pk_mul_f32 v[184:185], v[46:47], v[172:173]
	v_pk_mul_f32 v[186:187], v[44:45], v[170:171]
	v_pk_mul_f32 v[188:189], v[34:35], v[172:173]
	v_pk_mul_f32 v[190:191], v[32:33], v[170:171]
	v_pk_mul_f32 v[172:173], v[38:39], v[172:173]
	v_pk_mul_f32 v[170:171], v[36:37], v[170:171]
	s_waitcnt vmcnt(0)
; __device__ __forceinline__ unsigned cvt_pk_bf16(float lo, float hi) { unsigned r; asm volatile("v_cvt_pk_bf16_f32 %0, %1, %2" : "=v"(r) : "v"(lo), "v"(hi)); return r; }
;     __device__ __forceinline__ void operator()(const f32x4 (&acc)[2][2][4][2], const Unit& u, int wr, int wc, int fr, int fq) const {
;     ...
;                 for (int m = 0; m < 4; ++m) { const int row = row0 + ai * HALF + m * 16, t = row & (SEQ - 1);
;                     const f32x4 c4 = *(const f32x4*)(cosT + t * 64 + e0), s4 = *(const f32x4*)(sinT + t * 64 + e0);
;                     bf16_t* rowp = O + (size_t)row * ldc + colt + cin;
; #pragma unroll
;                     for (int bj = 0; bj < 2; ++bj) { const f32x4 x1 = acc[ai][bj][m][0], x2 = acc[ai][bj][m][1];
;                         const f32x4 o1 = x1 * c4 - x2 * s4, o2 = x2 * c4 + x1 * s4;
;                         ks[bj][0] += o1; ks[bj][1] += o2;
;                         u32x4 w; w.x = cvt_pk_bf16(o1[0], o1[1]); w.y = cvt_pk_bf16(o1[2], o1[3]); w.z = cvt_pk_bf16(o2[0], o2[1]); w.w = cvt_pk_bf16(o2[2], o2[3]);
;                         *(u32x4*)(rowp + bj * HALF) = w; } }
;             if (km) {
;                 const int b = u.pm >> 4, blk = u.pm & 15;
; #pragma unroll
;                 for (int bj = 0; bj < 2; ++bj) { const int h = (colt + bj * HALF - km_lo) >> 7;
; #pragma unroll
;                     for (int n = 0; n < 2; ++n)
; #pragma unroll
;                         for (int j = 0; j < 4; ++j) { float v = ks[bj][n][j];
;                             v += __shfl_xor(v, 1); v += __shfl_xor(v, 2); v += __shfl_xor(v, 4); v += __shfl_xor(v, 8);
;                             if (fr == 0) atomicAdd(kmean + ((size_t)((b * 8 + h) * 16 + blk)) * 128 + cin + 4 * n + j, v * (1.0f / 256.0f)); } }
	v_pk_fma_f32 v[46:47], v[46:47], v[176:177], v[180:181] neg_lo:[0,0,1] neg_hi:[0,0,1]
	v_pk_fma_f32 v[44:45], v[44:45], v[174:175], v[182:183] neg_lo:[0,0,1] neg_hi:[0,0,1]
	v_pk_fma_f32 v[42:43], v[42:43], v[176:177], v[184:185]
	v_pk_fma_f32 v[40:41], v[40:41], v[174:175], v[186:187]
	v_pk_fma_f32 v[34:35], v[34:35], v[176:177], v[172:173]
	v_pk_fma_f32 v[32:33], v[32:33], v[174:175], v[170:171]
	v_cvt_pk_bf16_f32 v170, v44, v45
	v_cvt_pk_bf16_f32 v171, v46, v47
	v_cvt_pk_bf16_f32 v172, v40, v41
	v_cvt_pk_bf16_f32 v173, v42, v43
	v_pk_fma_f32 v[38:39], v[38:39], v[176:177], v[188:189] neg_lo:[0,0,1] neg_hi:[0,0,1]
	v_pk_fma_f32 v[36:37], v[36:37], v[174:175], v[190:191] neg_lo:[0,0,1] neg_hi:[0,0,1]
	global_store_dwordx4 v[166:167], v[170:173], off sc0 sc1
	s_nop 1
	v_cvt_pk_bf16_f32 v170, v36, v37
	v_cvt_pk_bf16_f32 v171, v38, v39
	v_cvt_pk_bf16_f32 v172, v32, v33
	v_cvt_pk_bf16_f32 v173, v34, v35
	global_store_dwordx4 v[166:167], v[170:173], off offset:256 sc0 sc1
	global_load_dwordx4 v[170:173], v[178:179], off
	v_lshl_add_u64 v[166:167], v[140:141], 0, v[136:137]
	global_load_dwordx4 v[174:177], v[166:167], off
	v_mad_i64_i32 v[166:167], s[22:23], v165, s51, v[158:159]
	v_lshlrev_b32_e32 v136, 8, v164
	v_lshl_add_u64 v[166:167], v[166:167], 0, s[20:21]
	v_lshl_add_u64 v[166:167], v[166:167], 0, v[156:157]
	v_and_b32_e32 v136, 0xfff00, v136
	v_lshl_add_u64 v[178:179], v[142:143], 0, v[136:137]
	v_mad_i64_i32 v[158:159], s[22:23], v164, s51, v[158:159]
	v_lshl_add_u64 v[158:159], v[158:159], 0, s[20:21]
	v_lshl_add_u64 v[158:159], v[158:159], 0, v[156:157]
	s_waitcnt vmcnt(1)
	v_pk_mul_f32 v[180:181], v[26:27], v[172:173]
	v_pk_mul_f32 v[182:183], v[24:25], v[170:171]
	v_pk_mul_f32 v[184:185], v[30:31], v[172:173]
	v_pk_mul_f32 v[186:187], v[28:29], v[170:171]
	v_pk_mul_f32 v[188:189], v[18:19], v[172:173]
	v_pk_mul_f32 v[190:191], v[16:17], v[170:171]
	v_pk_mul_f32 v[172:173], v[22:23], v[172:173]
	v_pk_mul_f32 v[170:171], v[20:21], v[170:171]
	s_waitcnt vmcnt(0)
	v_pk_fma_f32 v[30:31], v[30:31], v[176:177], v[180:181] neg_lo:[0,0,1] neg_hi:[0,0,1]
	v_pk_fma_f32 v[28:29], v[28:29], v[174:175], v[182:183] neg_lo:[0,0,1] neg_hi:[0,0,1]
	v_pk_fma_f32 v[26:27], v[26:27], v[176:177], v[184:185]
	v_pk_fma_f32 v[24:25], v[24:25], v[174:175], v[186:187]
	v_pk_fma_f32 v[18:19], v[18:19], v[176:177], v[172:173]
	v_pk_fma_f32 v[16:17], v[16:17], v[174:175], v[170:171]
	v_cvt_pk_bf16_f32 v170, v28, v29
	v_cvt_pk_bf16_f32 v171, v30, v31
	v_cvt_pk_bf16_f32 v172, v24, v25
	v_cvt_pk_bf16_f32 v173, v26, v27
	v_pk_fma_f32 v[22:23], v[22:23], v[176:177], v[188:189] neg_lo:[0,0,1] neg_hi:[0,0,1]
	v_pk_fma_f32 v[20:21], v[20:21], v[174:175], v[190:191] neg_lo:[0,0,1] neg_hi:[0,0,1]
	global_store_dwordx4 v[166:167], v[170:173], off sc0 sc1
	s_nop 1
	v_cvt_pk_bf16_f32 v170, v20, v21
	v_cvt_pk_bf16_f32 v171, v22, v23
	v_cvt_pk_bf16_f32 v172, v16, v17
	v_cvt_pk_bf16_f32 v173, v18, v19
	global_store_dwordx4 v[166:167], v[170:173], off offset:256 sc0 sc1
	global_load_dwordx4 v[170:173], v[178:179], off
	v_lshl_add_u64 v[166:167], v[140:141], 0, v[136:137]
	global_load_dwordx4 v[174:177], v[166:167], off
	s_waitcnt vmcnt(1)
	v_pk_mul_f32 v[156:157], v[10:11], v[172:173]
	v_pk_mul_f32 v[164:165], v[8:9], v[170:171]
	v_pk_mul_f32 v[166:167], v[14:15], v[172:173]
	v_pk_mul_f32 v[178:179], v[12:13], v[170:171]
	v_pk_mul_f32 v[180:181], v[2:3], v[172:173]
	v_pk_mul_f32 v[182:183], v[0:1], v[170:171]
	v_pk_mul_f32 v[172:173], v[6:7], v[172:173]
	v_pk_mul_f32 v[170:171], v[4:5], v[170:171]
	s_waitcnt vmcnt(0)
	v_pk_fma_f32 v[14:15], v[14:15], v[176:177], v[156:157] neg_lo:[0,0,1] neg_hi:[0,0,1]
	v_pk_fma_f32 v[156:157], v[12:13], v[174:175], v[164:165] neg_lo:[0,0,1] neg_hi:[0,0,1]
	v_pk_fma_f32 v[10:11], v[10:11], v[176:177], v[166:167]
	v_pk_fma_f32 v[12:13], v[8:9], v[174:175], v[178:179]
	v_pk_fma_f32 v[6:7], v[6:7], v[176:177], v[180:181] neg_lo:[0,0,1] neg_hi:[0,0,1]
	v_pk_fma_f32 v[4:5], v[4:5], v[174:175], v[182:183] neg_lo:[0,0,1] neg_hi:[0,0,1]
	v_pk_fma_f32 v[2:3], v[2:3], v[176:177], v[172:173]
	v_pk_fma_f32 v[0:1], v[0:1], v[174:175], v[170:171]
	v_cvt_pk_bf16_f32 v164, v156, v157
	v_cvt_pk_bf16_f32 v165, v14, v15
	v_cvt_pk_bf16_f32 v166, v12, v13
	v_cvt_pk_bf16_f32 v167, v10, v11
	global_store_dwordx4 v[158:159], v[164:167], off sc0 sc1
	s_nop 1
	v_cvt_pk_bf16_f32 v164, v4, v5
	v_cvt_pk_bf16_f32 v165, v6, v7
	v_cvt_pk_bf16_f32 v166, v0, v1
	v_cvt_pk_bf16_f32 v167, v2, v3
	global_store_dwordx4 v[158:159], v[164:167], off offset:256 sc0 sc1
	s_cbranch_scc1 .LBB0_801
	v_pk_add_f32 v[8:9], v[124:125], 0 op_sel_hi:[1,0]
	s_ashr_i32 s20, s55, 1
	v_pk_add_f32 v[8:9], v[8:9], v[108:109]
	s_and_b32 s23, s20, -8
	v_pk_add_f32 v[8:9], v[8:9], v[92:93]
	s_add_i32 s20, s8, 0xfffff000
	v_pk_add_f32 v[8:9], v[8:9], v[76:77]
	s_lshr_b32 s20, s20, 7
	v_pk_add_f32 v[8:9], v[8:9], v[60:61]
	s_add_i32 s20, s20, s23
	v_pk_add_f32 v[8:9], v[8:9], v[44:45]
	s_and_b32 s22, s55, 15
	v_pk_add_f32 v[8:9], v[8:9], v[28:29]
	s_lshl_b32 s20, s20, 4
	v_pk_add_f32 v[28:29], v[8:9], v[156:157]
	v_and_b32_e32 v9, 64, v163
	v_xor_b32_e32 v8, 1, v163
	v_add_u32_e32 v9, 64, v9
	v_cmp_lt_i32_e32 vcc, v8, v9
	s_or_b32 s20, s20, s22
	s_ashr_i32 s21, s20, 31
	v_cndmask_b32_e32 v8, v163, v8, vcc
	v_lshlrev_b32_e32 v44, 2, v8
	ds_bpermute_b32 v61, v44, v28
	v_xor_b32_e32 v8, 2, v163
	v_cmp_lt_i32_e32 vcc, v8, v9
	s_lshl_b64 s[20:21], s[20:21], 9
	s_waitcnt lgkmcnt(0)
	v_add_f32_e32 v61, v28, v61
	v_cndmask_b32_e32 v8, v163, v8, vcc
	v_lshlrev_b32_e32 v45, 2, v8
	v_xor_b32_e32 v8, 4, v163
	v_cmp_lt_i32_e32 vcc, v8, v9
	ds_bpermute_b32 v76, v45, v61
	s_nop 0
	v_cndmask_b32_e32 v8, v163, v8, vcc
	v_lshlrev_b32_e32 v60, 2, v8
	v_xor_b32_e32 v8, 8, v163
	v_cmp_lt_i32_e32 vcc, v8, v9
	s_nop 1
	v_cndmask_b32_e32 v8, v163, v8, vcc
	v_lshlrev_b32_e32 v28, 2, v8
	s_waitcnt lgkmcnt(0)
	v_add_f32_e32 v8, v61, v76
	ds_bpermute_b32 v9, v60, v8
	s_waitcnt lgkmcnt(0)
	v_add_f32_e32 v61, v8, v9
	ds_bpermute_b32 v76, v28, v61
	v_lshl_add_u64 v[8:9], v[144:145], 0, s[20:21]
	s_and_saveexec_b64 s[20:21], s[0:1]
	s_cbranch_execz .LBB0_770
	s_waitcnt lgkmcnt(0)
	v_add_f32_e32 v61, v61, v76
	v_mul_f32_e32 v61, 0x3b800000, v61
	global_atomic_add_f32 v[8:9], v61, off

; __device__ __forceinline__ unsigned pk2(float lo, float hi) { unsigned r; asm("v_cvt_pk_bf16_f32 %0, %1, %2" : "=v"(r) : "v"(lo), "v"(hi)); return r; }
; template <int MODE> ...
;     ...
;     if (hiw && pend) ATT_PV(lds + bprev * BUFB);
;     __syncthreads();
;     if (hasnext) {
; #pragma unroll
;         for (int i = 0; i < 2; ++i) { const int grow = nx.rowbase + (nx.kp0 + srow + 32 * i) * nx.rowstride;
;             kr[i] = *(const u32x4*)(nx.Kp + (size_t)grow * nx.ld + sch * 8); vr[i] = *(const u32x4*)(nx.Vp + (size_t)grow * nx.ld + sch * 8); } }
;     ...
; #pragma unroll
;     for (int qt = 0; qt < 2; ++qt) {
;         const int orow = rowbase + (qw0 + 16 * qt + c15) * rowstride;
;         const float inv = (MODE == SB) ? 1.0f : 1.0f / lrun[qt];
; #pragma unroll
;         for (int dt = 0; dt < 8; ++dt) { const f32x4 v = o[qt][dt] * inv; u32x2 w; w.x = pk2(v[0], v[1]); w.y = pk2(v[2], v[3]);
;             *(u32x2*)(Op + (size_t)orow * ldo + 16 * dt + 4 * g) = w; }
.LBB0_860:
	s_and_b64 s[2:3], s[24:25], exec
	s_cselect_b32 s6, s68, 0
	s_cselect_b32 s3, s19, s43
	s_cselect_b32 s2, s18, s42
	v_add_u32_e32 v0, s6, v190
	s_cselect_b32 s5, s21, s45
	s_cselect_b32 s4, s20, s44
	s_waitcnt vmcnt(7)
	v_lshl_add_u64 v[2:3], s[2:3], 0, v[22:23]
	v_add_u32_e32 v12, s40, v0
	v_add_u32_e32 v0, s41, v0
	v_lshl_add_u64 v[4:5], s[4:5], 0, v[22:23]
	v_mad_i64_i32 v[6:7], s[2:3], v12, s94, v[2:3]
	v_mad_i64_i32 v[2:3], s[2:3], v0, s94, v[2:3]
	s_barrier
	global_load_dwordx4 v[8:11], v[6:7], off
	v_mad_i64_i32 v[6:7], s[2:3], v12, s94, v[4:5]
	global_load_dwordx4 v[12:15], v[2:3], off
	v_mad_i64_i32 v[2:3], s[2:3], v0, s94, v[4:5]
	global_load_dwordx4 v[16:19], v[6:7], off
	global_load_dwordx4 v[20:23], v[2:3], off
	v_lshlrev_b32_e32 v0, 1, v191
	v_lshl_add_u64 v[2:3], s[22:23], 0, v[0:1]
	v_mad_i64_i32 v[4:5], s[2:3], v189, s97, v[2:3]
	v_cvt_pk_bf16_f32 v6, v128, v129
	v_cvt_pk_bf16_f32 v7, v130, v131
	global_store_dwordx2 v[4:5], v[6:7], off sc0 sc1
	v_cvt_pk_bf16_f32 v6, v124, v125
	v_cvt_pk_bf16_f32 v7, v126, v127
	global_store_dwordx2 v[4:5], v[6:7], off offset:32 sc0 sc1
	v_cvt_pk_bf16_f32 v6, v120, v121
	v_cvt_pk_bf16_f32 v7, v122, v123
	global_store_dwordx2 v[4:5], v[6:7], off offset:64 sc0 sc1
	v_cvt_pk_bf16_f32 v6, v116, v117
	v_cvt_pk_bf16_f32 v7, v118, v119
	global_store_dwordx2 v[4:5], v[6:7], off offset:96 sc0 sc1
	v_cvt_pk_bf16_f32 v6, v112, v113
	v_cvt_pk_bf16_f32 v7, v114, v115
	global_store_dwordx2 v[4:5], v[6:7], off offset:128 sc0 sc1
	v_cvt_pk_bf16_f32 v6, v108, v109
	v_cvt_pk_bf16_f32 v7, v110, v111
	global_store_dwordx2 v[4:5], v[6:7], off offset:160 sc0 sc1
	v_cvt_pk_bf16_f32 v6, v104, v105
	v_cvt_pk_bf16_f32 v7, v106, v107
	global_store_dwordx2 v[4:5], v[6:7], off offset:192 sc0 sc1
	v_cvt_pk_bf16_f32 v6, v100, v101
	v_cvt_pk_bf16_f32 v7, v102, v103
	global_store_dwordx2 v[4:5], v[6:7], off offset:224 sc0 sc1
	v_mad_i64_i32 v[2:3], s[2:3], v161, s97, v[2:3]
	v_cvt_pk_bf16_f32 v4, v96, v97
	v_cvt_pk_bf16_f32 v5, v98, v99
	global_store_dwordx2 v[2:3], v[4:5], off sc0 sc1
	v_cvt_pk_bf16_f32 v4, v92, v93
	v_cvt_pk_bf16_f32 v5, v94, v95
	global_store_dwordx2 v[2:3], v[4:5], off offset:32 sc0 sc1
	v_cvt_pk_bf16_f32 v4, v88, v89
	v_cvt_pk_bf16_f32 v5, v90, v91
	global_store_dwordx2 v[2:3], v[4:5], off offset:64 sc0 sc1
	v_cvt_pk_bf16_f32 v4, v84, v85
	v_cvt_pk_bf16_f32 v5, v86, v87
	global_store_dwordx2 v[2:3], v[4:5], off offset:96 sc0 sc1
	v_cvt_pk_bf16_f32 v4, v52, v53
	v_cvt_pk_bf16_f32 v5, v54, v55
	global_store_dwordx2 v[2:3], v[4:5], off offset:128 sc0 sc1
	v_cvt_pk_bf16_f32 v4, v48, v49
	v_cvt_pk_bf16_f32 v5, v50, v51
	global_store_dwordx2 v[2:3], v[4:5], off offset:160 sc0 sc1
	v_cvt_pk_bf16_f32 v4, v44, v45
	v_cvt_pk_bf16_f32 v5, v46, v47
	s_mov_b64 s[2:3], -1
	s_mov_b64 s[24:25], 0
	s_and_b64 vcc, exec, s[46:47]
	global_store_dwordx2 v[2:3], v[4:5], off offset:192 sc0 sc1
	v_cvt_pk_bf16_f32 v4, v40, v41
	v_cvt_pk_bf16_f32 v5, v42, v43
	global_store_dwordx2 v[2:3], v[4:5], off offset:224 sc0 sc1
	s_cbranch_vccnz .LBB0_887

; __device__ __forceinline__ unsigned pk2(float lo, float hi) { unsigned r; asm("v_cvt_pk_bf16_f32 %0, %1, %2" : "=v"(r) : "v"(lo), "v"(hi)); return r; }
; template <int MODE> ...
;     ...
;     for (int qt = 0; qt < 2; ++qt) {
;         const int orow = rowbase + (qw0 + 16 * qt + c15) * rowstride;
;         const float inv = (MODE == SB) ? 1.0f : 1.0f / lrun[qt];
; #pragma unroll
;         for (int dt = 0; dt < 8; ++dt) { const f32x4 v = o[qt][dt] * inv; u32x2 w; w.x = pk2(v[0], v[1]); w.y = pk2(v[2], v[3]);
;             *(u32x2*)(Op + (size_t)orow * ldo + 16 * dt + 4 * g) = w; }
.LBB0_888:
	v_div_scale_f32 v86, s[2:3], v164, v164, 1.0
	v_rcp_f32_e32 v87, v86
	v_lshlrev_b32_e32 v0, 1, v153
	v_lshl_add_u64 v[84:85], s[48:49], 0, v[0:1]
	s_mov_b64 s[54:55], 0
	v_fma_f32 v0, -v86, v87, 1.0
	v_fmac_f32_e32 v87, v0, v87
	v_div_scale_f32 v0, vcc, 1.0, v164, 1.0
	v_mul_f32_e32 v88, v0, v87
	v_fma_f32 v89, -v86, v88, v0
	v_fmac_f32_e32 v88, v89, v87
	v_fma_f32 v0, -v86, v88, v0
	v_div_fmas_f32 v0, v0, v87, v88
	v_div_fixup_f32 v0, v0, v164, 1.0
	v_pk_mul_f32 v[56:57], v[0:1], v[56:57] op_sel_hi:[0,1]
	v_mad_i64_i32 v[86:87], s[2:3], v156, s97, v[84:85]
	v_pk_mul_f32 v[82:83], v[0:1], v[82:83] op_sel_hi:[0,1]
	v_pk_mul_f32 v[80:81], v[0:1], v[80:81] op_sel_hi:[0,1]
	v_pk_mul_f32 v[78:79], v[0:1], v[78:79] op_sel_hi:[0,1]
	v_pk_mul_f32 v[76:77], v[0:1], v[76:77] op_sel_hi:[0,1]
	v_pk_mul_f32 v[74:75], v[0:1], v[74:75] op_sel_hi:[0,1]
	v_pk_mul_f32 v[72:73], v[0:1], v[72:73] op_sel_hi:[0,1]
	v_pk_mul_f32 v[70:71], v[0:1], v[70:71] op_sel_hi:[0,1]
	v_pk_mul_f32 v[68:69], v[0:1], v[68:69] op_sel_hi:[0,1]
	v_pk_mul_f32 v[66:67], v[0:1], v[66:67] op_sel_hi:[0,1]
	v_pk_mul_f32 v[64:65], v[0:1], v[64:65] op_sel_hi:[0,1]
	v_pk_mul_f32 v[62:63], v[0:1], v[62:63] op_sel_hi:[0,1]
	v_pk_mul_f32 v[60:61], v[0:1], v[60:61] op_sel_hi:[0,1]
	v_pk_mul_f32 v[58:59], v[0:1], v[58:59] op_sel_hi:[0,1]
	v_cvt_pk_bf16_f32 v56, v56, v57
	v_pk_mul_f32 v[54:55], v[0:1], v[54:55] op_sel_hi:[0,1]
	v_pk_mul_f32 v[52:53], v[0:1], v[52:53] op_sel_hi:[0,1]
	v_div_scale_f32 v0, s[2:3], v7, v7, 1.0
	v_cvt_pk_bf16_f32 v57, v58, v59
	global_store_dwordx2 v[86:87], v[56:57], off offset:192 sc0 sc1
	v_rcp_f32_e32 v56, v0
	v_cvt_pk_bf16_f32 v52, v52, v53
	v_cvt_pk_bf16_f32 v53, v54, v55
	global_store_dwordx2 v[86:87], v[52:53], off offset:224 sc0 sc1
	v_fma_f32 v52, -v0, v56, 1.0
	v_fmac_f32_e32 v56, v52, v56
	v_div_scale_f32 v52, vcc, 1.0, v7, 1.0
	v_mul_f32_e32 v53, v52, v56
	v_fma_f32 v54, -v0, v53, v52
	v_fmac_f32_e32 v53, v54, v56
	v_fma_f32 v0, -v0, v53, v52
	v_div_fmas_f32 v0, v0, v56, v53
	v_div_fixup_f32 v0, v0, v7, 1.0
	v_mad_i64_i32 v[6:7], s[2:3], v6, s97, v[84:85]
	v_pk_mul_f32 v[48:49], v[0:1], v[48:49] op_sel_hi:[0,1]
	v_pk_mul_f32 v[44:45], v[0:1], v[44:45] op_sel_hi:[0,1]
	v_pk_mul_f32 v[40:41], v[0:1], v[40:41] op_sel_hi:[0,1]
	v_pk_mul_f32 v[36:37], v[0:1], v[36:37] op_sel_hi:[0,1]
	v_pk_mul_f32 v[32:33], v[0:1], v[32:33] op_sel_hi:[0,1]
	v_pk_mul_f32 v[28:29], v[0:1], v[28:29] op_sel_hi:[0,1]
	v_pk_mul_f32 v[24:25], v[0:1], v[24:25] op_sel_hi:[0,1]
	v_pk_mul_f32 v[2:3], v[0:1], v[2:3] op_sel_hi:[0,1]
	s_and_b64 vcc, exec, s[52:53]
	v_cvt_pk_bf16_f32 v80, v80, v81
	v_cvt_pk_bf16_f32 v81, v82, v83
	global_store_dwordx2 v[86:87], v[80:81], off sc0 sc1
	v_cvt_pk_bf16_f32 v76, v76, v77
	v_cvt_pk_bf16_f32 v77, v78, v79
	global_store_dwordx2 v[86:87], v[76:77], off offset:32 sc0 sc1
	v_cvt_pk_bf16_f32 v72, v72, v73
	v_cvt_pk_bf16_f32 v73, v74, v75
	global_store_dwordx2 v[86:87], v[72:73], off offset:64 sc0 sc1
	v_cvt_pk_bf16_f32 v68, v68, v69
	v_cvt_pk_bf16_f32 v69, v70, v71
	global_store_dwordx2 v[86:87], v[68:69], off offset:96 sc0 sc1
	v_cvt_pk_bf16_f32 v64, v64, v65
	v_cvt_pk_bf16_f32 v65, v66, v67
	global_store_dwordx2 v[86:87], v[64:65], off offset:128 sc0 sc1
	v_cvt_pk_bf16_f32 v60, v60, v61
	v_cvt_pk_bf16_f32 v61, v62, v63
	global_store_dwordx2 v[86:87], v[60:61], off offset:160 sc0 sc1
	v_pk_mul_f32 v[50:51], v[0:1], v[50:51] op_sel_hi:[0,1]
	v_cvt_pk_bf16_f32 v48, v48, v49
	v_cvt_pk_bf16_f32 v49, v50, v51
	global_store_dwordx2 v[6:7], v[48:49], off sc0 sc1
	v_pk_mul_f32 v[46:47], v[0:1], v[46:47] op_sel_hi:[0,1]
	v_cvt_pk_bf16_f32 v44, v44, v45
	v_cvt_pk_bf16_f32 v45, v46, v47
	global_store_dwordx2 v[6:7], v[44:45], off offset:32 sc0 sc1
	v_pk_mul_f32 v[42:43], v[0:1], v[42:43] op_sel_hi:[0,1]
	v_cvt_pk_bf16_f32 v40, v40, v41
	v_cvt_pk_bf16_f32 v41, v42, v43
	global_store_dwordx2 v[6:7], v[40:41], off offset:64 sc0 sc1
	v_pk_mul_f32 v[38:39], v[0:1], v[38:39] op_sel_hi:[0,1]
	v_cvt_pk_bf16_f32 v36, v36, v37
	v_cvt_pk_bf16_f32 v37, v38, v39
	global_store_dwordx2 v[6:7], v[36:37], off offset:96 sc0 sc1
	v_pk_mul_f32 v[34:35], v[0:1], v[34:35] op_sel_hi:[0,1]
	v_cvt_pk_bf16_f32 v32, v32, v33
	v_cvt_pk_bf16_f32 v33, v34, v35
	global_store_dwordx2 v[6:7], v[32:33], off offset:128 sc0 sc1
	v_pk_mul_f32 v[30:31], v[0:1], v[30:31] op_sel_hi:[0,1]
	v_cvt_pk_bf16_f32 v28, v28, v29
	v_cvt_pk_bf16_f32 v29, v30, v31
	global_store_dwordx2 v[6:7], v[28:29], off offset:160 sc0 sc1
	v_pk_mul_f32 v[26:27], v[0:1], v[26:27] op_sel_hi:[0,1]
	v_cvt_pk_bf16_f32 v24, v24, v25
	v_cvt_pk_bf16_f32 v25, v26, v27
	global_store_dwordx2 v[6:7], v[24:25], off offset:192 sc0 sc1
	v_pk_mul_f32 v[4:5], v[0:1], v[4:5] op_sel_hi:[0,1]
	v_cvt_pk_bf16_f32 v2, v2, v3
	v_cvt_pk_bf16_f32 v3, v4, v5
	global_store_dwordx2 v[6:7], v[2:3], off offset:224 sc0 sc1
	s_cbranch_vccnz .LBB0_858

; __device__ __forceinline__ void resid_rows(const float* prev, const bf16_t* Y, const float* ga, const bf16_t* F, const float* gc, float* xout, const float* gb, bf16_t* hn, int gw, int NGW, int lane) {
;     for (int m = gw; m < MTOK; m += NGW) {
;         f32x4 y[8]; float s = 0.f;
; #pragma unroll
;         for (int j = 0; j < 8; ++j) { const u32x2 w = *(const u32x2*)(Y + (size_t)m * LDH + 4 * lane + 256 * j); y[j] = (f32x4){bflo(w.x), bfhi(w.x), bflo(w.y), bfhi(w.y)};
;             s += (y[j][0] * y[j][0] + y[j][1] * y[j][1]) + (y[j][2] * y[j][2] + y[j][3] * y[j][3]); }
;         const float rs = 1.0f / sqrtf(wave_sum(s) * (1.0f / D_MODEL) + EPS);
;         f32x4 x1[8];
; #pragma unroll
;         for (int j = 0; j < 8; ++j) { const f32x4 pv = *(const f32x4*)(prev + (size_t)m * D_MODEL + 4 * lane + 256 * j); const f32x4 gv = *(const f32x4*)(ga + 4 * lane + 256 * j);
;             x1[j] = pv + y[j] * rs * gv; }
;         if (F) {
;             float s2 = 0.f;
; #pragma unroll
;             for (int j = 0; j < 8; ++j) { const u32x2 w = *(const u32x2*)(F + (size_t)m * LDH + 4 * lane + 256 * j); y[j] = (f32x4){bflo(w.x), bfhi(w.x), bflo(w.y), bfhi(w.y)};
;                 s2 += (y[j][0] * y[j][0] + y[j][1] * y[j][1]) + (y[j][2] * y[j][2] + y[j][3] * y[j][3]); }
.LBB0_1091:
	global_load_dwordx2 v[92:93], v[90:91], off
	global_load_dwordx2 v[94:95], v[90:91], off offset:512
	global_load_dwordx2 v[96:97], v[90:91], off offset:1024
	global_load_dwordx2 v[98:99], v[90:91], off offset:1536
	global_load_dwordx2 v[102:103], v[90:91], off offset:2048
	global_load_dwordx2 v[104:105], v[90:91], off offset:2560
	global_load_dwordx2 v[106:107], v[90:91], off offset:3072
	global_load_dwordx2 v[108:109], v[90:91], off offset:3584
	global_load_dwordx4 v[0:3], v[88:89], off offset:-4096
	global_load_dwordx4 v[4:7], v[88:89], off offset:-3072
	global_load_dwordx4 v[12:15], v[68:69], off
	global_load_dwordx4 v[8:11], v[68:69], off offset:1024
	global_load_dwordx4 v[16:19], v[88:89], off offset:-2048
	global_load_dwordx4 v[20:23], v[88:89], off offset:-1024
	global_load_dwordx4 v[28:31], v[68:69], off offset:2048
	global_load_dwordx4 v[24:27], v[68:69], off offset:3072
	global_load_dwordx4 v[32:35], v[88:89], off
	global_load_dwordx4 v[36:39], v[88:89], off offset:1024
	global_load_dwordx4 v[40:43], v[82:83], off
	global_load_dwordx4 v[44:47], v[84:85], off
	global_load_dwordx4 v[48:51], v[88:89], off offset:2048
	global_load_dwordx4 v[52:55], v[88:89], off offset:3072
	global_load_dwordx4 v[56:59], v[86:87], off
	global_load_dwordx4 v[60:63], v[80:81], off
	global_load_dwordx4 v[64:67], v[70:71], off
	v_add_co_u32_e32 v100, vcc, s7, v90
	s_add_i32 s8, s8, s60
	s_nop 0
	v_addc_co_u32_e32 v101, vcc, 0, v91, vcc
	v_lshl_add_u64 v[88:89], v[88:89], 0, s[4:5]
	v_lshl_add_u64 v[90:91], v[90:91], 0, s[82:83]
	s_cmpk_lt_i32 s8, 0x4000
	s_waitcnt vmcnt(24)
	v_lshlrev_b32_e32 v118, 16, v92
	v_and_b32_e32 v119, 0xffff0000, v92
	v_lshlrev_b32_e32 v92, 16, v93
	v_and_b32_e32 v93, 0xffff0000, v93
	s_waitcnt vmcnt(23)
	v_lshlrev_b32_e32 v121, 16, v95
	v_lshlrev_b32_e32 v120, 16, v94
	v_and_b32_e32 v95, 0xffff0000, v95
	v_and_b32_e32 v94, 0xffff0000, v94
	s_waitcnt vmcnt(22)
	v_and_b32_e32 v123, 0xffff0000, v96
	s_waitcnt vmcnt(21)
	v_lshlrev_b32_e32 v125, 16, v98
	s_waitcnt vmcnt(17)
	v_lshlrev_b32_e32 v135, 16, v108
	v_mul_f32_e32 v124, v93, v93
	v_pk_mul_f32 v[138:139], v[94:95], v[94:95]
	v_mul_f32_e32 v134, v119, v119
	v_lshlrev_b32_e32 v122, 16, v96
	v_lshlrev_b32_e32 v96, 16, v97
	v_and_b32_e32 v97, 0xffff0000, v97
	v_lshlrev_b32_e32 v129, 16, v103
	v_lshlrev_b32_e32 v128, 16, v102
	v_and_b32_e32 v103, 0xffff0000, v103
	v_and_b32_e32 v102, 0xffff0000, v102
	v_lshlrev_b32_e32 v131, 16, v105
	v_lshlrev_b32_e32 v130, 16, v104
	v_and_b32_e32 v105, 0xffff0000, v105
	v_and_b32_e32 v104, 0xffff0000, v104
	v_mov_b32_e32 v141, v125
	v_mul_f32_e32 v140, v123, v123
	v_mov_b32_e32 v154, v120
	v_mov_b32_e32 v155, v94
	v_mov_b32_e32 v94, v121
	v_pk_fma_f32 v[160:161], v[92:93], v[92:93], v[124:125] op_sel_hi:[1,1,0]
	v_pk_fma_f32 v[120:121], v[120:121], v[120:121], v[138:139]
	v_pk_fma_f32 v[138:139], v[118:119], v[118:119], v[134:135] op_sel_hi:[1,1,0]
	v_and_b32_e32 v127, 0xffff0000, v98
	v_lshlrev_b32_e32 v98, 16, v99
	v_and_b32_e32 v99, 0xffff0000, v99
	v_mul_f32_e32 v142, v97, v97
	v_pk_mul_f32 v[144:145], v[102:103], v[102:103]
	v_pk_mul_f32 v[146:147], v[104:105], v[104:105]
	v_mov_b32_e32 v143, v135
	v_pk_fma_f32 v[162:163], v[122:123], v[122:123], v[140:141] op_sel_hi:[1,1,0]
	v_mov_b32_e32 v124, v138
	v_mov_b32_e32 v140, v160
	v_mul_f32_e32 v149, v127, v127
	v_mul_f32_e32 v153, v98, v98
	v_mul_f32_e32 v166, v99, v99
	v_mov_b32_e32 v126, v125
	v_mov_b32_e32 v156, v128
	v_mov_b32_e32 v157, v102
	v_mov_b32_e32 v102, v129
	v_mov_b32_e32 v158, v131
	v_mov_b32_e32 v159, v105
	v_pk_fma_f32 v[164:165], v[96:97], v[96:97], v[142:143] op_sel_hi:[1,1,0]
	v_pk_fma_f32 v[128:129], v[128:129], v[128:129], v[144:145]
	v_pk_fma_f32 v[144:145], v[130:131], v[130:131], v[146:147]
	v_mov_b32_e32 v131, v104
	v_pk_add_f32 v[104:105], v[138:139], v[160:161]
	v_pk_add_f32 v[120:121], v[120:121], v[120:121] op_sel:[0,1] op_sel_hi:[1,0]
	v_pk_mul_f32 v[124:125], v[124:125], v[140:141]
	v_mov_b32_e32 v163, v153
	v_mov_b32_e32 v165, v166
	v_mov_b32_e32 v121, v149
	v_mov_b32_e32 v105, v125
	v_pk_add_f32 v[140:141], v[162:163], v[164:165]
	v_pk_add_f32 v[104:105], v[104:105], v[120:121]
	v_lshlrev_b32_e32 v132, 16, v106
	v_pk_add_f32 v[104:105], v[104:105], v[140:141]
	v_and_b32_e32 v133, 0xffff0000, v106
	v_lshlrev_b32_e32 v106, 16, v107
	v_and_b32_e32 v107, 0xffff0000, v107
	v_pk_add_f32 v[128:129], v[128:129], v[128:129] op_sel:[0,1] op_sel_hi:[1,0]
	v_pk_add_f32 v[104:105], v[104:105], v[104:105] op_sel:[0,1] op_sel_hi:[1,0]
	v_and_b32_e32 v137, 0xffff0000, v108
	v_lshlrev_b32_e32 v108, 16, v109
	v_and_b32_e32 v109, 0xffff0000, v109
	v_mul_f32_e32 v150, v133, v133
	v_mul_f32_e32 v152, v107, v107
	v_mov_b32_e32 v142, v128
	v_mov_b32_e32 v134, v104
	v_mul_f32_e32 v167, v137, v137
	v_mul_f32_e32 v170, v108, v108
	v_mul_f32_e32 v171, v109, v109
	v_pk_fma_f32 v[146:147], v[132:133], v[132:133], v[150:151] op_sel_hi:[1,1,0]
	v_pk_fma_f32 v[150:151], v[106:107], v[106:107], v[152:153] op_sel_hi:[1,1,0]
	v_pk_add_f32 v[138:139], v[144:145], v[144:145] op_sel:[0,1] op_sel_hi:[1,0]
	v_pk_add_f32 v[104:105], v[104:105], v[128:129]
	v_pk_mul_f32 v[120:121], v[134:135], v[142:143]
	v_mov_b32_e32 v147, v170
	v_mov_b32_e32 v151, v171
	v_mov_b32_e32 v139, v167
	v_mov_b32_e32 v105, v121
	v_pk_add_f32 v[144:145], v[146:147], v[150:151]
	v_pk_add_f32 v[104:105], v[104:105], v[138:139]
	v_mov_b32_e32 v136, v135
	v_pk_add_f32 v[104:105], v[104:105], v[144:145]
	s_nop 0
	v_add_f32_e32 v104, v104, v105
	ds_bpermute_b32 v105, v110, v104
	s_waitcnt lgkmcnt(0)
	v_add_f32_e32 v104, v104, v105
	ds_bpermute_b32 v105, v111, v104
	s_waitcnt lgkmcnt(0)
; __device__ __forceinline__ void row_norm_store(const f32x4 (&v)[8], const float* gain, bf16_t* orow, int lane) {
;     float s = 0.f;
; #pragma unroll
;     for (int j = 0; j < 8; ++j) s += (v[j][0] * v[j][0] + v[j][1] * v[j][1]) + (v[j][2] * v[j][2] + v[j][3] * v[j][3]);
;     const float rs = 1.0f / sqrtf(wave_sum(s) * (1.0f / D_MODEL) + EPS);
; __device__ __forceinline__ void resid_rows(const float* prev, const bf16_t* Y, const float* ga, const bf16_t* F, const float* gc, float* xout, const float* gb, bf16_t* hn, int gw, int NGW, int lane) {
;     ...
;         const float rs = 1.0f / sqrtf(wave_sum(s) * (1.0f / D_MODEL) + EPS);
;         f32x4 x1[8];
; #pragma unroll
;         for (int j = 0; j < 8; ++j) { const f32x4 pv = *(const f32x4*)(prev + (size_t)m * D_MODEL + 4 * lane + 256 * j); const f32x4 gv = *(const f32x4*)(ga + 4 * lane + 256 * j);
;             x1[j] = pv + y[j] * rs * gv; }
	v_add_f32_e32 v104, v104, v105
	ds_bpermute_b32 v105, v112, v104
	s_waitcnt lgkmcnt(0)
	v_add_f32_e32 v104, v104, v105
	ds_bpermute_b32 v105, v113, v104
	s_waitcnt lgkmcnt(0)
	v_add_f32_e32 v104, v104, v105
	ds_bpermute_b32 v105, v114, v104
	s_waitcnt lgkmcnt(0)
	v_add_f32_e32 v104, v104, v105
	ds_bpermute_b32 v105, v115, v104
	s_waitcnt lgkmcnt(0)
	v_add_f32_e32 v104, v104, v105
	v_fmamk_f32 v104, v104, 0x3a000000, v116
	v_mul_f32_e32 v105, 0x4f800000, v104
	v_cmp_gt_f32_e32 vcc, s6, v104
	s_nop 1
	v_cndmask_b32_e32 v104, v104, v105, vcc
	v_sqrt_f32_e32 v105, v104
	s_nop 0
	v_add_u32_e32 v120, -1, v105
	v_add_u32_e32 v121, 1, v105
	v_fma_f32 v124, -v120, v105, v104
	v_fma_f32 v125, -v121, v105, v104
	v_cmp_ge_f32_e64 s[0:1], 0, v124
	s_nop 1
	v_cndmask_b32_e64 v105, v105, v120, s[0:1]
	v_cmp_lt_f32_e64 s[0:1], 0, v125
	s_nop 1
	v_cndmask_b32_e64 v105, v105, v121, s[0:1]
	v_mul_f32_e32 v120, 0x37800000, v105
	v_cndmask_b32_e32 v105, v105, v120, vcc
	v_cmp_class_f32_e32 vcc, v104, v117
	s_nop 1
	v_cndmask_b32_e32 v104, v105, v104, vcc
	v_div_scale_f32 v105, s[0:1], v104, v104, 1.0
	v_rcp_f32_e32 v121, v105
	v_div_scale_f32 v120, vcc, 1.0, v104, 1.0
	v_fma_f32 v124, -v105, v121, 1.0
	v_fmac_f32_e32 v121, v124, v121
	v_mul_f32_e32 v124, v120, v121
	v_fma_f32 v125, -v105, v124, v120
	v_fmac_f32_e32 v124, v125, v121
	v_fma_f32 v105, -v105, v124, v120
	v_div_fmas_f32 v105, v105, v121, v124
	v_div_fixup_f32 v104, v105, v104, 1.0
	v_pk_mul_f32 v[118:119], v[104:105], v[118:119] op_sel_hi:[0,1]
	v_pk_mul_f32 v[92:93], v[104:105], v[92:93] op_sel_hi:[0,1]
	v_pk_mul_f32 v[120:121], v[104:105], v[154:155] op_sel_hi:[0,1]
	v_pk_mul_f32 v[94:95], v[104:105], v[94:95] op_sel_hi:[0,1]
	v_pk_mul_f32 v[96:97], v[104:105], v[96:97] op_sel_hi:[0,1]
	v_pk_mul_f32 v[122:123], v[104:105], v[122:123] op_sel_hi:[0,1]
	v_pk_mul_f32 v[98:99], v[98:99], v[104:105] op_sel_hi:[1,0]
	v_pk_mul_f32 v[102:103], v[104:105], v[102:103] op_sel_hi:[0,1]
	v_pk_mul_f32 v[128:129], v[104:105], v[158:159] op_sel_hi:[0,1]
	s_waitcnt vmcnt(14)
	v_pk_fma_f32 v[2:3], v[14:15], v[92:93], v[2:3]
	v_pk_fma_f32 v[0:1], v[12:13], v[118:119], v[0:1]
	s_waitcnt vmcnt(13)
	v_pk_fma_f32 v[6:7], v[10:11], v[94:95], v[6:7]
	v_pk_fma_f32 v[4:5], v[8:9], v[120:121], v[4:5]
	v_pk_mul_f32 v[124:125], v[126:127], v[104:105] op_sel_hi:[1,0]
	v_pk_mul_f32 v[126:127], v[104:105], v[156:157] op_sel_hi:[0,1]
	v_pk_mul_f32 v[130:131], v[104:105], v[130:131] op_sel_hi:[0,1]
	s_waitcnt vmcnt(10)
	v_pk_fma_f32 v[8:9], v[28:29], v[122:123], v[16:17]
	v_pk_fma_f32 v[10:11], v[30:31], v[96:97], v[18:19]
	s_waitcnt vmcnt(9)
	v_pk_fma_f32 v[12:13], v[26:27], v[98:99], v[22:23]
	s_waitcnt vmcnt(1)
	v_pk_fma_f32 v[16:17], v[62:63], v[102:103], v[34:35]
	v_pk_fma_f32 v[22:23], v[42:43], v[128:129], v[38:39]
	v_mov_b32_e32 v34, v1
	v_mov_b32_e32 v35, v5
	v_mov_b32_e32 v38, v3
	v_mov_b32_e32 v39, v7
	v_pk_mul_f32 v[134:135], v[136:137], v[104:105] op_sel_hi:[1,0]
	v_pk_fma_f32 v[14:15], v[24:25], v[124:125], v[20:21]
	v_pk_fma_f32 v[18:19], v[60:61], v[126:127], v[32:33]
	v_pk_fma_f32 v[20:21], v[40:41], v[130:131], v[36:37]
	v_mov_b32_e32 v32, v0
	v_mov_b32_e32 v33, v4
	v_mov_b32_e32 v36, v2
	v_mov_b32_e32 v37, v6
	v_pk_mul_f32 v[40:41], v[10:11], v[10:11]
	v_pk_mul_f32 v[42:43], v[8:9], v[8:9]
	v_pk_mul_f32 v[34:35], v[34:35], v[34:35]
	v_pk_mul_f32 v[38:39], v[38:39], v[38:39]
	v_pk_mul_f32 v[132:133], v[104:105], v[132:133] op_sel_hi:[0,1]
	v_pk_mul_f32 v[106:107], v[104:105], v[106:107] op_sel_hi:[0,1]
	v_pk_fma_f32 v[30:31], v[134:135], v[56:57], v[52:53]
	v_pk_mov_b32 v[56:57], v[42:43], v[40:41] op_sel:[1,0]
	v_mov_b32_e32 v43, v41
	v_pk_fma_f32 v[32:33], v[32:33], v[32:33], v[34:35]
	v_pk_fma_f32 v[34:35], v[36:37], v[36:37], v[38:39]
	v_pk_fma_f32 v[24:25], v[46:47], v[106:107], v[50:51]
	v_pk_fma_f32 v[26:27], v[44:45], v[132:133], v[48:49]
	v_mul_f32_e32 v44, v14, v14
	v_mul_f32_e32 v46, v12, v12
	v_pk_add_f32 v[36:37], v[56:57], v[42:43]
	v_pk_add_f32 v[32:33], v[32:33], v[34:35]
	v_pk_fma_f32 v[40:41], v[14:15], v[14:15], v[44:45] op_sel_hi:[1,1,0]
	v_pk_fma_f32 v[44:45], v[12:13], v[12:13], v[46:47] op_sel_hi:[1,1,0]
	v_pk_add_f32 v[34:35], v[36:37], v[36:37] op_sel_hi:[0,1]
	v_pk_add_f32 v[32:33], v[32:33], v[32:33] op_sel_hi:[0,1]
	v_pk_mul_f32 v[48:49], v[22:23], v[22:23]
	v_pk_mul_f32 v[50:51], v[20:21], v[20:21]
	v_mul_f32_e32 v40, v18, v18
	v_mul_f32_e32 v44, v19, v19
	v_mul_f32_e32 v34, v16, v16
	v_mul_f32_e32 v32, v17, v17
	v_pk_mul_f32 v[104:105], v[108:109], v[104:105] op_sel_hi:[1,0]
	v_pk_mov_b32 v[46:47], v[50:51], v[48:49] op_sel:[1,0]
	v_mov_b32_e32 v51, v49
	v_pk_add_f32 v[36:37], v[40:41], v[44:45]
	v_pk_add_f32 v[32:33], v[34:35], v[32:33]
	v_pk_fma_f32 v[28:29], v[104:105], v[58:59], v[54:55]
	v_mul_f32_e32 v52, v26, v26
	v_mul_f32_e32 v54, v24, v24
	v_pk_add_f32 v[38:39], v[46:47], v[50:51]
	v_pk_add_f32 v[32:33], v[36:37], v[32:33]
	v_pk_fma_f32 v[48:49], v[26:27], v[26:27], v[52:53] op_sel_hi:[1,1,0]
	v_pk_fma_f32 v[52:53], v[24:25], v[24:25], v[54:55] op_sel_hi:[1,1,0]
	v_pk_add_f32 v[38:39], v[38:39], v[38:39] op_sel_hi:[0,1]
	v_pk_add_f32 v[32:33], v[32:33], v[32:33] op_sel_hi:[0,1]
	v_mul_f32_e32 v48, v30, v30
	v_mul_f32_e32 v52, v31, v31
	v_mul_f32_e32 v38, v28, v28
	v_mul_f32_e32 v32, v29, v29
	v_pk_add_f32 v[40:41], v[48:49], v[52:53]
	v_pk_add_f32 v[32:33], v[38:39], v[32:33]
	s_nop 0
	v_pk_add_f32 v[32:33], v[40:41], v[32:33]
	s_nop 0
	v_add_f32_e32 v32, v32, v33
	ds_bpermute_b32 v33, v110, v32
	s_waitcnt lgkmcnt(0)
; __device__ __forceinline__ unsigned pk2(float lo, float hi) { unsigned r; asm("v_cvt_pk_bf16_f32 %0, %1, %2" : "=v"(r) : "v"(lo), "v"(hi)); return r; }
; __device__ __forceinline__ void row_norm_store(const f32x4 (&v)[8], const float* gain, bf16_t* orow, int lane) {
;     float s = 0.f;
; #pragma unroll
;     for (int j = 0; j < 8; ++j) s += (v[j][0] * v[j][0] + v[j][1] * v[j][1]) + (v[j][2] * v[j][2] + v[j][3] * v[j][3]);
;     const float rs = 1.0f / sqrtf(wave_sum(s) * (1.0f / D_MODEL) + EPS);
; #pragma unroll
;     for (int j = 0; j < 8; ++j) { const f32x4 gv = *(const f32x4*)(gain + 4 * lane + 256 * j); const f32x4 y = v[j] * rs * gv;
;         u32x2 w; w.x = pk2(y[0], y[1]); w.y = pk2(y[2], y[3]); *(u32x2*)(orow + 4 * lane + 256 * j) = w; }
	v_add_f32_e32 v32, v32, v33
	ds_bpermute_b32 v33, v111, v32
	s_waitcnt lgkmcnt(0)
	v_add_f32_e32 v32, v32, v33
	ds_bpermute_b32 v33, v112, v32
	s_waitcnt lgkmcnt(0)
	v_add_f32_e32 v32, v32, v33
	ds_bpermute_b32 v33, v113, v32
	s_waitcnt lgkmcnt(0)
	v_add_f32_e32 v32, v32, v33
	ds_bpermute_b32 v33, v114, v32
	s_waitcnt lgkmcnt(0)
	v_add_f32_e32 v32, v32, v33
	ds_bpermute_b32 v33, v115, v32
	s_waitcnt lgkmcnt(0)
	v_add_f32_e32 v32, v32, v33
	v_fmamk_f32 v32, v32, 0x3a000000, v116
	v_mul_f32_e32 v33, 0x4f800000, v32
	v_cmp_gt_f32_e32 vcc, s6, v32
	s_nop 1
	v_cndmask_b32_e32 v32, v32, v33, vcc
	v_sqrt_f32_e32 v33, v32
	s_nop 0
	v_add_u32_e32 v34, -1, v33
	v_add_u32_e32 v35, 1, v33
	v_fma_f32 v36, -v34, v33, v32
	v_fma_f32 v37, -v35, v33, v32
	v_cmp_ge_f32_e64 s[0:1], 0, v36
	s_nop 1
	v_cndmask_b32_e64 v33, v33, v34, s[0:1]
	v_cmp_lt_f32_e64 s[0:1], 0, v37
	s_nop 1
	v_cndmask_b32_e64 v33, v33, v35, s[0:1]
	v_mul_f32_e32 v34, 0x37800000, v33
	v_cndmask_b32_e32 v33, v33, v34, vcc
	v_cmp_class_f32_e32 vcc, v32, v117
	s_nop 1
	v_cndmask_b32_e32 v32, v33, v32, vcc
	v_div_scale_f32 v33, s[0:1], v32, v32, 1.0
	v_rcp_f32_e32 v35, v33
	v_div_scale_f32 v34, vcc, 1.0, v32, 1.0
	v_fma_f32 v36, -v33, v35, 1.0
	v_fmac_f32_e32 v35, v36, v35
	v_mul_f32_e32 v36, v34, v35
	v_fma_f32 v37, -v33, v36, v34
	v_fmac_f32_e32 v36, v37, v35
	v_fma_f32 v33, -v33, v36, v34
	v_div_fmas_f32 v33, v33, v35, v36
	v_div_fixup_f32 v32, v33, v32, 1.0
	v_pk_mul_f32 v[0:1], v[0:1], v[32:33] op_sel_hi:[1,0]
	v_pk_mul_f32 v[2:3], v[2:3], v[32:33] op_sel_hi:[1,0]
	s_waitcnt vmcnt(0)
	v_pk_mul_f32 v[0:1], v[64:65], v[0:1]
	v_pk_mul_f32 v[2:3], v[66:67], v[2:3]
	v_cvt_pk_bf16_f32 v0, v0, v1
	v_pk_mul_f32 v[4:5], v[4:5], v[32:33] op_sel_hi:[1,0]
	v_cvt_pk_bf16_f32 v1, v2, v3
	global_store_dwordx2 v[100:101], v[0:1], off sc0 sc1
	v_pk_mul_f32 v[6:7], v[6:7], v[32:33] op_sel_hi:[1,0]
	v_pk_mul_f32 v[0:1], v[176:177], v[4:5]
	v_pk_mul_f32 v[2:3], v[178:179], v[6:7]
	v_cvt_pk_bf16_f32 v0, v0, v1
	v_pk_mul_f32 v[4:5], v[8:9], v[32:33] op_sel_hi:[1,0]
	v_cvt_pk_bf16_f32 v1, v2, v3
	global_store_dwordx2 v[100:101], v[0:1], off offset:512 sc0 sc1
	v_pk_mul_f32 v[6:7], v[10:11], v[32:33] op_sel_hi:[1,0]
	v_pk_mul_f32 v[0:1], v[180:181], v[4:5]
	v_pk_mul_f32 v[2:3], v[182:183], v[6:7]
	v_cvt_pk_bf16_f32 v0, v0, v1
	v_pk_mul_f32 v[4:5], v[14:15], v[32:33] op_sel_hi:[1,0]
	v_cvt_pk_bf16_f32 v1, v2, v3
	global_store_dwordx2 v[100:101], v[0:1], off offset:1024 sc0 sc1
	v_pk_mul_f32 v[6:7], v[12:13], v[32:33] op_sel_hi:[1,0]
	v_pk_mul_f32 v[0:1], v[184:185], v[4:5]
	v_pk_mul_f32 v[2:3], v[186:187], v[6:7]
	v_cvt_pk_bf16_f32 v0, v0, v1
	v_pk_mul_f32 v[4:5], v[18:19], v[32:33] op_sel_hi:[1,0]
	v_cvt_pk_bf16_f32 v1, v2, v3
	global_store_dwordx2 v[100:101], v[0:1], off offset:1536 sc0 sc1
	v_pk_mul_f32 v[6:7], v[16:17], v[32:33] op_sel_hi:[1,0]
	v_pk_mul_f32 v[0:1], v[188:189], v[4:5]
	v_pk_mul_f32 v[2:3], v[190:191], v[6:7]
	v_cvt_pk_bf16_f32 v0, v0, v1
	v_pk_mul_f32 v[4:5], v[20:21], v[32:33] op_sel_hi:[1,0]
	v_cvt_pk_bf16_f32 v1, v2, v3
	global_store_dwordx2 v[100:101], v[0:1], off offset:2048 sc0 sc1
	v_pk_mul_f32 v[6:7], v[22:23], v[32:33] op_sel_hi:[1,0]
	v_pk_mul_f32 v[0:1], v[4:5], v[192:193]
	v_pk_mul_f32 v[2:3], v[6:7], v[194:195]
	v_cvt_pk_bf16_f32 v0, v0, v1
	v_pk_mul_f32 v[4:5], v[26:27], v[32:33] op_sel_hi:[1,0]
	v_cvt_pk_bf16_f32 v1, v2, v3
	global_store_dwordx2 v[100:101], v[0:1], off offset:2560 sc0 sc1
	v_pk_mul_f32 v[6:7], v[24:25], v[32:33] op_sel_hi:[1,0]
	v_pk_mul_f32 v[0:1], v[4:5], v[196:197]
	v_pk_mul_f32 v[2:3], v[6:7], v[198:199]
	v_cvt_pk_bf16_f32 v0, v0, v1
	v_pk_mul_f32 v[4:5], v[30:31], v[32:33] op_sel_hi:[1,0]
	v_cvt_pk_bf16_f32 v1, v2, v3
	global_store_dwordx2 v[100:101], v[0:1], off offset:3072 sc0 sc1
	v_pk_mul_f32 v[6:7], v[28:29], v[32:33] op_sel_hi:[1,0]
	v_pk_mul_f32 v[0:1], v[4:5], v[200:201]
	v_pk_mul_f32 v[2:3], v[6:7], v[202:203]
	v_cvt_pk_bf16_f32 v0, v0, v1
	s_nop 0
	v_cvt_pk_bf16_f32 v1, v2, v3
	global_store_dwordx2 v[100:101], v[0:1], off offset:3584 sc0 sc1
	s_cbranch_scc1 .LBB0_1091

; __device__ __forceinline__ void resid_rows(const float* prev, const bf16_t* Y, const float* ga, const bf16_t* F, const float* gc, float* xout, const float* gb, bf16_t* hn, int gw, int NGW, int lane) {
;     ...
;         for (int j = 0; j < 8; ++j) { const u32x2 w = *(const u32x2*)(Y + (size_t)m * LDH + 4 * lane + 256 * j); y[j] = (f32x4){bflo(w.x), bfhi(w.x), bflo(w.y), bfhi(w.y)};
;             s += (y[j][0] * y[j][0] + y[j][1] * y[j][1]) + (y[j][2] * y[j][2] + y[j][3] * y[j][3]); }
;         const float rs = 1.0f / sqrtf(wave_sum(s) * (1.0f / D_MODEL) + EPS);
;         f32x4 x1[8];
; #pragma unroll
;         for (int j = 0; j < 8; ++j) { const f32x4 pv = *(const f32x4*)(prev + (size_t)m * D_MODEL + 4 * lane + 256 * j); const f32x4 gv = *(const f32x4*)(ga + 4 * lane + 256 * j);
;             x1[j] = pv + y[j] * rs * gv; }
;         if (F) {
;             float s2 = 0.f;
; #pragma unroll
;             for (int j = 0; j < 8; ++j) { const u32x2 w = *(const u32x2*)(F + (size_t)m * LDH + 4 * lane + 256 * j); y[j] = (f32x4){bflo(w.x), bfhi(w.x), bflo(w.y), bfhi(w.y)};
;                 s2 += (y[j][0] * y[j][0] + y[j][1] * y[j][1]) + (y[j][2] * y[j][2] + y[j][3] * y[j][3]); }
;             const float rs2 = 1.0f / sqrtf(wave_sum(s2) * (1.0f / D_MODEL) + EPS);
.LBB0_1295:
	global_load_dwordx2 v[0:1], v[30:31], off
	global_load_dwordx2 v[2:3], v[30:31], off offset:512
	global_load_dwordx2 v[4:5], v[30:31], off offset:1024
	global_load_dwordx2 v[6:7], v[30:31], off offset:1536
	global_load_dwordx2 v[32:33], v[30:31], off offset:2048
	global_load_dwordx2 v[34:35], v[30:31], off offset:2560
	global_load_dwordx2 v[36:37], v[30:31], off offset:3072
	global_load_dwordx2 v[62:63], v[30:31], off offset:3584
	v_add_co_u32_e32 v38, vcc, s8, v30
	s_waitcnt vmcnt(7)
	v_and_b32_e32 v59, 0xffff0000, v0
	v_addc_co_u32_e32 v39, vcc, 0, v31, vcc
	global_load_dwordx2 v[66:67], v[38:39], off
	global_load_dwordx2 v[70:71], v[38:39], off offset:512
	global_load_dwordx2 v[74:75], v[38:39], off offset:1024
	global_load_dwordx2 v[78:79], v[38:39], off offset:1536
	global_load_dwordx2 v[82:83], v[38:39], off offset:2048
	global_load_dwordx2 v[86:87], v[38:39], off offset:2560
	global_load_dwordx2 v[90:91], v[38:39], off offset:3072
	s_waitcnt lgkmcnt(0)
	global_load_dwordx2 v[104:105], v[38:39], off offset:3584
	v_and_b32_e32 v61, 0xffff0000, v1
	s_waitcnt vmcnt(14)
	v_and_b32_e32 v55, 0xffff0000, v2
	v_and_b32_e32 v57, 0xffff0000, v3
	v_lshlrev_b32_e32 v58, 16, v0
	v_lshlrev_b32_e32 v60, 16, v1
	v_lshlrev_b32_e32 v54, 16, v2
	v_lshlrev_b32_e32 v56, 16, v3
	s_waitcnt vmcnt(13)
	v_and_b32_e32 v51, 0xffff0000, v4
	v_and_b32_e32 v53, 0xffff0000, v5
	s_waitcnt vmcnt(11)
	v_and_b32_e32 v43, 0xffff0000, v32
	v_and_b32_e32 v45, 0xffff0000, v33
	v_mul_f32_e32 v0, v59, v59
	v_mul_f32_e32 v1, v61, v61
	v_mul_f32_e32 v2, v55, v55
	v_mul_f32_e32 v3, v57, v57
	v_lshlrev_b32_e32 v50, 16, v4
	v_lshlrev_b32_e32 v52, 16, v5
	v_lshlrev_b32_e32 v42, 16, v32
	v_lshlrev_b32_e32 v44, 16, v33
	v_mul_f32_e32 v4, v51, v51
	v_mul_f32_e32 v5, v53, v53
	v_mul_f32_e32 v33, v43, v43
	v_mul_f32_e32 v64, v45, v45
	v_fmac_f32_e32 v0, v58, v58
	v_fmac_f32_e32 v1, v60, v60
	v_fmac_f32_e32 v2, v54, v54
	v_fmac_f32_e32 v3, v56, v56
	v_and_b32_e32 v47, 0xffff0000, v6
	v_and_b32_e32 v49, 0xffff0000, v7
	s_waitcnt vmcnt(10)
	v_lshlrev_b32_e32 v38, 16, v34
	v_and_b32_e32 v39, 0xffff0000, v34
	v_lshlrev_b32_e32 v40, 16, v35
	v_and_b32_e32 v41, 0xffff0000, v35
	s_waitcnt vmcnt(9)
	v_lshlrev_b32_e32 v34, 16, v36
	v_and_b32_e32 v35, 0xffff0000, v36
	v_lshlrev_b32_e32 v36, 16, v37
	v_and_b32_e32 v37, 0xffff0000, v37
	v_fmac_f32_e32 v4, v50, v50
	v_fmac_f32_e32 v5, v52, v52
	v_fmac_f32_e32 v33, v42, v42
	v_fmac_f32_e32 v64, v44, v44
	v_add_f32_e32 v0, v0, v1
	v_add_f32_e32 v1, v2, v3
	v_lshlrev_b32_e32 v46, 16, v6
	v_lshlrev_b32_e32 v48, 16, v7
	s_waitcnt vmcnt(8)
	v_lshlrev_b32_e32 v32, 16, v62
	v_mul_f32_e32 v6, v47, v47
	v_mul_f32_e32 v7, v49, v49
	v_mul_f32_e32 v65, v39, v39
	v_mul_f32_e32 v68, v41, v41
	v_mul_f32_e32 v69, v35, v35
	v_mul_f32_e32 v72, v37, v37
	v_add_f32_e32 v2, v4, v5
	v_add_f32_e32 v4, v33, v64
	v_add_f32_e32 v0, v0, v1
	v_and_b32_e32 v33, 0xffff0000, v62
	v_lshlrev_b32_e32 v62, 16, v63
	v_and_b32_e32 v63, 0xffff0000, v63
	v_fmac_f32_e32 v6, v46, v46
	v_fmac_f32_e32 v7, v48, v48
	v_fmac_f32_e32 v65, v38, v38
	v_fmac_f32_e32 v68, v40, v40
	v_fmac_f32_e32 v69, v34, v34
	v_fmac_f32_e32 v72, v36, v36
	v_add_f32_e32 v0, v0, v2
	v_mul_f32_e32 v1, v33, v33
	v_mul_f32_e32 v2, v63, v63
	v_add_f32_e32 v3, v6, v7
	v_add_f32_e32 v5, v65, v68
	v_add_f32_e32 v6, v69, v72
	v_fmac_f32_e32 v1, v32, v32
	v_fmac_f32_e32 v2, v62, v62
	s_waitcnt vmcnt(7)
	v_and_b32_e32 v65, 0xffff0000, v66
	v_and_b32_e32 v69, 0xffff0000, v67
	v_add_f32_e32 v0, v0, v3
	v_add_f32_e32 v1, v1, v2
	v_lshlrev_b32_e32 v64, 16, v66
	v_lshlrev_b32_e32 v68, 16, v67
	v_mul_f32_e32 v2, v65, v65
	v_mul_f32_e32 v3, v69, v69
	v_fmac_f32_e32 v2, v64, v64
	v_fmac_f32_e32 v3, v68, v68
	s_waitcnt vmcnt(6)
	v_lshlrev_b32_e32 v66, 16, v70
	v_and_b32_e32 v67, 0xffff0000, v70
	v_lshlrev_b32_e32 v70, 16, v71
	v_and_b32_e32 v71, 0xffff0000, v71
	v_add_f32_e32 v0, v0, v4
	v_add_f32_e32 v2, v2, v3
	v_mul_f32_e32 v3, v67, v67
	v_mul_f32_e32 v4, v71, v71
	v_fmac_f32_e32 v3, v66, v66
	v_fmac_f32_e32 v4, v70, v70
	v_add_f32_e32 v3, v3, v4
	s_waitcnt vmcnt(5)
	v_lshlrev_b32_e32 v72, 16, v74
	v_and_b32_e32 v73, 0xffff0000, v74
	v_lshlrev_b32_e32 v74, 16, v75
	v_and_b32_e32 v75, 0xffff0000, v75
	v_add_f32_e32 v2, v2, v3
	v_mul_f32_e32 v3, v73, v73
	v_mul_f32_e32 v4, v75, v75
	v_fmac_f32_e32 v3, v72, v72
	v_fmac_f32_e32 v4, v74, v74
	v_add_f32_e32 v3, v3, v4
	s_waitcnt vmcnt(4)
	v_lshlrev_b32_e32 v76, 16, v78
	v_and_b32_e32 v77, 0xffff0000, v78
	v_lshlrev_b32_e32 v78, 16, v79
	v_and_b32_e32 v79, 0xffff0000, v79
	v_add_f32_e32 v2, v2, v3
	v_mul_f32_e32 v3, v77, v77
	v_mul_f32_e32 v4, v79, v79
	v_fmac_f32_e32 v3, v76, v76
	v_fmac_f32_e32 v4, v78, v78
	v_add_f32_e32 v3, v3, v4
	s_waitcnt vmcnt(3)
	v_lshlrev_b32_e32 v80, 16, v82
	v_and_b32_e32 v81, 0xffff0000, v82
	v_lshlrev_b32_e32 v82, 16, v83
	v_and_b32_e32 v83, 0xffff0000, v83
	v_add_f32_e32 v2, v2, v3
	v_mul_f32_e32 v3, v81, v81
	v_mul_f32_e32 v4, v83, v83
	v_fmac_f32_e32 v3, v80, v80
	v_fmac_f32_e32 v4, v82, v82
	v_add_f32_e32 v3, v3, v4
	s_waitcnt vmcnt(2)
	v_and_b32_e32 v85, 0xffff0000, v86
	v_and_b32_e32 v89, 0xffff0000, v87
	v_add_f32_e32 v2, v2, v3
	v_lshlrev_b32_e32 v84, 16, v86
	v_lshlrev_b32_e32 v88, 16, v87
	v_mul_f32_e32 v3, v85, v85
	v_mul_f32_e32 v4, v89, v89
	v_fmac_f32_e32 v3, v84, v84
	v_fmac_f32_e32 v4, v88, v88
	v_add_f32_e32 v3, v3, v4
	s_waitcnt vmcnt(1)
	v_and_b32_e32 v93, 0xffff0000, v90
	v_and_b32_e32 v95, 0xffff0000, v91
	v_add_f32_e32 v2, v2, v3
	v_lshlrev_b32_e32 v92, 16, v90
	v_lshlrev_b32_e32 v94, 16, v91
	v_mul_f32_e32 v3, v93, v93
	v_mul_f32_e32 v4, v95, v95
	v_fmac_f32_e32 v3, v92, v92
	v_fmac_f32_e32 v4, v94, v94
	v_add_f32_e32 v3, v3, v4
	s_waitcnt vmcnt(0)
	v_and_b32_e32 v91, 0xffff0000, v104
	v_and_b32_e32 v87, 0xffff0000, v105
	v_add_f32_e32 v2, v2, v3
	v_lshlrev_b32_e32 v90, 16, v104
	v_lshlrev_b32_e32 v86, 16, v105
	v_mul_f32_e32 v3, v91, v91
	v_mul_f32_e32 v4, v87, v87
	v_add_f32_e32 v0, v0, v5
	v_fmac_f32_e32 v3, v90, v90
	v_fmac_f32_e32 v4, v86, v86
	v_add_f32_e32 v0, v0, v6
	v_add_f32_e32 v3, v3, v4
	v_add_f32_e32 v0, v0, v1
	v_add_f32_e32 v2, v2, v3
	ds_bpermute_b32 v1, v96, v0
	ds_bpermute_b32 v3, v96, v2
	s_and_b64 vcc, exec, s[0:1]
	s_waitcnt lgkmcnt(1)
	v_add_f32_e32 v0, v0, v1
	s_waitcnt lgkmcnt(0)
	v_add_f32_e32 v2, v2, v3
	ds_bpermute_b32 v1, v97, v0
	ds_bpermute_b32 v3, v97, v2
	s_waitcnt lgkmcnt(1)
	v_add_f32_e32 v0, v0, v1
	s_waitcnt lgkmcnt(0)
	v_add_f32_e32 v2, v2, v3
	ds_bpermute_b32 v1, v98, v0
	ds_bpermute_b32 v3, v98, v2
	s_waitcnt lgkmcnt(1)
	v_add_f32_e32 v0, v0, v1
	s_waitcnt lgkmcnt(0)
	v_add_f32_e32 v2, v2, v3
	ds_bpermute_b32 v1, v99, v0
	ds_bpermute_b32 v3, v99, v2
	s_waitcnt lgkmcnt(1)
	v_add_f32_e32 v0, v0, v1
	s_waitcnt lgkmcnt(0)
	v_add_f32_e32 v2, v2, v3
	ds_bpermute_b32 v1, v100, v0
	ds_bpermute_b32 v3, v100, v2
	s_waitcnt lgkmcnt(1)
	v_add_f32_e32 v106, v0, v1
	s_waitcnt lgkmcnt(0)
	v_add_f32_e32 v104, v2, v3
	ds_bpermute_b32 v107, v101, v106
	ds_bpermute_b32 v105, v101, v104
	s_cbranch_vccnz .LBB0_1294
; __device__ __forceinline__ void resid_rows(const float* prev, const bf16_t* Y, const float* ga, const bf16_t* F, const float* gc, float* xout, const float* gb, bf16_t* hn, int gw, int NGW, int lane) {
;     ...
;         const float rs = 1.0f / sqrtf(wave_sum(s) * (1.0f / D_MODEL) + EPS);
;         f32x4 x1[8];
; #pragma unroll
;         for (int j = 0; j < 8; ++j) { const f32x4 pv = *(const f32x4*)(prev + (size_t)m * D_MODEL + 4 * lane + 256 * j); const f32x4 gv = *(const f32x4*)(ga + 4 * lane + 256 * j);
;             x1[j] = pv + y[j] * rs * gv; }
;         if (F) {
;             float s2 = 0.f;
; #pragma unroll
;             for (int j = 0; j < 8; ++j) { const u32x2 w = *(const u32x2*)(F + (size_t)m * LDH + 4 * lane + 256 * j); y[j] = (f32x4){bflo(w.x), bfhi(w.x), bflo(w.y), bfhi(w.y)};
;                 s2 += (y[j][0] * y[j][0] + y[j][1] * y[j][1]) + (y[j][2] * y[j][2] + y[j][3] * y[j][3]); }
;             const float rs2 = 1.0f / sqrtf(wave_sum(s2) * (1.0f / D_MODEL) + EPS);
; #pragma unroll
;             for (int j = 0; j < 8; ++j) { const f32x4 gv = *(const f32x4*)(gc + 4 * lane + 256 * j); x1[j] = x1[j] + y[j] * rs2 * gv; }
	global_load_dwordx4 v[0:3], v[28:29], off offset:-4096
	global_load_dwordx4 v[4:7], v[8:9], off
	s_waitcnt lgkmcnt(1)
	v_add_f32_e32 v184, v106, v107
	s_waitcnt lgkmcnt(0)
	v_add_f32_e32 v185, v104, v105
	v_fmamk_f32 v184, v184, 0x3a000000, v102
	v_fmamk_f32 v185, v185, 0x3a000000, v102
	global_load_dwordx4 v[104:107], v[28:29], off offset:-3072
	global_load_dwordx4 v[108:111], v[8:9], off offset:1024
	global_load_dwordx4 v[112:115], v[10:11], off
	global_load_dwordx4 v[116:119], v[10:11], off offset:1024
	global_load_dwordx4 v[120:123], v[28:29], off offset:-2048
	global_load_dwordx4 v[124:127], v[28:29], off offset:-1024
	global_load_dwordx4 v[128:131], v[8:9], off offset:2048
	global_load_dwordx4 v[132:135], v[8:9], off offset:3072
	global_load_dwordx4 v[136:139], v[10:11], off offset:2048
	global_load_dwordx4 v[140:143], v[10:11], off offset:3072
	global_load_dwordx4 v[144:147], v[28:29], off
	global_load_dwordx4 v[148:151], v[28:29], off offset:1024
	global_load_dwordx4 v[152:155], v[12:13], off
	global_load_dwordx4 v[156:159], v[14:15], off
	global_load_dwordx4 v[160:163], v[20:21], off
	global_load_dwordx4 v[164:167], v[22:23], off
	global_load_dwordx4 v[168:171], v[28:29], off offset:2048
	global_load_dwordx4 v[172:175], v[28:29], off offset:3072
	global_load_dwordx4 v[176:179], v[16:17], off
	global_load_dwordx4 v[180:183], v[18:19], off
	v_mul_f32_e32 v186, 0x4f800000, v184
	v_mul_f32_e32 v187, 0x4f800000, v185
	v_cmp_gt_f32_e32 vcc, s9, v184
	v_cmp_gt_f32_e64 s[2:3], s9, v185
	s_nop 0
	v_cndmask_b32_e32 v192, v184, v186, vcc
	v_cndmask_b32_e64 v193, v185, v187, s[2:3]
	global_load_dwordx4 v[184:187], v[24:25], off
	global_load_dwordx4 v[188:191], v[26:27], off
	v_sqrt_f32_e32 v194, v192
	v_sqrt_f32_e32 v195, v193
	v_add_u32_e32 v196, -1, v194
	v_add_u32_e32 v198, -1, v195
	v_fma_f32 v200, -v196, v194, v192
	v_add_u32_e32 v197, 1, v194
	v_fma_f32 v202, -v198, v195, v193
	v_cmp_ge_f32_e64 s[4:5], 0, v200
	v_add_u32_e32 v199, 1, v195
	v_fma_f32 v201, -v197, v194, v192
	v_cndmask_b32_e64 v194, v194, v196, s[4:5]
	v_cmp_ge_f32_e64 s[4:5], 0, v202
	v_fma_f32 v203, -v199, v195, v193
	s_nop 0
	v_cndmask_b32_e64 v195, v195, v198, s[4:5]
	v_cmp_lt_f32_e64 s[4:5], 0, v201
	s_nop 1
	v_cndmask_b32_e64 v194, v194, v197, s[4:5]
	v_cmp_lt_f32_e64 s[4:5], 0, v203
	v_mul_f32_e32 v196, 0x37800000, v194
	v_cndmask_b32_e32 v194, v194, v196, vcc
	v_cndmask_b32_e64 v195, v195, v199, s[4:5]
	v_cmp_class_f32_e32 vcc, v192, v103
	v_mul_f32_e32 v197, 0x37800000, v195
	v_cndmask_b32_e64 v195, v195, v197, s[2:3]
	v_cndmask_b32_e32 v192, v194, v192, vcc
	v_div_scale_f32 v194, s[2:3], v192, v192, 1.0
	v_rcp_f32_e32 v196, v194
	v_cmp_class_f32_e32 vcc, v193, v103
	v_fma_f32 v199, -v194, v196, 1.0
	s_nop 0
	v_cndmask_b32_e32 v193, v195, v193, vcc
	v_div_scale_f32 v195, vcc, 1.0, v192, 1.0
	v_fmac_f32_e32 v196, v199, v196
	v_mul_f32_e32 v199, v195, v196
	v_fma_f32 v200, -v194, v199, v195
	v_div_scale_f32 v197, s[2:3], v193, v193, 1.0
	v_fmac_f32_e32 v199, v200, v196
	v_rcp_f32_e32 v198, v197
	v_fma_f32 v194, -v194, v199, v195
	v_div_fmas_f32 v194, v194, v196, v199
	v_div_fixup_f32 v192, v194, v192, 1.0
	v_pk_mul_f32 v[58:59], v[58:59], v[192:193] op_sel_hi:[1,0]
	v_pk_mul_f32 v[60:61], v[60:61], v[192:193] op_sel_hi:[1,0]
	v_pk_mul_f32 v[50:51], v[50:51], v[192:193] op_sel_hi:[1,0]
	v_pk_mul_f32 v[52:53], v[52:53], v[192:193] op_sel_hi:[1,0]
	v_pk_mul_f32 v[46:47], v[46:47], v[192:193] op_sel_hi:[1,0]
	v_pk_mul_f32 v[48:49], v[48:49], v[192:193] op_sel_hi:[1,0]
	v_pk_mul_f32 v[42:43], v[42:43], v[192:193] op_sel_hi:[1,0]
	v_pk_mul_f32 v[44:45], v[44:45], v[192:193] op_sel_hi:[1,0]
	v_pk_mul_f32 v[38:39], v[38:39], v[192:193] op_sel_hi:[1,0]
	s_waitcnt vmcnt(15)
	v_pk_fma_f32 v[50:51], v[50:51], v[128:129], v[120:121]
	v_pk_fma_f32 v[52:53], v[52:53], v[130:131], v[122:123]
	s_waitcnt vmcnt(14)
; __device__ __forceinline__ void resid_rows(const float* prev, const bf16_t* Y, const float* ga, const bf16_t* F, const float* gc, float* xout, const float* gb, bf16_t* hn, int gw, int NGW, int lane) {
;     ...
;             for (int j = 0; j < 8; ++j) { const f32x4 gv = *(const f32x4*)(gc + 4 * lane + 256 * j); x1[j] = x1[j] + y[j] * rs2 * gv; }
;         }
;         if (xout) {
; #pragma unroll
;             for (int j = 0; j < 8; ++j) *(f32x4*)(xout + (size_t)m * D_MODEL + 4 * lane + 256 * j) = x1[j]; }
	v_pk_fma_f32 v[46:47], v[46:47], v[132:133], v[124:125]
	v_pk_fma_f32 v[48:49], v[48:49], v[134:135], v[126:127]
	v_pk_mul_f32 v[40:41], v[40:41], v[192:193] op_sel_hi:[1,0]
	v_pk_mul_f32 v[34:35], v[34:35], v[192:193] op_sel_hi:[1,0]
	s_waitcnt vmcnt(9)
	v_pk_fma_f32 v[42:43], v[42:43], v[152:153], v[144:145]
	v_pk_fma_f32 v[44:45], v[44:45], v[154:155], v[146:147]
	v_pk_fma_f32 v[0:1], v[58:59], v[4:5], v[0:1]
	v_fma_f32 v4, -v197, v198, 1.0
	v_fmac_f32_e32 v198, v4, v198
	v_div_scale_f32 v4, vcc, 1.0, v193, 1.0
	v_mul_f32_e32 v5, v4, v198
	v_pk_fma_f32 v[2:3], v[60:61], v[6:7], v[2:3]
	v_fma_f32 v6, -v197, v5, v4
	v_fmac_f32_e32 v5, v6, v198
	v_fma_f32 v4, -v197, v5, v4
	v_div_fmas_f32 v4, v4, v198, v5
	v_div_fixup_f32 v58, v4, v193, 1.0
	v_pk_mul_f32 v[4:5], v[64:65], v[58:59] op_sel_hi:[1,0]
	v_pk_mul_f32 v[6:7], v[68:69], v[58:59] op_sel_hi:[1,0]
	v_pk_fma_f32 v[0:1], v[4:5], v[112:113], v[0:1]
	v_pk_fma_f32 v[2:3], v[6:7], v[114:115], v[2:3]
	v_pk_mul_f32 v[4:5], v[56:57], v[192:193] op_sel_hi:[1,0]
	v_pk_mul_f32 v[6:7], v[54:55], v[192:193] op_sel_hi:[1,0]
	v_pk_fma_f32 v[4:5], v[4:5], v[110:111], v[106:107]
	v_pk_fma_f32 v[54:55], v[6:7], v[108:109], v[104:105]
	v_pk_mul_f32 v[56:57], v[66:67], v[58:59] op_sel_hi:[1,0]
	v_pk_mul_f32 v[6:7], v[70:71], v[58:59] op_sel_hi:[1,0]
	s_waitcnt vmcnt(8)
	v_pk_fma_f32 v[38:39], v[38:39], v[156:157], v[148:149]
	v_pk_fma_f32 v[6:7], v[6:7], v[118:119], v[4:5]
	v_pk_fma_f32 v[4:5], v[56:57], v[116:117], v[54:55]
	v_pk_mul_f32 v[54:55], v[72:73], v[58:59] op_sel_hi:[1,0]
	v_pk_mul_f32 v[56:57], v[74:75], v[58:59] op_sel_hi:[1,0]
	v_pk_fma_f32 v[50:51], v[54:55], v[136:137], v[50:51]
	v_pk_mul_f32 v[54:55], v[76:77], v[58:59] op_sel_hi:[1,0]
	v_pk_fma_f32 v[52:53], v[56:57], v[138:139], v[52:53]
	v_pk_mul_f32 v[56:57], v[78:79], v[58:59] op_sel_hi:[1,0]
	v_pk_fma_f32 v[46:47], v[54:55], v[140:141], v[46:47]
	v_pk_mul_f32 v[54:55], v[80:81], v[58:59] op_sel_hi:[1,0]
	v_pk_fma_f32 v[48:49], v[56:57], v[142:143], v[48:49]
	v_pk_mul_f32 v[56:57], v[82:83], v[58:59] op_sel_hi:[1,0]
	s_waitcnt vmcnt(7)
	v_pk_fma_f32 v[42:43], v[54:55], v[160:161], v[42:43]
	v_pk_mul_f32 v[54:55], v[84:85], v[58:59] op_sel_hi:[1,0]
	v_pk_fma_f32 v[44:45], v[56:57], v[162:163], v[44:45]
	v_pk_fma_f32 v[40:41], v[40:41], v[158:159], v[150:151]
	v_pk_mul_f32 v[56:57], v[88:89], v[58:59] op_sel_hi:[1,0]
	s_waitcnt vmcnt(6)
	v_pk_fma_f32 v[38:39], v[54:55], v[164:165], v[38:39]
	v_pk_mul_f32 v[36:37], v[36:37], v[192:193] op_sel_hi:[1,0]
	s_waitcnt vmcnt(3)
	v_pk_fma_f32 v[34:35], v[34:35], v[176:177], v[168:169]
	v_pk_mul_f32 v[54:55], v[92:93], v[58:59] op_sel_hi:[1,0]
	v_pk_fma_f32 v[40:41], v[56:57], v[166:167], v[40:41]
	v_pk_fma_f32 v[36:37], v[36:37], v[178:179], v[170:171]
	v_pk_mul_f32 v[56:57], v[94:95], v[58:59] op_sel_hi:[1,0]
	s_waitcnt vmcnt(1)
	v_pk_fma_f32 v[34:35], v[54:55], v[184:185], v[34:35]
	v_pk_mul_f32 v[54:55], v[62:63], v[192:193] op_sel_hi:[1,0]
	v_pk_mul_f32 v[32:33], v[32:33], v[192:193] op_sel_hi:[1,0]
	v_pk_fma_f32 v[36:37], v[56:57], v[186:187], v[36:37]
	v_pk_fma_f32 v[32:33], v[32:33], v[180:181], v[172:173]
	v_pk_fma_f32 v[54:55], v[54:55], v[182:183], v[174:175]
	v_pk_mul_f32 v[60:61], v[90:91], v[58:59] op_sel_hi:[1,0]
	v_pk_mul_f32 v[56:57], v[86:87], v[58:59] op_sel_hi:[1,0]
	s_waitcnt vmcnt(0)
	v_pk_fma_f32 v[56:57], v[56:57], v[190:191], v[54:55]
	v_pk_fma_f32 v[54:55], v[60:61], v[188:189], v[32:33]
	global_store_dwordx4 v[28:29], v[0:3], off offset:-4096 sc0 sc1
	global_store_dwordx4 v[28:29], v[4:7], off offset:-3072 sc0 sc1
	global_store_dwordx4 v[28:29], v[50:53], off offset:-2048 sc0 sc1
	global_store_dwordx4 v[28:29], v[46:49], off offset:-1024 sc0 sc1
	global_store_dwordx4 v[28:29], v[42:45], off sc0 sc1
	global_store_dwordx4 v[28:29], v[38:41], off offset:1024 sc0 sc1
	global_store_dwordx4 v[28:29], v[34:37], off offset:2048 sc0 sc1
	global_store_dwordx4 v[28:29], v[54:57], off offset:3072 sc0 sc1
	s_branch .LBB0_1294
